# v35 + GEMM 32-MFMA blocks re-ordered so the src1 fragment is held for 4 consecutive MFMAs (k-step 0 for all 16 tiles, then k-step 1)
# baseline (speedup 1.0000x reference)
.LBB0_274:
	ds_read_b128 v[146:149], v153
	ds_read_b128 v[156:159], v153 offset:1024
	ds_read_b128 v[160:163], v153 offset:2048
	ds_read_b128 v[164:167], v153 offset:3072
	ds_read_b128 v[168:171], v154
	ds_read_b128 v[172:175], v154 offset:1024
	ds_read_b128 v[176:179], v154 offset:2048
	ds_read_b128 v[180:183], v154 offset:3072
	s_add_u32 s34, s76, 0xfff80080
	s_addc_u32 s35, s77, -1
	s_cmp_eq_u32 s85, 28
	s_cselect_b32 s79, s0, s35
	s_cselect_b32 s78, s1, s34
	s_cselect_b32 s35, s67, s84
	s_cselect_b32 s34, s69, s83
	v_lshl_add_u64 v[218:219], s[76:77], 0, v[138:139]
	s_add_i32 m0, s54, 0xc000
	ds_read_b128 v[184:187], v155
	ds_read_b128 v[188:191], v155 offset:1024
	ds_read_b128 v[192:195], v155 offset:2048
	ds_read_b128 v[196:199], v155 offset:3072
	ds_read_b128 v[200:203], v155 offset:4096
	ds_read_b128 v[204:207], v155 offset:5120
	ds_read_b128 v[208:211], v155 offset:6144
	ds_read_b128 v[212:215], v155 offset:7168
	global_load_lds_dwordx4 v[218:219], off
	v_lshl_add_u64 v[218:219], s[76:77], 0, v[140:141]
	s_add_i32 m0, s54, 0xe000
	s_nop 0
	global_load_lds_dwordx4 v[218:219], off
	s_waitcnt vmcnt(8)
	s_waitcnt lgkmcnt(0)
	s_barrier
	s_setprio 1
	s_waitcnt lgkmcnt(0)
	v_mfma_f32_16x16x32_bf16 v[126:129], v[146:149], v[184:187], v[126:129]
	v_mfma_f32_16x16x32_bf16 v[118:121], v[160:163], v[184:187], v[118:121]
	v_mfma_f32_16x16x32_bf16 v[122:125], v[168:171], v[184:187], v[122:125]
	v_mfma_f32_16x16x32_bf16 v[114:117], v[176:179], v[184:187], v[114:117]
	v_mfma_f32_16x16x32_bf16 v[110:113], v[146:149], v[192:195], v[110:113]
	v_mfma_f32_16x16x32_bf16 v[102:105], v[160:163], v[192:195], v[102:105]
	v_mfma_f32_16x16x32_bf16 v[106:109], v[168:171], v[192:195], v[106:109]
	v_mfma_f32_16x16x32_bf16 v[98:101], v[176:179], v[192:195], v[98:101]
	v_mfma_f32_16x16x32_bf16 v[94:97], v[146:149], v[200:203], v[94:97]
	v_mfma_f32_16x16x32_bf16 v[86:89], v[160:163], v[200:203], v[86:89]
	v_mfma_f32_16x16x32_bf16 v[90:93], v[168:171], v[200:203], v[90:93]
	v_mfma_f32_16x16x32_bf16 v[82:85], v[176:179], v[200:203], v[82:85]
	v_mfma_f32_16x16x32_bf16 v[78:81], v[146:149], v[208:211], v[78:81]
	v_mfma_f32_16x16x32_bf16 v[70:73], v[160:163], v[208:211], v[70:73]
	v_mfma_f32_16x16x32_bf16 v[74:77], v[168:171], v[208:211], v[74:77]
	v_mfma_f32_16x16x32_bf16 v[66:69], v[176:179], v[208:211], v[66:69]
	s_setprio 0
	s_setprio 1
	v_mfma_f32_16x16x32_bf16 v[126:129], v[156:159], v[188:191], v[126:129]
	v_mfma_f32_16x16x32_bf16 v[118:121], v[164:167], v[188:191], v[118:121]
	v_mfma_f32_16x16x32_bf16 v[122:125], v[172:175], v[188:191], v[122:125]
	v_mfma_f32_16x16x32_bf16 v[114:117], v[180:183], v[188:191], v[114:117]
	v_mfma_f32_16x16x32_bf16 v[110:113], v[156:159], v[196:199], v[110:113]
	v_mfma_f32_16x16x32_bf16 v[102:105], v[164:167], v[196:199], v[102:105]
	v_mfma_f32_16x16x32_bf16 v[106:109], v[172:175], v[196:199], v[106:109]
	v_mfma_f32_16x16x32_bf16 v[98:101], v[180:183], v[196:199], v[98:101]
	v_mfma_f32_16x16x32_bf16 v[94:97], v[156:159], v[204:207], v[94:97]
	v_mfma_f32_16x16x32_bf16 v[86:89], v[164:167], v[204:207], v[86:89]
	v_mfma_f32_16x16x32_bf16 v[90:93], v[172:175], v[204:207], v[90:93]
	v_mfma_f32_16x16x32_bf16 v[82:85], v[180:183], v[204:207], v[82:85]
	v_mfma_f32_16x16x32_bf16 v[78:81], v[156:159], v[212:215], v[78:81]
	v_mfma_f32_16x16x32_bf16 v[70:73], v[164:167], v[212:215], v[70:73]
	v_mfma_f32_16x16x32_bf16 v[74:77], v[172:175], v[212:215], v[74:77]
	v_mfma_f32_16x16x32_bf16 v[66:69], v[180:183], v[212:215], v[66:69]
	s_setprio 0
	s_barrier
	s_add_i32 s62, s75, s33
	v_lshl_add_u64 v[218:219], s[34:35], 0, v[134:135]
	s_mov_b32 m0, s62
	ds_read_b128 v[184:187], v155 offset:16384
	ds_read_b128 v[188:191], v155 offset:17408
	ds_read_b128 v[192:195], v155 offset:18432
	ds_read_b128 v[196:199], v155 offset:19456
	ds_read_b128 v[200:203], v155 offset:20480
	ds_read_b128 v[204:207], v155 offset:21504
	ds_read_b128 v[208:211], v155 offset:22528
	ds_read_b128 v[212:215], v155 offset:23552
	global_load_lds_dwordx4 v[218:219], off
	s_add_i32 m0, s62, 0x2000
	s_add_u32 s62, s34, 0x80000
	v_lshl_add_u64 v[220:221], s[34:35], 0, v[130:131]
	s_addc_u32 s63, s35, 0
	s_add_i32 s86, s80, s33
	global_load_lds_dwordx4 v[220:221], off
	v_lshl_add_u64 v[222:223], s[62:63], 0, v[134:135]
	s_mov_b32 m0, s86
	v_lshl_add_u64 v[224:225], s[78:79], 0, v[132:133]
	global_load_lds_dwordx4 v[222:223], off
	v_lshl_add_u64 v[222:223], s[62:63], 0, v[130:131]
	s_add_i32 m0, s86, 0x2000
	s_nop 0
	global_load_lds_dwordx4 v[222:223], off
	v_lshl_add_u64 v[222:223], s[78:79], 0, v[136:137]
	s_mov_b32 m0, s54
	s_nop 0
	global_load_lds_dwordx4 v[222:223], off
	s_mov_b32 m0, s55
	s_nop 0
	global_load_lds_dwordx4 v[224:225], off
	s_waitcnt vmcnt(8)
	s_waitcnt lgkmcnt(0)
	s_barrier
	s_setprio 1
	s_waitcnt lgkmcnt(0)
	v_mfma_f32_16x16x32_bf16 v[62:65], v[146:149], v[184:187], v[62:65]
	v_mfma_f32_16x16x32_bf16 v[54:57], v[160:163], v[184:187], v[54:57]
	v_mfma_f32_16x16x32_bf16 v[58:61], v[168:171], v[184:187], v[58:61]
	v_mfma_f32_16x16x32_bf16 v[50:53], v[176:179], v[184:187], v[50:53]
	v_mfma_f32_16x16x32_bf16 v[46:49], v[146:149], v[192:195], v[46:49]
	v_mfma_f32_16x16x32_bf16 v[38:41], v[160:163], v[192:195], v[38:41]
	v_mfma_f32_16x16x32_bf16 v[42:45], v[168:171], v[192:195], v[42:45]
	v_mfma_f32_16x16x32_bf16 v[34:37], v[176:179], v[192:195], v[34:37]
	v_mfma_f32_16x16x32_bf16 v[30:33], v[146:149], v[200:203], v[30:33]
	v_mfma_f32_16x16x32_bf16 v[22:25], v[160:163], v[200:203], v[22:25]
	v_mfma_f32_16x16x32_bf16 v[26:29], v[168:171], v[200:203], v[26:29]
	v_mfma_f32_16x16x32_bf16 v[18:21], v[176:179], v[200:203], v[18:21]
	v_mfma_f32_16x16x32_bf16 v[14:17], v[146:149], v[208:211], v[14:17]
	v_mfma_f32_16x16x32_bf16 v[6:9], v[160:163], v[208:211], v[6:9]
	v_mfma_f32_16x16x32_bf16 v[10:13], v[168:171], v[208:211], v[10:13]
	v_mfma_f32_16x16x32_bf16 v[2:5], v[176:179], v[208:211], v[2:5]
	s_setprio 0
	s_setprio 1
	v_mfma_f32_16x16x32_bf16 v[62:65], v[156:159], v[188:191], v[62:65]
	v_mfma_f32_16x16x32_bf16 v[54:57], v[164:167], v[188:191], v[54:57]
	v_mfma_f32_16x16x32_bf16 v[58:61], v[172:175], v[188:191], v[58:61]
	v_mfma_f32_16x16x32_bf16 v[50:53], v[180:183], v[188:191], v[50:53]
	v_mfma_f32_16x16x32_bf16 v[46:49], v[156:159], v[196:199], v[46:49]
	v_mfma_f32_16x16x32_bf16 v[38:41], v[164:167], v[196:199], v[38:41]
	v_mfma_f32_16x16x32_bf16 v[42:45], v[172:175], v[196:199], v[42:45]
	v_mfma_f32_16x16x32_bf16 v[34:37], v[180:183], v[196:199], v[34:37]
	v_mfma_f32_16x16x32_bf16 v[30:33], v[156:159], v[204:207], v[30:33]
	v_mfma_f32_16x16x32_bf16 v[22:25], v[164:167], v[204:207], v[22:25]
	v_mfma_f32_16x16x32_bf16 v[26:29], v[172:175], v[204:207], v[26:29]
	v_mfma_f32_16x16x32_bf16 v[18:21], v[180:183], v[204:207], v[18:21]
	v_mfma_f32_16x16x32_bf16 v[14:17], v[156:159], v[212:215], v[14:17]
	v_mfma_f32_16x16x32_bf16 v[6:9], v[164:167], v[212:215], v[6:9]
	v_mfma_f32_16x16x32_bf16 v[10:13], v[172:175], v[212:215], v[10:13]
	v_mfma_f32_16x16x32_bf16 v[2:5], v[180:183], v[212:215], v[2:5]
	s_setprio 0
	s_barrier
	s_add_i32 s86, 0, 0x18000
	s_add_i32 s87, 0, 0x1c000
	v_add_u32_e32 v164, s86, v151
	v_add_u32_e32 v180, s87, v151
	ds_read_b128 v[146:149], v164
	ds_read_b128 v[156:159], v164 offset:1024
	ds_read_b128 v[160:163], v164 offset:2048
	ds_read_b128 v[164:167], v164 offset:3072
	ds_read_b128 v[168:171], v180
	ds_read_b128 v[172:175], v180 offset:1024
	ds_read_b128 v[176:179], v180 offset:2048
	ds_read_b128 v[180:183], v180 offset:3072
	s_add_u32 s62, s78, 0x80000
	s_addc_u32 s63, s79, 0
	s_mov_b32 m0, s56
	v_lshl_add_u64 v[226:227], s[62:63], 0, v[136:137]
	ds_read_b128 v[184:187], v155 offset:32768
	ds_read_b128 v[188:191], v155 offset:33792
	ds_read_b128 v[192:195], v155 offset:34816
	ds_read_b128 v[196:199], v155 offset:35840
	ds_read_b128 v[200:203], v155 offset:36864
	ds_read_b128 v[204:207], v155 offset:37888
	ds_read_b128 v[208:211], v155 offset:38912
	ds_read_b128 v[212:215], v155 offset:39936
	global_load_lds_dwordx4 v[226:227], off
	v_lshl_add_u64 v[226:227], s[62:63], 0, v[132:133]
	s_mov_b32 m0, s57
	s_nop 0
	global_load_lds_dwordx4 v[226:227], off
	s_waitcnt vmcnt(8)
	s_waitcnt lgkmcnt(0)
	s_barrier
	s_setprio 1
	s_waitcnt lgkmcnt(0)
	v_mfma_f32_16x16x32_bf16 v[126:129], v[146:149], v[184:187], v[126:129]
	v_mfma_f32_16x16x32_bf16 v[118:121], v[160:163], v[184:187], v[118:121]
	v_mfma_f32_16x16x32_bf16 v[122:125], v[168:171], v[184:187], v[122:125]
	v_mfma_f32_16x16x32_bf16 v[114:117], v[176:179], v[184:187], v[114:117]
	v_mfma_f32_16x16x32_bf16 v[110:113], v[146:149], v[192:195], v[110:113]
	v_mfma_f32_16x16x32_bf16 v[102:105], v[160:163], v[192:195], v[102:105]
	v_mfma_f32_16x16x32_bf16 v[106:109], v[168:171], v[192:195], v[106:109]
	v_mfma_f32_16x16x32_bf16 v[98:101], v[176:179], v[192:195], v[98:101]
	v_mfma_f32_16x16x32_bf16 v[94:97], v[146:149], v[200:203], v[94:97]
	v_mfma_f32_16x16x32_bf16 v[86:89], v[160:163], v[200:203], v[86:89]
	v_mfma_f32_16x16x32_bf16 v[90:93], v[168:171], v[200:203], v[90:93]
	v_mfma_f32_16x16x32_bf16 v[82:85], v[176:179], v[200:203], v[82:85]
	v_mfma_f32_16x16x32_bf16 v[78:81], v[146:149], v[208:211], v[78:81]
	v_mfma_f32_16x16x32_bf16 v[70:73], v[160:163], v[208:211], v[70:73]
	v_mfma_f32_16x16x32_bf16 v[74:77], v[168:171], v[208:211], v[74:77]
	v_mfma_f32_16x16x32_bf16 v[66:69], v[176:179], v[208:211], v[66:69]
	s_setprio 0
	s_setprio 1
	v_mfma_f32_16x16x32_bf16 v[126:129], v[156:159], v[188:191], v[126:129]
	v_mfma_f32_16x16x32_bf16 v[118:121], v[164:167], v[188:191], v[118:121]
	v_mfma_f32_16x16x32_bf16 v[122:125], v[172:175], v[188:191], v[122:125]
	v_mfma_f32_16x16x32_bf16 v[114:117], v[180:183], v[188:191], v[114:117]
	v_mfma_f32_16x16x32_bf16 v[110:113], v[156:159], v[196:199], v[110:113]
	v_mfma_f32_16x16x32_bf16 v[102:105], v[164:167], v[196:199], v[102:105]
	v_mfma_f32_16x16x32_bf16 v[106:109], v[172:175], v[196:199], v[106:109]
	v_mfma_f32_16x16x32_bf16 v[98:101], v[180:183], v[196:199], v[98:101]
	v_mfma_f32_16x16x32_bf16 v[94:97], v[156:159], v[204:207], v[94:97]
	v_mfma_f32_16x16x32_bf16 v[86:89], v[164:167], v[204:207], v[86:89]
	v_mfma_f32_16x16x32_bf16 v[90:93], v[172:175], v[204:207], v[90:93]
	v_mfma_f32_16x16x32_bf16 v[82:85], v[180:183], v[204:207], v[82:85]
	v_mfma_f32_16x16x32_bf16 v[78:81], v[156:159], v[212:215], v[78:81]
	v_mfma_f32_16x16x32_bf16 v[70:73], v[164:167], v[212:215], v[70:73]
	v_mfma_f32_16x16x32_bf16 v[74:77], v[172:175], v[212:215], v[74:77]
	v_mfma_f32_16x16x32_bf16 v[66:69], v[180:183], v[212:215], v[66:69]
	s_setprio 0
	s_barrier
	s_add_i32 s62, s86, s33
	v_lshl_add_u64 v[218:219], v[218:219], 0, s[8:9]
	s_mov_b32 m0, s62
	ds_read_b128 v[184:187], v155 offset:49152
	ds_read_b128 v[188:191], v155 offset:50176
	ds_read_b128 v[192:195], v155 offset:51200
	ds_read_b128 v[196:199], v155 offset:52224
	ds_read_b128 v[200:203], v155 offset:53248
	ds_read_b128 v[204:207], v155 offset:54272
	ds_read_b128 v[208:211], v155 offset:55296
	ds_read_b128 v[212:215], v155 offset:56320
	global_load_lds_dwordx4 v[218:219], off
	s_add_i32 m0, s62, 0x2000
	s_add_u32 s34, s34, 0x80080
	v_lshl_add_u64 v[218:219], v[220:221], 0, s[8:9]
	s_addc_u32 s35, s35, 0
	s_add_i32 s62, s87, s33
	global_load_lds_dwordx4 v[218:219], off
	v_lshl_add_u64 v[218:219], s[34:35], 0, v[134:135]
	s_mov_b32 m0, s62
	s_nop 0
	global_load_lds_dwordx4 v[218:219], off
	v_lshl_add_u64 v[218:219], s[34:35], 0, v[130:131]
	s_add_i32 m0, s62, 0x2000
	s_nop 0
	global_load_lds_dwordx4 v[218:219], off
	v_lshl_add_u64 v[218:219], v[222:223], 0, s[8:9]
	s_mov_b32 m0, s59
	s_nop 0
	global_load_lds_dwordx4 v[218:219], off
	v_lshl_add_u64 v[218:219], v[224:225], 0, s[8:9]
	s_mov_b32 m0, s60
	s_nop 0
	global_load_lds_dwordx4 v[218:219], off
	s_waitcnt vmcnt(8)
	s_waitcnt lgkmcnt(0)
	s_barrier
	s_setprio 1
	s_waitcnt lgkmcnt(0)
	v_mfma_f32_16x16x32_bf16 v[62:65], v[146:149], v[184:187], v[62:65]
	v_mfma_f32_16x16x32_bf16 v[54:57], v[160:163], v[184:187], v[54:57]
	v_mfma_f32_16x16x32_bf16 v[58:61], v[168:171], v[184:187], v[58:61]
	v_mfma_f32_16x16x32_bf16 v[50:53], v[176:179], v[184:187], v[50:53]
	v_mfma_f32_16x16x32_bf16 v[46:49], v[146:149], v[192:195], v[46:49]
	v_mfma_f32_16x16x32_bf16 v[38:41], v[160:163], v[192:195], v[38:41]
	v_mfma_f32_16x16x32_bf16 v[42:45], v[168:171], v[192:195], v[42:45]
	v_mfma_f32_16x16x32_bf16 v[34:37], v[176:179], v[192:195], v[34:37]
	v_mfma_f32_16x16x32_bf16 v[30:33], v[146:149], v[200:203], v[30:33]
	v_mfma_f32_16x16x32_bf16 v[22:25], v[160:163], v[200:203], v[22:25]
	v_mfma_f32_16x16x32_bf16 v[26:29], v[168:171], v[200:203], v[26:29]
	v_mfma_f32_16x16x32_bf16 v[18:21], v[176:179], v[200:203], v[18:21]
	v_mfma_f32_16x16x32_bf16 v[14:17], v[146:149], v[208:211], v[14:17]
	v_mfma_f32_16x16x32_bf16 v[6:9], v[160:163], v[208:211], v[6:9]
	v_mfma_f32_16x16x32_bf16 v[10:13], v[168:171], v[208:211], v[10:13]
	v_mfma_f32_16x16x32_bf16 v[2:5], v[176:179], v[208:211], v[2:5]
	s_setprio 0
	s_setprio 1
	v_mfma_f32_16x16x32_bf16 v[62:65], v[156:159], v[188:191], v[62:65]
	v_mfma_f32_16x16x32_bf16 v[54:57], v[164:167], v[188:191], v[54:57]
	v_mfma_f32_16x16x32_bf16 v[58:61], v[172:175], v[188:191], v[58:61]
	v_mfma_f32_16x16x32_bf16 v[50:53], v[180:183], v[188:191], v[50:53]
	v_mfma_f32_16x16x32_bf16 v[46:49], v[156:159], v[196:199], v[46:49]
	v_mfma_f32_16x16x32_bf16 v[38:41], v[164:167], v[196:199], v[38:41]
	v_mfma_f32_16x16x32_bf16 v[42:45], v[172:175], v[196:199], v[42:45]
	v_mfma_f32_16x16x32_bf16 v[34:37], v[180:183], v[196:199], v[34:37]
	v_mfma_f32_16x16x32_bf16 v[30:33], v[156:159], v[204:207], v[30:33]
	v_mfma_f32_16x16x32_bf16 v[22:25], v[164:167], v[204:207], v[22:25]
	v_mfma_f32_16x16x32_bf16 v[26:29], v[172:175], v[204:207], v[26:29]
	v_mfma_f32_16x16x32_bf16 v[18:21], v[180:183], v[204:207], v[18:21]
	v_mfma_f32_16x16x32_bf16 v[14:17], v[156:159], v[212:215], v[14:17]
	v_mfma_f32_16x16x32_bf16 v[6:9], v[164:167], v[212:215], v[6:9]
	v_mfma_f32_16x16x32_bf16 v[10:13], v[172:175], v[212:215], v[10:13]
	v_mfma_f32_16x16x32_bf16 v[2:5], v[180:183], v[212:215], v[2:5]
	s_setprio 0
	s_barrier
	s_add_i32 s85, s85, 2
	s_add_u32 s76, s76, 0x100
	s_addc_u32 s77, s77, 0
	s_add_u32 s83, s83, 0x100
	s_addc_u32 s84, s84, 0
	s_cmp_gt_u32 s85, 29
	s_cbranch_scc0 .LBB0_274
	v_mov_b32_e32 v160, 0xbfb8aa3b
	s_and_b64 vcc, exec, s[64:65]
	s_cbranch_vccz .LBB0_277
	s_barrier

.LBB0_387:
	ds_read_b128 v[146:149], v154
	ds_read_b128 v[158:161], v154 offset:1024
	ds_read_b128 v[162:165], v154 offset:2048
	ds_read_b128 v[166:169], v154 offset:3072
	ds_read_b128 v[170:173], v155
	ds_read_b128 v[174:177], v155 offset:1024
	ds_read_b128 v[178:181], v155 offset:2048
	ds_read_b128 v[182:185], v155 offset:3072
	s_add_u32 s34, s72, 0xffea0080
	s_addc_u32 s35, s73, -1
	s_cmpk_eq_i32 s81, 0x54
	s_cselect_b32 s75, s5, s35
	s_cselect_b32 s74, s4, s34
	s_cselect_b32 s35, s71, s1
	s_cselect_b32 s34, s70, s0
	v_lshl_add_u64 v[150:151], s[72:73], 0, v[138:139]
	s_add_i32 m0, s53, 0xc000
	ds_read_b128 v[186:189], v156
	ds_read_b128 v[190:193], v156 offset:1024
	ds_read_b128 v[194:197], v156 offset:2048
	ds_read_b128 v[198:201], v156 offset:3072
	ds_read_b128 v[202:205], v156 offset:4096
	ds_read_b128 v[206:209], v156 offset:5120
	ds_read_b128 v[210:213], v156 offset:6144
	ds_read_b128 v[218:221], v156 offset:7168
	global_load_lds_dwordx4 v[150:151], off
	v_lshl_add_u64 v[150:151], s[72:73], 0, v[140:141]
	s_add_i32 m0, s53, 0xe000
	s_nop 0
	global_load_lds_dwordx4 v[150:151], off
	s_waitcnt vmcnt(8)
	s_waitcnt lgkmcnt(0)
	s_barrier
	s_setprio 1
	s_waitcnt lgkmcnt(0)
	v_mfma_f32_16x16x32_bf16 v[126:129], v[146:149], v[186:189], v[126:129]
	v_mfma_f32_16x16x32_bf16 v[122:125], v[162:165], v[186:189], v[122:125]
	v_mfma_f32_16x16x32_bf16 v[110:113], v[170:173], v[186:189], v[110:113]
	v_mfma_f32_16x16x32_bf16 v[106:109], v[178:181], v[186:189], v[106:109]
	v_mfma_f32_16x16x32_bf16 v[118:121], v[146:149], v[194:197], v[118:121]
	v_mfma_f32_16x16x32_bf16 v[114:117], v[162:165], v[194:197], v[114:117]
	v_mfma_f32_16x16x32_bf16 v[102:105], v[170:173], v[194:197], v[102:105]
	v_mfma_f32_16x16x32_bf16 v[98:101], v[178:181], v[194:197], v[98:101]
	v_mfma_f32_16x16x32_bf16 v[94:97], v[146:149], v[202:205], v[94:97]
	v_mfma_f32_16x16x32_bf16 v[90:93], v[162:165], v[202:205], v[90:93]
	v_mfma_f32_16x16x32_bf16 v[78:81], v[170:173], v[202:205], v[78:81]
	v_mfma_f32_16x16x32_bf16 v[74:77], v[178:181], v[202:205], v[74:77]
	v_mfma_f32_16x16x32_bf16 v[86:89], v[146:149], v[210:213], v[86:89]
	v_mfma_f32_16x16x32_bf16 v[82:85], v[162:165], v[210:213], v[82:85]
	v_mfma_f32_16x16x32_bf16 v[70:73], v[170:173], v[210:213], v[70:73]
	v_mfma_f32_16x16x32_bf16 v[66:69], v[178:181], v[210:213], v[66:69]
	s_setprio 0
	s_setprio 1
	v_mfma_f32_16x16x32_bf16 v[126:129], v[158:161], v[190:193], v[126:129]
	v_mfma_f32_16x16x32_bf16 v[122:125], v[166:169], v[190:193], v[122:125]
	v_mfma_f32_16x16x32_bf16 v[110:113], v[174:177], v[190:193], v[110:113]
	v_mfma_f32_16x16x32_bf16 v[106:109], v[182:185], v[190:193], v[106:109]
	v_mfma_f32_16x16x32_bf16 v[118:121], v[158:161], v[198:201], v[118:121]
	v_mfma_f32_16x16x32_bf16 v[114:117], v[166:169], v[198:201], v[114:117]
	v_mfma_f32_16x16x32_bf16 v[102:105], v[174:177], v[198:201], v[102:105]
	v_mfma_f32_16x16x32_bf16 v[98:101], v[182:185], v[198:201], v[98:101]
	v_mfma_f32_16x16x32_bf16 v[94:97], v[158:161], v[206:209], v[94:97]
	v_mfma_f32_16x16x32_bf16 v[90:93], v[166:169], v[206:209], v[90:93]
	v_mfma_f32_16x16x32_bf16 v[78:81], v[174:177], v[206:209], v[78:81]
	v_mfma_f32_16x16x32_bf16 v[74:77], v[182:185], v[206:209], v[74:77]
	v_mfma_f32_16x16x32_bf16 v[86:89], v[158:161], v[218:221], v[86:89]
	v_mfma_f32_16x16x32_bf16 v[82:85], v[166:169], v[218:221], v[82:85]
	v_mfma_f32_16x16x32_bf16 v[70:73], v[174:177], v[218:221], v[70:73]
	v_mfma_f32_16x16x32_bf16 v[66:69], v[182:185], v[218:221], v[66:69]
	s_setprio 0
	s_barrier
	s_add_i32 s62, s61, s52
	v_lshl_add_u64 v[150:151], s[34:35], 0, v[132:133]
	s_mov_b32 m0, s62
	ds_read_b128 v[186:189], v156 offset:16384
	ds_read_b128 v[190:193], v156 offset:17408
	ds_read_b128 v[194:197], v156 offset:18432
	ds_read_b128 v[198:201], v156 offset:19456
	ds_read_b128 v[202:205], v156 offset:20480
	ds_read_b128 v[206:209], v156 offset:21504
	ds_read_b128 v[210:213], v156 offset:22528
	ds_read_b128 v[218:221], v156 offset:23552
	global_load_lds_dwordx4 v[150:151], off
	s_add_i32 m0, s62, 0x2000
	s_add_u32 s62, s34, 0x160000
	v_lshl_add_u64 v[214:215], s[34:35], 0, v[136:137]
	s_addc_u32 s63, s35, 0
	s_add_i32 s82, s76, s52
	global_load_lds_dwordx4 v[214:215], off
	v_lshl_add_u64 v[222:223], s[62:63], 0, v[132:133]
	s_mov_b32 m0, s82
	v_lshl_add_u64 v[224:225], s[74:75], 0, v[134:135]
	global_load_lds_dwordx4 v[222:223], off
	v_lshl_add_u64 v[222:223], s[62:63], 0, v[136:137]
	s_add_i32 m0, s82, 0x2000
	s_nop 0
	global_load_lds_dwordx4 v[222:223], off
	v_lshl_add_u64 v[222:223], s[74:75], 0, v[130:131]
	s_mov_b32 m0, s53
	s_nop 0
	global_load_lds_dwordx4 v[222:223], off
	s_mov_b32 m0, s54
	s_nop 0
	global_load_lds_dwordx4 v[224:225], off
	s_waitcnt vmcnt(8)
	s_waitcnt lgkmcnt(0)
	s_barrier
	s_setprio 1
	s_waitcnt lgkmcnt(0)
	v_mfma_f32_16x16x32_bf16 v[62:65], v[146:149], v[186:189], v[62:65]
	v_mfma_f32_16x16x32_bf16 v[58:61], v[162:165], v[186:189], v[58:61]
	v_mfma_f32_16x16x32_bf16 v[46:49], v[170:173], v[186:189], v[46:49]
	v_mfma_f32_16x16x32_bf16 v[42:45], v[178:181], v[186:189], v[42:45]
	v_mfma_f32_16x16x32_bf16 v[54:57], v[146:149], v[194:197], v[54:57]
	v_mfma_f32_16x16x32_bf16 v[50:53], v[162:165], v[194:197], v[50:53]
	v_mfma_f32_16x16x32_bf16 v[38:41], v[170:173], v[194:197], v[38:41]
	v_mfma_f32_16x16x32_bf16 v[34:37], v[178:181], v[194:197], v[34:37]
	v_mfma_f32_16x16x32_bf16 v[30:33], v[146:149], v[202:205], v[30:33]
	v_mfma_f32_16x16x32_bf16 v[26:29], v[162:165], v[202:205], v[26:29]
	v_mfma_f32_16x16x32_bf16 v[14:17], v[170:173], v[202:205], v[14:17]
	v_mfma_f32_16x16x32_bf16 v[10:13], v[178:181], v[202:205], v[10:13]
	v_mfma_f32_16x16x32_bf16 v[22:25], v[146:149], v[210:213], v[22:25]
	v_mfma_f32_16x16x32_bf16 v[18:21], v[162:165], v[210:213], v[18:21]
	v_mfma_f32_16x16x32_bf16 v[6:9], v[170:173], v[210:213], v[6:9]
	v_mfma_f32_16x16x32_bf16 v[2:5], v[178:181], v[210:213], v[2:5]
	s_setprio 0
	s_setprio 1
	v_mfma_f32_16x16x32_bf16 v[62:65], v[158:161], v[190:193], v[62:65]
	v_mfma_f32_16x16x32_bf16 v[58:61], v[166:169], v[190:193], v[58:61]
	v_mfma_f32_16x16x32_bf16 v[46:49], v[174:177], v[190:193], v[46:49]
	v_mfma_f32_16x16x32_bf16 v[42:45], v[182:185], v[190:193], v[42:45]
	v_mfma_f32_16x16x32_bf16 v[54:57], v[158:161], v[198:201], v[54:57]
	v_mfma_f32_16x16x32_bf16 v[50:53], v[166:169], v[198:201], v[50:53]
	v_mfma_f32_16x16x32_bf16 v[38:41], v[174:177], v[198:201], v[38:41]
	v_mfma_f32_16x16x32_bf16 v[34:37], v[182:185], v[198:201], v[34:37]
	v_mfma_f32_16x16x32_bf16 v[30:33], v[158:161], v[206:209], v[30:33]
	v_mfma_f32_16x16x32_bf16 v[26:29], v[166:169], v[206:209], v[26:29]
	v_mfma_f32_16x16x32_bf16 v[14:17], v[174:177], v[206:209], v[14:17]
	v_mfma_f32_16x16x32_bf16 v[10:13], v[182:185], v[206:209], v[10:13]
	v_mfma_f32_16x16x32_bf16 v[22:25], v[158:161], v[218:221], v[22:25]
	v_mfma_f32_16x16x32_bf16 v[18:21], v[166:169], v[218:221], v[18:21]
	v_mfma_f32_16x16x32_bf16 v[6:9], v[174:177], v[218:221], v[6:9]
	v_mfma_f32_16x16x32_bf16 v[2:5], v[182:185], v[218:221], v[2:5]
	s_setprio 0
	s_barrier
	s_add_i32 s82, 0, 0x18000
	v_add_u32_e32 v157, s82, v152
	s_add_i32 s83, 0, 0x1c000
	ds_read_b128 v[146:149], v157
	ds_read_b128 v[158:161], v157 offset:1024
	ds_read_b128 v[162:165], v157 offset:2048
	ds_read_b128 v[166:169], v157 offset:3072
	v_add_u32_e32 v157, s83, v152
	ds_read_b128 v[170:173], v157
	ds_read_b128 v[174:177], v157 offset:1024
	ds_read_b128 v[178:181], v157 offset:2048
	ds_read_b128 v[182:185], v157 offset:3072
	s_add_u32 s62, s74, 0x160000
	s_addc_u32 s63, s75, 0
	s_mov_b32 m0, s55
	v_lshl_add_u64 v[226:227], s[62:63], 0, v[130:131]
	ds_read_b128 v[186:189], v156 offset:32768
	ds_read_b128 v[190:193], v156 offset:33792
	ds_read_b128 v[194:197], v156 offset:34816
	ds_read_b128 v[198:201], v156 offset:35840
	ds_read_b128 v[202:205], v156 offset:36864
	ds_read_b128 v[206:209], v156 offset:37888
	ds_read_b128 v[210:213], v156 offset:38912
	ds_read_b128 v[218:221], v156 offset:39936
	global_load_lds_dwordx4 v[226:227], off
	v_lshl_add_u64 v[226:227], s[62:63], 0, v[134:135]
	s_mov_b32 m0, s56
	s_nop 0
	global_load_lds_dwordx4 v[226:227], off
	s_waitcnt vmcnt(8)
	s_waitcnt lgkmcnt(0)
	s_barrier
	s_setprio 1
	s_waitcnt lgkmcnt(0)
	v_mfma_f32_16x16x32_bf16 v[126:129], v[146:149], v[186:189], v[126:129]
	v_mfma_f32_16x16x32_bf16 v[122:125], v[162:165], v[186:189], v[122:125]
	v_mfma_f32_16x16x32_bf16 v[110:113], v[170:173], v[186:189], v[110:113]
	v_mfma_f32_16x16x32_bf16 v[106:109], v[178:181], v[186:189], v[106:109]
	v_mfma_f32_16x16x32_bf16 v[118:121], v[146:149], v[194:197], v[118:121]
	v_mfma_f32_16x16x32_bf16 v[114:117], v[162:165], v[194:197], v[114:117]
	v_mfma_f32_16x16x32_bf16 v[102:105], v[170:173], v[194:197], v[102:105]
	v_mfma_f32_16x16x32_bf16 v[98:101], v[178:181], v[194:197], v[98:101]
	v_mfma_f32_16x16x32_bf16 v[94:97], v[146:149], v[202:205], v[94:97]
	v_mfma_f32_16x16x32_bf16 v[90:93], v[162:165], v[202:205], v[90:93]
	v_mfma_f32_16x16x32_bf16 v[78:81], v[170:173], v[202:205], v[78:81]
	v_mfma_f32_16x16x32_bf16 v[74:77], v[178:181], v[202:205], v[74:77]
	v_mfma_f32_16x16x32_bf16 v[86:89], v[146:149], v[210:213], v[86:89]
	v_mfma_f32_16x16x32_bf16 v[82:85], v[162:165], v[210:213], v[82:85]
	v_mfma_f32_16x16x32_bf16 v[70:73], v[170:173], v[210:213], v[70:73]
	v_mfma_f32_16x16x32_bf16 v[66:69], v[178:181], v[210:213], v[66:69]
	s_setprio 0
	s_setprio 1
	v_mfma_f32_16x16x32_bf16 v[126:129], v[158:161], v[190:193], v[126:129]
	v_mfma_f32_16x16x32_bf16 v[122:125], v[166:169], v[190:193], v[122:125]
	v_mfma_f32_16x16x32_bf16 v[110:113], v[174:177], v[190:193], v[110:113]
	v_mfma_f32_16x16x32_bf16 v[106:109], v[182:185], v[190:193], v[106:109]
	v_mfma_f32_16x16x32_bf16 v[118:121], v[158:161], v[198:201], v[118:121]
	v_mfma_f32_16x16x32_bf16 v[114:117], v[166:169], v[198:201], v[114:117]
	v_mfma_f32_16x16x32_bf16 v[102:105], v[174:177], v[198:201], v[102:105]
	v_mfma_f32_16x16x32_bf16 v[98:101], v[182:185], v[198:201], v[98:101]
	v_mfma_f32_16x16x32_bf16 v[94:97], v[158:161], v[206:209], v[94:97]
	v_mfma_f32_16x16x32_bf16 v[90:93], v[166:169], v[206:209], v[90:93]
	v_mfma_f32_16x16x32_bf16 v[78:81], v[174:177], v[206:209], v[78:81]
	v_mfma_f32_16x16x32_bf16 v[74:77], v[182:185], v[206:209], v[74:77]
	v_mfma_f32_16x16x32_bf16 v[86:89], v[158:161], v[218:221], v[86:89]
	v_mfma_f32_16x16x32_bf16 v[82:85], v[166:169], v[218:221], v[82:85]
	v_mfma_f32_16x16x32_bf16 v[70:73], v[174:177], v[218:221], v[70:73]
	v_mfma_f32_16x16x32_bf16 v[66:69], v[182:185], v[218:221], v[66:69]
	s_setprio 0
	s_barrier
	s_add_i32 s62, s82, s52
	v_lshl_add_u64 v[150:151], v[150:151], 0, s[66:67]
	s_mov_b32 m0, s62
	ds_read_b128 v[186:189], v156 offset:49152
	ds_read_b128 v[190:193], v156 offset:50176
	ds_read_b128 v[194:197], v156 offset:51200
	ds_read_b128 v[198:201], v156 offset:52224
	ds_read_b128 v[202:205], v156 offset:53248
	ds_read_b128 v[206:209], v156 offset:54272
	ds_read_b128 v[210:213], v156 offset:55296
	ds_read_b128 v[218:221], v156 offset:56320
	global_load_lds_dwordx4 v[150:151], off
	s_add_i32 m0, s62, 0x2000
	s_add_u32 s34, s34, 0x160080
	v_lshl_add_u64 v[150:151], v[214:215], 0, s[66:67]
	s_addc_u32 s35, s35, 0
	s_add_i32 s62, s83, s52
	global_load_lds_dwordx4 v[150:151], off
	v_lshl_add_u64 v[150:151], s[34:35], 0, v[132:133]
	s_mov_b32 m0, s62
	s_nop 0
	global_load_lds_dwordx4 v[150:151], off
	v_lshl_add_u64 v[150:151], s[34:35], 0, v[136:137]
	s_add_i32 m0, s62, 0x2000
	s_nop 0
	global_load_lds_dwordx4 v[150:151], off
	v_lshl_add_u64 v[150:151], v[222:223], 0, s[66:67]
	s_mov_b32 m0, s58
	s_nop 0
	global_load_lds_dwordx4 v[150:151], off
	v_lshl_add_u64 v[150:151], v[224:225], 0, s[66:67]
	s_mov_b32 m0, s59
	s_nop 0
	global_load_lds_dwordx4 v[150:151], off
	s_waitcnt vmcnt(8)
	s_waitcnt lgkmcnt(0)
	s_barrier
	s_setprio 1
	s_waitcnt lgkmcnt(0)
	v_mfma_f32_16x16x32_bf16 v[62:65], v[146:149], v[186:189], v[62:65]
	v_mfma_f32_16x16x32_bf16 v[58:61], v[162:165], v[186:189], v[58:61]
	v_mfma_f32_16x16x32_bf16 v[46:49], v[170:173], v[186:189], v[46:49]
	v_mfma_f32_16x16x32_bf16 v[42:45], v[178:181], v[186:189], v[42:45]
	v_mfma_f32_16x16x32_bf16 v[54:57], v[146:149], v[194:197], v[54:57]
	v_mfma_f32_16x16x32_bf16 v[50:53], v[162:165], v[194:197], v[50:53]
	v_mfma_f32_16x16x32_bf16 v[38:41], v[170:173], v[194:197], v[38:41]
	v_mfma_f32_16x16x32_bf16 v[34:37], v[178:181], v[194:197], v[34:37]
	v_mfma_f32_16x16x32_bf16 v[30:33], v[146:149], v[202:205], v[30:33]
	v_mfma_f32_16x16x32_bf16 v[26:29], v[162:165], v[202:205], v[26:29]
	v_mfma_f32_16x16x32_bf16 v[14:17], v[170:173], v[202:205], v[14:17]
	v_mfma_f32_16x16x32_bf16 v[10:13], v[178:181], v[202:205], v[10:13]
	v_mfma_f32_16x16x32_bf16 v[22:25], v[146:149], v[210:213], v[22:25]
	v_mfma_f32_16x16x32_bf16 v[18:21], v[162:165], v[210:213], v[18:21]
	v_mfma_f32_16x16x32_bf16 v[6:9], v[170:173], v[210:213], v[6:9]
	v_mfma_f32_16x16x32_bf16 v[2:5], v[178:181], v[210:213], v[2:5]
	s_setprio 0
	s_setprio 1
	v_mfma_f32_16x16x32_bf16 v[62:65], v[158:161], v[190:193], v[62:65]
	v_mfma_f32_16x16x32_bf16 v[58:61], v[166:169], v[190:193], v[58:61]
	v_mfma_f32_16x16x32_bf16 v[46:49], v[174:177], v[190:193], v[46:49]
	v_mfma_f32_16x16x32_bf16 v[42:45], v[182:185], v[190:193], v[42:45]
	v_mfma_f32_16x16x32_bf16 v[54:57], v[158:161], v[198:201], v[54:57]
	v_mfma_f32_16x16x32_bf16 v[50:53], v[166:169], v[198:201], v[50:53]
	v_mfma_f32_16x16x32_bf16 v[38:41], v[174:177], v[198:201], v[38:41]
	v_mfma_f32_16x16x32_bf16 v[34:37], v[182:185], v[198:201], v[34:37]
	v_mfma_f32_16x16x32_bf16 v[30:33], v[158:161], v[206:209], v[30:33]
	v_mfma_f32_16x16x32_bf16 v[26:29], v[166:169], v[206:209], v[26:29]
	v_mfma_f32_16x16x32_bf16 v[14:17], v[174:177], v[206:209], v[14:17]
	v_mfma_f32_16x16x32_bf16 v[10:13], v[182:185], v[206:209], v[10:13]
	v_mfma_f32_16x16x32_bf16 v[22:25], v[158:161], v[218:221], v[22:25]
	v_mfma_f32_16x16x32_bf16 v[18:21], v[166:169], v[218:221], v[18:21]
	v_mfma_f32_16x16x32_bf16 v[6:9], v[174:177], v[218:221], v[6:9]
	v_mfma_f32_16x16x32_bf16 v[2:5], v[182:185], v[218:221], v[2:5]
	s_setprio 0
	s_barrier
	s_add_i32 s81, s81, 2
	s_add_u32 s72, s72, 0x100
	s_addc_u32 s73, s73, 0
	s_add_u32 s0, s0, 0x100
	s_addc_u32 s1, s1, 0
	s_cmpk_gt_u32 s81, 0x55
	s_cbranch_scc0 .LBB0_387
	s_and_b64 vcc, exec, s[68:69]
	s_cbranch_vccz .LBB0_390
	s_barrier

.LBB0_518:
	ds_read_b128 v[160:163], v155
	ds_read_b128 v[164:167], v155 offset:1024
	ds_read_b128 v[168:171], v155 offset:2048
	ds_read_b128 v[172:175], v155 offset:3072
	ds_read_b128 v[176:179], v156
	ds_read_b128 v[180:183], v156 offset:1024
	ds_read_b128 v[184:187], v156 offset:2048
	ds_read_b128 v[188:191], v156 offset:3072
	s_add_u32 s34, s90, 0xfff80080
	s_addc_u32 s35, s91, -1
	s_cmp_eq_u32 s83, 28
	s_cselect_b32 s93, s0, s35
	s_cselect_b32 s92, s1, s34
	s_cselect_b32 s35, s7, s68
	s_cselect_b32 s34, s9, s52
	v_lshl_add_u64 v[152:153], s[90:91], 0, v[144:145]
	s_add_i32 m0, s56, 0xc000
	ds_read_b128 v[192:195], v157
	ds_read_b128 v[196:199], v157 offset:1024
	ds_read_b128 v[200:203], v157 offset:2048
	ds_read_b128 v[204:207], v157 offset:3072
	ds_read_b128 v[208:211], v157 offset:4096
	ds_read_b128 v[212:215], v157 offset:5120
	ds_read_b128 v[218:221], v157 offset:6144
	ds_read_b128 v[222:225], v157 offset:7168
	global_load_lds_dwordx4 v[152:153], off
	v_lshl_add_u64 v[152:153], s[90:91], 0, v[146:147]
	s_add_i32 m0, s56, 0xe000
	s_nop 0
	global_load_lds_dwordx4 v[152:153], off
	s_waitcnt vmcnt(8)
	s_waitcnt lgkmcnt(0)
	s_barrier
	s_setprio 1
	s_waitcnt lgkmcnt(0)
	v_mfma_f32_16x16x32_bf16 v[126:129], v[160:163], v[192:195], v[126:129]
	v_mfma_f32_16x16x32_bf16 v[122:125], v[168:171], v[192:195], v[122:125]
	v_mfma_f32_16x16x32_bf16 v[118:121], v[176:179], v[192:195], v[118:121]
	v_mfma_f32_16x16x32_bf16 v[114:117], v[184:187], v[192:195], v[114:117]
	v_mfma_f32_16x16x32_bf16 v[110:113], v[160:163], v[200:203], v[110:113]
	v_mfma_f32_16x16x32_bf16 v[106:109], v[168:171], v[200:203], v[106:109]
	v_mfma_f32_16x16x32_bf16 v[102:105], v[176:179], v[200:203], v[102:105]
	v_mfma_f32_16x16x32_bf16 v[98:101], v[184:187], v[200:203], v[98:101]
	v_mfma_f32_16x16x32_bf16 v[94:97], v[160:163], v[208:211], v[94:97]
	v_mfma_f32_16x16x32_bf16 v[90:93], v[168:171], v[208:211], v[90:93]
	v_mfma_f32_16x16x32_bf16 v[86:89], v[176:179], v[208:211], v[86:89]
	v_mfma_f32_16x16x32_bf16 v[82:85], v[184:187], v[208:211], v[82:85]
	v_mfma_f32_16x16x32_bf16 v[78:81], v[160:163], v[218:221], v[78:81]
	v_mfma_f32_16x16x32_bf16 v[74:77], v[168:171], v[218:221], v[74:77]
	v_mfma_f32_16x16x32_bf16 v[70:73], v[176:179], v[218:221], v[70:73]
	v_mfma_f32_16x16x32_bf16 v[66:69], v[184:187], v[218:221], v[66:69]
	s_setprio 0
	s_setprio 1
	v_mfma_f32_16x16x32_bf16 v[126:129], v[164:167], v[196:199], v[126:129]
	v_mfma_f32_16x16x32_bf16 v[122:125], v[172:175], v[196:199], v[122:125]
	v_mfma_f32_16x16x32_bf16 v[118:121], v[180:183], v[196:199], v[118:121]
	v_mfma_f32_16x16x32_bf16 v[114:117], v[188:191], v[196:199], v[114:117]
	v_mfma_f32_16x16x32_bf16 v[110:113], v[164:167], v[204:207], v[110:113]
	v_mfma_f32_16x16x32_bf16 v[106:109], v[172:175], v[204:207], v[106:109]
	v_mfma_f32_16x16x32_bf16 v[102:105], v[180:183], v[204:207], v[102:105]
	v_mfma_f32_16x16x32_bf16 v[98:101], v[188:191], v[204:207], v[98:101]
	v_mfma_f32_16x16x32_bf16 v[94:97], v[164:167], v[212:215], v[94:97]
	v_mfma_f32_16x16x32_bf16 v[90:93], v[172:175], v[212:215], v[90:93]
	v_mfma_f32_16x16x32_bf16 v[86:89], v[180:183], v[212:215], v[86:89]
	v_mfma_f32_16x16x32_bf16 v[82:85], v[188:191], v[212:215], v[82:85]
	v_mfma_f32_16x16x32_bf16 v[78:81], v[164:167], v[222:225], v[78:81]
	v_mfma_f32_16x16x32_bf16 v[74:77], v[172:175], v[222:225], v[74:77]
	v_mfma_f32_16x16x32_bf16 v[70:73], v[180:183], v[222:225], v[70:73]
	v_mfma_f32_16x16x32_bf16 v[66:69], v[188:191], v[222:225], v[66:69]
	s_setprio 0
	s_barrier
	s_add_i32 s53, s75, s30
	v_lshl_add_u64 v[152:153], s[34:35], 0, v[132:133]
	s_mov_b32 m0, s53
	ds_read_b128 v[192:195], v157 offset:16384
	ds_read_b128 v[196:199], v157 offset:17408
	ds_read_b128 v[200:203], v157 offset:18432
	ds_read_b128 v[204:207], v157 offset:19456
	ds_read_b128 v[208:211], v157 offset:20480
	ds_read_b128 v[212:215], v157 offset:21504
	ds_read_b128 v[218:221], v157 offset:22528
	ds_read_b128 v[222:225], v157 offset:23552
	global_load_lds_dwordx4 v[152:153], off
	s_add_i32 m0, s53, 0x2000
	s_add_u32 s54, s34, 0x80000
	v_lshl_add_u64 v[226:227], s[34:35], 0, v[136:137]
	s_addc_u32 s55, s35, 0
	s_add_i32 s53, s94, s30
	global_load_lds_dwordx4 v[226:227], off
	v_lshl_add_u64 v[228:229], s[54:55], 0, v[132:133]
	s_mov_b32 m0, s53
	v_lshl_add_u64 v[230:231], s[92:93], 0, v[134:135]
	global_load_lds_dwordx4 v[228:229], off
	v_lshl_add_u64 v[228:229], s[54:55], 0, v[136:137]
	s_add_i32 m0, s53, 0x2000
	s_nop 0
	global_load_lds_dwordx4 v[228:229], off
	v_lshl_add_u64 v[228:229], s[92:93], 0, v[130:131]
	s_mov_b32 m0, s56
	s_nop 0
	global_load_lds_dwordx4 v[228:229], off
	s_mov_b32 m0, s57
	s_nop 0
	global_load_lds_dwordx4 v[230:231], off
	s_waitcnt vmcnt(8)
	s_waitcnt lgkmcnt(0)
	s_barrier
	s_setprio 1
	s_waitcnt lgkmcnt(0)
	v_mfma_f32_16x16x32_bf16 v[62:65], v[160:163], v[192:195], v[62:65]
	v_mfma_f32_16x16x32_bf16 v[58:61], v[168:171], v[192:195], v[58:61]
	v_mfma_f32_16x16x32_bf16 v[54:57], v[176:179], v[192:195], v[54:57]
	v_mfma_f32_16x16x32_bf16 v[50:53], v[184:187], v[192:195], v[50:53]
	v_mfma_f32_16x16x32_bf16 v[46:49], v[160:163], v[200:203], v[46:49]
	v_mfma_f32_16x16x32_bf16 v[42:45], v[168:171], v[200:203], v[42:45]
	v_mfma_f32_16x16x32_bf16 v[38:41], v[176:179], v[200:203], v[38:41]
	v_mfma_f32_16x16x32_bf16 v[34:37], v[184:187], v[200:203], v[34:37]
	v_mfma_f32_16x16x32_bf16 v[30:33], v[160:163], v[208:211], v[30:33]
	v_mfma_f32_16x16x32_bf16 v[26:29], v[168:171], v[208:211], v[26:29]
	v_mfma_f32_16x16x32_bf16 v[22:25], v[176:179], v[208:211], v[22:25]
	v_mfma_f32_16x16x32_bf16 v[18:21], v[184:187], v[208:211], v[18:21]
	v_mfma_f32_16x16x32_bf16 v[14:17], v[160:163], v[218:221], v[14:17]
	v_mfma_f32_16x16x32_bf16 v[10:13], v[168:171], v[218:221], v[10:13]
	v_mfma_f32_16x16x32_bf16 v[6:9], v[176:179], v[218:221], v[6:9]
	v_mfma_f32_16x16x32_bf16 v[2:5], v[184:187], v[218:221], v[2:5]
	s_setprio 0
	s_setprio 1
	v_mfma_f32_16x16x32_bf16 v[62:65], v[164:167], v[196:199], v[62:65]
	v_mfma_f32_16x16x32_bf16 v[58:61], v[172:175], v[196:199], v[58:61]
	v_mfma_f32_16x16x32_bf16 v[54:57], v[180:183], v[196:199], v[54:57]
	v_mfma_f32_16x16x32_bf16 v[50:53], v[188:191], v[196:199], v[50:53]
	v_mfma_f32_16x16x32_bf16 v[46:49], v[164:167], v[204:207], v[46:49]
	v_mfma_f32_16x16x32_bf16 v[42:45], v[172:175], v[204:207], v[42:45]
	v_mfma_f32_16x16x32_bf16 v[38:41], v[180:183], v[204:207], v[38:41]
	v_mfma_f32_16x16x32_bf16 v[34:37], v[188:191], v[204:207], v[34:37]
	v_mfma_f32_16x16x32_bf16 v[30:33], v[164:167], v[212:215], v[30:33]
	v_mfma_f32_16x16x32_bf16 v[26:29], v[172:175], v[212:215], v[26:29]
	v_mfma_f32_16x16x32_bf16 v[22:25], v[180:183], v[212:215], v[22:25]
	v_mfma_f32_16x16x32_bf16 v[18:21], v[188:191], v[212:215], v[18:21]
	v_mfma_f32_16x16x32_bf16 v[14:17], v[164:167], v[222:225], v[14:17]
	v_mfma_f32_16x16x32_bf16 v[10:13], v[172:175], v[222:225], v[10:13]
	v_mfma_f32_16x16x32_bf16 v[6:9], v[180:183], v[222:225], v[6:9]
	v_mfma_f32_16x16x32_bf16 v[2:5], v[188:191], v[222:225], v[2:5]
	s_setprio 0
	s_barrier
	s_add_i32 s53, 0, 0x18000
	v_add_u32_e32 v138, s53, v154
	s_add_i32 s62, 0, 0x1c000
	ds_read_b128 v[160:163], v138
	ds_read_b128 v[164:167], v138 offset:1024
	ds_read_b128 v[168:171], v138 offset:2048
	ds_read_b128 v[172:175], v138 offset:3072
	v_add_u32_e32 v138, s62, v154
	ds_read_b128 v[176:179], v138
	ds_read_b128 v[180:183], v138 offset:1024
	ds_read_b128 v[184:187], v138 offset:2048
	ds_read_b128 v[188:191], v138 offset:3072
	s_add_u32 s54, s92, 0x80000
	s_addc_u32 s55, s93, 0
	s_mov_b32 m0, s58
	v_lshl_add_u64 v[232:233], s[54:55], 0, v[130:131]
	ds_read_b128 v[192:195], v157 offset:32768
	ds_read_b128 v[196:199], v157 offset:33792
	ds_read_b128 v[200:203], v157 offset:34816
	ds_read_b128 v[204:207], v157 offset:35840
	ds_read_b128 v[208:211], v157 offset:36864
	ds_read_b128 v[212:215], v157 offset:37888
	ds_read_b128 v[218:221], v157 offset:38912
	ds_read_b128 v[222:225], v157 offset:39936
	global_load_lds_dwordx4 v[232:233], off
	v_lshl_add_u64 v[232:233], s[54:55], 0, v[134:135]
	s_mov_b32 m0, s59
	s_nop 0
	global_load_lds_dwordx4 v[232:233], off
	s_waitcnt vmcnt(8)
	s_waitcnt lgkmcnt(0)
	s_barrier
	s_setprio 1
	s_waitcnt lgkmcnt(0)
	v_mfma_f32_16x16x32_bf16 v[126:129], v[160:163], v[192:195], v[126:129]
	v_mfma_f32_16x16x32_bf16 v[122:125], v[168:171], v[192:195], v[122:125]
	v_mfma_f32_16x16x32_bf16 v[118:121], v[176:179], v[192:195], v[118:121]
	v_mfma_f32_16x16x32_bf16 v[114:117], v[184:187], v[192:195], v[114:117]
	v_mfma_f32_16x16x32_bf16 v[110:113], v[160:163], v[200:203], v[110:113]
	v_mfma_f32_16x16x32_bf16 v[106:109], v[168:171], v[200:203], v[106:109]
	v_mfma_f32_16x16x32_bf16 v[102:105], v[176:179], v[200:203], v[102:105]
	v_mfma_f32_16x16x32_bf16 v[98:101], v[184:187], v[200:203], v[98:101]
	v_mfma_f32_16x16x32_bf16 v[94:97], v[160:163], v[208:211], v[94:97]
	v_mfma_f32_16x16x32_bf16 v[90:93], v[168:171], v[208:211], v[90:93]
	v_mfma_f32_16x16x32_bf16 v[86:89], v[176:179], v[208:211], v[86:89]
	v_mfma_f32_16x16x32_bf16 v[82:85], v[184:187], v[208:211], v[82:85]
	v_mfma_f32_16x16x32_bf16 v[78:81], v[160:163], v[218:221], v[78:81]
	v_mfma_f32_16x16x32_bf16 v[74:77], v[168:171], v[218:221], v[74:77]
	v_mfma_f32_16x16x32_bf16 v[70:73], v[176:179], v[218:221], v[70:73]
	v_mfma_f32_16x16x32_bf16 v[66:69], v[184:187], v[218:221], v[66:69]
	s_setprio 0
	s_setprio 1
	v_mfma_f32_16x16x32_bf16 v[126:129], v[164:167], v[196:199], v[126:129]
	v_mfma_f32_16x16x32_bf16 v[122:125], v[172:175], v[196:199], v[122:125]
	v_mfma_f32_16x16x32_bf16 v[118:121], v[180:183], v[196:199], v[118:121]
	v_mfma_f32_16x16x32_bf16 v[114:117], v[188:191], v[196:199], v[114:117]
	v_mfma_f32_16x16x32_bf16 v[110:113], v[164:167], v[204:207], v[110:113]
	v_mfma_f32_16x16x32_bf16 v[106:109], v[172:175], v[204:207], v[106:109]
	v_mfma_f32_16x16x32_bf16 v[102:105], v[180:183], v[204:207], v[102:105]
	v_mfma_f32_16x16x32_bf16 v[98:101], v[188:191], v[204:207], v[98:101]
	v_mfma_f32_16x16x32_bf16 v[94:97], v[164:167], v[212:215], v[94:97]
	v_mfma_f32_16x16x32_bf16 v[90:93], v[172:175], v[212:215], v[90:93]
	v_mfma_f32_16x16x32_bf16 v[86:89], v[180:183], v[212:215], v[86:89]
	v_mfma_f32_16x16x32_bf16 v[82:85], v[188:191], v[212:215], v[82:85]
	v_mfma_f32_16x16x32_bf16 v[78:81], v[164:167], v[222:225], v[78:81]
	v_mfma_f32_16x16x32_bf16 v[74:77], v[172:175], v[222:225], v[74:77]
	v_mfma_f32_16x16x32_bf16 v[70:73], v[180:183], v[222:225], v[70:73]
	v_mfma_f32_16x16x32_bf16 v[66:69], v[188:191], v[222:225], v[66:69]
	s_setprio 0
	s_barrier
	s_add_i32 s53, s53, s30
	v_lshl_add_u64 v[152:153], v[152:153], 0, s[76:77]
	s_mov_b32 m0, s53
	ds_read_b128 v[192:195], v157 offset:49152
	ds_read_b128 v[196:199], v157 offset:50176
	ds_read_b128 v[200:203], v157 offset:51200
	ds_read_b128 v[204:207], v157 offset:52224
	ds_read_b128 v[208:211], v157 offset:53248
	ds_read_b128 v[212:215], v157 offset:54272
	ds_read_b128 v[218:221], v157 offset:55296
	ds_read_b128 v[222:225], v157 offset:56320
	global_load_lds_dwordx4 v[152:153], off
	s_add_i32 m0, s53, 0x2000
	s_add_u32 s34, s34, 0x80080
	v_lshl_add_u64 v[152:153], v[226:227], 0, s[76:77]
	s_addc_u32 s35, s35, 0
	s_add_i32 s53, s62, s30
	global_load_lds_dwordx4 v[152:153], off
	v_lshl_add_u64 v[152:153], s[34:35], 0, v[132:133]
	s_mov_b32 m0, s53
	s_nop 0
	global_load_lds_dwordx4 v[152:153], off
	v_lshl_add_u64 v[152:153], s[34:35], 0, v[136:137]
	s_add_i32 m0, s53, 0x2000
	s_nop 0
	global_load_lds_dwordx4 v[152:153], off
	v_lshl_add_u64 v[152:153], v[228:229], 0, s[76:77]
	s_mov_b32 m0, s61
	s_nop 0
	global_load_lds_dwordx4 v[152:153], off
	v_lshl_add_u64 v[152:153], v[230:231], 0, s[76:77]
	s_mov_b32 m0, s72
	s_nop 0
	global_load_lds_dwordx4 v[152:153], off
	s_waitcnt vmcnt(8)
	s_waitcnt lgkmcnt(0)
	s_barrier
	s_setprio 1
	s_waitcnt lgkmcnt(0)
	v_mfma_f32_16x16x32_bf16 v[62:65], v[160:163], v[192:195], v[62:65]
	v_mfma_f32_16x16x32_bf16 v[58:61], v[168:171], v[192:195], v[58:61]
	v_mfma_f32_16x16x32_bf16 v[54:57], v[176:179], v[192:195], v[54:57]
	v_mfma_f32_16x16x32_bf16 v[50:53], v[184:187], v[192:195], v[50:53]
	v_mfma_f32_16x16x32_bf16 v[46:49], v[160:163], v[200:203], v[46:49]
	v_mfma_f32_16x16x32_bf16 v[42:45], v[168:171], v[200:203], v[42:45]
	v_mfma_f32_16x16x32_bf16 v[38:41], v[176:179], v[200:203], v[38:41]
	v_mfma_f32_16x16x32_bf16 v[34:37], v[184:187], v[200:203], v[34:37]
	v_mfma_f32_16x16x32_bf16 v[30:33], v[160:163], v[208:211], v[30:33]
	v_mfma_f32_16x16x32_bf16 v[26:29], v[168:171], v[208:211], v[26:29]
	v_mfma_f32_16x16x32_bf16 v[22:25], v[176:179], v[208:211], v[22:25]
	v_mfma_f32_16x16x32_bf16 v[18:21], v[184:187], v[208:211], v[18:21]
	v_mfma_f32_16x16x32_bf16 v[14:17], v[160:163], v[218:221], v[14:17]
	v_mfma_f32_16x16x32_bf16 v[10:13], v[168:171], v[218:221], v[10:13]
	v_mfma_f32_16x16x32_bf16 v[6:9], v[176:179], v[218:221], v[6:9]
	v_mfma_f32_16x16x32_bf16 v[2:5], v[184:187], v[218:221], v[2:5]
	s_setprio 0
	s_setprio 1
	v_mfma_f32_16x16x32_bf16 v[62:65], v[164:167], v[196:199], v[62:65]
	v_mfma_f32_16x16x32_bf16 v[58:61], v[172:175], v[196:199], v[58:61]
	v_mfma_f32_16x16x32_bf16 v[54:57], v[180:183], v[196:199], v[54:57]
	v_mfma_f32_16x16x32_bf16 v[50:53], v[188:191], v[196:199], v[50:53]
	v_mfma_f32_16x16x32_bf16 v[46:49], v[164:167], v[204:207], v[46:49]
	v_mfma_f32_16x16x32_bf16 v[42:45], v[172:175], v[204:207], v[42:45]
	v_mfma_f32_16x16x32_bf16 v[38:41], v[180:183], v[204:207], v[38:41]
	v_mfma_f32_16x16x32_bf16 v[34:37], v[188:191], v[204:207], v[34:37]
	v_mfma_f32_16x16x32_bf16 v[30:33], v[164:167], v[212:215], v[30:33]
	v_mfma_f32_16x16x32_bf16 v[26:29], v[172:175], v[212:215], v[26:29]
	v_mfma_f32_16x16x32_bf16 v[22:25], v[180:183], v[212:215], v[22:25]
	v_mfma_f32_16x16x32_bf16 v[18:21], v[188:191], v[212:215], v[18:21]
	v_mfma_f32_16x16x32_bf16 v[14:17], v[164:167], v[222:225], v[14:17]
	v_mfma_f32_16x16x32_bf16 v[10:13], v[172:175], v[222:225], v[10:13]
	v_mfma_f32_16x16x32_bf16 v[6:9], v[180:183], v[222:225], v[6:9]
	v_mfma_f32_16x16x32_bf16 v[2:5], v[188:191], v[222:225], v[2:5]
	s_setprio 0
	s_barrier
	s_add_i32 s83, s83, 2
	s_add_u32 s90, s90, 0x100
	s_addc_u32 s91, s91, 0
	s_add_u32 s52, s52, 0x100
	s_addc_u32 s68, s68, 0
	s_cmp_gt_u32 s83, 29
	s_cbranch_scc0 .LBB0_518
	s_and_b64 vcc, exec, s[78:79]
	s_cbranch_vccz .LBB0_521
	s_barrier

.LBB0_685:
	ds_read_b128 v[146:149], v165
	ds_read_b128 v[150:153], v165 offset:1024
	ds_read_b128 v[168:171], v165 offset:2048
	ds_read_b128 v[172:175], v165 offset:3072
	ds_read_b128 v[176:179], v166
	ds_read_b128 v[180:183], v166 offset:1024
	ds_read_b128 v[184:187], v166 offset:2048
	ds_read_b128 v[188:191], v166 offset:3072
	s_add_u32 s34, s84, 0xfffe0080
	s_addc_u32 s35, s85, -1
	s_cmp_eq_u32 s89, 4
	s_cselect_b32 s87, s0, s35
	s_cselect_b32 s86, s1, s34
	s_cselect_b32 s35, s52, s88
	s_cselect_b32 s34, s71, s77
	v_lshl_add_u64 v[226:227], s[84:85], 0, v[138:139]
	s_add_i32 m0, s33, 0xc000
	ds_read_b128 v[192:195], v167
	ds_read_b128 v[196:199], v167 offset:1024
	ds_read_b128 v[200:203], v167 offset:2048
	ds_read_b128 v[204:207], v167 offset:3072
	ds_read_b128 v[208:211], v167 offset:4096
	ds_read_b128 v[212:215], v167 offset:5120
	ds_read_b128 v[218:221], v167 offset:6144
	ds_read_b128 v[222:225], v167 offset:7168
	global_load_lds_dwordx4 v[226:227], off
	v_lshl_add_u64 v[226:227], s[84:85], 0, v[140:141]
	s_add_i32 m0, s33, 0xe000
	s_nop 0
	global_load_lds_dwordx4 v[226:227], off
	s_waitcnt vmcnt(8)
	s_waitcnt lgkmcnt(0)
	s_barrier
	s_setprio 1
	s_waitcnt lgkmcnt(0)
	v_mfma_f32_16x16x32_bf16 v[126:129], v[146:149], v[192:195], v[126:129]
	v_mfma_f32_16x16x32_bf16 v[122:125], v[168:171], v[192:195], v[122:125]
	v_mfma_f32_16x16x32_bf16 v[118:121], v[176:179], v[192:195], v[118:121]
	v_mfma_f32_16x16x32_bf16 v[110:113], v[184:187], v[192:195], v[110:113]
	v_mfma_f32_16x16x32_bf16 v[114:117], v[146:149], v[200:203], v[114:117]
	v_mfma_f32_16x16x32_bf16 v[106:109], v[168:171], v[200:203], v[106:109]
	v_mfma_f32_16x16x32_bf16 v[102:105], v[176:179], v[200:203], v[102:105]
	v_mfma_f32_16x16x32_bf16 v[94:97], v[184:187], v[200:203], v[94:97]
	v_mfma_f32_16x16x32_bf16 v[98:101], v[146:149], v[208:211], v[98:101]
	v_mfma_f32_16x16x32_bf16 v[90:93], v[168:171], v[208:211], v[90:93]
	v_mfma_f32_16x16x32_bf16 v[86:89], v[176:179], v[208:211], v[86:89]
	v_mfma_f32_16x16x32_bf16 v[78:81], v[184:187], v[208:211], v[78:81]
	v_mfma_f32_16x16x32_bf16 v[82:85], v[146:149], v[218:221], v[82:85]
	v_mfma_f32_16x16x32_bf16 v[74:77], v[168:171], v[218:221], v[74:77]
	v_mfma_f32_16x16x32_bf16 v[70:73], v[176:179], v[218:221], v[70:73]
	v_mfma_f32_16x16x32_bf16 v[66:69], v[184:187], v[218:221], v[66:69]
	s_setprio 0
	s_setprio 1
	v_mfma_f32_16x16x32_bf16 v[126:129], v[150:153], v[196:199], v[126:129]
	v_mfma_f32_16x16x32_bf16 v[122:125], v[172:175], v[196:199], v[122:125]
	v_mfma_f32_16x16x32_bf16 v[118:121], v[180:183], v[196:199], v[118:121]
	v_mfma_f32_16x16x32_bf16 v[110:113], v[188:191], v[196:199], v[110:113]
	v_mfma_f32_16x16x32_bf16 v[114:117], v[150:153], v[204:207], v[114:117]
	v_mfma_f32_16x16x32_bf16 v[106:109], v[172:175], v[204:207], v[106:109]
	v_mfma_f32_16x16x32_bf16 v[102:105], v[180:183], v[204:207], v[102:105]
	v_mfma_f32_16x16x32_bf16 v[94:97], v[188:191], v[204:207], v[94:97]
	v_mfma_f32_16x16x32_bf16 v[98:101], v[150:153], v[212:215], v[98:101]
	v_mfma_f32_16x16x32_bf16 v[90:93], v[172:175], v[212:215], v[90:93]
	v_mfma_f32_16x16x32_bf16 v[86:89], v[180:183], v[212:215], v[86:89]
	v_mfma_f32_16x16x32_bf16 v[78:81], v[188:191], v[212:215], v[78:81]
	v_mfma_f32_16x16x32_bf16 v[82:85], v[150:153], v[222:225], v[82:85]
	v_mfma_f32_16x16x32_bf16 v[74:77], v[172:175], v[222:225], v[74:77]
	v_mfma_f32_16x16x32_bf16 v[70:73], v[180:183], v[222:225], v[70:73]
	v_mfma_f32_16x16x32_bf16 v[66:69], v[188:191], v[222:225], v[66:69]
	s_setprio 0
	s_barrier
	s_add_i32 s53, s73, s12
	v_lshl_add_u64 v[226:227], s[34:35], 0, v[132:133]
	s_mov_b32 m0, s53
	ds_read_b128 v[192:195], v167 offset:16384
	ds_read_b128 v[196:199], v167 offset:17408
	ds_read_b128 v[200:203], v167 offset:18432
	ds_read_b128 v[204:207], v167 offset:19456
	ds_read_b128 v[208:211], v167 offset:20480
	ds_read_b128 v[212:215], v167 offset:21504
	ds_read_b128 v[218:221], v167 offset:22528
	ds_read_b128 v[222:225], v167 offset:23552
	global_load_lds_dwordx4 v[226:227], off
	s_add_i32 m0, s53, 0x2000
	s_add_u32 s54, s34, 0x20000
	v_lshl_add_u64 v[228:229], s[34:35], 0, v[136:137]
	s_addc_u32 s55, s35, 0
	s_add_i32 s53, s74, s12
	global_load_lds_dwordx4 v[228:229], off
	v_lshl_add_u64 v[230:231], s[54:55], 0, v[132:133]
	s_mov_b32 m0, s53
	v_lshl_add_u64 v[232:233], s[86:87], 0, v[134:135]
	global_load_lds_dwordx4 v[230:231], off
	v_lshl_add_u64 v[230:231], s[54:55], 0, v[136:137]
	s_add_i32 m0, s53, 0x2000
	s_nop 0
	global_load_lds_dwordx4 v[230:231], off
	v_lshl_add_u64 v[230:231], s[86:87], 0, v[130:131]
	s_mov_b32 m0, s33
	s_nop 0
	global_load_lds_dwordx4 v[230:231], off
	s_mov_b32 m0, s56
	s_nop 0
	global_load_lds_dwordx4 v[232:233], off
	s_waitcnt vmcnt(8)
	s_waitcnt lgkmcnt(0)
	s_barrier
	s_setprio 1
	s_waitcnt lgkmcnt(0)
	v_mfma_f32_16x16x32_bf16 v[62:65], v[146:149], v[192:195], v[62:65]
	v_mfma_f32_16x16x32_bf16 v[58:61], v[168:171], v[192:195], v[58:61]
	v_mfma_f32_16x16x32_bf16 v[54:57], v[176:179], v[192:195], v[54:57]
	v_mfma_f32_16x16x32_bf16 v[46:49], v[184:187], v[192:195], v[46:49]
	v_mfma_f32_16x16x32_bf16 v[50:53], v[146:149], v[200:203], v[50:53]
	v_mfma_f32_16x16x32_bf16 v[42:45], v[168:171], v[200:203], v[42:45]
	v_mfma_f32_16x16x32_bf16 v[38:41], v[176:179], v[200:203], v[38:41]
	v_mfma_f32_16x16x32_bf16 v[30:33], v[184:187], v[200:203], v[30:33]
	v_mfma_f32_16x16x32_bf16 v[34:37], v[146:149], v[208:211], v[34:37]
	v_mfma_f32_16x16x32_bf16 v[26:29], v[168:171], v[208:211], v[26:29]
	v_mfma_f32_16x16x32_bf16 v[22:25], v[176:179], v[208:211], v[22:25]
	v_mfma_f32_16x16x32_bf16 v[14:17], v[184:187], v[208:211], v[14:17]
	v_mfma_f32_16x16x32_bf16 v[18:21], v[146:149], v[218:221], v[18:21]
	v_mfma_f32_16x16x32_bf16 v[10:13], v[168:171], v[218:221], v[10:13]
	v_mfma_f32_16x16x32_bf16 v[6:9], v[176:179], v[218:221], v[6:9]
	v_mfma_f32_16x16x32_bf16 v[2:5], v[184:187], v[218:221], v[2:5]
	s_setprio 0
	s_setprio 1
	v_mfma_f32_16x16x32_bf16 v[62:65], v[150:153], v[196:199], v[62:65]
	v_mfma_f32_16x16x32_bf16 v[58:61], v[172:175], v[196:199], v[58:61]
	v_mfma_f32_16x16x32_bf16 v[54:57], v[180:183], v[196:199], v[54:57]
	v_mfma_f32_16x16x32_bf16 v[46:49], v[188:191], v[196:199], v[46:49]
	v_mfma_f32_16x16x32_bf16 v[50:53], v[150:153], v[204:207], v[50:53]
	v_mfma_f32_16x16x32_bf16 v[42:45], v[172:175], v[204:207], v[42:45]
	v_mfma_f32_16x16x32_bf16 v[38:41], v[180:183], v[204:207], v[38:41]
	v_mfma_f32_16x16x32_bf16 v[30:33], v[188:191], v[204:207], v[30:33]
	v_mfma_f32_16x16x32_bf16 v[34:37], v[150:153], v[212:215], v[34:37]
	v_mfma_f32_16x16x32_bf16 v[26:29], v[172:175], v[212:215], v[26:29]
	v_mfma_f32_16x16x32_bf16 v[22:25], v[180:183], v[212:215], v[22:25]
	v_mfma_f32_16x16x32_bf16 v[14:17], v[188:191], v[212:215], v[14:17]
	v_mfma_f32_16x16x32_bf16 v[18:21], v[150:153], v[222:225], v[18:21]
	v_mfma_f32_16x16x32_bf16 v[10:13], v[172:175], v[222:225], v[10:13]
	v_mfma_f32_16x16x32_bf16 v[6:9], v[180:183], v[222:225], v[6:9]
	v_mfma_f32_16x16x32_bf16 v[2:5], v[188:191], v[222:225], v[2:5]
	s_setprio 0
	s_barrier
	s_add_i32 s53, 0, 0x18000
	s_add_i32 s62, 0, 0x1c000
	v_add_u32_e32 v172, s53, v162
	v_add_u32_e32 v188, s62, v162
	ds_read_b128 v[146:149], v172
	ds_read_b128 v[150:153], v172 offset:1024
	ds_read_b128 v[168:171], v172 offset:2048
	ds_read_b128 v[172:175], v172 offset:3072
	ds_read_b128 v[176:179], v188
	ds_read_b128 v[180:183], v188 offset:1024
	ds_read_b128 v[184:187], v188 offset:2048
	ds_read_b128 v[188:191], v188 offset:3072
	s_add_u32 s54, s86, 0x20000
	s_addc_u32 s55, s87, 0
	s_mov_b32 m0, s57
	v_lshl_add_u64 v[234:235], s[54:55], 0, v[130:131]
	ds_read_b128 v[192:195], v167 offset:32768
	ds_read_b128 v[196:199], v167 offset:33792
	ds_read_b128 v[200:203], v167 offset:34816
	ds_read_b128 v[204:207], v167 offset:35840
	ds_read_b128 v[208:211], v167 offset:36864
	ds_read_b128 v[212:215], v167 offset:37888
	ds_read_b128 v[218:221], v167 offset:38912
	ds_read_b128 v[222:225], v167 offset:39936
	global_load_lds_dwordx4 v[234:235], off
	v_lshl_add_u64 v[234:235], s[54:55], 0, v[134:135]
	s_mov_b32 m0, s58
	s_nop 0
	global_load_lds_dwordx4 v[234:235], off
	s_waitcnt vmcnt(8)
	s_waitcnt lgkmcnt(0)
	s_barrier
	s_setprio 1
	s_waitcnt lgkmcnt(0)
	v_mfma_f32_16x16x32_bf16 v[126:129], v[146:149], v[192:195], v[126:129]
	v_mfma_f32_16x16x32_bf16 v[122:125], v[168:171], v[192:195], v[122:125]
	v_mfma_f32_16x16x32_bf16 v[118:121], v[176:179], v[192:195], v[118:121]
	v_mfma_f32_16x16x32_bf16 v[110:113], v[184:187], v[192:195], v[110:113]
	v_mfma_f32_16x16x32_bf16 v[114:117], v[146:149], v[200:203], v[114:117]
	v_mfma_f32_16x16x32_bf16 v[106:109], v[168:171], v[200:203], v[106:109]
	v_mfma_f32_16x16x32_bf16 v[102:105], v[176:179], v[200:203], v[102:105]
	v_mfma_f32_16x16x32_bf16 v[94:97], v[184:187], v[200:203], v[94:97]
	v_mfma_f32_16x16x32_bf16 v[98:101], v[146:149], v[208:211], v[98:101]
	v_mfma_f32_16x16x32_bf16 v[90:93], v[168:171], v[208:211], v[90:93]
	v_mfma_f32_16x16x32_bf16 v[86:89], v[176:179], v[208:211], v[86:89]
	v_mfma_f32_16x16x32_bf16 v[78:81], v[184:187], v[208:211], v[78:81]
	v_mfma_f32_16x16x32_bf16 v[82:85], v[146:149], v[218:221], v[82:85]
	v_mfma_f32_16x16x32_bf16 v[74:77], v[168:171], v[218:221], v[74:77]
	v_mfma_f32_16x16x32_bf16 v[70:73], v[176:179], v[218:221], v[70:73]
	v_mfma_f32_16x16x32_bf16 v[66:69], v[184:187], v[218:221], v[66:69]
	s_setprio 0
	s_setprio 1
	v_mfma_f32_16x16x32_bf16 v[126:129], v[150:153], v[196:199], v[126:129]
	v_mfma_f32_16x16x32_bf16 v[122:125], v[172:175], v[196:199], v[122:125]
	v_mfma_f32_16x16x32_bf16 v[118:121], v[180:183], v[196:199], v[118:121]
	v_mfma_f32_16x16x32_bf16 v[110:113], v[188:191], v[196:199], v[110:113]
	v_mfma_f32_16x16x32_bf16 v[114:117], v[150:153], v[204:207], v[114:117]
	v_mfma_f32_16x16x32_bf16 v[106:109], v[172:175], v[204:207], v[106:109]
	v_mfma_f32_16x16x32_bf16 v[102:105], v[180:183], v[204:207], v[102:105]
	v_mfma_f32_16x16x32_bf16 v[94:97], v[188:191], v[204:207], v[94:97]
	v_mfma_f32_16x16x32_bf16 v[98:101], v[150:153], v[212:215], v[98:101]
	v_mfma_f32_16x16x32_bf16 v[90:93], v[172:175], v[212:215], v[90:93]
	v_mfma_f32_16x16x32_bf16 v[86:89], v[180:183], v[212:215], v[86:89]
	v_mfma_f32_16x16x32_bf16 v[78:81], v[188:191], v[212:215], v[78:81]
	v_mfma_f32_16x16x32_bf16 v[82:85], v[150:153], v[222:225], v[82:85]
	v_mfma_f32_16x16x32_bf16 v[74:77], v[172:175], v[222:225], v[74:77]
	v_mfma_f32_16x16x32_bf16 v[70:73], v[180:183], v[222:225], v[70:73]
	v_mfma_f32_16x16x32_bf16 v[66:69], v[188:191], v[222:225], v[66:69]
	s_setprio 0
	s_barrier
	s_add_i32 s53, s53, s12
	v_lshl_add_u64 v[226:227], v[226:227], 0, s[8:9]
	s_mov_b32 m0, s53
	ds_read_b128 v[192:195], v167 offset:49152
	ds_read_b128 v[196:199], v167 offset:50176
	ds_read_b128 v[200:203], v167 offset:51200
	ds_read_b128 v[204:207], v167 offset:52224
	ds_read_b128 v[208:211], v167 offset:53248
	ds_read_b128 v[212:215], v167 offset:54272
	ds_read_b128 v[218:221], v167 offset:55296
	ds_read_b128 v[222:225], v167 offset:56320
	global_load_lds_dwordx4 v[226:227], off
	s_add_i32 m0, s53, 0x2000
	s_add_u32 s34, s34, 0x20080
	v_lshl_add_u64 v[226:227], v[228:229], 0, s[8:9]
	s_addc_u32 s35, s35, 0
	s_add_i32 s53, s62, s12
	global_load_lds_dwordx4 v[226:227], off
	v_lshl_add_u64 v[226:227], s[34:35], 0, v[132:133]
	s_mov_b32 m0, s53
	s_nop 0
	global_load_lds_dwordx4 v[226:227], off
	v_lshl_add_u64 v[226:227], s[34:35], 0, v[136:137]
	s_add_i32 m0, s53, 0x2000
	s_nop 0
	global_load_lds_dwordx4 v[226:227], off
	v_lshl_add_u64 v[226:227], v[230:231], 0, s[8:9]
	s_mov_b32 m0, s60
	s_nop 0
	global_load_lds_dwordx4 v[226:227], off
	v_lshl_add_u64 v[226:227], v[232:233], 0, s[8:9]
	s_mov_b32 m0, s61
	s_nop 0
	global_load_lds_dwordx4 v[226:227], off
	s_waitcnt vmcnt(8)
	s_waitcnt lgkmcnt(0)
	s_barrier
	s_setprio 1
	s_waitcnt lgkmcnt(0)
	v_mfma_f32_16x16x32_bf16 v[62:65], v[146:149], v[192:195], v[62:65]
	v_mfma_f32_16x16x32_bf16 v[58:61], v[168:171], v[192:195], v[58:61]
	v_mfma_f32_16x16x32_bf16 v[54:57], v[176:179], v[192:195], v[54:57]
	v_mfma_f32_16x16x32_bf16 v[46:49], v[184:187], v[192:195], v[46:49]
	v_mfma_f32_16x16x32_bf16 v[50:53], v[146:149], v[200:203], v[50:53]
	v_mfma_f32_16x16x32_bf16 v[42:45], v[168:171], v[200:203], v[42:45]
	v_mfma_f32_16x16x32_bf16 v[38:41], v[176:179], v[200:203], v[38:41]
	v_mfma_f32_16x16x32_bf16 v[30:33], v[184:187], v[200:203], v[30:33]
	v_mfma_f32_16x16x32_bf16 v[34:37], v[146:149], v[208:211], v[34:37]
	v_mfma_f32_16x16x32_bf16 v[26:29], v[168:171], v[208:211], v[26:29]
	v_mfma_f32_16x16x32_bf16 v[22:25], v[176:179], v[208:211], v[22:25]
	v_mfma_f32_16x16x32_bf16 v[14:17], v[184:187], v[208:211], v[14:17]
	v_mfma_f32_16x16x32_bf16 v[18:21], v[146:149], v[218:221], v[18:21]
	v_mfma_f32_16x16x32_bf16 v[10:13], v[168:171], v[218:221], v[10:13]
	v_mfma_f32_16x16x32_bf16 v[6:9], v[176:179], v[218:221], v[6:9]
	v_mfma_f32_16x16x32_bf16 v[2:5], v[184:187], v[218:221], v[2:5]
	s_setprio 0
	s_setprio 1
	v_mfma_f32_16x16x32_bf16 v[62:65], v[150:153], v[196:199], v[62:65]
	v_mfma_f32_16x16x32_bf16 v[58:61], v[172:175], v[196:199], v[58:61]
	v_mfma_f32_16x16x32_bf16 v[54:57], v[180:183], v[196:199], v[54:57]
	v_mfma_f32_16x16x32_bf16 v[46:49], v[188:191], v[196:199], v[46:49]
	v_mfma_f32_16x16x32_bf16 v[50:53], v[150:153], v[204:207], v[50:53]
	v_mfma_f32_16x16x32_bf16 v[42:45], v[172:175], v[204:207], v[42:45]
	v_mfma_f32_16x16x32_bf16 v[38:41], v[180:183], v[204:207], v[38:41]
	v_mfma_f32_16x16x32_bf16 v[30:33], v[188:191], v[204:207], v[30:33]
	v_mfma_f32_16x16x32_bf16 v[34:37], v[150:153], v[212:215], v[34:37]
	v_mfma_f32_16x16x32_bf16 v[26:29], v[172:175], v[212:215], v[26:29]
	v_mfma_f32_16x16x32_bf16 v[22:25], v[180:183], v[212:215], v[22:25]
	v_mfma_f32_16x16x32_bf16 v[14:17], v[188:191], v[212:215], v[14:17]
	v_mfma_f32_16x16x32_bf16 v[18:21], v[150:153], v[222:225], v[18:21]
	v_mfma_f32_16x16x32_bf16 v[10:13], v[172:175], v[222:225], v[10:13]
	v_mfma_f32_16x16x32_bf16 v[6:9], v[180:183], v[222:225], v[6:9]
	v_mfma_f32_16x16x32_bf16 v[2:5], v[188:191], v[222:225], v[2:5]
	s_setprio 0
	s_barrier
	s_add_i32 s89, s89, 2
	s_add_u32 s84, s84, 0x100
	s_addc_u32 s85, s85, 0
	s_add_u32 s77, s77, 0x100
	s_addc_u32 s88, s88, 0
	s_cmp_gt_u32 s89, 5
	s_cbranch_scc0 .LBB0_685
	s_and_b64 vcc, exec, s[66:67]
	s_cbranch_vccz .LBB0_688
	s_barrier

.LBB0_715:
	ds_read_b128 v[146:149], v1
	ds_read_b128 v[160:163], v1 offset:1024
	ds_read_b128 v[164:167], v1 offset:2048
	ds_read_b128 v[168:171], v1 offset:3072
	ds_read_b128 v[172:175], v154
	ds_read_b128 v[176:179], v154 offset:1024
	ds_read_b128 v[180:183], v154 offset:2048
	ds_read_b128 v[184:187], v154 offset:3072
	s_add_u32 s34, s84, 0xfffe0080
	s_addc_u32 s35, s85, -1
	s_cmp_eq_u32 s88, 4
	s_cselect_b32 s87, s0, s35
	s_cselect_b32 s86, s1, s34
	s_cselect_b32 s35, s52, s83
	s_cselect_b32 s34, s71, s77
	v_lshl_add_u64 v[150:151], s[84:85], 0, v[138:139]
	s_add_i32 m0, s33, 0xc000
	ds_read_b128 v[188:191], v155
	ds_read_b128 v[192:195], v155 offset:1024
	ds_read_b128 v[196:199], v155 offset:2048
	ds_read_b128 v[200:203], v155 offset:3072
	ds_read_b128 v[204:207], v155 offset:4096
	ds_read_b128 v[208:211], v155 offset:5120
	ds_read_b128 v[212:215], v155 offset:6144
	ds_read_b128 v[218:221], v155 offset:7168
	global_load_lds_dwordx4 v[150:151], off
	v_lshl_add_u64 v[150:151], s[84:85], 0, v[140:141]
	s_add_i32 m0, s33, 0xe000
	s_nop 0
	global_load_lds_dwordx4 v[150:151], off
	s_waitcnt vmcnt(8)
	s_waitcnt lgkmcnt(0)
	s_barrier
	s_setprio 1
	s_waitcnt lgkmcnt(0)
	v_mfma_f32_16x16x32_bf16 v[126:129], v[146:149], v[188:191], v[126:129]
	v_mfma_f32_16x16x32_bf16 v[122:125], v[164:167], v[188:191], v[122:125]
	v_mfma_f32_16x16x32_bf16 v[118:121], v[172:175], v[188:191], v[118:121]
	v_mfma_f32_16x16x32_bf16 v[114:117], v[180:183], v[188:191], v[114:117]
	v_mfma_f32_16x16x32_bf16 v[110:113], v[146:149], v[196:199], v[110:113]
	v_mfma_f32_16x16x32_bf16 v[106:109], v[164:167], v[196:199], v[106:109]
	v_mfma_f32_16x16x32_bf16 v[102:105], v[172:175], v[196:199], v[102:105]
	v_mfma_f32_16x16x32_bf16 v[98:101], v[180:183], v[196:199], v[98:101]
	v_mfma_f32_16x16x32_bf16 v[94:97], v[146:149], v[204:207], v[94:97]
	v_mfma_f32_16x16x32_bf16 v[90:93], v[164:167], v[204:207], v[90:93]
	v_mfma_f32_16x16x32_bf16 v[86:89], v[172:175], v[204:207], v[86:89]
	v_mfma_f32_16x16x32_bf16 v[82:85], v[180:183], v[204:207], v[82:85]
	v_mfma_f32_16x16x32_bf16 v[78:81], v[146:149], v[212:215], v[78:81]
	v_mfma_f32_16x16x32_bf16 v[74:77], v[164:167], v[212:215], v[74:77]
	v_mfma_f32_16x16x32_bf16 v[70:73], v[172:175], v[212:215], v[70:73]
	v_mfma_f32_16x16x32_bf16 v[66:69], v[180:183], v[212:215], v[66:69]
	s_setprio 0
	s_setprio 1
	v_mfma_f32_16x16x32_bf16 v[126:129], v[160:163], v[192:195], v[126:129]
	v_mfma_f32_16x16x32_bf16 v[122:125], v[168:171], v[192:195], v[122:125]
	v_mfma_f32_16x16x32_bf16 v[118:121], v[176:179], v[192:195], v[118:121]
	v_mfma_f32_16x16x32_bf16 v[114:117], v[184:187], v[192:195], v[114:117]
	v_mfma_f32_16x16x32_bf16 v[110:113], v[160:163], v[200:203], v[110:113]
	v_mfma_f32_16x16x32_bf16 v[106:109], v[168:171], v[200:203], v[106:109]
	v_mfma_f32_16x16x32_bf16 v[102:105], v[176:179], v[200:203], v[102:105]
	v_mfma_f32_16x16x32_bf16 v[98:101], v[184:187], v[200:203], v[98:101]
	v_mfma_f32_16x16x32_bf16 v[94:97], v[160:163], v[208:211], v[94:97]
	v_mfma_f32_16x16x32_bf16 v[90:93], v[168:171], v[208:211], v[90:93]
	v_mfma_f32_16x16x32_bf16 v[86:89], v[176:179], v[208:211], v[86:89]
	v_mfma_f32_16x16x32_bf16 v[82:85], v[184:187], v[208:211], v[82:85]
	v_mfma_f32_16x16x32_bf16 v[78:81], v[160:163], v[218:221], v[78:81]
	v_mfma_f32_16x16x32_bf16 v[74:77], v[168:171], v[218:221], v[74:77]
	v_mfma_f32_16x16x32_bf16 v[70:73], v[176:179], v[218:221], v[70:73]
	v_mfma_f32_16x16x32_bf16 v[66:69], v[184:187], v[218:221], v[66:69]
	s_setprio 0
	s_barrier
	s_add_i32 s53, s73, s13
	v_lshl_add_u64 v[150:151], s[34:35], 0, v[132:133]
	s_mov_b32 m0, s53
	ds_read_b128 v[188:191], v155 offset:16384
	ds_read_b128 v[192:195], v155 offset:17408
	ds_read_b128 v[196:199], v155 offset:18432
	ds_read_b128 v[200:203], v155 offset:19456
	ds_read_b128 v[204:207], v155 offset:20480
	ds_read_b128 v[208:211], v155 offset:21504
	ds_read_b128 v[212:215], v155 offset:22528
	ds_read_b128 v[218:221], v155 offset:23552
	global_load_lds_dwordx4 v[150:151], off
	s_add_i32 m0, s53, 0x2000
	s_add_u32 s54, s34, 0x20000
	v_lshl_add_u64 v[222:223], s[34:35], 0, v[136:137]
	s_addc_u32 s55, s35, 0
	s_add_i32 s53, s74, s13
	global_load_lds_dwordx4 v[222:223], off
	v_lshl_add_u64 v[224:225], s[54:55], 0, v[132:133]
	s_mov_b32 m0, s53
	v_lshl_add_u64 v[226:227], s[86:87], 0, v[134:135]
	global_load_lds_dwordx4 v[224:225], off
	v_lshl_add_u64 v[224:225], s[54:55], 0, v[136:137]
	s_add_i32 m0, s53, 0x2000
	s_nop 0
	global_load_lds_dwordx4 v[224:225], off
	v_lshl_add_u64 v[224:225], s[86:87], 0, v[130:131]
	s_mov_b32 m0, s33
	s_nop 0
	global_load_lds_dwordx4 v[224:225], off
	s_mov_b32 m0, s56
	s_nop 0
	global_load_lds_dwordx4 v[226:227], off
	s_waitcnt vmcnt(8)
	s_waitcnt lgkmcnt(0)
	s_barrier
	s_setprio 1
	s_waitcnt lgkmcnt(0)
	v_mfma_f32_16x16x32_bf16 v[62:65], v[146:149], v[188:191], v[62:65]
	v_mfma_f32_16x16x32_bf16 v[58:61], v[164:167], v[188:191], v[58:61]
	v_mfma_f32_16x16x32_bf16 v[54:57], v[172:175], v[188:191], v[54:57]
	v_mfma_f32_16x16x32_bf16 v[46:49], v[180:183], v[188:191], v[46:49]
	v_mfma_f32_16x16x32_bf16 v[50:53], v[146:149], v[196:199], v[50:53]
	v_mfma_f32_16x16x32_bf16 v[42:45], v[164:167], v[196:199], v[42:45]
	v_mfma_f32_16x16x32_bf16 v[38:41], v[172:175], v[196:199], v[38:41]
	v_mfma_f32_16x16x32_bf16 v[30:33], v[180:183], v[196:199], v[30:33]
	v_mfma_f32_16x16x32_bf16 v[34:37], v[146:149], v[204:207], v[34:37]
	v_mfma_f32_16x16x32_bf16 v[26:29], v[164:167], v[204:207], v[26:29]
	v_mfma_f32_16x16x32_bf16 v[22:25], v[172:175], v[204:207], v[22:25]
	v_mfma_f32_16x16x32_bf16 v[14:17], v[180:183], v[204:207], v[14:17]
	v_mfma_f32_16x16x32_bf16 v[18:21], v[146:149], v[212:215], v[18:21]
	v_mfma_f32_16x16x32_bf16 v[10:13], v[164:167], v[212:215], v[10:13]
	v_mfma_f32_16x16x32_bf16 v[6:9], v[172:175], v[212:215], v[6:9]
	v_mfma_f32_16x16x32_bf16 v[2:5], v[180:183], v[212:215], v[2:5]
	s_setprio 0
	s_setprio 1
	v_mfma_f32_16x16x32_bf16 v[62:65], v[160:163], v[192:195], v[62:65]
	v_mfma_f32_16x16x32_bf16 v[58:61], v[168:171], v[192:195], v[58:61]
	v_mfma_f32_16x16x32_bf16 v[54:57], v[176:179], v[192:195], v[54:57]
	v_mfma_f32_16x16x32_bf16 v[46:49], v[184:187], v[192:195], v[46:49]
	v_mfma_f32_16x16x32_bf16 v[50:53], v[160:163], v[200:203], v[50:53]
	v_mfma_f32_16x16x32_bf16 v[42:45], v[168:171], v[200:203], v[42:45]
	v_mfma_f32_16x16x32_bf16 v[38:41], v[176:179], v[200:203], v[38:41]
	v_mfma_f32_16x16x32_bf16 v[30:33], v[184:187], v[200:203], v[30:33]
	v_mfma_f32_16x16x32_bf16 v[34:37], v[160:163], v[208:211], v[34:37]
	v_mfma_f32_16x16x32_bf16 v[26:29], v[168:171], v[208:211], v[26:29]
	v_mfma_f32_16x16x32_bf16 v[22:25], v[176:179], v[208:211], v[22:25]
	v_mfma_f32_16x16x32_bf16 v[14:17], v[184:187], v[208:211], v[14:17]
	v_mfma_f32_16x16x32_bf16 v[18:21], v[160:163], v[218:221], v[18:21]
	v_mfma_f32_16x16x32_bf16 v[10:13], v[168:171], v[218:221], v[10:13]
	v_mfma_f32_16x16x32_bf16 v[6:9], v[176:179], v[218:221], v[6:9]
	v_mfma_f32_16x16x32_bf16 v[2:5], v[184:187], v[218:221], v[2:5]
	s_setprio 0
	s_barrier
	s_add_i32 s53, 0, 0x18000
	v_add_u32_e32 v156, s53, v153
	s_add_i32 s62, 0, 0x1c000
	ds_read_b128 v[146:149], v156
	ds_read_b128 v[160:163], v156 offset:1024
	ds_read_b128 v[164:167], v156 offset:2048
	ds_read_b128 v[168:171], v156 offset:3072
	v_add_u32_e32 v156, s62, v153
	ds_read_b128 v[172:175], v156
	ds_read_b128 v[176:179], v156 offset:1024
	ds_read_b128 v[180:183], v156 offset:2048
	ds_read_b128 v[184:187], v156 offset:3072
	s_add_u32 s54, s86, 0x20000
	s_addc_u32 s55, s87, 0
	s_mov_b32 m0, s57
	v_lshl_add_u64 v[228:229], s[54:55], 0, v[130:131]
	ds_read_b128 v[188:191], v155 offset:32768
	ds_read_b128 v[192:195], v155 offset:33792
	ds_read_b128 v[196:199], v155 offset:34816
	ds_read_b128 v[200:203], v155 offset:35840
	ds_read_b128 v[204:207], v155 offset:36864
	ds_read_b128 v[208:211], v155 offset:37888
	ds_read_b128 v[212:215], v155 offset:38912
	ds_read_b128 v[218:221], v155 offset:39936
	global_load_lds_dwordx4 v[228:229], off
	v_lshl_add_u64 v[228:229], s[54:55], 0, v[134:135]
	s_mov_b32 m0, s58
	s_nop 0
	global_load_lds_dwordx4 v[228:229], off
	s_waitcnt vmcnt(8)
	s_waitcnt lgkmcnt(0)
	s_barrier
	s_setprio 1
	s_waitcnt lgkmcnt(0)
	v_mfma_f32_16x16x32_bf16 v[126:129], v[146:149], v[188:191], v[126:129]
	v_mfma_f32_16x16x32_bf16 v[122:125], v[164:167], v[188:191], v[122:125]
	v_mfma_f32_16x16x32_bf16 v[118:121], v[172:175], v[188:191], v[118:121]
	v_mfma_f32_16x16x32_bf16 v[114:117], v[180:183], v[188:191], v[114:117]
	v_mfma_f32_16x16x32_bf16 v[110:113], v[146:149], v[196:199], v[110:113]
	v_mfma_f32_16x16x32_bf16 v[106:109], v[164:167], v[196:199], v[106:109]
	v_mfma_f32_16x16x32_bf16 v[102:105], v[172:175], v[196:199], v[102:105]
	v_mfma_f32_16x16x32_bf16 v[98:101], v[180:183], v[196:199], v[98:101]
	v_mfma_f32_16x16x32_bf16 v[94:97], v[146:149], v[204:207], v[94:97]
	v_mfma_f32_16x16x32_bf16 v[90:93], v[164:167], v[204:207], v[90:93]
	v_mfma_f32_16x16x32_bf16 v[86:89], v[172:175], v[204:207], v[86:89]
	v_mfma_f32_16x16x32_bf16 v[82:85], v[180:183], v[204:207], v[82:85]
	v_mfma_f32_16x16x32_bf16 v[78:81], v[146:149], v[212:215], v[78:81]
	v_mfma_f32_16x16x32_bf16 v[74:77], v[164:167], v[212:215], v[74:77]
	v_mfma_f32_16x16x32_bf16 v[70:73], v[172:175], v[212:215], v[70:73]
	v_mfma_f32_16x16x32_bf16 v[66:69], v[180:183], v[212:215], v[66:69]
	s_setprio 0
	s_setprio 1
	v_mfma_f32_16x16x32_bf16 v[126:129], v[160:163], v[192:195], v[126:129]
	v_mfma_f32_16x16x32_bf16 v[122:125], v[168:171], v[192:195], v[122:125]
	v_mfma_f32_16x16x32_bf16 v[118:121], v[176:179], v[192:195], v[118:121]
	v_mfma_f32_16x16x32_bf16 v[114:117], v[184:187], v[192:195], v[114:117]
	v_mfma_f32_16x16x32_bf16 v[110:113], v[160:163], v[200:203], v[110:113]
	v_mfma_f32_16x16x32_bf16 v[106:109], v[168:171], v[200:203], v[106:109]
	v_mfma_f32_16x16x32_bf16 v[102:105], v[176:179], v[200:203], v[102:105]
	v_mfma_f32_16x16x32_bf16 v[98:101], v[184:187], v[200:203], v[98:101]
	v_mfma_f32_16x16x32_bf16 v[94:97], v[160:163], v[208:211], v[94:97]
	v_mfma_f32_16x16x32_bf16 v[90:93], v[168:171], v[208:211], v[90:93]
	v_mfma_f32_16x16x32_bf16 v[86:89], v[176:179], v[208:211], v[86:89]
	v_mfma_f32_16x16x32_bf16 v[82:85], v[184:187], v[208:211], v[82:85]
	v_mfma_f32_16x16x32_bf16 v[78:81], v[160:163], v[218:221], v[78:81]
	v_mfma_f32_16x16x32_bf16 v[74:77], v[168:171], v[218:221], v[74:77]
	v_mfma_f32_16x16x32_bf16 v[70:73], v[176:179], v[218:221], v[70:73]
	v_mfma_f32_16x16x32_bf16 v[66:69], v[184:187], v[218:221], v[66:69]
	s_setprio 0
	s_barrier
	s_add_i32 s53, s53, s13
	v_lshl_add_u64 v[150:151], v[150:151], 0, s[8:9]
	s_mov_b32 m0, s53
	ds_read_b128 v[188:191], v155 offset:49152
	ds_read_b128 v[192:195], v155 offset:50176
	ds_read_b128 v[196:199], v155 offset:51200
	ds_read_b128 v[200:203], v155 offset:52224
	ds_read_b128 v[204:207], v155 offset:53248
	ds_read_b128 v[208:211], v155 offset:54272
	ds_read_b128 v[212:215], v155 offset:55296
	ds_read_b128 v[218:221], v155 offset:56320
	global_load_lds_dwordx4 v[150:151], off
	s_add_i32 m0, s53, 0x2000
	s_add_u32 s34, s34, 0x20080
	v_lshl_add_u64 v[150:151], v[222:223], 0, s[8:9]
	s_addc_u32 s35, s35, 0
	s_add_i32 s53, s62, s13
	global_load_lds_dwordx4 v[150:151], off
	v_lshl_add_u64 v[150:151], s[34:35], 0, v[132:133]
	s_mov_b32 m0, s53
	s_nop 0
	global_load_lds_dwordx4 v[150:151], off
	v_lshl_add_u64 v[150:151], s[34:35], 0, v[136:137]
	s_add_i32 m0, s53, 0x2000
	s_nop 0
	global_load_lds_dwordx4 v[150:151], off
	v_lshl_add_u64 v[150:151], v[224:225], 0, s[8:9]
	s_mov_b32 m0, s60
	s_nop 0
	global_load_lds_dwordx4 v[150:151], off
	v_lshl_add_u64 v[150:151], v[226:227], 0, s[8:9]
	s_mov_b32 m0, s61
	s_nop 0
	global_load_lds_dwordx4 v[150:151], off
	s_waitcnt vmcnt(8)
	s_waitcnt lgkmcnt(0)
	s_barrier
	s_setprio 1
	s_waitcnt lgkmcnt(0)
	v_mfma_f32_16x16x32_bf16 v[62:65], v[146:149], v[188:191], v[62:65]
	v_mfma_f32_16x16x32_bf16 v[58:61], v[164:167], v[188:191], v[58:61]
	v_mfma_f32_16x16x32_bf16 v[54:57], v[172:175], v[188:191], v[54:57]
	v_mfma_f32_16x16x32_bf16 v[46:49], v[180:183], v[188:191], v[46:49]
	v_mfma_f32_16x16x32_bf16 v[50:53], v[146:149], v[196:199], v[50:53]
	v_mfma_f32_16x16x32_bf16 v[42:45], v[164:167], v[196:199], v[42:45]
	v_mfma_f32_16x16x32_bf16 v[38:41], v[172:175], v[196:199], v[38:41]
	v_mfma_f32_16x16x32_bf16 v[30:33], v[180:183], v[196:199], v[30:33]
	v_mfma_f32_16x16x32_bf16 v[34:37], v[146:149], v[204:207], v[34:37]
	v_mfma_f32_16x16x32_bf16 v[26:29], v[164:167], v[204:207], v[26:29]
	v_mfma_f32_16x16x32_bf16 v[22:25], v[172:175], v[204:207], v[22:25]
	v_mfma_f32_16x16x32_bf16 v[14:17], v[180:183], v[204:207], v[14:17]
	v_mfma_f32_16x16x32_bf16 v[18:21], v[146:149], v[212:215], v[18:21]
	v_mfma_f32_16x16x32_bf16 v[10:13], v[164:167], v[212:215], v[10:13]
	v_mfma_f32_16x16x32_bf16 v[6:9], v[172:175], v[212:215], v[6:9]
	v_mfma_f32_16x16x32_bf16 v[2:5], v[180:183], v[212:215], v[2:5]
	s_setprio 0
	s_setprio 1
	v_mfma_f32_16x16x32_bf16 v[62:65], v[160:163], v[192:195], v[62:65]
	v_mfma_f32_16x16x32_bf16 v[58:61], v[168:171], v[192:195], v[58:61]
	v_mfma_f32_16x16x32_bf16 v[54:57], v[176:179], v[192:195], v[54:57]
	v_mfma_f32_16x16x32_bf16 v[46:49], v[184:187], v[192:195], v[46:49]
	v_mfma_f32_16x16x32_bf16 v[50:53], v[160:163], v[200:203], v[50:53]
	v_mfma_f32_16x16x32_bf16 v[42:45], v[168:171], v[200:203], v[42:45]
	v_mfma_f32_16x16x32_bf16 v[38:41], v[176:179], v[200:203], v[38:41]
	v_mfma_f32_16x16x32_bf16 v[30:33], v[184:187], v[200:203], v[30:33]
	v_mfma_f32_16x16x32_bf16 v[34:37], v[160:163], v[208:211], v[34:37]
	v_mfma_f32_16x16x32_bf16 v[26:29], v[168:171], v[208:211], v[26:29]
	v_mfma_f32_16x16x32_bf16 v[22:25], v[176:179], v[208:211], v[22:25]
	v_mfma_f32_16x16x32_bf16 v[14:17], v[184:187], v[208:211], v[14:17]
	v_mfma_f32_16x16x32_bf16 v[18:21], v[160:163], v[218:221], v[18:21]
	v_mfma_f32_16x16x32_bf16 v[10:13], v[168:171], v[218:221], v[10:13]
	v_mfma_f32_16x16x32_bf16 v[6:9], v[176:179], v[218:221], v[6:9]
	v_mfma_f32_16x16x32_bf16 v[2:5], v[184:187], v[218:221], v[2:5]
	s_setprio 0
	s_barrier
	s_add_i32 s88, s88, 2
	s_add_u32 s84, s84, 0x100
	s_addc_u32 s85, s85, 0
	s_add_u32 s77, s77, 0x100
	s_addc_u32 s83, s83, 0
	s_cmp_gt_u32 s88, 5
	s_cbranch_scc0 .LBB0_715
	s_and_b64 vcc, exec, s[66:67]
	s_cbranch_vccz .LBB0_718
	s_barrier

.LBB0_995:
	ds_read_b128 v[146:149], v164
	ds_read_b128 v[150:153], v164 offset:1024
	ds_read_b128 v[154:157], v164 offset:2048
	ds_read_b128 v[158:161], v164 offset:3072
	ds_read_b128 v[168:171], v165
	ds_read_b128 v[172:175], v165 offset:1024
	ds_read_b128 v[176:179], v165 offset:2048
	ds_read_b128 v[180:183], v165 offset:3072
	s_add_u32 s34, s88, 0xfff80080
	s_addc_u32 s35, s89, -1
	s_cmp_eq_u32 s81, 28
	s_cselect_b32 s91, s0, s35
	s_cselect_b32 s90, s1, s34
	s_cselect_b32 s35, s52, s77
	s_cselect_b32 s34, s74, s75
	v_lshl_add_u64 v[218:219], s[88:89], 0, v[138:139]
	s_add_i32 m0, s33, 0xc000
	ds_read_b128 v[184:187], v166
	ds_read_b128 v[188:191], v166 offset:1024
	ds_read_b128 v[192:195], v166 offset:2048
	ds_read_b128 v[196:199], v166 offset:3072
	ds_read_b128 v[200:203], v166 offset:4096
	ds_read_b128 v[204:207], v166 offset:5120
	ds_read_b128 v[208:211], v166 offset:6144
	ds_read_b128 v[212:215], v166 offset:7168
	global_load_lds_dwordx4 v[218:219], off
	v_lshl_add_u64 v[218:219], s[88:89], 0, v[140:141]
	s_add_i32 m0, s33, 0xe000
	s_nop 0
	global_load_lds_dwordx4 v[218:219], off
	s_waitcnt vmcnt(8)
	s_waitcnt lgkmcnt(0)
	s_barrier
	s_setprio 1
	s_waitcnt lgkmcnt(0)
	v_mfma_f32_16x16x32_bf16 v[126:129], v[146:149], v[184:187], v[126:129]
	v_mfma_f32_16x16x32_bf16 v[122:125], v[154:157], v[184:187], v[122:125]
	v_mfma_f32_16x16x32_bf16 v[118:121], v[168:171], v[184:187], v[118:121]
	v_mfma_f32_16x16x32_bf16 v[114:117], v[176:179], v[184:187], v[114:117]
	v_mfma_f32_16x16x32_bf16 v[110:113], v[146:149], v[192:195], v[110:113]
	v_mfma_f32_16x16x32_bf16 v[106:109], v[154:157], v[192:195], v[106:109]
	v_mfma_f32_16x16x32_bf16 v[102:105], v[168:171], v[192:195], v[102:105]
	v_mfma_f32_16x16x32_bf16 v[98:101], v[176:179], v[192:195], v[98:101]
	v_mfma_f32_16x16x32_bf16 v[94:97], v[146:149], v[200:203], v[94:97]
	v_mfma_f32_16x16x32_bf16 v[90:93], v[154:157], v[200:203], v[90:93]
	v_mfma_f32_16x16x32_bf16 v[86:89], v[168:171], v[200:203], v[86:89]
	v_mfma_f32_16x16x32_bf16 v[82:85], v[176:179], v[200:203], v[82:85]
	v_mfma_f32_16x16x32_bf16 v[78:81], v[146:149], v[208:211], v[78:81]
	v_mfma_f32_16x16x32_bf16 v[74:77], v[154:157], v[208:211], v[74:77]
	v_mfma_f32_16x16x32_bf16 v[70:73], v[168:171], v[208:211], v[70:73]
	v_mfma_f32_16x16x32_bf16 v[66:69], v[176:179], v[208:211], v[66:69]
	s_setprio 0
	s_setprio 1
	v_mfma_f32_16x16x32_bf16 v[126:129], v[150:153], v[188:191], v[126:129]
	v_mfma_f32_16x16x32_bf16 v[122:125], v[158:161], v[188:191], v[122:125]
	v_mfma_f32_16x16x32_bf16 v[118:121], v[172:175], v[188:191], v[118:121]
	v_mfma_f32_16x16x32_bf16 v[114:117], v[180:183], v[188:191], v[114:117]
	v_mfma_f32_16x16x32_bf16 v[110:113], v[150:153], v[196:199], v[110:113]
	v_mfma_f32_16x16x32_bf16 v[106:109], v[158:161], v[196:199], v[106:109]
	v_mfma_f32_16x16x32_bf16 v[102:105], v[172:175], v[196:199], v[102:105]
	v_mfma_f32_16x16x32_bf16 v[98:101], v[180:183], v[196:199], v[98:101]
	v_mfma_f32_16x16x32_bf16 v[94:97], v[150:153], v[204:207], v[94:97]
	v_mfma_f32_16x16x32_bf16 v[90:93], v[158:161], v[204:207], v[90:93]
	v_mfma_f32_16x16x32_bf16 v[86:89], v[172:175], v[204:207], v[86:89]
	v_mfma_f32_16x16x32_bf16 v[82:85], v[180:183], v[204:207], v[82:85]
	v_mfma_f32_16x16x32_bf16 v[78:81], v[150:153], v[212:215], v[78:81]
	v_mfma_f32_16x16x32_bf16 v[74:77], v[158:161], v[212:215], v[74:77]
	v_mfma_f32_16x16x32_bf16 v[70:73], v[172:175], v[212:215], v[70:73]
	v_mfma_f32_16x16x32_bf16 v[66:69], v[180:183], v[212:215], v[66:69]
	s_setprio 0
	s_barrier
	s_add_i32 s53, s71, s31
	v_lshl_add_u64 v[218:219], s[34:35], 0, v[132:133]
	s_mov_b32 m0, s53
	ds_read_b128 v[184:187], v166 offset:16384
	ds_read_b128 v[188:191], v166 offset:17408
	ds_read_b128 v[192:195], v166 offset:18432
	ds_read_b128 v[196:199], v166 offset:19456
	ds_read_b128 v[200:203], v166 offset:20480
	ds_read_b128 v[204:207], v166 offset:21504
	ds_read_b128 v[208:211], v166 offset:22528
	ds_read_b128 v[212:215], v166 offset:23552
	global_load_lds_dwordx4 v[218:219], off
	s_add_i32 m0, s53, 0x2000
	s_add_u32 s54, s34, 0x80000
	v_lshl_add_u64 v[220:221], s[34:35], 0, v[136:137]
	s_addc_u32 s55, s35, 0
	s_add_i32 s53, s72, s31
	global_load_lds_dwordx4 v[220:221], off
	v_lshl_add_u64 v[222:223], s[54:55], 0, v[132:133]
	s_mov_b32 m0, s53
	v_lshl_add_u64 v[224:225], s[90:91], 0, v[134:135]
	global_load_lds_dwordx4 v[222:223], off
	v_lshl_add_u64 v[222:223], s[54:55], 0, v[136:137]
	s_add_i32 m0, s53, 0x2000
	s_nop 0
	global_load_lds_dwordx4 v[222:223], off
	v_lshl_add_u64 v[222:223], s[90:91], 0, v[130:131]
	s_mov_b32 m0, s33
	s_nop 0
	global_load_lds_dwordx4 v[222:223], off
	s_mov_b32 m0, s56
	s_nop 0
	global_load_lds_dwordx4 v[224:225], off
	s_waitcnt vmcnt(8)
	s_waitcnt lgkmcnt(0)
	s_barrier
	s_setprio 1
	s_waitcnt lgkmcnt(0)
	v_mfma_f32_16x16x32_bf16 v[62:65], v[146:149], v[184:187], v[62:65]
	v_mfma_f32_16x16x32_bf16 v[58:61], v[154:157], v[184:187], v[58:61]
	v_mfma_f32_16x16x32_bf16 v[54:57], v[168:171], v[184:187], v[54:57]
	v_mfma_f32_16x16x32_bf16 v[50:53], v[176:179], v[184:187], v[50:53]
	v_mfma_f32_16x16x32_bf16 v[46:49], v[146:149], v[192:195], v[46:49]
	v_mfma_f32_16x16x32_bf16 v[42:45], v[154:157], v[192:195], v[42:45]
	v_mfma_f32_16x16x32_bf16 v[38:41], v[168:171], v[192:195], v[38:41]
	v_mfma_f32_16x16x32_bf16 v[34:37], v[176:179], v[192:195], v[34:37]
	v_mfma_f32_16x16x32_bf16 v[30:33], v[146:149], v[200:203], v[30:33]
	v_mfma_f32_16x16x32_bf16 v[26:29], v[154:157], v[200:203], v[26:29]
	v_mfma_f32_16x16x32_bf16 v[22:25], v[168:171], v[200:203], v[22:25]
	v_mfma_f32_16x16x32_bf16 v[18:21], v[176:179], v[200:203], v[18:21]
	v_mfma_f32_16x16x32_bf16 v[14:17], v[146:149], v[208:211], v[14:17]
	v_mfma_f32_16x16x32_bf16 v[10:13], v[154:157], v[208:211], v[10:13]
	v_mfma_f32_16x16x32_bf16 v[6:9], v[168:171], v[208:211], v[6:9]
	v_mfma_f32_16x16x32_bf16 v[2:5], v[176:179], v[208:211], v[2:5]
	s_setprio 0
	s_setprio 1
	v_mfma_f32_16x16x32_bf16 v[62:65], v[150:153], v[188:191], v[62:65]
	v_mfma_f32_16x16x32_bf16 v[58:61], v[158:161], v[188:191], v[58:61]
	v_mfma_f32_16x16x32_bf16 v[54:57], v[172:175], v[188:191], v[54:57]
	v_mfma_f32_16x16x32_bf16 v[50:53], v[180:183], v[188:191], v[50:53]
	v_mfma_f32_16x16x32_bf16 v[46:49], v[150:153], v[196:199], v[46:49]
	v_mfma_f32_16x16x32_bf16 v[42:45], v[158:161], v[196:199], v[42:45]
	v_mfma_f32_16x16x32_bf16 v[38:41], v[172:175], v[196:199], v[38:41]
	v_mfma_f32_16x16x32_bf16 v[34:37], v[180:183], v[196:199], v[34:37]
	v_mfma_f32_16x16x32_bf16 v[30:33], v[150:153], v[204:207], v[30:33]
	v_mfma_f32_16x16x32_bf16 v[26:29], v[158:161], v[204:207], v[26:29]
	v_mfma_f32_16x16x32_bf16 v[22:25], v[172:175], v[204:207], v[22:25]
	v_mfma_f32_16x16x32_bf16 v[18:21], v[180:183], v[204:207], v[18:21]
	v_mfma_f32_16x16x32_bf16 v[14:17], v[150:153], v[212:215], v[14:17]
	v_mfma_f32_16x16x32_bf16 v[10:13], v[158:161], v[212:215], v[10:13]
	v_mfma_f32_16x16x32_bf16 v[6:9], v[172:175], v[212:215], v[6:9]
	v_mfma_f32_16x16x32_bf16 v[2:5], v[180:183], v[212:215], v[2:5]
	s_setprio 0
	s_barrier
	s_add_i32 s53, 0, 0x18000
	s_add_i32 s62, 0, 0x1c000
	v_add_u32_e32 v158, s53, v162
	v_add_u32_e32 v167, s62, v162
	ds_read_b128 v[146:149], v158
	ds_read_b128 v[150:153], v158 offset:1024
	ds_read_b128 v[154:157], v158 offset:2048
	ds_read_b128 v[158:161], v158 offset:3072
	ds_read_b128 v[168:171], v167
	ds_read_b128 v[172:175], v167 offset:1024
	ds_read_b128 v[176:179], v167 offset:2048
	ds_read_b128 v[180:183], v167 offset:3072
	s_add_u32 s54, s90, 0x80000
	s_addc_u32 s55, s91, 0
	s_mov_b32 m0, s57
	v_lshl_add_u64 v[226:227], s[54:55], 0, v[130:131]
	ds_read_b128 v[184:187], v166 offset:32768
	ds_read_b128 v[188:191], v166 offset:33792
	ds_read_b128 v[192:195], v166 offset:34816
	ds_read_b128 v[196:199], v166 offset:35840
	ds_read_b128 v[200:203], v166 offset:36864
	ds_read_b128 v[204:207], v166 offset:37888
	ds_read_b128 v[208:211], v166 offset:38912
	ds_read_b128 v[212:215], v166 offset:39936
	global_load_lds_dwordx4 v[226:227], off
	v_lshl_add_u64 v[226:227], s[54:55], 0, v[134:135]
	s_mov_b32 m0, s58
	s_nop 0
	global_load_lds_dwordx4 v[226:227], off
	s_waitcnt vmcnt(8)
	s_waitcnt lgkmcnt(0)
	s_barrier
	s_setprio 1
	s_waitcnt lgkmcnt(0)
	v_mfma_f32_16x16x32_bf16 v[126:129], v[146:149], v[184:187], v[126:129]
	v_mfma_f32_16x16x32_bf16 v[122:125], v[154:157], v[184:187], v[122:125]
	v_mfma_f32_16x16x32_bf16 v[118:121], v[168:171], v[184:187], v[118:121]
	v_mfma_f32_16x16x32_bf16 v[114:117], v[176:179], v[184:187], v[114:117]
	v_mfma_f32_16x16x32_bf16 v[110:113], v[146:149], v[192:195], v[110:113]
	v_mfma_f32_16x16x32_bf16 v[106:109], v[154:157], v[192:195], v[106:109]
	v_mfma_f32_16x16x32_bf16 v[102:105], v[168:171], v[192:195], v[102:105]
	v_mfma_f32_16x16x32_bf16 v[98:101], v[176:179], v[192:195], v[98:101]
	v_mfma_f32_16x16x32_bf16 v[94:97], v[146:149], v[200:203], v[94:97]
	v_mfma_f32_16x16x32_bf16 v[90:93], v[154:157], v[200:203], v[90:93]
	v_mfma_f32_16x16x32_bf16 v[86:89], v[168:171], v[200:203], v[86:89]
	v_mfma_f32_16x16x32_bf16 v[82:85], v[176:179], v[200:203], v[82:85]
	v_mfma_f32_16x16x32_bf16 v[78:81], v[146:149], v[208:211], v[78:81]
	v_mfma_f32_16x16x32_bf16 v[74:77], v[154:157], v[208:211], v[74:77]
	v_mfma_f32_16x16x32_bf16 v[70:73], v[168:171], v[208:211], v[70:73]
	v_mfma_f32_16x16x32_bf16 v[66:69], v[176:179], v[208:211], v[66:69]
	s_setprio 0
	s_setprio 1
	v_mfma_f32_16x16x32_bf16 v[126:129], v[150:153], v[188:191], v[126:129]
	v_mfma_f32_16x16x32_bf16 v[122:125], v[158:161], v[188:191], v[122:125]
	v_mfma_f32_16x16x32_bf16 v[118:121], v[172:175], v[188:191], v[118:121]
	v_mfma_f32_16x16x32_bf16 v[114:117], v[180:183], v[188:191], v[114:117]
	v_mfma_f32_16x16x32_bf16 v[110:113], v[150:153], v[196:199], v[110:113]
	v_mfma_f32_16x16x32_bf16 v[106:109], v[158:161], v[196:199], v[106:109]
	v_mfma_f32_16x16x32_bf16 v[102:105], v[172:175], v[196:199], v[102:105]
	v_mfma_f32_16x16x32_bf16 v[98:101], v[180:183], v[196:199], v[98:101]
	v_mfma_f32_16x16x32_bf16 v[94:97], v[150:153], v[204:207], v[94:97]
	v_mfma_f32_16x16x32_bf16 v[90:93], v[158:161], v[204:207], v[90:93]
	v_mfma_f32_16x16x32_bf16 v[86:89], v[172:175], v[204:207], v[86:89]
	v_mfma_f32_16x16x32_bf16 v[82:85], v[180:183], v[204:207], v[82:85]
	v_mfma_f32_16x16x32_bf16 v[78:81], v[150:153], v[212:215], v[78:81]
	v_mfma_f32_16x16x32_bf16 v[74:77], v[158:161], v[212:215], v[74:77]
	v_mfma_f32_16x16x32_bf16 v[70:73], v[172:175], v[212:215], v[70:73]
	v_mfma_f32_16x16x32_bf16 v[66:69], v[180:183], v[212:215], v[66:69]
	s_setprio 0
	s_barrier
	s_add_i32 s53, s53, s31
	v_lshl_add_u64 v[218:219], v[218:219], 0, s[8:9]
	s_mov_b32 m0, s53
	ds_read_b128 v[184:187], v166 offset:49152
	ds_read_b128 v[188:191], v166 offset:50176
	ds_read_b128 v[192:195], v166 offset:51200
	ds_read_b128 v[196:199], v166 offset:52224
	ds_read_b128 v[200:203], v166 offset:53248
	ds_read_b128 v[204:207], v166 offset:54272
	ds_read_b128 v[208:211], v166 offset:55296
	ds_read_b128 v[212:215], v166 offset:56320
	global_load_lds_dwordx4 v[218:219], off
	s_add_i32 m0, s53, 0x2000
	s_add_u32 s34, s34, 0x80080
	v_lshl_add_u64 v[218:219], v[220:221], 0, s[8:9]
	s_addc_u32 s35, s35, 0
	s_add_i32 s53, s62, s31
	global_load_lds_dwordx4 v[218:219], off
	v_lshl_add_u64 v[218:219], s[34:35], 0, v[132:133]
	s_mov_b32 m0, s53
	s_nop 0
	global_load_lds_dwordx4 v[218:219], off
	v_lshl_add_u64 v[218:219], s[34:35], 0, v[136:137]
	s_add_i32 m0, s53, 0x2000
	s_nop 0
	global_load_lds_dwordx4 v[218:219], off
	v_lshl_add_u64 v[218:219], v[222:223], 0, s[8:9]
	s_mov_b32 m0, s60
	s_nop 0
	global_load_lds_dwordx4 v[218:219], off
	v_lshl_add_u64 v[218:219], v[224:225], 0, s[8:9]
	s_mov_b32 m0, s61
	s_nop 0
	global_load_lds_dwordx4 v[218:219], off
	s_waitcnt vmcnt(8)
	s_waitcnt lgkmcnt(0)
	s_barrier
	s_setprio 1
	s_waitcnt lgkmcnt(0)
	v_mfma_f32_16x16x32_bf16 v[62:65], v[146:149], v[184:187], v[62:65]
	v_mfma_f32_16x16x32_bf16 v[58:61], v[154:157], v[184:187], v[58:61]
	v_mfma_f32_16x16x32_bf16 v[54:57], v[168:171], v[184:187], v[54:57]
	v_mfma_f32_16x16x32_bf16 v[50:53], v[176:179], v[184:187], v[50:53]
	v_mfma_f32_16x16x32_bf16 v[46:49], v[146:149], v[192:195], v[46:49]
	v_mfma_f32_16x16x32_bf16 v[42:45], v[154:157], v[192:195], v[42:45]
	v_mfma_f32_16x16x32_bf16 v[38:41], v[168:171], v[192:195], v[38:41]
	v_mfma_f32_16x16x32_bf16 v[34:37], v[176:179], v[192:195], v[34:37]
	v_mfma_f32_16x16x32_bf16 v[30:33], v[146:149], v[200:203], v[30:33]
	v_mfma_f32_16x16x32_bf16 v[26:29], v[154:157], v[200:203], v[26:29]
	v_mfma_f32_16x16x32_bf16 v[22:25], v[168:171], v[200:203], v[22:25]
	v_mfma_f32_16x16x32_bf16 v[18:21], v[176:179], v[200:203], v[18:21]
	v_mfma_f32_16x16x32_bf16 v[14:17], v[146:149], v[208:211], v[14:17]
	v_mfma_f32_16x16x32_bf16 v[10:13], v[154:157], v[208:211], v[10:13]
	v_mfma_f32_16x16x32_bf16 v[6:9], v[168:171], v[208:211], v[6:9]
	v_mfma_f32_16x16x32_bf16 v[2:5], v[176:179], v[208:211], v[2:5]
	s_setprio 0
	s_setprio 1
	v_mfma_f32_16x16x32_bf16 v[62:65], v[150:153], v[188:191], v[62:65]
	v_mfma_f32_16x16x32_bf16 v[58:61], v[158:161], v[188:191], v[58:61]
	v_mfma_f32_16x16x32_bf16 v[54:57], v[172:175], v[188:191], v[54:57]
	v_mfma_f32_16x16x32_bf16 v[50:53], v[180:183], v[188:191], v[50:53]
	v_mfma_f32_16x16x32_bf16 v[46:49], v[150:153], v[196:199], v[46:49]
	v_mfma_f32_16x16x32_bf16 v[42:45], v[158:161], v[196:199], v[42:45]
	v_mfma_f32_16x16x32_bf16 v[38:41], v[172:175], v[196:199], v[38:41]
	v_mfma_f32_16x16x32_bf16 v[34:37], v[180:183], v[196:199], v[34:37]
	v_mfma_f32_16x16x32_bf16 v[30:33], v[150:153], v[204:207], v[30:33]
	v_mfma_f32_16x16x32_bf16 v[26:29], v[158:161], v[204:207], v[26:29]
	v_mfma_f32_16x16x32_bf16 v[22:25], v[172:175], v[204:207], v[22:25]
	v_mfma_f32_16x16x32_bf16 v[18:21], v[180:183], v[204:207], v[18:21]
	v_mfma_f32_16x16x32_bf16 v[14:17], v[150:153], v[212:215], v[14:17]
	v_mfma_f32_16x16x32_bf16 v[10:13], v[158:161], v[212:215], v[10:13]
	v_mfma_f32_16x16x32_bf16 v[6:9], v[172:175], v[212:215], v[6:9]
	v_mfma_f32_16x16x32_bf16 v[2:5], v[180:183], v[212:215], v[2:5]
	s_setprio 0
	s_barrier
	s_add_i32 s81, s81, 2
	s_add_u32 s88, s88, 0x100
	s_addc_u32 s89, s89, 0
	s_add_u32 s75, s75, 0x100
	s_addc_u32 s77, s77, 0
	s_cmp_gt_u32 s81, 29
	s_cbranch_scc0 .LBB0_995
	s_and_b64 vcc, exec, s[78:79]
	s_cbranch_vccz .LBB0_998
	s_barrier

.LBB0_1124:
	ds_read_b128 v[146:149], v153
	ds_read_b128 v[156:159], v153 offset:1024
	ds_read_b128 v[160:163], v153 offset:2048
	ds_read_b128 v[164:167], v153 offset:3072
	ds_read_b128 v[168:171], v154
	ds_read_b128 v[172:175], v154 offset:1024
	ds_read_b128 v[176:179], v154 offset:2048
	ds_read_b128 v[180:183], v154 offset:3072
	s_add_u32 s34, s88, 0xfff80080
	s_addc_u32 s35, s89, -1
	s_cmp_eq_u32 s92, 28
	s_cselect_b32 s91, s0, s35
	s_cselect_b32 s90, s1, s34
	s_cselect_b32 s35, s52, s83
	s_cselect_b32 s34, s77, s81
	v_lshl_add_u64 v[218:219], s[88:89], 0, v[138:139]
	s_add_i32 m0, s56, 0xc000
	ds_read_b128 v[184:187], v155
	ds_read_b128 v[188:191], v155 offset:1024
	ds_read_b128 v[192:195], v155 offset:2048
	ds_read_b128 v[196:199], v155 offset:3072
	ds_read_b128 v[200:203], v155 offset:4096
	ds_read_b128 v[204:207], v155 offset:5120
	ds_read_b128 v[208:211], v155 offset:6144
	ds_read_b128 v[212:215], v155 offset:7168
	global_load_lds_dwordx4 v[218:219], off
	v_lshl_add_u64 v[218:219], s[88:89], 0, v[140:141]
	s_add_i32 m0, s56, 0xe000
	s_nop 0
	global_load_lds_dwordx4 v[218:219], off
	s_waitcnt vmcnt(8)
	s_waitcnt lgkmcnt(0)
	s_barrier
	s_setprio 1
	s_waitcnt lgkmcnt(0)
	v_mfma_f32_16x16x32_bf16 v[126:129], v[146:149], v[184:187], v[126:129]
	v_mfma_f32_16x16x32_bf16 v[118:121], v[160:163], v[184:187], v[118:121]
	v_mfma_f32_16x16x32_bf16 v[122:125], v[168:171], v[184:187], v[122:125]
	v_mfma_f32_16x16x32_bf16 v[114:117], v[176:179], v[184:187], v[114:117]
	v_mfma_f32_16x16x32_bf16 v[110:113], v[146:149], v[192:195], v[110:113]
	v_mfma_f32_16x16x32_bf16 v[102:105], v[160:163], v[192:195], v[102:105]
	v_mfma_f32_16x16x32_bf16 v[106:109], v[168:171], v[192:195], v[106:109]
	v_mfma_f32_16x16x32_bf16 v[98:101], v[176:179], v[192:195], v[98:101]
	v_mfma_f32_16x16x32_bf16 v[94:97], v[146:149], v[200:203], v[94:97]
	v_mfma_f32_16x16x32_bf16 v[86:89], v[160:163], v[200:203], v[86:89]
	v_mfma_f32_16x16x32_bf16 v[90:93], v[168:171], v[200:203], v[90:93]
	v_mfma_f32_16x16x32_bf16 v[82:85], v[176:179], v[200:203], v[82:85]
	v_mfma_f32_16x16x32_bf16 v[78:81], v[146:149], v[208:211], v[78:81]
	v_mfma_f32_16x16x32_bf16 v[70:73], v[160:163], v[208:211], v[70:73]
	v_mfma_f32_16x16x32_bf16 v[74:77], v[168:171], v[208:211], v[74:77]
	v_mfma_f32_16x16x32_bf16 v[66:69], v[176:179], v[208:211], v[66:69]
	s_setprio 0
	s_setprio 1
	v_mfma_f32_16x16x32_bf16 v[126:129], v[156:159], v[188:191], v[126:129]
	v_mfma_f32_16x16x32_bf16 v[118:121], v[164:167], v[188:191], v[118:121]
	v_mfma_f32_16x16x32_bf16 v[122:125], v[172:175], v[188:191], v[122:125]
	v_mfma_f32_16x16x32_bf16 v[114:117], v[180:183], v[188:191], v[114:117]
	v_mfma_f32_16x16x32_bf16 v[110:113], v[156:159], v[196:199], v[110:113]
	v_mfma_f32_16x16x32_bf16 v[102:105], v[164:167], v[196:199], v[102:105]
	v_mfma_f32_16x16x32_bf16 v[106:109], v[172:175], v[196:199], v[106:109]
	v_mfma_f32_16x16x32_bf16 v[98:101], v[180:183], v[196:199], v[98:101]
	v_mfma_f32_16x16x32_bf16 v[94:97], v[156:159], v[204:207], v[94:97]
	v_mfma_f32_16x16x32_bf16 v[86:89], v[164:167], v[204:207], v[86:89]
	v_mfma_f32_16x16x32_bf16 v[90:93], v[172:175], v[204:207], v[90:93]
	v_mfma_f32_16x16x32_bf16 v[82:85], v[180:183], v[204:207], v[82:85]
	v_mfma_f32_16x16x32_bf16 v[78:81], v[156:159], v[212:215], v[78:81]
	v_mfma_f32_16x16x32_bf16 v[70:73], v[164:167], v[212:215], v[70:73]
	v_mfma_f32_16x16x32_bf16 v[74:77], v[172:175], v[212:215], v[74:77]
	v_mfma_f32_16x16x32_bf16 v[66:69], v[180:183], v[212:215], v[66:69]
	s_setprio 0
	s_barrier
	s_add_i32 s53, s72, s30
	v_lshl_add_u64 v[218:219], s[34:35], 0, v[134:135]
	s_mov_b32 m0, s53
	ds_read_b128 v[184:187], v155 offset:16384
	ds_read_b128 v[188:191], v155 offset:17408
	ds_read_b128 v[192:195], v155 offset:18432
	ds_read_b128 v[196:199], v155 offset:19456
	ds_read_b128 v[200:203], v155 offset:20480
	ds_read_b128 v[204:207], v155 offset:21504
	ds_read_b128 v[208:211], v155 offset:22528
	ds_read_b128 v[212:215], v155 offset:23552
	global_load_lds_dwordx4 v[218:219], off
	s_add_i32 m0, s53, 0x2000
	s_add_u32 s54, s34, 0x80000
	v_lshl_add_u64 v[220:221], s[34:35], 0, v[130:131]
	s_addc_u32 s55, s35, 0
	s_add_i32 s53, s73, s30
	global_load_lds_dwordx4 v[220:221], off
	v_lshl_add_u64 v[222:223], s[54:55], 0, v[134:135]
	s_mov_b32 m0, s53
	v_lshl_add_u64 v[224:225], s[90:91], 0, v[132:133]
	global_load_lds_dwordx4 v[222:223], off
	v_lshl_add_u64 v[222:223], s[54:55], 0, v[130:131]
	s_add_i32 m0, s53, 0x2000
	s_nop 0
	global_load_lds_dwordx4 v[222:223], off
	v_lshl_add_u64 v[222:223], s[90:91], 0, v[136:137]
	s_mov_b32 m0, s56
	s_nop 0
	global_load_lds_dwordx4 v[222:223], off
	s_mov_b32 m0, s57
	s_nop 0
	global_load_lds_dwordx4 v[224:225], off
	s_waitcnt vmcnt(8)
	s_waitcnt lgkmcnt(0)
	s_barrier
	s_setprio 1
	s_waitcnt lgkmcnt(0)
	v_mfma_f32_16x16x32_bf16 v[62:65], v[146:149], v[184:187], v[62:65]
	v_mfma_f32_16x16x32_bf16 v[54:57], v[160:163], v[184:187], v[54:57]
	v_mfma_f32_16x16x32_bf16 v[58:61], v[168:171], v[184:187], v[58:61]
	v_mfma_f32_16x16x32_bf16 v[50:53], v[176:179], v[184:187], v[50:53]
	v_mfma_f32_16x16x32_bf16 v[46:49], v[146:149], v[192:195], v[46:49]
	v_mfma_f32_16x16x32_bf16 v[38:41], v[160:163], v[192:195], v[38:41]
	v_mfma_f32_16x16x32_bf16 v[42:45], v[168:171], v[192:195], v[42:45]
	v_mfma_f32_16x16x32_bf16 v[34:37], v[176:179], v[192:195], v[34:37]
	v_mfma_f32_16x16x32_bf16 v[30:33], v[146:149], v[200:203], v[30:33]
	v_mfma_f32_16x16x32_bf16 v[22:25], v[160:163], v[200:203], v[22:25]
	v_mfma_f32_16x16x32_bf16 v[26:29], v[168:171], v[200:203], v[26:29]
	v_mfma_f32_16x16x32_bf16 v[18:21], v[176:179], v[200:203], v[18:21]
	v_mfma_f32_16x16x32_bf16 v[14:17], v[146:149], v[208:211], v[14:17]
	v_mfma_f32_16x16x32_bf16 v[6:9], v[160:163], v[208:211], v[6:9]
	v_mfma_f32_16x16x32_bf16 v[10:13], v[168:171], v[208:211], v[10:13]
	v_mfma_f32_16x16x32_bf16 v[2:5], v[176:179], v[208:211], v[2:5]
	s_setprio 0
	s_setprio 1
	v_mfma_f32_16x16x32_bf16 v[62:65], v[156:159], v[188:191], v[62:65]
	v_mfma_f32_16x16x32_bf16 v[54:57], v[164:167], v[188:191], v[54:57]
	v_mfma_f32_16x16x32_bf16 v[58:61], v[172:175], v[188:191], v[58:61]
	v_mfma_f32_16x16x32_bf16 v[50:53], v[180:183], v[188:191], v[50:53]
	v_mfma_f32_16x16x32_bf16 v[46:49], v[156:159], v[196:199], v[46:49]
	v_mfma_f32_16x16x32_bf16 v[38:41], v[164:167], v[196:199], v[38:41]
	v_mfma_f32_16x16x32_bf16 v[42:45], v[172:175], v[196:199], v[42:45]
	v_mfma_f32_16x16x32_bf16 v[34:37], v[180:183], v[196:199], v[34:37]
	v_mfma_f32_16x16x32_bf16 v[30:33], v[156:159], v[204:207], v[30:33]
	v_mfma_f32_16x16x32_bf16 v[22:25], v[164:167], v[204:207], v[22:25]
	v_mfma_f32_16x16x32_bf16 v[26:29], v[172:175], v[204:207], v[26:29]
	v_mfma_f32_16x16x32_bf16 v[18:21], v[180:183], v[204:207], v[18:21]
	v_mfma_f32_16x16x32_bf16 v[14:17], v[156:159], v[212:215], v[14:17]
	v_mfma_f32_16x16x32_bf16 v[6:9], v[164:167], v[212:215], v[6:9]
	v_mfma_f32_16x16x32_bf16 v[10:13], v[172:175], v[212:215], v[10:13]
	v_mfma_f32_16x16x32_bf16 v[2:5], v[180:183], v[212:215], v[2:5]
	s_setprio 0
	s_barrier
	s_add_i32 s53, 0, 0x18000
	s_add_i32 s62, 0, 0x1c000
	v_add_u32_e32 v164, s53, v151
	v_add_u32_e32 v180, s62, v151
	ds_read_b128 v[146:149], v164
	ds_read_b128 v[156:159], v164 offset:1024
	ds_read_b128 v[160:163], v164 offset:2048
	ds_read_b128 v[164:167], v164 offset:3072
	ds_read_b128 v[168:171], v180
	ds_read_b128 v[172:175], v180 offset:1024
	ds_read_b128 v[176:179], v180 offset:2048
	ds_read_b128 v[180:183], v180 offset:3072
	s_add_u32 s54, s90, 0x80000
	s_addc_u32 s55, s91, 0
	s_mov_b32 m0, s58
	v_lshl_add_u64 v[226:227], s[54:55], 0, v[136:137]
	ds_read_b128 v[184:187], v155 offset:32768
	ds_read_b128 v[188:191], v155 offset:33792
	ds_read_b128 v[192:195], v155 offset:34816
	ds_read_b128 v[196:199], v155 offset:35840
	ds_read_b128 v[200:203], v155 offset:36864
	ds_read_b128 v[204:207], v155 offset:37888
	ds_read_b128 v[208:211], v155 offset:38912
	ds_read_b128 v[212:215], v155 offset:39936
	global_load_lds_dwordx4 v[226:227], off
	v_lshl_add_u64 v[226:227], s[54:55], 0, v[132:133]
	s_mov_b32 m0, s59
	s_nop 0
	global_load_lds_dwordx4 v[226:227], off
	s_waitcnt vmcnt(8)
	s_waitcnt lgkmcnt(0)
	s_barrier
	s_setprio 1
	s_waitcnt lgkmcnt(0)
	v_mfma_f32_16x16x32_bf16 v[126:129], v[146:149], v[184:187], v[126:129]
	v_mfma_f32_16x16x32_bf16 v[118:121], v[160:163], v[184:187], v[118:121]
	v_mfma_f32_16x16x32_bf16 v[122:125], v[168:171], v[184:187], v[122:125]
	v_mfma_f32_16x16x32_bf16 v[114:117], v[176:179], v[184:187], v[114:117]
	v_mfma_f32_16x16x32_bf16 v[110:113], v[146:149], v[192:195], v[110:113]
	v_mfma_f32_16x16x32_bf16 v[102:105], v[160:163], v[192:195], v[102:105]
	v_mfma_f32_16x16x32_bf16 v[106:109], v[168:171], v[192:195], v[106:109]
	v_mfma_f32_16x16x32_bf16 v[98:101], v[176:179], v[192:195], v[98:101]
	v_mfma_f32_16x16x32_bf16 v[94:97], v[146:149], v[200:203], v[94:97]
	v_mfma_f32_16x16x32_bf16 v[86:89], v[160:163], v[200:203], v[86:89]
	v_mfma_f32_16x16x32_bf16 v[90:93], v[168:171], v[200:203], v[90:93]
	v_mfma_f32_16x16x32_bf16 v[82:85], v[176:179], v[200:203], v[82:85]
	v_mfma_f32_16x16x32_bf16 v[78:81], v[146:149], v[208:211], v[78:81]
	v_mfma_f32_16x16x32_bf16 v[70:73], v[160:163], v[208:211], v[70:73]
	v_mfma_f32_16x16x32_bf16 v[74:77], v[168:171], v[208:211], v[74:77]
	v_mfma_f32_16x16x32_bf16 v[66:69], v[176:179], v[208:211], v[66:69]
	s_setprio 0
	s_setprio 1
	v_mfma_f32_16x16x32_bf16 v[126:129], v[156:159], v[188:191], v[126:129]
	v_mfma_f32_16x16x32_bf16 v[118:121], v[164:167], v[188:191], v[118:121]
	v_mfma_f32_16x16x32_bf16 v[122:125], v[172:175], v[188:191], v[122:125]
	v_mfma_f32_16x16x32_bf16 v[114:117], v[180:183], v[188:191], v[114:117]
	v_mfma_f32_16x16x32_bf16 v[110:113], v[156:159], v[196:199], v[110:113]
	v_mfma_f32_16x16x32_bf16 v[102:105], v[164:167], v[196:199], v[102:105]
	v_mfma_f32_16x16x32_bf16 v[106:109], v[172:175], v[196:199], v[106:109]
	v_mfma_f32_16x16x32_bf16 v[98:101], v[180:183], v[196:199], v[98:101]
	v_mfma_f32_16x16x32_bf16 v[94:97], v[156:159], v[204:207], v[94:97]
	v_mfma_f32_16x16x32_bf16 v[86:89], v[164:167], v[204:207], v[86:89]
	v_mfma_f32_16x16x32_bf16 v[90:93], v[172:175], v[204:207], v[90:93]
	v_mfma_f32_16x16x32_bf16 v[82:85], v[180:183], v[204:207], v[82:85]
	v_mfma_f32_16x16x32_bf16 v[78:81], v[156:159], v[212:215], v[78:81]
	v_mfma_f32_16x16x32_bf16 v[70:73], v[164:167], v[212:215], v[70:73]
	v_mfma_f32_16x16x32_bf16 v[74:77], v[172:175], v[212:215], v[74:77]
	v_mfma_f32_16x16x32_bf16 v[66:69], v[180:183], v[212:215], v[66:69]
	s_setprio 0
	s_barrier
	s_add_i32 s53, s53, s30
	v_lshl_add_u64 v[218:219], v[218:219], 0, s[8:9]
	s_mov_b32 m0, s53
	ds_read_b128 v[184:187], v155 offset:49152
	ds_read_b128 v[188:191], v155 offset:50176
	ds_read_b128 v[192:195], v155 offset:51200
	ds_read_b128 v[196:199], v155 offset:52224
	ds_read_b128 v[200:203], v155 offset:53248
	ds_read_b128 v[204:207], v155 offset:54272
	ds_read_b128 v[208:211], v155 offset:55296
	ds_read_b128 v[212:215], v155 offset:56320
	global_load_lds_dwordx4 v[218:219], off
	s_add_i32 m0, s53, 0x2000
	s_add_u32 s34, s34, 0x80080
	v_lshl_add_u64 v[218:219], v[220:221], 0, s[8:9]
	s_addc_u32 s35, s35, 0
	s_add_i32 s53, s62, s30
	global_load_lds_dwordx4 v[218:219], off
	v_lshl_add_u64 v[218:219], s[34:35], 0, v[134:135]
	s_mov_b32 m0, s53
	s_nop 0
	global_load_lds_dwordx4 v[218:219], off
	v_lshl_add_u64 v[218:219], s[34:35], 0, v[130:131]
	s_add_i32 m0, s53, 0x2000
	s_nop 0
	global_load_lds_dwordx4 v[218:219], off
	v_lshl_add_u64 v[218:219], v[222:223], 0, s[8:9]
	s_mov_b32 m0, s61
	s_nop 0
	global_load_lds_dwordx4 v[218:219], off
	v_lshl_add_u64 v[218:219], v[224:225], 0, s[8:9]
	s_mov_b32 m0, s70
	s_nop 0
	global_load_lds_dwordx4 v[218:219], off
	s_waitcnt vmcnt(8)
	s_waitcnt lgkmcnt(0)
	s_barrier
	s_setprio 1
	s_waitcnt lgkmcnt(0)
	v_mfma_f32_16x16x32_bf16 v[62:65], v[146:149], v[184:187], v[62:65]
	v_mfma_f32_16x16x32_bf16 v[54:57], v[160:163], v[184:187], v[54:57]
	v_mfma_f32_16x16x32_bf16 v[58:61], v[168:171], v[184:187], v[58:61]
	v_mfma_f32_16x16x32_bf16 v[50:53], v[176:179], v[184:187], v[50:53]
	v_mfma_f32_16x16x32_bf16 v[46:49], v[146:149], v[192:195], v[46:49]
	v_mfma_f32_16x16x32_bf16 v[38:41], v[160:163], v[192:195], v[38:41]
	v_mfma_f32_16x16x32_bf16 v[42:45], v[168:171], v[192:195], v[42:45]
	v_mfma_f32_16x16x32_bf16 v[34:37], v[176:179], v[192:195], v[34:37]
	v_mfma_f32_16x16x32_bf16 v[30:33], v[146:149], v[200:203], v[30:33]
	v_mfma_f32_16x16x32_bf16 v[22:25], v[160:163], v[200:203], v[22:25]
	v_mfma_f32_16x16x32_bf16 v[26:29], v[168:171], v[200:203], v[26:29]
	v_mfma_f32_16x16x32_bf16 v[18:21], v[176:179], v[200:203], v[18:21]
	v_mfma_f32_16x16x32_bf16 v[14:17], v[146:149], v[208:211], v[14:17]
	v_mfma_f32_16x16x32_bf16 v[6:9], v[160:163], v[208:211], v[6:9]
	v_mfma_f32_16x16x32_bf16 v[10:13], v[168:171], v[208:211], v[10:13]
	v_mfma_f32_16x16x32_bf16 v[2:5], v[176:179], v[208:211], v[2:5]
	s_setprio 0
	s_setprio 1
	v_mfma_f32_16x16x32_bf16 v[62:65], v[156:159], v[188:191], v[62:65]
	v_mfma_f32_16x16x32_bf16 v[54:57], v[164:167], v[188:191], v[54:57]
	v_mfma_f32_16x16x32_bf16 v[58:61], v[172:175], v[188:191], v[58:61]
	v_mfma_f32_16x16x32_bf16 v[50:53], v[180:183], v[188:191], v[50:53]
	v_mfma_f32_16x16x32_bf16 v[46:49], v[156:159], v[196:199], v[46:49]
	v_mfma_f32_16x16x32_bf16 v[38:41], v[164:167], v[196:199], v[38:41]
	v_mfma_f32_16x16x32_bf16 v[42:45], v[172:175], v[196:199], v[42:45]
	v_mfma_f32_16x16x32_bf16 v[34:37], v[180:183], v[196:199], v[34:37]
	v_mfma_f32_16x16x32_bf16 v[30:33], v[156:159], v[204:207], v[30:33]
	v_mfma_f32_16x16x32_bf16 v[22:25], v[164:167], v[204:207], v[22:25]
	v_mfma_f32_16x16x32_bf16 v[26:29], v[172:175], v[204:207], v[26:29]
	v_mfma_f32_16x16x32_bf16 v[18:21], v[180:183], v[204:207], v[18:21]
	v_mfma_f32_16x16x32_bf16 v[14:17], v[156:159], v[212:215], v[14:17]
	v_mfma_f32_16x16x32_bf16 v[6:9], v[164:167], v[212:215], v[6:9]
	v_mfma_f32_16x16x32_bf16 v[10:13], v[172:175], v[212:215], v[10:13]
	v_mfma_f32_16x16x32_bf16 v[2:5], v[180:183], v[212:215], v[2:5]
	s_setprio 0
	s_barrier
	s_add_i32 s92, s92, 2
	s_add_u32 s88, s88, 0x100
	s_addc_u32 s89, s89, 0
	s_add_u32 s81, s81, 0x100
	s_addc_u32 s83, s83, 0
	s_cmp_gt_u32 s92, 29
	s_cbranch_scc0 .LBB0_1124
	v_mov_b32_e32 v157, 0xbfb8aa3b
	s_and_b64 vcc, exec, s[78:79]
	s_cbranch_vccz .LBB0_1127
	s_barrier

.LBB0_1237:
	ds_read_b128 v[146:149], v164
	ds_read_b128 v[150:153], v164 offset:1024
	ds_read_b128 v[154:157], v164 offset:2048
	ds_read_b128 v[158:161], v164 offset:3072
	ds_read_b128 v[168:171], v165
	ds_read_b128 v[172:175], v165 offset:1024
	ds_read_b128 v[176:179], v165 offset:2048
	ds_read_b128 v[180:183], v165 offset:3072
	s_add_u32 s34, s76, 0xffea0080
	s_addc_u32 s35, s77, -1
	s_cmpk_eq_i32 s52, 0x54
	s_cselect_b32 s85, s5, s35
	s_cselect_b32 s84, s4, s34
	s_cselect_b32 s35, s83, s1
	s_cselect_b32 s34, s82, s0
	v_lshl_add_u64 v[218:219], s[76:77], 0, v[138:139]
	s_add_i32 m0, s33, 0xc000
	ds_read_b128 v[184:187], v166
	ds_read_b128 v[188:191], v166 offset:1024
	ds_read_b128 v[192:195], v166 offset:2048
	ds_read_b128 v[196:199], v166 offset:3072
	ds_read_b128 v[200:203], v166 offset:4096
	ds_read_b128 v[204:207], v166 offset:5120
	ds_read_b128 v[208:211], v166 offset:6144
	ds_read_b128 v[212:215], v166 offset:7168
	global_load_lds_dwordx4 v[218:219], off
	v_lshl_add_u64 v[218:219], s[76:77], 0, v[140:141]
	s_add_i32 m0, s33, 0xe000
	s_nop 0
	global_load_lds_dwordx4 v[218:219], off
	s_waitcnt vmcnt(8)
	s_waitcnt lgkmcnt(0)
	s_barrier
	s_setprio 1
	s_waitcnt lgkmcnt(0)
	v_mfma_f32_16x16x32_bf16 v[126:129], v[146:149], v[184:187], v[126:129]
	v_mfma_f32_16x16x32_bf16 v[122:125], v[154:157], v[184:187], v[122:125]
	v_mfma_f32_16x16x32_bf16 v[118:121], v[168:171], v[184:187], v[118:121]
	v_mfma_f32_16x16x32_bf16 v[114:117], v[176:179], v[184:187], v[114:117]
	v_mfma_f32_16x16x32_bf16 v[110:113], v[146:149], v[192:195], v[110:113]
	v_mfma_f32_16x16x32_bf16 v[106:109], v[154:157], v[192:195], v[106:109]
	v_mfma_f32_16x16x32_bf16 v[102:105], v[168:171], v[192:195], v[102:105]
	v_mfma_f32_16x16x32_bf16 v[98:101], v[176:179], v[192:195], v[98:101]
	v_mfma_f32_16x16x32_bf16 v[94:97], v[146:149], v[200:203], v[94:97]
	v_mfma_f32_16x16x32_bf16 v[90:93], v[154:157], v[200:203], v[90:93]
	v_mfma_f32_16x16x32_bf16 v[86:89], v[168:171], v[200:203], v[86:89]
	v_mfma_f32_16x16x32_bf16 v[82:85], v[176:179], v[200:203], v[82:85]
	v_mfma_f32_16x16x32_bf16 v[78:81], v[146:149], v[208:211], v[78:81]
	v_mfma_f32_16x16x32_bf16 v[74:77], v[154:157], v[208:211], v[74:77]
	v_mfma_f32_16x16x32_bf16 v[70:73], v[168:171], v[208:211], v[70:73]
	v_mfma_f32_16x16x32_bf16 v[66:69], v[176:179], v[208:211], v[66:69]
	s_setprio 0
	s_setprio 1
	v_mfma_f32_16x16x32_bf16 v[126:129], v[150:153], v[188:191], v[126:129]
	v_mfma_f32_16x16x32_bf16 v[122:125], v[158:161], v[188:191], v[122:125]
	v_mfma_f32_16x16x32_bf16 v[118:121], v[172:175], v[188:191], v[118:121]
	v_mfma_f32_16x16x32_bf16 v[114:117], v[180:183], v[188:191], v[114:117]
	v_mfma_f32_16x16x32_bf16 v[110:113], v[150:153], v[196:199], v[110:113]
	v_mfma_f32_16x16x32_bf16 v[106:109], v[158:161], v[196:199], v[106:109]
	v_mfma_f32_16x16x32_bf16 v[102:105], v[172:175], v[196:199], v[102:105]
	v_mfma_f32_16x16x32_bf16 v[98:101], v[180:183], v[196:199], v[98:101]
	v_mfma_f32_16x16x32_bf16 v[94:97], v[150:153], v[204:207], v[94:97]
	v_mfma_f32_16x16x32_bf16 v[90:93], v[158:161], v[204:207], v[90:93]
	v_mfma_f32_16x16x32_bf16 v[86:89], v[172:175], v[204:207], v[86:89]
	v_mfma_f32_16x16x32_bf16 v[82:85], v[180:183], v[204:207], v[82:85]
	v_mfma_f32_16x16x32_bf16 v[78:81], v[150:153], v[212:215], v[78:81]
	v_mfma_f32_16x16x32_bf16 v[74:77], v[158:161], v[212:215], v[74:77]
	v_mfma_f32_16x16x32_bf16 v[70:73], v[172:175], v[212:215], v[70:73]
	v_mfma_f32_16x16x32_bf16 v[66:69], v[180:183], v[212:215], v[66:69]
	s_setprio 0
	s_barrier
	s_add_i32 s53, s71, s31
	v_lshl_add_u64 v[218:219], s[34:35], 0, v[132:133]
	s_mov_b32 m0, s53
	ds_read_b128 v[184:187], v166 offset:16384
	ds_read_b128 v[188:191], v166 offset:17408
	ds_read_b128 v[192:195], v166 offset:18432
	ds_read_b128 v[196:199], v166 offset:19456
	ds_read_b128 v[200:203], v166 offset:20480
	ds_read_b128 v[204:207], v166 offset:21504
	ds_read_b128 v[208:211], v166 offset:22528
	ds_read_b128 v[212:215], v166 offset:23552
	global_load_lds_dwordx4 v[218:219], off
	s_add_i32 m0, s53, 0x2000
	s_add_u32 s54, s34, 0x160000
	v_lshl_add_u64 v[220:221], s[34:35], 0, v[136:137]
	s_addc_u32 s55, s35, 0
	s_add_i32 s53, s72, s31
	global_load_lds_dwordx4 v[220:221], off
	v_lshl_add_u64 v[222:223], s[54:55], 0, v[132:133]
	s_mov_b32 m0, s53
	v_lshl_add_u64 v[224:225], s[84:85], 0, v[134:135]
	global_load_lds_dwordx4 v[222:223], off
	v_lshl_add_u64 v[222:223], s[54:55], 0, v[136:137]
	s_add_i32 m0, s53, 0x2000
	s_nop 0
	global_load_lds_dwordx4 v[222:223], off
	v_lshl_add_u64 v[222:223], s[84:85], 0, v[130:131]
	s_mov_b32 m0, s33
	s_nop 0
	global_load_lds_dwordx4 v[222:223], off
	s_mov_b32 m0, s56
	s_nop 0
	global_load_lds_dwordx4 v[224:225], off
	s_waitcnt vmcnt(8)
	s_waitcnt lgkmcnt(0)
	s_barrier
	s_setprio 1
	s_waitcnt lgkmcnt(0)
	v_mfma_f32_16x16x32_bf16 v[62:65], v[146:149], v[184:187], v[62:65]
	v_mfma_f32_16x16x32_bf16 v[58:61], v[154:157], v[184:187], v[58:61]
	v_mfma_f32_16x16x32_bf16 v[54:57], v[168:171], v[184:187], v[54:57]
	v_mfma_f32_16x16x32_bf16 v[50:53], v[176:179], v[184:187], v[50:53]
	v_mfma_f32_16x16x32_bf16 v[46:49], v[146:149], v[192:195], v[46:49]
	v_mfma_f32_16x16x32_bf16 v[42:45], v[154:157], v[192:195], v[42:45]
	v_mfma_f32_16x16x32_bf16 v[38:41], v[168:171], v[192:195], v[38:41]
	v_mfma_f32_16x16x32_bf16 v[34:37], v[176:179], v[192:195], v[34:37]
	v_mfma_f32_16x16x32_bf16 v[30:33], v[146:149], v[200:203], v[30:33]
	v_mfma_f32_16x16x32_bf16 v[26:29], v[154:157], v[200:203], v[26:29]
	v_mfma_f32_16x16x32_bf16 v[22:25], v[168:171], v[200:203], v[22:25]
	v_mfma_f32_16x16x32_bf16 v[18:21], v[176:179], v[200:203], v[18:21]
	v_mfma_f32_16x16x32_bf16 v[14:17], v[146:149], v[208:211], v[14:17]
	v_mfma_f32_16x16x32_bf16 v[10:13], v[154:157], v[208:211], v[10:13]
	v_mfma_f32_16x16x32_bf16 v[6:9], v[168:171], v[208:211], v[6:9]
	v_mfma_f32_16x16x32_bf16 v[2:5], v[176:179], v[208:211], v[2:5]
	s_setprio 0
	s_setprio 1
	v_mfma_f32_16x16x32_bf16 v[62:65], v[150:153], v[188:191], v[62:65]
	v_mfma_f32_16x16x32_bf16 v[58:61], v[158:161], v[188:191], v[58:61]
	v_mfma_f32_16x16x32_bf16 v[54:57], v[172:175], v[188:191], v[54:57]
	v_mfma_f32_16x16x32_bf16 v[50:53], v[180:183], v[188:191], v[50:53]
	v_mfma_f32_16x16x32_bf16 v[46:49], v[150:153], v[196:199], v[46:49]
	v_mfma_f32_16x16x32_bf16 v[42:45], v[158:161], v[196:199], v[42:45]
	v_mfma_f32_16x16x32_bf16 v[38:41], v[172:175], v[196:199], v[38:41]
	v_mfma_f32_16x16x32_bf16 v[34:37], v[180:183], v[196:199], v[34:37]
	v_mfma_f32_16x16x32_bf16 v[30:33], v[150:153], v[204:207], v[30:33]
	v_mfma_f32_16x16x32_bf16 v[26:29], v[158:161], v[204:207], v[26:29]
	v_mfma_f32_16x16x32_bf16 v[22:25], v[172:175], v[204:207], v[22:25]
	v_mfma_f32_16x16x32_bf16 v[18:21], v[180:183], v[204:207], v[18:21]
	v_mfma_f32_16x16x32_bf16 v[14:17], v[150:153], v[212:215], v[14:17]
	v_mfma_f32_16x16x32_bf16 v[10:13], v[158:161], v[212:215], v[10:13]
	v_mfma_f32_16x16x32_bf16 v[6:9], v[172:175], v[212:215], v[6:9]
	v_mfma_f32_16x16x32_bf16 v[2:5], v[180:183], v[212:215], v[2:5]
	s_setprio 0
	s_barrier
	s_add_i32 s53, 0, 0x18000
	s_add_i32 s62, 0, 0x1c000
	v_add_u32_e32 v158, s53, v162
	v_add_u32_e32 v167, s62, v162
	ds_read_b128 v[146:149], v158
	ds_read_b128 v[150:153], v158 offset:1024
	ds_read_b128 v[154:157], v158 offset:2048
	ds_read_b128 v[158:161], v158 offset:3072
	ds_read_b128 v[168:171], v167
	ds_read_b128 v[172:175], v167 offset:1024
	ds_read_b128 v[176:179], v167 offset:2048
	ds_read_b128 v[180:183], v167 offset:3072
	s_add_u32 s54, s84, 0x160000
	s_addc_u32 s55, s85, 0
	s_mov_b32 m0, s57
	v_lshl_add_u64 v[226:227], s[54:55], 0, v[130:131]
	ds_read_b128 v[184:187], v166 offset:32768
	ds_read_b128 v[188:191], v166 offset:33792
	ds_read_b128 v[192:195], v166 offset:34816
	ds_read_b128 v[196:199], v166 offset:35840
	ds_read_b128 v[200:203], v166 offset:36864
	ds_read_b128 v[204:207], v166 offset:37888
	ds_read_b128 v[208:211], v166 offset:38912
	ds_read_b128 v[212:215], v166 offset:39936
	global_load_lds_dwordx4 v[226:227], off
	v_lshl_add_u64 v[226:227], s[54:55], 0, v[134:135]
	s_mov_b32 m0, s58
	s_nop 0
	global_load_lds_dwordx4 v[226:227], off
	s_waitcnt vmcnt(8)
	s_waitcnt lgkmcnt(0)
	s_barrier
	s_setprio 1
	s_waitcnt lgkmcnt(0)
	v_mfma_f32_16x16x32_bf16 v[126:129], v[146:149], v[184:187], v[126:129]
	v_mfma_f32_16x16x32_bf16 v[122:125], v[154:157], v[184:187], v[122:125]
	v_mfma_f32_16x16x32_bf16 v[118:121], v[168:171], v[184:187], v[118:121]
	v_mfma_f32_16x16x32_bf16 v[114:117], v[176:179], v[184:187], v[114:117]
	v_mfma_f32_16x16x32_bf16 v[110:113], v[146:149], v[192:195], v[110:113]
	v_mfma_f32_16x16x32_bf16 v[106:109], v[154:157], v[192:195], v[106:109]
	v_mfma_f32_16x16x32_bf16 v[102:105], v[168:171], v[192:195], v[102:105]
	v_mfma_f32_16x16x32_bf16 v[98:101], v[176:179], v[192:195], v[98:101]
	v_mfma_f32_16x16x32_bf16 v[94:97], v[146:149], v[200:203], v[94:97]
	v_mfma_f32_16x16x32_bf16 v[90:93], v[154:157], v[200:203], v[90:93]
	v_mfma_f32_16x16x32_bf16 v[86:89], v[168:171], v[200:203], v[86:89]
	v_mfma_f32_16x16x32_bf16 v[82:85], v[176:179], v[200:203], v[82:85]
	v_mfma_f32_16x16x32_bf16 v[78:81], v[146:149], v[208:211], v[78:81]
	v_mfma_f32_16x16x32_bf16 v[74:77], v[154:157], v[208:211], v[74:77]
	v_mfma_f32_16x16x32_bf16 v[70:73], v[168:171], v[208:211], v[70:73]
	v_mfma_f32_16x16x32_bf16 v[66:69], v[176:179], v[208:211], v[66:69]
	s_setprio 0
	s_setprio 1
	v_mfma_f32_16x16x32_bf16 v[126:129], v[150:153], v[188:191], v[126:129]
	v_mfma_f32_16x16x32_bf16 v[122:125], v[158:161], v[188:191], v[122:125]
	v_mfma_f32_16x16x32_bf16 v[118:121], v[172:175], v[188:191], v[118:121]
	v_mfma_f32_16x16x32_bf16 v[114:117], v[180:183], v[188:191], v[114:117]
	v_mfma_f32_16x16x32_bf16 v[110:113], v[150:153], v[196:199], v[110:113]
	v_mfma_f32_16x16x32_bf16 v[106:109], v[158:161], v[196:199], v[106:109]
	v_mfma_f32_16x16x32_bf16 v[102:105], v[172:175], v[196:199], v[102:105]
	v_mfma_f32_16x16x32_bf16 v[98:101], v[180:183], v[196:199], v[98:101]
	v_mfma_f32_16x16x32_bf16 v[94:97], v[150:153], v[204:207], v[94:97]
	v_mfma_f32_16x16x32_bf16 v[90:93], v[158:161], v[204:207], v[90:93]
	v_mfma_f32_16x16x32_bf16 v[86:89], v[172:175], v[204:207], v[86:89]
	v_mfma_f32_16x16x32_bf16 v[82:85], v[180:183], v[204:207], v[82:85]
	v_mfma_f32_16x16x32_bf16 v[78:81], v[150:153], v[212:215], v[78:81]
	v_mfma_f32_16x16x32_bf16 v[74:77], v[158:161], v[212:215], v[74:77]
	v_mfma_f32_16x16x32_bf16 v[70:73], v[172:175], v[212:215], v[70:73]
	v_mfma_f32_16x16x32_bf16 v[66:69], v[180:183], v[212:215], v[66:69]
	s_setprio 0
	s_barrier
	s_add_i32 s53, s53, s31
	v_lshl_add_u64 v[218:219], v[218:219], 0, s[78:79]
	s_mov_b32 m0, s53
	ds_read_b128 v[184:187], v166 offset:49152
	ds_read_b128 v[188:191], v166 offset:50176
	ds_read_b128 v[192:195], v166 offset:51200
	ds_read_b128 v[196:199], v166 offset:52224
	ds_read_b128 v[200:203], v166 offset:53248
	ds_read_b128 v[204:207], v166 offset:54272
	ds_read_b128 v[208:211], v166 offset:55296
	ds_read_b128 v[212:215], v166 offset:56320
	global_load_lds_dwordx4 v[218:219], off
	s_add_i32 m0, s53, 0x2000
	s_add_u32 s34, s34, 0x160080
	v_lshl_add_u64 v[218:219], v[220:221], 0, s[78:79]
	s_addc_u32 s35, s35, 0
	s_add_i32 s53, s62, s31
	global_load_lds_dwordx4 v[218:219], off
	v_lshl_add_u64 v[218:219], s[34:35], 0, v[132:133]
	s_mov_b32 m0, s53
	s_nop 0
	global_load_lds_dwordx4 v[218:219], off
	v_lshl_add_u64 v[218:219], s[34:35], 0, v[136:137]
	s_add_i32 m0, s53, 0x2000
	s_nop 0
	global_load_lds_dwordx4 v[218:219], off
	v_lshl_add_u64 v[218:219], v[222:223], 0, s[78:79]
	s_mov_b32 m0, s60
	s_nop 0
	global_load_lds_dwordx4 v[218:219], off
	v_lshl_add_u64 v[218:219], v[224:225], 0, s[78:79]
	s_mov_b32 m0, s61
	s_nop 0
	global_load_lds_dwordx4 v[218:219], off
	s_waitcnt vmcnt(8)
	s_waitcnt lgkmcnt(0)
	s_barrier
	s_setprio 1
	s_waitcnt lgkmcnt(0)
	v_mfma_f32_16x16x32_bf16 v[62:65], v[146:149], v[184:187], v[62:65]
	v_mfma_f32_16x16x32_bf16 v[58:61], v[154:157], v[184:187], v[58:61]
	v_mfma_f32_16x16x32_bf16 v[54:57], v[168:171], v[184:187], v[54:57]
	v_mfma_f32_16x16x32_bf16 v[50:53], v[176:179], v[184:187], v[50:53]
	v_mfma_f32_16x16x32_bf16 v[46:49], v[146:149], v[192:195], v[46:49]
	v_mfma_f32_16x16x32_bf16 v[42:45], v[154:157], v[192:195], v[42:45]
	v_mfma_f32_16x16x32_bf16 v[38:41], v[168:171], v[192:195], v[38:41]
	v_mfma_f32_16x16x32_bf16 v[34:37], v[176:179], v[192:195], v[34:37]
	v_mfma_f32_16x16x32_bf16 v[30:33], v[146:149], v[200:203], v[30:33]
	v_mfma_f32_16x16x32_bf16 v[26:29], v[154:157], v[200:203], v[26:29]
	v_mfma_f32_16x16x32_bf16 v[22:25], v[168:171], v[200:203], v[22:25]
	v_mfma_f32_16x16x32_bf16 v[18:21], v[176:179], v[200:203], v[18:21]
	v_mfma_f32_16x16x32_bf16 v[14:17], v[146:149], v[208:211], v[14:17]
	v_mfma_f32_16x16x32_bf16 v[10:13], v[154:157], v[208:211], v[10:13]
	v_mfma_f32_16x16x32_bf16 v[6:9], v[168:171], v[208:211], v[6:9]
	v_mfma_f32_16x16x32_bf16 v[2:5], v[176:179], v[208:211], v[2:5]
	s_setprio 0
	s_setprio 1
	v_mfma_f32_16x16x32_bf16 v[62:65], v[150:153], v[188:191], v[62:65]
	v_mfma_f32_16x16x32_bf16 v[58:61], v[158:161], v[188:191], v[58:61]
	v_mfma_f32_16x16x32_bf16 v[54:57], v[172:175], v[188:191], v[54:57]
	v_mfma_f32_16x16x32_bf16 v[50:53], v[180:183], v[188:191], v[50:53]
	v_mfma_f32_16x16x32_bf16 v[46:49], v[150:153], v[196:199], v[46:49]
	v_mfma_f32_16x16x32_bf16 v[42:45], v[158:161], v[196:199], v[42:45]
	v_mfma_f32_16x16x32_bf16 v[38:41], v[172:175], v[196:199], v[38:41]
	v_mfma_f32_16x16x32_bf16 v[34:37], v[180:183], v[196:199], v[34:37]
	v_mfma_f32_16x16x32_bf16 v[30:33], v[150:153], v[204:207], v[30:33]
	v_mfma_f32_16x16x32_bf16 v[26:29], v[158:161], v[204:207], v[26:29]
	v_mfma_f32_16x16x32_bf16 v[22:25], v[172:175], v[204:207], v[22:25]
	v_mfma_f32_16x16x32_bf16 v[18:21], v[180:183], v[204:207], v[18:21]
	v_mfma_f32_16x16x32_bf16 v[14:17], v[150:153], v[212:215], v[14:17]
	v_mfma_f32_16x16x32_bf16 v[10:13], v[158:161], v[212:215], v[10:13]
	v_mfma_f32_16x16x32_bf16 v[6:9], v[172:175], v[212:215], v[6:9]
	v_mfma_f32_16x16x32_bf16 v[2:5], v[180:183], v[212:215], v[2:5]
	s_setprio 0
	s_barrier
	s_add_i32 s52, s52, 2
	s_add_u32 s76, s76, 0x100
	s_addc_u32 s77, s77, 0
	s_add_u32 s0, s0, 0x100
	s_addc_u32 s1, s1, 0
	s_cmpk_gt_u32 s52, 0x55
	s_cbranch_scc0 .LBB0_1237
	s_and_b64 vcc, exec, s[80:81]
	s_cbranch_vccz .LBB0_1240
	s_barrier

.LBB0_1624:
	ds_read_b128 v[154:157], v151
	ds_read_b128 v[158:161], v151 offset:1024
	ds_read_b128 v[162:165], v151 offset:2048
	ds_read_b128 v[166:169], v151 offset:3072
	ds_read_b128 v[170:173], v152
	ds_read_b128 v[174:177], v152 offset:1024
	ds_read_b128 v[178:181], v152 offset:2048
	ds_read_b128 v[182:185], v152 offset:3072
	s_add_u32 s34, s88, 0xfff80080
	s_addc_u32 s35, s89, -1
	s_cmp_eq_u32 s83, 28
	s_cselect_b32 s91, s0, s35
	s_cselect_b32 s90, s1, s34
	s_cselect_b32 s35, s52, s81
	s_cselect_b32 s34, s75, s77
	v_lshl_add_u64 v[146:147], s[88:89], 0, v[138:139]
	s_add_i32 m0, s33, 0xc000
	ds_read_b128 v[186:189], v153
	ds_read_b128 v[190:193], v153 offset:1024
	ds_read_b128 v[194:197], v153 offset:2048
	ds_read_b128 v[198:201], v153 offset:3072
	ds_read_b128 v[202:205], v153 offset:4096
	ds_read_b128 v[206:209], v153 offset:5120
	ds_read_b128 v[210:213], v153 offset:6144
	ds_read_b128 v[218:221], v153 offset:7168
	global_load_lds_dwordx4 v[146:147], off
	v_lshl_add_u64 v[146:147], s[88:89], 0, v[140:141]
	s_add_i32 m0, s33, 0xe000
	s_nop 0
	global_load_lds_dwordx4 v[146:147], off
	s_waitcnt vmcnt(8)
	s_waitcnt lgkmcnt(0)
	s_barrier
	s_setprio 1
	s_waitcnt lgkmcnt(0)
	v_mfma_f32_16x16x32_bf16 v[126:129], v[154:157], v[186:189], v[126:129]
	v_mfma_f32_16x16x32_bf16 v[122:125], v[162:165], v[186:189], v[122:125]
	v_mfma_f32_16x16x32_bf16 v[118:121], v[170:173], v[186:189], v[118:121]
	v_mfma_f32_16x16x32_bf16 v[110:113], v[178:181], v[186:189], v[110:113]
	v_mfma_f32_16x16x32_bf16 v[114:117], v[154:157], v[194:197], v[114:117]
	v_mfma_f32_16x16x32_bf16 v[106:109], v[162:165], v[194:197], v[106:109]
	v_mfma_f32_16x16x32_bf16 v[102:105], v[170:173], v[194:197], v[102:105]
	v_mfma_f32_16x16x32_bf16 v[94:97], v[178:181], v[194:197], v[94:97]
	v_mfma_f32_16x16x32_bf16 v[98:101], v[154:157], v[202:205], v[98:101]
	v_mfma_f32_16x16x32_bf16 v[90:93], v[162:165], v[202:205], v[90:93]
	v_mfma_f32_16x16x32_bf16 v[86:89], v[170:173], v[202:205], v[86:89]
	v_mfma_f32_16x16x32_bf16 v[78:81], v[178:181], v[202:205], v[78:81]
	v_mfma_f32_16x16x32_bf16 v[82:85], v[154:157], v[210:213], v[82:85]
	v_mfma_f32_16x16x32_bf16 v[74:77], v[162:165], v[210:213], v[74:77]
	v_mfma_f32_16x16x32_bf16 v[70:73], v[170:173], v[210:213], v[70:73]
	v_mfma_f32_16x16x32_bf16 v[66:69], v[178:181], v[210:213], v[66:69]
	s_setprio 0
	s_setprio 1
	v_mfma_f32_16x16x32_bf16 v[126:129], v[158:161], v[190:193], v[126:129]
	v_mfma_f32_16x16x32_bf16 v[122:125], v[166:169], v[190:193], v[122:125]
	v_mfma_f32_16x16x32_bf16 v[118:121], v[174:177], v[190:193], v[118:121]
	v_mfma_f32_16x16x32_bf16 v[110:113], v[182:185], v[190:193], v[110:113]
	v_mfma_f32_16x16x32_bf16 v[114:117], v[158:161], v[198:201], v[114:117]
	v_mfma_f32_16x16x32_bf16 v[106:109], v[166:169], v[198:201], v[106:109]
	v_mfma_f32_16x16x32_bf16 v[102:105], v[174:177], v[198:201], v[102:105]
	v_mfma_f32_16x16x32_bf16 v[94:97], v[182:185], v[198:201], v[94:97]
	v_mfma_f32_16x16x32_bf16 v[98:101], v[158:161], v[206:209], v[98:101]
	v_mfma_f32_16x16x32_bf16 v[90:93], v[166:169], v[206:209], v[90:93]
	v_mfma_f32_16x16x32_bf16 v[86:89], v[174:177], v[206:209], v[86:89]
	v_mfma_f32_16x16x32_bf16 v[78:81], v[182:185], v[206:209], v[78:81]
	v_mfma_f32_16x16x32_bf16 v[82:85], v[158:161], v[218:221], v[82:85]
	v_mfma_f32_16x16x32_bf16 v[74:77], v[166:169], v[218:221], v[74:77]
	v_mfma_f32_16x16x32_bf16 v[70:73], v[174:177], v[218:221], v[70:73]
	v_mfma_f32_16x16x32_bf16 v[66:69], v[182:185], v[218:221], v[66:69]
	s_setprio 0
	s_barrier
	s_add_i32 s53, s71, s12
	v_lshl_add_u64 v[146:147], s[34:35], 0, v[134:135]
	s_mov_b32 m0, s53
	ds_read_b128 v[186:189], v153 offset:16384
	ds_read_b128 v[190:193], v153 offset:17408
	ds_read_b128 v[194:197], v153 offset:18432
	ds_read_b128 v[198:201], v153 offset:19456
	ds_read_b128 v[202:205], v153 offset:20480
	ds_read_b128 v[206:209], v153 offset:21504
	ds_read_b128 v[210:213], v153 offset:22528
	ds_read_b128 v[218:221], v153 offset:23552
	global_load_lds_dwordx4 v[146:147], off
	s_add_i32 m0, s53, 0x2000
	s_add_u32 s54, s34, 0x80000
	v_lshl_add_u64 v[214:215], s[34:35], 0, v[130:131]
	s_addc_u32 s55, s35, 0
	s_add_i32 s53, s72, s12
	global_load_lds_dwordx4 v[214:215], off
	v_lshl_add_u64 v[222:223], s[54:55], 0, v[134:135]
	s_mov_b32 m0, s53
	v_lshl_add_u64 v[224:225], s[90:91], 0, v[132:133]
	global_load_lds_dwordx4 v[222:223], off
	v_lshl_add_u64 v[222:223], s[54:55], 0, v[130:131]
	s_add_i32 m0, s53, 0x2000
	s_nop 0
	global_load_lds_dwordx4 v[222:223], off
	v_lshl_add_u64 v[222:223], s[90:91], 0, v[136:137]
	s_mov_b32 m0, s33
	s_nop 0
	global_load_lds_dwordx4 v[222:223], off
	s_mov_b32 m0, s56
	s_nop 0
	global_load_lds_dwordx4 v[224:225], off
	s_waitcnt vmcnt(8)
	s_waitcnt lgkmcnt(0)
	s_barrier
	s_setprio 1
	s_waitcnt lgkmcnt(0)
	v_mfma_f32_16x16x32_bf16 v[62:65], v[154:157], v[186:189], v[62:65]
	v_mfma_f32_16x16x32_bf16 v[58:61], v[162:165], v[186:189], v[58:61]
	v_mfma_f32_16x16x32_bf16 v[54:57], v[170:173], v[186:189], v[54:57]
	v_mfma_f32_16x16x32_bf16 v[46:49], v[178:181], v[186:189], v[46:49]
	v_mfma_f32_16x16x32_bf16 v[50:53], v[154:157], v[194:197], v[50:53]
	v_mfma_f32_16x16x32_bf16 v[42:45], v[162:165], v[194:197], v[42:45]
	v_mfma_f32_16x16x32_bf16 v[38:41], v[170:173], v[194:197], v[38:41]
	v_mfma_f32_16x16x32_bf16 v[30:33], v[178:181], v[194:197], v[30:33]
	v_mfma_f32_16x16x32_bf16 v[34:37], v[154:157], v[202:205], v[34:37]
	v_mfma_f32_16x16x32_bf16 v[26:29], v[162:165], v[202:205], v[26:29]
	v_mfma_f32_16x16x32_bf16 v[22:25], v[170:173], v[202:205], v[22:25]
	v_mfma_f32_16x16x32_bf16 v[14:17], v[178:181], v[202:205], v[14:17]
	v_mfma_f32_16x16x32_bf16 v[18:21], v[154:157], v[210:213], v[18:21]
	v_mfma_f32_16x16x32_bf16 v[10:13], v[162:165], v[210:213], v[10:13]
	v_mfma_f32_16x16x32_bf16 v[6:9], v[170:173], v[210:213], v[6:9]
	v_mfma_f32_16x16x32_bf16 v[2:5], v[178:181], v[210:213], v[2:5]
	s_setprio 0
	s_setprio 1
	v_mfma_f32_16x16x32_bf16 v[62:65], v[158:161], v[190:193], v[62:65]
	v_mfma_f32_16x16x32_bf16 v[58:61], v[166:169], v[190:193], v[58:61]
	v_mfma_f32_16x16x32_bf16 v[54:57], v[174:177], v[190:193], v[54:57]
	v_mfma_f32_16x16x32_bf16 v[46:49], v[182:185], v[190:193], v[46:49]
	v_mfma_f32_16x16x32_bf16 v[50:53], v[158:161], v[198:201], v[50:53]
	v_mfma_f32_16x16x32_bf16 v[42:45], v[166:169], v[198:201], v[42:45]
	v_mfma_f32_16x16x32_bf16 v[38:41], v[174:177], v[198:201], v[38:41]
	v_mfma_f32_16x16x32_bf16 v[30:33], v[182:185], v[198:201], v[30:33]
	v_mfma_f32_16x16x32_bf16 v[34:37], v[158:161], v[206:209], v[34:37]
	v_mfma_f32_16x16x32_bf16 v[26:29], v[166:169], v[206:209], v[26:29]
	v_mfma_f32_16x16x32_bf16 v[22:25], v[174:177], v[206:209], v[22:25]
	v_mfma_f32_16x16x32_bf16 v[14:17], v[182:185], v[206:209], v[14:17]
	v_mfma_f32_16x16x32_bf16 v[18:21], v[158:161], v[218:221], v[18:21]
	v_mfma_f32_16x16x32_bf16 v[10:13], v[166:169], v[218:221], v[10:13]
	v_mfma_f32_16x16x32_bf16 v[6:9], v[174:177], v[218:221], v[6:9]
	v_mfma_f32_16x16x32_bf16 v[2:5], v[182:185], v[218:221], v[2:5]
	s_setprio 0
	s_barrier
	s_add_i32 s53, 0, 0x18000
	s_add_i32 s62, 0, 0x1c000
	v_add_u32_e32 v166, s53, v149
	v_add_u32_e32 v182, s62, v149
	ds_read_b128 v[154:157], v166
	ds_read_b128 v[158:161], v166 offset:1024
	ds_read_b128 v[162:165], v166 offset:2048
	ds_read_b128 v[166:169], v166 offset:3072
	ds_read_b128 v[170:173], v182
	ds_read_b128 v[174:177], v182 offset:1024
	ds_read_b128 v[178:181], v182 offset:2048
	ds_read_b128 v[182:185], v182 offset:3072
	s_add_u32 s54, s90, 0x80000
	s_addc_u32 s55, s91, 0
	s_mov_b32 m0, s57
	v_lshl_add_u64 v[226:227], s[54:55], 0, v[136:137]
	ds_read_b128 v[186:189], v153 offset:32768
	ds_read_b128 v[190:193], v153 offset:33792
	ds_read_b128 v[194:197], v153 offset:34816
	ds_read_b128 v[198:201], v153 offset:35840
	ds_read_b128 v[202:205], v153 offset:36864
	ds_read_b128 v[206:209], v153 offset:37888
	ds_read_b128 v[210:213], v153 offset:38912
	ds_read_b128 v[218:221], v153 offset:39936
	global_load_lds_dwordx4 v[226:227], off
	v_lshl_add_u64 v[226:227], s[54:55], 0, v[132:133]
	s_mov_b32 m0, s58
	s_nop 0
	global_load_lds_dwordx4 v[226:227], off
	s_waitcnt vmcnt(8)
	s_waitcnt lgkmcnt(0)
	s_barrier
	s_setprio 1
	s_waitcnt lgkmcnt(0)
	v_mfma_f32_16x16x32_bf16 v[126:129], v[154:157], v[186:189], v[126:129]
	v_mfma_f32_16x16x32_bf16 v[122:125], v[162:165], v[186:189], v[122:125]
	v_mfma_f32_16x16x32_bf16 v[118:121], v[170:173], v[186:189], v[118:121]
	v_mfma_f32_16x16x32_bf16 v[110:113], v[178:181], v[186:189], v[110:113]
	v_mfma_f32_16x16x32_bf16 v[114:117], v[154:157], v[194:197], v[114:117]
	v_mfma_f32_16x16x32_bf16 v[106:109], v[162:165], v[194:197], v[106:109]
	v_mfma_f32_16x16x32_bf16 v[102:105], v[170:173], v[194:197], v[102:105]
	v_mfma_f32_16x16x32_bf16 v[94:97], v[178:181], v[194:197], v[94:97]
	v_mfma_f32_16x16x32_bf16 v[98:101], v[154:157], v[202:205], v[98:101]
	v_mfma_f32_16x16x32_bf16 v[90:93], v[162:165], v[202:205], v[90:93]
	v_mfma_f32_16x16x32_bf16 v[86:89], v[170:173], v[202:205], v[86:89]
	v_mfma_f32_16x16x32_bf16 v[78:81], v[178:181], v[202:205], v[78:81]
	v_mfma_f32_16x16x32_bf16 v[82:85], v[154:157], v[210:213], v[82:85]
	v_mfma_f32_16x16x32_bf16 v[74:77], v[162:165], v[210:213], v[74:77]
	v_mfma_f32_16x16x32_bf16 v[70:73], v[170:173], v[210:213], v[70:73]
	v_mfma_f32_16x16x32_bf16 v[66:69], v[178:181], v[210:213], v[66:69]
	s_setprio 0
	s_setprio 1
	v_mfma_f32_16x16x32_bf16 v[126:129], v[158:161], v[190:193], v[126:129]
	v_mfma_f32_16x16x32_bf16 v[122:125], v[166:169], v[190:193], v[122:125]
	v_mfma_f32_16x16x32_bf16 v[118:121], v[174:177], v[190:193], v[118:121]
	v_mfma_f32_16x16x32_bf16 v[110:113], v[182:185], v[190:193], v[110:113]
	v_mfma_f32_16x16x32_bf16 v[114:117], v[158:161], v[198:201], v[114:117]
	v_mfma_f32_16x16x32_bf16 v[106:109], v[166:169], v[198:201], v[106:109]
	v_mfma_f32_16x16x32_bf16 v[102:105], v[174:177], v[198:201], v[102:105]
	v_mfma_f32_16x16x32_bf16 v[94:97], v[182:185], v[198:201], v[94:97]
	v_mfma_f32_16x16x32_bf16 v[98:101], v[158:161], v[206:209], v[98:101]
	v_mfma_f32_16x16x32_bf16 v[90:93], v[166:169], v[206:209], v[90:93]
	v_mfma_f32_16x16x32_bf16 v[86:89], v[174:177], v[206:209], v[86:89]
	v_mfma_f32_16x16x32_bf16 v[78:81], v[182:185], v[206:209], v[78:81]
	v_mfma_f32_16x16x32_bf16 v[82:85], v[158:161], v[218:221], v[82:85]
	v_mfma_f32_16x16x32_bf16 v[74:77], v[166:169], v[218:221], v[74:77]
	v_mfma_f32_16x16x32_bf16 v[70:73], v[174:177], v[218:221], v[70:73]
	v_mfma_f32_16x16x32_bf16 v[66:69], v[182:185], v[218:221], v[66:69]
	s_setprio 0
	s_barrier
	s_add_i32 s53, s53, s12
	v_lshl_add_u64 v[146:147], v[146:147], 0, s[8:9]
	s_mov_b32 m0, s53
	ds_read_b128 v[186:189], v153 offset:49152
	ds_read_b128 v[190:193], v153 offset:50176
	ds_read_b128 v[194:197], v153 offset:51200
	ds_read_b128 v[198:201], v153 offset:52224
	ds_read_b128 v[202:205], v153 offset:53248
	ds_read_b128 v[206:209], v153 offset:54272
	ds_read_b128 v[210:213], v153 offset:55296
	ds_read_b128 v[218:221], v153 offset:56320
	global_load_lds_dwordx4 v[146:147], off
	s_add_i32 m0, s53, 0x2000
	s_add_u32 s34, s34, 0x80080
	v_lshl_add_u64 v[146:147], v[214:215], 0, s[8:9]
	s_addc_u32 s35, s35, 0
	s_add_i32 s53, s62, s12
	global_load_lds_dwordx4 v[146:147], off
	v_lshl_add_u64 v[146:147], s[34:35], 0, v[134:135]
	s_mov_b32 m0, s53
	s_nop 0
	global_load_lds_dwordx4 v[146:147], off
	v_lshl_add_u64 v[146:147], s[34:35], 0, v[130:131]
	s_add_i32 m0, s53, 0x2000
	s_nop 0
	global_load_lds_dwordx4 v[146:147], off
	v_lshl_add_u64 v[146:147], v[222:223], 0, s[8:9]
	s_mov_b32 m0, s60
	s_nop 0
	global_load_lds_dwordx4 v[146:147], off
	v_lshl_add_u64 v[146:147], v[224:225], 0, s[8:9]
	s_mov_b32 m0, s61
	s_nop 0
	global_load_lds_dwordx4 v[146:147], off
	s_waitcnt vmcnt(8)
	s_waitcnt lgkmcnt(0)
	s_barrier
	s_setprio 1
	s_waitcnt lgkmcnt(0)
	v_mfma_f32_16x16x32_bf16 v[62:65], v[154:157], v[186:189], v[62:65]
	v_mfma_f32_16x16x32_bf16 v[58:61], v[162:165], v[186:189], v[58:61]
	v_mfma_f32_16x16x32_bf16 v[54:57], v[170:173], v[186:189], v[54:57]
	v_mfma_f32_16x16x32_bf16 v[46:49], v[178:181], v[186:189], v[46:49]
	v_mfma_f32_16x16x32_bf16 v[50:53], v[154:157], v[194:197], v[50:53]
	v_mfma_f32_16x16x32_bf16 v[42:45], v[162:165], v[194:197], v[42:45]
	v_mfma_f32_16x16x32_bf16 v[38:41], v[170:173], v[194:197], v[38:41]
	v_mfma_f32_16x16x32_bf16 v[30:33], v[178:181], v[194:197], v[30:33]
	v_mfma_f32_16x16x32_bf16 v[34:37], v[154:157], v[202:205], v[34:37]
	v_mfma_f32_16x16x32_bf16 v[26:29], v[162:165], v[202:205], v[26:29]
	v_mfma_f32_16x16x32_bf16 v[22:25], v[170:173], v[202:205], v[22:25]
	v_mfma_f32_16x16x32_bf16 v[14:17], v[178:181], v[202:205], v[14:17]
	v_mfma_f32_16x16x32_bf16 v[18:21], v[154:157], v[210:213], v[18:21]
	v_mfma_f32_16x16x32_bf16 v[10:13], v[162:165], v[210:213], v[10:13]
	v_mfma_f32_16x16x32_bf16 v[6:9], v[170:173], v[210:213], v[6:9]
	v_mfma_f32_16x16x32_bf16 v[2:5], v[178:181], v[210:213], v[2:5]
	s_setprio 0
	s_setprio 1
	v_mfma_f32_16x16x32_bf16 v[62:65], v[158:161], v[190:193], v[62:65]
	v_mfma_f32_16x16x32_bf16 v[58:61], v[166:169], v[190:193], v[58:61]
	v_mfma_f32_16x16x32_bf16 v[54:57], v[174:177], v[190:193], v[54:57]
	v_mfma_f32_16x16x32_bf16 v[46:49], v[182:185], v[190:193], v[46:49]
	v_mfma_f32_16x16x32_bf16 v[50:53], v[158:161], v[198:201], v[50:53]
	v_mfma_f32_16x16x32_bf16 v[42:45], v[166:169], v[198:201], v[42:45]
	v_mfma_f32_16x16x32_bf16 v[38:41], v[174:177], v[198:201], v[38:41]
	v_mfma_f32_16x16x32_bf16 v[30:33], v[182:185], v[198:201], v[30:33]
	v_mfma_f32_16x16x32_bf16 v[34:37], v[158:161], v[206:209], v[34:37]
	v_mfma_f32_16x16x32_bf16 v[26:29], v[166:169], v[206:209], v[26:29]
	v_mfma_f32_16x16x32_bf16 v[22:25], v[174:177], v[206:209], v[22:25]
	v_mfma_f32_16x16x32_bf16 v[14:17], v[182:185], v[206:209], v[14:17]
	v_mfma_f32_16x16x32_bf16 v[18:21], v[158:161], v[218:221], v[18:21]
	v_mfma_f32_16x16x32_bf16 v[10:13], v[166:169], v[218:221], v[10:13]
	v_mfma_f32_16x16x32_bf16 v[6:9], v[174:177], v[218:221], v[6:9]
	v_mfma_f32_16x16x32_bf16 v[2:5], v[182:185], v[218:221], v[2:5]
	s_setprio 0
	s_barrier
	s_add_i32 s83, s83, 2
	s_add_u32 s88, s88, 0x100
	s_addc_u32 s89, s89, 0
	s_add_u32 s77, s77, 0x100
	s_addc_u32 s81, s81, 0
	s_cmp_gt_u32 s83, 29
	s_cbranch_scc0 .LBB0_1624
	s_and_b64 vcc, exec, s[78:79]
	s_cbranch_vccz .LBB0_1627
	s_barrier

.LBB0_2089:
	ds_read_b128 v[130:133], v178
	ds_read_b128 v[134:137], v178 offset:1024
	ds_read_b128 v[138:141], v178 offset:2048
	ds_read_b128 v[142:145], v178 offset:3072
	ds_read_b128 v[162:165], v179
	ds_read_b128 v[166:169], v179 offset:1024
	ds_read_b128 v[170:173], v179 offset:2048
	ds_read_b128 v[182:185], v179 offset:3072
	s_add_u32 s34, s38, 0xffea0080
	s_addc_u32 s35, s39, -1
	s_cmpk_eq_i32 s52, 0x54
	s_cselect_b32 s41, s5, s35
	s_cselect_b32 s40, s4, s34
	s_cselect_b32 s35, s37, s1
	s_cselect_b32 s34, s36, s0
	v_lshl_add_u64 v[174:175], s[38:39], 0, v[154:155]
	s_add_i32 m0, s33, 0xc000
	ds_read_b128 v[186:189], v180
	ds_read_b128 v[190:193], v180 offset:1024
	ds_read_b128 v[194:197], v180 offset:2048
	ds_read_b128 v[198:201], v180 offset:3072
	ds_read_b128 v[202:205], v180 offset:4096
	ds_read_b128 v[206:209], v180 offset:5120
	ds_read_b128 v[210:213], v180 offset:6144
	ds_read_b128 v[218:221], v180 offset:7168
	global_load_lds_dwordx4 v[174:175], off
	v_lshl_add_u64 v[174:175], s[38:39], 0, v[156:157]
	s_add_i32 m0, s33, 0xe000
	s_nop 0
	global_load_lds_dwordx4 v[174:175], off
	s_waitcnt vmcnt(8)
	s_waitcnt lgkmcnt(0)
	s_barrier
	s_setprio 1
	s_waitcnt lgkmcnt(0)
	v_mfma_f32_16x16x32_bf16 v[126:129], v[130:133], v[186:189], v[126:129]
	v_mfma_f32_16x16x32_bf16 v[122:125], v[138:141], v[186:189], v[122:125]
	v_mfma_f32_16x16x32_bf16 v[118:121], v[162:165], v[186:189], v[118:121]
	v_mfma_f32_16x16x32_bf16 v[114:117], v[170:173], v[186:189], v[114:117]
	v_mfma_f32_16x16x32_bf16 v[110:113], v[130:133], v[194:197], v[110:113]
	v_mfma_f32_16x16x32_bf16 v[106:109], v[138:141], v[194:197], v[106:109]
	v_mfma_f32_16x16x32_bf16 v[102:105], v[162:165], v[194:197], v[102:105]
	v_mfma_f32_16x16x32_bf16 v[98:101], v[170:173], v[194:197], v[98:101]
	v_mfma_f32_16x16x32_bf16 v[94:97], v[130:133], v[202:205], v[94:97]
	v_mfma_f32_16x16x32_bf16 v[90:93], v[138:141], v[202:205], v[90:93]
	v_mfma_f32_16x16x32_bf16 v[86:89], v[162:165], v[202:205], v[86:89]
	v_mfma_f32_16x16x32_bf16 v[82:85], v[170:173], v[202:205], v[82:85]
	v_mfma_f32_16x16x32_bf16 v[78:81], v[130:133], v[210:213], v[78:81]
	v_mfma_f32_16x16x32_bf16 v[74:77], v[138:141], v[210:213], v[74:77]
	v_mfma_f32_16x16x32_bf16 v[70:73], v[162:165], v[210:213], v[70:73]
	v_mfma_f32_16x16x32_bf16 v[66:69], v[170:173], v[210:213], v[66:69]
	s_setprio 0
	s_setprio 1
	v_mfma_f32_16x16x32_bf16 v[126:129], v[134:137], v[190:193], v[126:129]
	v_mfma_f32_16x16x32_bf16 v[122:125], v[142:145], v[190:193], v[122:125]
	v_mfma_f32_16x16x32_bf16 v[118:121], v[166:169], v[190:193], v[118:121]
	v_mfma_f32_16x16x32_bf16 v[114:117], v[182:185], v[190:193], v[114:117]
	v_mfma_f32_16x16x32_bf16 v[110:113], v[134:137], v[198:201], v[110:113]
	v_mfma_f32_16x16x32_bf16 v[106:109], v[142:145], v[198:201], v[106:109]
	v_mfma_f32_16x16x32_bf16 v[102:105], v[166:169], v[198:201], v[102:105]
	v_mfma_f32_16x16x32_bf16 v[98:101], v[182:185], v[198:201], v[98:101]
	v_mfma_f32_16x16x32_bf16 v[94:97], v[134:137], v[206:209], v[94:97]
	v_mfma_f32_16x16x32_bf16 v[90:93], v[142:145], v[206:209], v[90:93]
	v_mfma_f32_16x16x32_bf16 v[86:89], v[166:169], v[206:209], v[86:89]
	v_mfma_f32_16x16x32_bf16 v[82:85], v[182:185], v[206:209], v[82:85]
	v_mfma_f32_16x16x32_bf16 v[78:81], v[134:137], v[218:221], v[78:81]
	v_mfma_f32_16x16x32_bf16 v[74:77], v[142:145], v[218:221], v[74:77]
	v_mfma_f32_16x16x32_bf16 v[70:73], v[166:169], v[218:221], v[70:73]
	v_mfma_f32_16x16x32_bf16 v[66:69], v[182:185], v[218:221], v[66:69]
	s_setprio 0
	s_barrier
	s_add_i32 s53, s61, s31
	v_lshl_add_u64 v[174:175], s[34:35], 0, v[148:149]
	s_mov_b32 m0, s53
	ds_read_b128 v[186:189], v180 offset:16384
	ds_read_b128 v[190:193], v180 offset:17408
	ds_read_b128 v[194:197], v180 offset:18432
	ds_read_b128 v[198:201], v180 offset:19456
	ds_read_b128 v[202:205], v180 offset:20480
	ds_read_b128 v[206:209], v180 offset:21504
	ds_read_b128 v[210:213], v180 offset:22528
	ds_read_b128 v[218:221], v180 offset:23552
	global_load_lds_dwordx4 v[174:175], off
	s_add_i32 m0, s53, 0x2000
	s_add_u32 s54, s34, 0x160000
	v_lshl_add_u64 v[214:215], s[34:35], 0, v[152:153]
	s_addc_u32 s55, s35, 0
	s_add_i32 s53, s70, s31
	global_load_lds_dwordx4 v[214:215], off
	v_lshl_add_u64 v[222:223], s[54:55], 0, v[148:149]
	s_mov_b32 m0, s53
	v_lshl_add_u64 v[224:225], s[40:41], 0, v[150:151]
	global_load_lds_dwordx4 v[222:223], off
	v_lshl_add_u64 v[222:223], s[54:55], 0, v[152:153]
	s_add_i32 m0, s53, 0x2000
	s_nop 0
	global_load_lds_dwordx4 v[222:223], off
	v_lshl_add_u64 v[222:223], s[40:41], 0, v[146:147]
	s_mov_b32 m0, s33
	s_nop 0
	global_load_lds_dwordx4 v[222:223], off
	s_mov_b32 m0, s46
	s_nop 0
	global_load_lds_dwordx4 v[224:225], off
	s_waitcnt vmcnt(8)
	s_waitcnt lgkmcnt(0)
	s_barrier
	s_setprio 1
	s_waitcnt lgkmcnt(0)
	v_mfma_f32_16x16x32_bf16 v[62:65], v[130:133], v[186:189], v[62:65]
	v_mfma_f32_16x16x32_bf16 v[58:61], v[138:141], v[186:189], v[58:61]
	v_mfma_f32_16x16x32_bf16 v[54:57], v[162:165], v[186:189], v[54:57]
	v_mfma_f32_16x16x32_bf16 v[46:49], v[170:173], v[186:189], v[46:49]
	v_mfma_f32_16x16x32_bf16 v[50:53], v[130:133], v[194:197], v[50:53]
	v_mfma_f32_16x16x32_bf16 v[42:45], v[138:141], v[194:197], v[42:45]
	v_mfma_f32_16x16x32_bf16 v[30:33], v[162:165], v[194:197], v[30:33]
	v_mfma_f32_16x16x32_bf16 v[26:29], v[170:173], v[194:197], v[26:29]
	v_mfma_f32_16x16x32_bf16 v[38:41], v[130:133], v[202:205], v[38:41]
	v_mfma_f32_16x16x32_bf16 v[34:37], v[138:141], v[202:205], v[34:37]
	v_mfma_f32_16x16x32_bf16 v[22:25], v[162:165], v[202:205], v[22:25]
	v_mfma_f32_16x16x32_bf16 v[18:21], v[170:173], v[202:205], v[18:21]
	v_mfma_f32_16x16x32_bf16 v[14:17], v[130:133], v[210:213], v[14:17]
	v_mfma_f32_16x16x32_bf16 v[10:13], v[138:141], v[210:213], v[10:13]
	v_mfma_f32_16x16x32_bf16 v[6:9], v[162:165], v[210:213], v[6:9]
	v_mfma_f32_16x16x32_bf16 v[2:5], v[170:173], v[210:213], v[2:5]
	s_setprio 0
	s_setprio 1
	v_mfma_f32_16x16x32_bf16 v[62:65], v[134:137], v[190:193], v[62:65]
	v_mfma_f32_16x16x32_bf16 v[58:61], v[142:145], v[190:193], v[58:61]
	v_mfma_f32_16x16x32_bf16 v[54:57], v[166:169], v[190:193], v[54:57]
	v_mfma_f32_16x16x32_bf16 v[46:49], v[182:185], v[190:193], v[46:49]
	v_mfma_f32_16x16x32_bf16 v[50:53], v[134:137], v[198:201], v[50:53]
	v_mfma_f32_16x16x32_bf16 v[42:45], v[142:145], v[198:201], v[42:45]
	v_mfma_f32_16x16x32_bf16 v[30:33], v[166:169], v[198:201], v[30:33]
	v_mfma_f32_16x16x32_bf16 v[26:29], v[182:185], v[198:201], v[26:29]
	v_mfma_f32_16x16x32_bf16 v[38:41], v[134:137], v[206:209], v[38:41]
	v_mfma_f32_16x16x32_bf16 v[34:37], v[142:145], v[206:209], v[34:37]
	v_mfma_f32_16x16x32_bf16 v[22:25], v[166:169], v[206:209], v[22:25]
	v_mfma_f32_16x16x32_bf16 v[18:21], v[182:185], v[206:209], v[18:21]
	v_mfma_f32_16x16x32_bf16 v[14:17], v[134:137], v[218:221], v[14:17]
	v_mfma_f32_16x16x32_bf16 v[10:13], v[142:145], v[218:221], v[10:13]
	v_mfma_f32_16x16x32_bf16 v[6:9], v[166:169], v[218:221], v[6:9]
	v_mfma_f32_16x16x32_bf16 v[2:5], v[182:185], v[218:221], v[2:5]
	s_setprio 0
	s_barrier
	s_add_i32 s53, 0, 0x18000
	s_add_i32 s54, 0, 0x1c000
	v_add_u32_e32 v142, s53, v176
	v_add_u32_e32 v181, s54, v176
	ds_read_b128 v[130:133], v142
	ds_read_b128 v[134:137], v142 offset:1024
	ds_read_b128 v[138:141], v142 offset:2048
	ds_read_b128 v[142:145], v142 offset:3072
	ds_read_b128 v[162:165], v181
	ds_read_b128 v[166:169], v181 offset:1024
	ds_read_b128 v[170:173], v181 offset:2048
	ds_read_b128 v[182:185], v181 offset:3072
	s_add_u32 s40, s40, 0x160000
	s_addc_u32 s41, s41, 0
	s_mov_b32 m0, s47
	v_lshl_add_u64 v[226:227], s[40:41], 0, v[146:147]
	ds_read_b128 v[186:189], v180 offset:32768
	ds_read_b128 v[190:193], v180 offset:33792
	ds_read_b128 v[194:197], v180 offset:34816
	ds_read_b128 v[198:201], v180 offset:35840
	ds_read_b128 v[202:205], v180 offset:36864
	ds_read_b128 v[206:209], v180 offset:37888
	ds_read_b128 v[210:213], v180 offset:38912
	ds_read_b128 v[218:221], v180 offset:39936
	global_load_lds_dwordx4 v[226:227], off
	v_lshl_add_u64 v[226:227], s[40:41], 0, v[150:151]
	s_mov_b32 m0, s56
	s_nop 0
	global_load_lds_dwordx4 v[226:227], off
	s_waitcnt vmcnt(8)
	s_waitcnt lgkmcnt(0)
	s_barrier
	s_setprio 1
	s_waitcnt lgkmcnt(0)
	v_mfma_f32_16x16x32_bf16 v[126:129], v[130:133], v[186:189], v[126:129]
	v_mfma_f32_16x16x32_bf16 v[122:125], v[138:141], v[186:189], v[122:125]
	v_mfma_f32_16x16x32_bf16 v[118:121], v[162:165], v[186:189], v[118:121]
	v_mfma_f32_16x16x32_bf16 v[114:117], v[170:173], v[186:189], v[114:117]
	v_mfma_f32_16x16x32_bf16 v[110:113], v[130:133], v[194:197], v[110:113]
	v_mfma_f32_16x16x32_bf16 v[106:109], v[138:141], v[194:197], v[106:109]
	v_mfma_f32_16x16x32_bf16 v[102:105], v[162:165], v[194:197], v[102:105]
	v_mfma_f32_16x16x32_bf16 v[98:101], v[170:173], v[194:197], v[98:101]
	v_mfma_f32_16x16x32_bf16 v[94:97], v[130:133], v[202:205], v[94:97]
	v_mfma_f32_16x16x32_bf16 v[90:93], v[138:141], v[202:205], v[90:93]
	v_mfma_f32_16x16x32_bf16 v[86:89], v[162:165], v[202:205], v[86:89]
	v_mfma_f32_16x16x32_bf16 v[82:85], v[170:173], v[202:205], v[82:85]
	v_mfma_f32_16x16x32_bf16 v[78:81], v[130:133], v[210:213], v[78:81]
	v_mfma_f32_16x16x32_bf16 v[74:77], v[138:141], v[210:213], v[74:77]
	v_mfma_f32_16x16x32_bf16 v[70:73], v[162:165], v[210:213], v[70:73]
	v_mfma_f32_16x16x32_bf16 v[66:69], v[170:173], v[210:213], v[66:69]
	s_setprio 0
	s_setprio 1
	v_mfma_f32_16x16x32_bf16 v[126:129], v[134:137], v[190:193], v[126:129]
	v_mfma_f32_16x16x32_bf16 v[122:125], v[142:145], v[190:193], v[122:125]
	v_mfma_f32_16x16x32_bf16 v[118:121], v[166:169], v[190:193], v[118:121]
	v_mfma_f32_16x16x32_bf16 v[114:117], v[182:185], v[190:193], v[114:117]
	v_mfma_f32_16x16x32_bf16 v[110:113], v[134:137], v[198:201], v[110:113]
	v_mfma_f32_16x16x32_bf16 v[106:109], v[142:145], v[198:201], v[106:109]
	v_mfma_f32_16x16x32_bf16 v[102:105], v[166:169], v[198:201], v[102:105]
	v_mfma_f32_16x16x32_bf16 v[98:101], v[182:185], v[198:201], v[98:101]
	v_mfma_f32_16x16x32_bf16 v[94:97], v[134:137], v[206:209], v[94:97]
	v_mfma_f32_16x16x32_bf16 v[90:93], v[142:145], v[206:209], v[90:93]
	v_mfma_f32_16x16x32_bf16 v[86:89], v[166:169], v[206:209], v[86:89]
	v_mfma_f32_16x16x32_bf16 v[82:85], v[182:185], v[206:209], v[82:85]
	v_mfma_f32_16x16x32_bf16 v[78:81], v[134:137], v[218:221], v[78:81]
	v_mfma_f32_16x16x32_bf16 v[74:77], v[142:145], v[218:221], v[74:77]
	v_mfma_f32_16x16x32_bf16 v[70:73], v[166:169], v[218:221], v[70:73]
	v_mfma_f32_16x16x32_bf16 v[66:69], v[182:185], v[218:221], v[66:69]
	s_setprio 0
	s_barrier
	s_add_i32 s40, s53, s31
	v_lshl_add_u64 v[174:175], v[174:175], 0, s[24:25]
	s_mov_b32 m0, s40
	ds_read_b128 v[186:189], v180 offset:49152
	ds_read_b128 v[190:193], v180 offset:50176
	ds_read_b128 v[194:197], v180 offset:51200
	ds_read_b128 v[198:201], v180 offset:52224
	ds_read_b128 v[202:205], v180 offset:53248
	ds_read_b128 v[206:209], v180 offset:54272
	ds_read_b128 v[210:213], v180 offset:55296
	ds_read_b128 v[218:221], v180 offset:56320
	global_load_lds_dwordx4 v[174:175], off
	s_add_i32 m0, s40, 0x2000
	s_add_u32 s34, s34, 0x160080
	v_lshl_add_u64 v[174:175], v[214:215], 0, s[24:25]
	s_addc_u32 s35, s35, 0
	s_add_i32 s40, s54, s31
	global_load_lds_dwordx4 v[174:175], off
	v_lshl_add_u64 v[174:175], s[34:35], 0, v[148:149]
	s_mov_b32 m0, s40
	s_nop 0
	global_load_lds_dwordx4 v[174:175], off
	v_lshl_add_u64 v[174:175], s[34:35], 0, v[152:153]
	s_add_i32 m0, s40, 0x2000
	s_nop 0
	global_load_lds_dwordx4 v[174:175], off
	v_lshl_add_u64 v[174:175], v[222:223], 0, s[24:25]
	s_mov_b32 m0, s58
	s_nop 0
	global_load_lds_dwordx4 v[174:175], off
	v_lshl_add_u64 v[174:175], v[224:225], 0, s[24:25]
	s_mov_b32 m0, s59
	s_nop 0
	global_load_lds_dwordx4 v[174:175], off
	s_waitcnt vmcnt(8)
	s_waitcnt lgkmcnt(0)
	s_barrier
	s_setprio 1
	s_waitcnt lgkmcnt(0)
	v_mfma_f32_16x16x32_bf16 v[62:65], v[130:133], v[186:189], v[62:65]
	v_mfma_f32_16x16x32_bf16 v[58:61], v[138:141], v[186:189], v[58:61]
	v_mfma_f32_16x16x32_bf16 v[54:57], v[162:165], v[186:189], v[54:57]
	v_mfma_f32_16x16x32_bf16 v[46:49], v[170:173], v[186:189], v[46:49]
	v_mfma_f32_16x16x32_bf16 v[50:53], v[130:133], v[194:197], v[50:53]
	v_mfma_f32_16x16x32_bf16 v[42:45], v[138:141], v[194:197], v[42:45]
	v_mfma_f32_16x16x32_bf16 v[30:33], v[162:165], v[194:197], v[30:33]
	v_mfma_f32_16x16x32_bf16 v[26:29], v[170:173], v[194:197], v[26:29]
	v_mfma_f32_16x16x32_bf16 v[38:41], v[130:133], v[202:205], v[38:41]
	v_mfma_f32_16x16x32_bf16 v[34:37], v[138:141], v[202:205], v[34:37]
	v_mfma_f32_16x16x32_bf16 v[22:25], v[162:165], v[202:205], v[22:25]
	v_mfma_f32_16x16x32_bf16 v[18:21], v[170:173], v[202:205], v[18:21]
	v_mfma_f32_16x16x32_bf16 v[14:17], v[130:133], v[210:213], v[14:17]
	v_mfma_f32_16x16x32_bf16 v[10:13], v[138:141], v[210:213], v[10:13]
	v_mfma_f32_16x16x32_bf16 v[6:9], v[162:165], v[210:213], v[6:9]
	v_mfma_f32_16x16x32_bf16 v[2:5], v[170:173], v[210:213], v[2:5]
	s_setprio 0
	s_setprio 1
	v_mfma_f32_16x16x32_bf16 v[62:65], v[134:137], v[190:193], v[62:65]
	v_mfma_f32_16x16x32_bf16 v[58:61], v[142:145], v[190:193], v[58:61]
	v_mfma_f32_16x16x32_bf16 v[54:57], v[166:169], v[190:193], v[54:57]
	v_mfma_f32_16x16x32_bf16 v[46:49], v[182:185], v[190:193], v[46:49]
	v_mfma_f32_16x16x32_bf16 v[50:53], v[134:137], v[198:201], v[50:53]
	v_mfma_f32_16x16x32_bf16 v[42:45], v[142:145], v[198:201], v[42:45]
	v_mfma_f32_16x16x32_bf16 v[30:33], v[166:169], v[198:201], v[30:33]
	v_mfma_f32_16x16x32_bf16 v[26:29], v[182:185], v[198:201], v[26:29]
	v_mfma_f32_16x16x32_bf16 v[38:41], v[134:137], v[206:209], v[38:41]
	v_mfma_f32_16x16x32_bf16 v[34:37], v[142:145], v[206:209], v[34:37]
	v_mfma_f32_16x16x32_bf16 v[22:25], v[166:169], v[206:209], v[22:25]
	v_mfma_f32_16x16x32_bf16 v[18:21], v[182:185], v[206:209], v[18:21]
	v_mfma_f32_16x16x32_bf16 v[14:17], v[134:137], v[218:221], v[14:17]
	v_mfma_f32_16x16x32_bf16 v[10:13], v[142:145], v[218:221], v[10:13]
	v_mfma_f32_16x16x32_bf16 v[6:9], v[166:169], v[218:221], v[6:9]
	v_mfma_f32_16x16x32_bf16 v[2:5], v[182:185], v[218:221], v[2:5]
	s_setprio 0
	s_barrier
	s_add_i32 s52, s52, 2
	s_add_u32 s38, s38, 0x100
	s_addc_u32 s39, s39, 0
	s_add_u32 s0, s0, 0x100
	s_addc_u32 s1, s1, 0
	s_cmpk_gt_u32 s52, 0x55
	s_cbranch_scc0 .LBB0_2089
	s_and_b64 vcc, exec, s[26:27]
	s_cbranch_vccz .LBB0_2092
	s_barrier

.LBB0_2218:
	ds_read_b128 v[146:149], v153
	ds_read_b128 v[156:159], v153 offset:1024
	ds_read_b128 v[160:163], v153 offset:2048
	ds_read_b128 v[164:167], v153 offset:3072
	ds_read_b128 v[168:171], v154
	ds_read_b128 v[172:175], v154 offset:1024
	ds_read_b128 v[176:179], v154 offset:2048
	ds_read_b128 v[180:183], v154 offset:3072
	s_add_u32 s34, s76, 0xfff80080
	s_addc_u32 s35, s77, -1
	s_cmp_eq_u32 s80, 28
	s_cselect_b32 s79, s0, s35
	s_cselect_b32 s78, s1, s34
	s_cselect_b32 s35, s27, s75
	s_cselect_b32 s34, s37, s52
	v_lshl_add_u64 v[218:219], s[76:77], 0, v[138:139]
	s_add_i32 m0, s47, 0xc000
	ds_read_b128 v[184:187], v155
	ds_read_b128 v[188:191], v155 offset:1024
	ds_read_b128 v[192:195], v155 offset:2048
	ds_read_b128 v[196:199], v155 offset:3072
	ds_read_b128 v[200:203], v155 offset:4096
	ds_read_b128 v[204:207], v155 offset:5120
	ds_read_b128 v[208:211], v155 offset:6144
	ds_read_b128 v[212:215], v155 offset:7168
	global_load_lds_dwordx4 v[218:219], off
	v_lshl_add_u64 v[218:219], s[76:77], 0, v[140:141]
	s_add_i32 m0, s47, 0xe000
	s_nop 0
	global_load_lds_dwordx4 v[218:219], off
	s_waitcnt vmcnt(8)
	s_waitcnt lgkmcnt(0)
	s_barrier
	s_setprio 1
	s_waitcnt lgkmcnt(0)
	v_mfma_f32_16x16x32_bf16 v[126:129], v[146:149], v[184:187], v[126:129]
	v_mfma_f32_16x16x32_bf16 v[118:121], v[160:163], v[184:187], v[118:121]
	v_mfma_f32_16x16x32_bf16 v[122:125], v[168:171], v[184:187], v[122:125]
	v_mfma_f32_16x16x32_bf16 v[114:117], v[176:179], v[184:187], v[114:117]
	v_mfma_f32_16x16x32_bf16 v[110:113], v[146:149], v[192:195], v[110:113]
	v_mfma_f32_16x16x32_bf16 v[102:105], v[160:163], v[192:195], v[102:105]
	v_mfma_f32_16x16x32_bf16 v[106:109], v[168:171], v[192:195], v[106:109]
	v_mfma_f32_16x16x32_bf16 v[98:101], v[176:179], v[192:195], v[98:101]
	v_mfma_f32_16x16x32_bf16 v[94:97], v[146:149], v[200:203], v[94:97]
	v_mfma_f32_16x16x32_bf16 v[86:89], v[160:163], v[200:203], v[86:89]
	v_mfma_f32_16x16x32_bf16 v[90:93], v[168:171], v[200:203], v[90:93]
	v_mfma_f32_16x16x32_bf16 v[82:85], v[176:179], v[200:203], v[82:85]
	v_mfma_f32_16x16x32_bf16 v[78:81], v[146:149], v[208:211], v[78:81]
	v_mfma_f32_16x16x32_bf16 v[70:73], v[160:163], v[208:211], v[70:73]
	v_mfma_f32_16x16x32_bf16 v[74:77], v[168:171], v[208:211], v[74:77]
	v_mfma_f32_16x16x32_bf16 v[66:69], v[176:179], v[208:211], v[66:69]
	s_setprio 0
	s_setprio 1
	v_mfma_f32_16x16x32_bf16 v[126:129], v[156:159], v[188:191], v[126:129]
	v_mfma_f32_16x16x32_bf16 v[118:121], v[164:167], v[188:191], v[118:121]
	v_mfma_f32_16x16x32_bf16 v[122:125], v[172:175], v[188:191], v[122:125]
	v_mfma_f32_16x16x32_bf16 v[114:117], v[180:183], v[188:191], v[114:117]
	v_mfma_f32_16x16x32_bf16 v[110:113], v[156:159], v[196:199], v[110:113]
	v_mfma_f32_16x16x32_bf16 v[102:105], v[164:167], v[196:199], v[102:105]
	v_mfma_f32_16x16x32_bf16 v[106:109], v[172:175], v[196:199], v[106:109]
	v_mfma_f32_16x16x32_bf16 v[98:101], v[180:183], v[196:199], v[98:101]
	v_mfma_f32_16x16x32_bf16 v[94:97], v[156:159], v[204:207], v[94:97]
	v_mfma_f32_16x16x32_bf16 v[86:89], v[164:167], v[204:207], v[86:89]
	v_mfma_f32_16x16x32_bf16 v[90:93], v[172:175], v[204:207], v[90:93]
	v_mfma_f32_16x16x32_bf16 v[82:85], v[180:183], v[204:207], v[82:85]
	v_mfma_f32_16x16x32_bf16 v[78:81], v[156:159], v[212:215], v[78:81]
	v_mfma_f32_16x16x32_bf16 v[70:73], v[164:167], v[212:215], v[70:73]
	v_mfma_f32_16x16x32_bf16 v[74:77], v[172:175], v[212:215], v[74:77]
	v_mfma_f32_16x16x32_bf16 v[66:69], v[180:183], v[212:215], v[66:69]
	s_setprio 0
	s_barrier
	s_add_i32 s53, s71, s30
	v_lshl_add_u64 v[218:219], s[34:35], 0, v[134:135]
	s_mov_b32 m0, s53
	ds_read_b128 v[184:187], v155 offset:16384
	ds_read_b128 v[188:191], v155 offset:17408
	ds_read_b128 v[192:195], v155 offset:18432
	ds_read_b128 v[196:199], v155 offset:19456
	ds_read_b128 v[200:203], v155 offset:20480
	ds_read_b128 v[204:207], v155 offset:21504
	ds_read_b128 v[208:211], v155 offset:22528
	ds_read_b128 v[212:215], v155 offset:23552
	global_load_lds_dwordx4 v[218:219], off
	s_add_i32 m0, s53, 0x2000
	s_add_u32 s54, s34, 0x80000
	v_lshl_add_u64 v[220:221], s[34:35], 0, v[130:131]
	s_addc_u32 s55, s35, 0
	s_add_i32 s53, s72, s30
	global_load_lds_dwordx4 v[220:221], off
	v_lshl_add_u64 v[222:223], s[54:55], 0, v[134:135]
	s_mov_b32 m0, s53
	v_lshl_add_u64 v[224:225], s[78:79], 0, v[132:133]
	global_load_lds_dwordx4 v[222:223], off
	v_lshl_add_u64 v[222:223], s[54:55], 0, v[130:131]
	s_add_i32 m0, s53, 0x2000
	s_nop 0
	global_load_lds_dwordx4 v[222:223], off
	v_lshl_add_u64 v[222:223], s[78:79], 0, v[136:137]
	s_mov_b32 m0, s47
	s_nop 0
	global_load_lds_dwordx4 v[222:223], off
	s_mov_b32 m0, s56
	s_nop 0
	global_load_lds_dwordx4 v[224:225], off
	s_waitcnt vmcnt(8)
	s_waitcnt lgkmcnt(0)
	s_barrier
	s_setprio 1
	s_waitcnt lgkmcnt(0)
	v_mfma_f32_16x16x32_bf16 v[62:65], v[146:149], v[184:187], v[62:65]
	v_mfma_f32_16x16x32_bf16 v[54:57], v[160:163], v[184:187], v[54:57]
	v_mfma_f32_16x16x32_bf16 v[58:61], v[168:171], v[184:187], v[58:61]
	v_mfma_f32_16x16x32_bf16 v[50:53], v[176:179], v[184:187], v[50:53]
	v_mfma_f32_16x16x32_bf16 v[46:49], v[146:149], v[192:195], v[46:49]
	v_mfma_f32_16x16x32_bf16 v[38:41], v[160:163], v[192:195], v[38:41]
	v_mfma_f32_16x16x32_bf16 v[42:45], v[168:171], v[192:195], v[42:45]
	v_mfma_f32_16x16x32_bf16 v[34:37], v[176:179], v[192:195], v[34:37]
	v_mfma_f32_16x16x32_bf16 v[30:33], v[146:149], v[200:203], v[30:33]
	v_mfma_f32_16x16x32_bf16 v[22:25], v[160:163], v[200:203], v[22:25]
	v_mfma_f32_16x16x32_bf16 v[26:29], v[168:171], v[200:203], v[26:29]
	v_mfma_f32_16x16x32_bf16 v[18:21], v[176:179], v[200:203], v[18:21]
	v_mfma_f32_16x16x32_bf16 v[14:17], v[146:149], v[208:211], v[14:17]
	v_mfma_f32_16x16x32_bf16 v[6:9], v[160:163], v[208:211], v[6:9]
	v_mfma_f32_16x16x32_bf16 v[10:13], v[168:171], v[208:211], v[10:13]
	v_mfma_f32_16x16x32_bf16 v[2:5], v[176:179], v[208:211], v[2:5]
	s_setprio 0
	s_setprio 1
	v_mfma_f32_16x16x32_bf16 v[62:65], v[156:159], v[188:191], v[62:65]
	v_mfma_f32_16x16x32_bf16 v[54:57], v[164:167], v[188:191], v[54:57]
	v_mfma_f32_16x16x32_bf16 v[58:61], v[172:175], v[188:191], v[58:61]
	v_mfma_f32_16x16x32_bf16 v[50:53], v[180:183], v[188:191], v[50:53]
	v_mfma_f32_16x16x32_bf16 v[46:49], v[156:159], v[196:199], v[46:49]
	v_mfma_f32_16x16x32_bf16 v[38:41], v[164:167], v[196:199], v[38:41]
	v_mfma_f32_16x16x32_bf16 v[42:45], v[172:175], v[196:199], v[42:45]
	v_mfma_f32_16x16x32_bf16 v[34:37], v[180:183], v[196:199], v[34:37]
	v_mfma_f32_16x16x32_bf16 v[30:33], v[156:159], v[204:207], v[30:33]
	v_mfma_f32_16x16x32_bf16 v[22:25], v[164:167], v[204:207], v[22:25]
	v_mfma_f32_16x16x32_bf16 v[26:29], v[172:175], v[204:207], v[26:29]
	v_mfma_f32_16x16x32_bf16 v[18:21], v[180:183], v[204:207], v[18:21]
	v_mfma_f32_16x16x32_bf16 v[14:17], v[156:159], v[212:215], v[14:17]
	v_mfma_f32_16x16x32_bf16 v[6:9], v[164:167], v[212:215], v[6:9]
	v_mfma_f32_16x16x32_bf16 v[10:13], v[172:175], v[212:215], v[10:13]
	v_mfma_f32_16x16x32_bf16 v[2:5], v[180:183], v[212:215], v[2:5]
	s_setprio 0
	s_barrier
	s_add_i32 s53, 0, 0x18000
	s_add_i32 s62, 0, 0x1c000
	v_add_u32_e32 v164, s53, v151
	v_add_u32_e32 v180, s62, v151
	ds_read_b128 v[146:149], v164
	ds_read_b128 v[156:159], v164 offset:1024
	ds_read_b128 v[160:163], v164 offset:2048
	ds_read_b128 v[164:167], v164 offset:3072
	ds_read_b128 v[168:171], v180
	ds_read_b128 v[172:175], v180 offset:1024
	ds_read_b128 v[176:179], v180 offset:2048
	ds_read_b128 v[180:183], v180 offset:3072
	s_add_u32 s54, s78, 0x80000
	s_addc_u32 s55, s79, 0
	s_mov_b32 m0, s57
	v_lshl_add_u64 v[226:227], s[54:55], 0, v[136:137]
	ds_read_b128 v[184:187], v155 offset:32768
	ds_read_b128 v[188:191], v155 offset:33792
	ds_read_b128 v[192:195], v155 offset:34816
	ds_read_b128 v[196:199], v155 offset:35840
	ds_read_b128 v[200:203], v155 offset:36864
	ds_read_b128 v[204:207], v155 offset:37888
	ds_read_b128 v[208:211], v155 offset:38912
	ds_read_b128 v[212:215], v155 offset:39936
	global_load_lds_dwordx4 v[226:227], off
	v_lshl_add_u64 v[226:227], s[54:55], 0, v[132:133]
	s_mov_b32 m0, s58
	s_nop 0
	global_load_lds_dwordx4 v[226:227], off
	s_waitcnt vmcnt(8)
	s_waitcnt lgkmcnt(0)
	s_barrier
	s_setprio 1
	s_waitcnt lgkmcnt(0)
	v_mfma_f32_16x16x32_bf16 v[126:129], v[146:149], v[184:187], v[126:129]
	v_mfma_f32_16x16x32_bf16 v[118:121], v[160:163], v[184:187], v[118:121]
	v_mfma_f32_16x16x32_bf16 v[122:125], v[168:171], v[184:187], v[122:125]
	v_mfma_f32_16x16x32_bf16 v[114:117], v[176:179], v[184:187], v[114:117]
	v_mfma_f32_16x16x32_bf16 v[110:113], v[146:149], v[192:195], v[110:113]
	v_mfma_f32_16x16x32_bf16 v[102:105], v[160:163], v[192:195], v[102:105]
	v_mfma_f32_16x16x32_bf16 v[106:109], v[168:171], v[192:195], v[106:109]
	v_mfma_f32_16x16x32_bf16 v[98:101], v[176:179], v[192:195], v[98:101]
	v_mfma_f32_16x16x32_bf16 v[94:97], v[146:149], v[200:203], v[94:97]
	v_mfma_f32_16x16x32_bf16 v[86:89], v[160:163], v[200:203], v[86:89]
	v_mfma_f32_16x16x32_bf16 v[90:93], v[168:171], v[200:203], v[90:93]
	v_mfma_f32_16x16x32_bf16 v[82:85], v[176:179], v[200:203], v[82:85]
	v_mfma_f32_16x16x32_bf16 v[78:81], v[146:149], v[208:211], v[78:81]
	v_mfma_f32_16x16x32_bf16 v[70:73], v[160:163], v[208:211], v[70:73]
	v_mfma_f32_16x16x32_bf16 v[74:77], v[168:171], v[208:211], v[74:77]
	v_mfma_f32_16x16x32_bf16 v[66:69], v[176:179], v[208:211], v[66:69]
	s_setprio 0
	s_setprio 1
	v_mfma_f32_16x16x32_bf16 v[126:129], v[156:159], v[188:191], v[126:129]
	v_mfma_f32_16x16x32_bf16 v[118:121], v[164:167], v[188:191], v[118:121]
	v_mfma_f32_16x16x32_bf16 v[122:125], v[172:175], v[188:191], v[122:125]
	v_mfma_f32_16x16x32_bf16 v[114:117], v[180:183], v[188:191], v[114:117]
	v_mfma_f32_16x16x32_bf16 v[110:113], v[156:159], v[196:199], v[110:113]
	v_mfma_f32_16x16x32_bf16 v[102:105], v[164:167], v[196:199], v[102:105]
	v_mfma_f32_16x16x32_bf16 v[106:109], v[172:175], v[196:199], v[106:109]
	v_mfma_f32_16x16x32_bf16 v[98:101], v[180:183], v[196:199], v[98:101]
	v_mfma_f32_16x16x32_bf16 v[94:97], v[156:159], v[204:207], v[94:97]
	v_mfma_f32_16x16x32_bf16 v[86:89], v[164:167], v[204:207], v[86:89]
	v_mfma_f32_16x16x32_bf16 v[90:93], v[172:175], v[204:207], v[90:93]
	v_mfma_f32_16x16x32_bf16 v[82:85], v[180:183], v[204:207], v[82:85]
	v_mfma_f32_16x16x32_bf16 v[78:81], v[156:159], v[212:215], v[78:81]
	v_mfma_f32_16x16x32_bf16 v[70:73], v[164:167], v[212:215], v[70:73]
	v_mfma_f32_16x16x32_bf16 v[74:77], v[172:175], v[212:215], v[74:77]
	v_mfma_f32_16x16x32_bf16 v[66:69], v[180:183], v[212:215], v[66:69]
	s_setprio 0
	s_barrier
	s_add_i32 s53, s53, s30
	v_lshl_add_u64 v[218:219], v[218:219], 0, s[8:9]
	s_mov_b32 m0, s53
	ds_read_b128 v[184:187], v155 offset:49152
	ds_read_b128 v[188:191], v155 offset:50176
	ds_read_b128 v[192:195], v155 offset:51200
	ds_read_b128 v[196:199], v155 offset:52224
	ds_read_b128 v[200:203], v155 offset:53248
	ds_read_b128 v[204:207], v155 offset:54272
	ds_read_b128 v[208:211], v155 offset:55296
	ds_read_b128 v[212:215], v155 offset:56320
	global_load_lds_dwordx4 v[218:219], off
	s_add_i32 m0, s53, 0x2000
	s_add_u32 s34, s34, 0x80080
	v_lshl_add_u64 v[218:219], v[220:221], 0, s[8:9]
	s_addc_u32 s35, s35, 0
	s_add_i32 s53, s62, s30
	global_load_lds_dwordx4 v[218:219], off
	v_lshl_add_u64 v[218:219], s[34:35], 0, v[134:135]
	s_mov_b32 m0, s53
	s_nop 0
	global_load_lds_dwordx4 v[218:219], off
	v_lshl_add_u64 v[218:219], s[34:35], 0, v[130:131]
	s_add_i32 m0, s53, 0x2000
	s_nop 0
	global_load_lds_dwordx4 v[218:219], off
	v_lshl_add_u64 v[218:219], v[222:223], 0, s[8:9]
	s_mov_b32 m0, s60
	s_nop 0
	global_load_lds_dwordx4 v[218:219], off
	v_lshl_add_u64 v[218:219], v[224:225], 0, s[8:9]
	s_mov_b32 m0, s61
	s_nop 0
	global_load_lds_dwordx4 v[218:219], off
	s_waitcnt vmcnt(8)
	s_waitcnt lgkmcnt(0)
	s_barrier
	s_setprio 1
	s_waitcnt lgkmcnt(0)
	v_mfma_f32_16x16x32_bf16 v[62:65], v[146:149], v[184:187], v[62:65]
	v_mfma_f32_16x16x32_bf16 v[54:57], v[160:163], v[184:187], v[54:57]
	v_mfma_f32_16x16x32_bf16 v[58:61], v[168:171], v[184:187], v[58:61]
	v_mfma_f32_16x16x32_bf16 v[50:53], v[176:179], v[184:187], v[50:53]
	v_mfma_f32_16x16x32_bf16 v[46:49], v[146:149], v[192:195], v[46:49]
	v_mfma_f32_16x16x32_bf16 v[38:41], v[160:163], v[192:195], v[38:41]
	v_mfma_f32_16x16x32_bf16 v[42:45], v[168:171], v[192:195], v[42:45]
	v_mfma_f32_16x16x32_bf16 v[34:37], v[176:179], v[192:195], v[34:37]
	v_mfma_f32_16x16x32_bf16 v[30:33], v[146:149], v[200:203], v[30:33]
	v_mfma_f32_16x16x32_bf16 v[22:25], v[160:163], v[200:203], v[22:25]
	v_mfma_f32_16x16x32_bf16 v[26:29], v[168:171], v[200:203], v[26:29]
	v_mfma_f32_16x16x32_bf16 v[18:21], v[176:179], v[200:203], v[18:21]
	v_mfma_f32_16x16x32_bf16 v[14:17], v[146:149], v[208:211], v[14:17]
	v_mfma_f32_16x16x32_bf16 v[6:9], v[160:163], v[208:211], v[6:9]
	v_mfma_f32_16x16x32_bf16 v[10:13], v[168:171], v[208:211], v[10:13]
	v_mfma_f32_16x16x32_bf16 v[2:5], v[176:179], v[208:211], v[2:5]
	s_setprio 0
	s_setprio 1
	v_mfma_f32_16x16x32_bf16 v[62:65], v[156:159], v[188:191], v[62:65]
	v_mfma_f32_16x16x32_bf16 v[54:57], v[164:167], v[188:191], v[54:57]
	v_mfma_f32_16x16x32_bf16 v[58:61], v[172:175], v[188:191], v[58:61]
	v_mfma_f32_16x16x32_bf16 v[50:53], v[180:183], v[188:191], v[50:53]
	v_mfma_f32_16x16x32_bf16 v[46:49], v[156:159], v[196:199], v[46:49]
	v_mfma_f32_16x16x32_bf16 v[38:41], v[164:167], v[196:199], v[38:41]
	v_mfma_f32_16x16x32_bf16 v[42:45], v[172:175], v[196:199], v[42:45]
	v_mfma_f32_16x16x32_bf16 v[34:37], v[180:183], v[196:199], v[34:37]
	v_mfma_f32_16x16x32_bf16 v[30:33], v[156:159], v[204:207], v[30:33]
	v_mfma_f32_16x16x32_bf16 v[22:25], v[164:167], v[204:207], v[22:25]
	v_mfma_f32_16x16x32_bf16 v[26:29], v[172:175], v[204:207], v[26:29]
	v_mfma_f32_16x16x32_bf16 v[18:21], v[180:183], v[204:207], v[18:21]
	v_mfma_f32_16x16x32_bf16 v[14:17], v[156:159], v[212:215], v[14:17]
	v_mfma_f32_16x16x32_bf16 v[6:9], v[164:167], v[212:215], v[6:9]
	v_mfma_f32_16x16x32_bf16 v[10:13], v[172:175], v[212:215], v[10:13]
	v_mfma_f32_16x16x32_bf16 v[2:5], v[180:183], v[212:215], v[2:5]
	s_setprio 0
	s_barrier
	s_add_i32 s80, s80, 2
	s_add_u32 s76, s76, 0x100
	s_addc_u32 s77, s77, 0
	s_add_u32 s52, s52, 0x100
	s_addc_u32 s75, s75, 0
	s_cmp_gt_u32 s80, 29
	s_cbranch_scc0 .LBB0_2218
	v_mov_b32_e32 v160, 0xbfb8aa3b
	s_and_b64 vcc, exec, s[24:25]
	s_cbranch_vccz .LBB0_2221
	s_barrier

.LBB0_2462:
	ds_read_b128 v[160:163], v155
	ds_read_b128 v[164:167], v155 offset:1024
	ds_read_b128 v[168:171], v155 offset:2048
	ds_read_b128 v[172:175], v155 offset:3072
	ds_read_b128 v[176:179], v156
	ds_read_b128 v[180:183], v156 offset:1024
	ds_read_b128 v[184:187], v156 offset:2048
	ds_read_b128 v[188:191], v156 offset:3072
	s_add_u32 s34, s76, 0xfff80080
	s_addc_u32 s35, s77, -1
	s_cmp_eq_u32 s74, 28
	s_cselect_b32 s89, s0, s35
	s_cselect_b32 s88, s1, s34
	s_cselect_b32 s35, s7, s52
	s_cselect_b32 s34, s9, s36
	v_lshl_add_u64 v[152:153], s[76:77], 0, v[144:145]
	s_add_i32 m0, s31, 0xc000
	ds_read_b128 v[192:195], v157
	ds_read_b128 v[196:199], v157 offset:1024
	ds_read_b128 v[200:203], v157 offset:2048
	ds_read_b128 v[204:207], v157 offset:3072
	ds_read_b128 v[208:211], v157 offset:4096
	ds_read_b128 v[212:215], v157 offset:5120
	ds_read_b128 v[218:221], v157 offset:6144
	ds_read_b128 v[222:225], v157 offset:7168
	global_load_lds_dwordx4 v[152:153], off
	v_lshl_add_u64 v[152:153], s[76:77], 0, v[146:147]
	s_add_i32 m0, s31, 0xe000
	s_nop 0
	global_load_lds_dwordx4 v[152:153], off
	s_waitcnt vmcnt(8)
	s_waitcnt lgkmcnt(0)
	s_barrier
	s_setprio 1
	s_waitcnt lgkmcnt(0)
	v_mfma_f32_16x16x32_bf16 v[126:129], v[160:163], v[192:195], v[126:129]
	v_mfma_f32_16x16x32_bf16 v[122:125], v[168:171], v[192:195], v[122:125]
	v_mfma_f32_16x16x32_bf16 v[118:121], v[176:179], v[192:195], v[118:121]
	v_mfma_f32_16x16x32_bf16 v[114:117], v[184:187], v[192:195], v[114:117]
	v_mfma_f32_16x16x32_bf16 v[110:113], v[160:163], v[200:203], v[110:113]
	v_mfma_f32_16x16x32_bf16 v[106:109], v[168:171], v[200:203], v[106:109]
	v_mfma_f32_16x16x32_bf16 v[102:105], v[176:179], v[200:203], v[102:105]
	v_mfma_f32_16x16x32_bf16 v[98:101], v[184:187], v[200:203], v[98:101]
	v_mfma_f32_16x16x32_bf16 v[94:97], v[160:163], v[208:211], v[94:97]
	v_mfma_f32_16x16x32_bf16 v[90:93], v[168:171], v[208:211], v[90:93]
	v_mfma_f32_16x16x32_bf16 v[86:89], v[176:179], v[208:211], v[86:89]
	v_mfma_f32_16x16x32_bf16 v[82:85], v[184:187], v[208:211], v[82:85]
	v_mfma_f32_16x16x32_bf16 v[78:81], v[160:163], v[218:221], v[78:81]
	v_mfma_f32_16x16x32_bf16 v[74:77], v[168:171], v[218:221], v[74:77]
	v_mfma_f32_16x16x32_bf16 v[70:73], v[176:179], v[218:221], v[70:73]
	v_mfma_f32_16x16x32_bf16 v[66:69], v[184:187], v[218:221], v[66:69]
	s_setprio 0
	s_setprio 1
	v_mfma_f32_16x16x32_bf16 v[126:129], v[164:167], v[196:199], v[126:129]
	v_mfma_f32_16x16x32_bf16 v[122:125], v[172:175], v[196:199], v[122:125]
	v_mfma_f32_16x16x32_bf16 v[118:121], v[180:183], v[196:199], v[118:121]
	v_mfma_f32_16x16x32_bf16 v[114:117], v[188:191], v[196:199], v[114:117]
	v_mfma_f32_16x16x32_bf16 v[110:113], v[164:167], v[204:207], v[110:113]
	v_mfma_f32_16x16x32_bf16 v[106:109], v[172:175], v[204:207], v[106:109]
	v_mfma_f32_16x16x32_bf16 v[102:105], v[180:183], v[204:207], v[102:105]
	v_mfma_f32_16x16x32_bf16 v[98:101], v[188:191], v[204:207], v[98:101]
	v_mfma_f32_16x16x32_bf16 v[94:97], v[164:167], v[212:215], v[94:97]
	v_mfma_f32_16x16x32_bf16 v[90:93], v[172:175], v[212:215], v[90:93]
	v_mfma_f32_16x16x32_bf16 v[86:89], v[180:183], v[212:215], v[86:89]
	v_mfma_f32_16x16x32_bf16 v[82:85], v[188:191], v[212:215], v[82:85]
	v_mfma_f32_16x16x32_bf16 v[78:81], v[164:167], v[222:225], v[78:81]
	v_mfma_f32_16x16x32_bf16 v[74:77], v[172:175], v[222:225], v[74:77]
	v_mfma_f32_16x16x32_bf16 v[70:73], v[180:183], v[222:225], v[70:73]
	v_mfma_f32_16x16x32_bf16 v[66:69], v[188:191], v[222:225], v[66:69]
	s_setprio 0
	s_barrier
	s_add_i32 s53, s71, s12
	v_lshl_add_u64 v[152:153], s[34:35], 0, v[132:133]
	s_mov_b32 m0, s53
	ds_read_b128 v[192:195], v157 offset:16384
	ds_read_b128 v[196:199], v157 offset:17408
	ds_read_b128 v[200:203], v157 offset:18432
	ds_read_b128 v[204:207], v157 offset:19456
	ds_read_b128 v[208:211], v157 offset:20480
	ds_read_b128 v[212:215], v157 offset:21504
	ds_read_b128 v[218:221], v157 offset:22528
	ds_read_b128 v[222:225], v157 offset:23552
	global_load_lds_dwordx4 v[152:153], off
	s_add_i32 m0, s53, 0x2000
	s_add_u32 s54, s34, 0x80000
	v_lshl_add_u64 v[226:227], s[34:35], 0, v[136:137]
	s_addc_u32 s55, s35, 0
	s_add_i32 s53, s72, s12
	global_load_lds_dwordx4 v[226:227], off
	v_lshl_add_u64 v[228:229], s[54:55], 0, v[132:133]
	s_mov_b32 m0, s53
	v_lshl_add_u64 v[230:231], s[88:89], 0, v[134:135]
	global_load_lds_dwordx4 v[228:229], off
	v_lshl_add_u64 v[228:229], s[54:55], 0, v[136:137]
	s_add_i32 m0, s53, 0x2000
	s_nop 0
	global_load_lds_dwordx4 v[228:229], off
	v_lshl_add_u64 v[228:229], s[88:89], 0, v[130:131]
	s_mov_b32 m0, s31
	s_nop 0
	global_load_lds_dwordx4 v[228:229], off
	s_mov_b32 m0, s33
	s_nop 0
	global_load_lds_dwordx4 v[230:231], off
	s_waitcnt vmcnt(8)
	s_waitcnt lgkmcnt(0)
	s_barrier
	s_setprio 1
	s_waitcnt lgkmcnt(0)
	v_mfma_f32_16x16x32_bf16 v[62:65], v[160:163], v[192:195], v[62:65]
	v_mfma_f32_16x16x32_bf16 v[58:61], v[168:171], v[192:195], v[58:61]
	v_mfma_f32_16x16x32_bf16 v[54:57], v[176:179], v[192:195], v[54:57]
	v_mfma_f32_16x16x32_bf16 v[50:53], v[184:187], v[192:195], v[50:53]
	v_mfma_f32_16x16x32_bf16 v[46:49], v[160:163], v[200:203], v[46:49]
	v_mfma_f32_16x16x32_bf16 v[42:45], v[168:171], v[200:203], v[42:45]
	v_mfma_f32_16x16x32_bf16 v[38:41], v[176:179], v[200:203], v[38:41]
	v_mfma_f32_16x16x32_bf16 v[34:37], v[184:187], v[200:203], v[34:37]
	v_mfma_f32_16x16x32_bf16 v[30:33], v[160:163], v[208:211], v[30:33]
	v_mfma_f32_16x16x32_bf16 v[26:29], v[168:171], v[208:211], v[26:29]
	v_mfma_f32_16x16x32_bf16 v[22:25], v[176:179], v[208:211], v[22:25]
	v_mfma_f32_16x16x32_bf16 v[18:21], v[184:187], v[208:211], v[18:21]
	v_mfma_f32_16x16x32_bf16 v[14:17], v[160:163], v[218:221], v[14:17]
	v_mfma_f32_16x16x32_bf16 v[10:13], v[168:171], v[218:221], v[10:13]
	v_mfma_f32_16x16x32_bf16 v[6:9], v[176:179], v[218:221], v[6:9]
	v_mfma_f32_16x16x32_bf16 v[2:5], v[184:187], v[218:221], v[2:5]
	s_setprio 0
	s_setprio 1
	v_mfma_f32_16x16x32_bf16 v[62:65], v[164:167], v[196:199], v[62:65]
	v_mfma_f32_16x16x32_bf16 v[58:61], v[172:175], v[196:199], v[58:61]
	v_mfma_f32_16x16x32_bf16 v[54:57], v[180:183], v[196:199], v[54:57]
	v_mfma_f32_16x16x32_bf16 v[50:53], v[188:191], v[196:199], v[50:53]
	v_mfma_f32_16x16x32_bf16 v[46:49], v[164:167], v[204:207], v[46:49]
	v_mfma_f32_16x16x32_bf16 v[42:45], v[172:175], v[204:207], v[42:45]
	v_mfma_f32_16x16x32_bf16 v[38:41], v[180:183], v[204:207], v[38:41]
	v_mfma_f32_16x16x32_bf16 v[34:37], v[188:191], v[204:207], v[34:37]
	v_mfma_f32_16x16x32_bf16 v[30:33], v[164:167], v[212:215], v[30:33]
	v_mfma_f32_16x16x32_bf16 v[26:29], v[172:175], v[212:215], v[26:29]
	v_mfma_f32_16x16x32_bf16 v[22:25], v[180:183], v[212:215], v[22:25]
	v_mfma_f32_16x16x32_bf16 v[18:21], v[188:191], v[212:215], v[18:21]
	v_mfma_f32_16x16x32_bf16 v[14:17], v[164:167], v[222:225], v[14:17]
	v_mfma_f32_16x16x32_bf16 v[10:13], v[172:175], v[222:225], v[10:13]
	v_mfma_f32_16x16x32_bf16 v[6:9], v[180:183], v[222:225], v[6:9]
	v_mfma_f32_16x16x32_bf16 v[2:5], v[188:191], v[222:225], v[2:5]
	s_setprio 0
	s_barrier
	s_add_i32 s53, 0, 0x18000
	v_add_u32_e32 v138, s53, v154
	s_add_i32 s62, 0, 0x1c000
	ds_read_b128 v[160:163], v138
	ds_read_b128 v[164:167], v138 offset:1024
	ds_read_b128 v[168:171], v138 offset:2048
	ds_read_b128 v[172:175], v138 offset:3072
	v_add_u32_e32 v138, s62, v154
	ds_read_b128 v[176:179], v138
	ds_read_b128 v[180:183], v138 offset:1024
	ds_read_b128 v[184:187], v138 offset:2048
	ds_read_b128 v[188:191], v138 offset:3072
	s_add_u32 s54, s88, 0x80000
	s_addc_u32 s55, s89, 0
	s_mov_b32 m0, s56
	v_lshl_add_u64 v[232:233], s[54:55], 0, v[130:131]
	ds_read_b128 v[192:195], v157 offset:32768
	ds_read_b128 v[196:199], v157 offset:33792
	ds_read_b128 v[200:203], v157 offset:34816
	ds_read_b128 v[204:207], v157 offset:35840
	ds_read_b128 v[208:211], v157 offset:36864
	ds_read_b128 v[212:215], v157 offset:37888
	ds_read_b128 v[218:221], v157 offset:38912
	ds_read_b128 v[222:225], v157 offset:39936
	global_load_lds_dwordx4 v[232:233], off
	v_lshl_add_u64 v[232:233], s[54:55], 0, v[134:135]
	s_mov_b32 m0, s57
	s_nop 0
	global_load_lds_dwordx4 v[232:233], off
	s_waitcnt vmcnt(8)
	s_waitcnt lgkmcnt(0)
	s_barrier
	s_setprio 1
	s_waitcnt lgkmcnt(0)
	v_mfma_f32_16x16x32_bf16 v[126:129], v[160:163], v[192:195], v[126:129]
	v_mfma_f32_16x16x32_bf16 v[122:125], v[168:171], v[192:195], v[122:125]
	v_mfma_f32_16x16x32_bf16 v[118:121], v[176:179], v[192:195], v[118:121]
	v_mfma_f32_16x16x32_bf16 v[114:117], v[184:187], v[192:195], v[114:117]
	v_mfma_f32_16x16x32_bf16 v[110:113], v[160:163], v[200:203], v[110:113]
	v_mfma_f32_16x16x32_bf16 v[106:109], v[168:171], v[200:203], v[106:109]
	v_mfma_f32_16x16x32_bf16 v[102:105], v[176:179], v[200:203], v[102:105]
	v_mfma_f32_16x16x32_bf16 v[98:101], v[184:187], v[200:203], v[98:101]
	v_mfma_f32_16x16x32_bf16 v[94:97], v[160:163], v[208:211], v[94:97]
	v_mfma_f32_16x16x32_bf16 v[90:93], v[168:171], v[208:211], v[90:93]
	v_mfma_f32_16x16x32_bf16 v[86:89], v[176:179], v[208:211], v[86:89]
	v_mfma_f32_16x16x32_bf16 v[82:85], v[184:187], v[208:211], v[82:85]
	v_mfma_f32_16x16x32_bf16 v[78:81], v[160:163], v[218:221], v[78:81]
	v_mfma_f32_16x16x32_bf16 v[74:77], v[168:171], v[218:221], v[74:77]
	v_mfma_f32_16x16x32_bf16 v[70:73], v[176:179], v[218:221], v[70:73]
	v_mfma_f32_16x16x32_bf16 v[66:69], v[184:187], v[218:221], v[66:69]
	s_setprio 0
	s_setprio 1
	v_mfma_f32_16x16x32_bf16 v[126:129], v[164:167], v[196:199], v[126:129]
	v_mfma_f32_16x16x32_bf16 v[122:125], v[172:175], v[196:199], v[122:125]
	v_mfma_f32_16x16x32_bf16 v[118:121], v[180:183], v[196:199], v[118:121]
	v_mfma_f32_16x16x32_bf16 v[114:117], v[188:191], v[196:199], v[114:117]
	v_mfma_f32_16x16x32_bf16 v[110:113], v[164:167], v[204:207], v[110:113]
	v_mfma_f32_16x16x32_bf16 v[106:109], v[172:175], v[204:207], v[106:109]
	v_mfma_f32_16x16x32_bf16 v[102:105], v[180:183], v[204:207], v[102:105]
	v_mfma_f32_16x16x32_bf16 v[98:101], v[188:191], v[204:207], v[98:101]
	v_mfma_f32_16x16x32_bf16 v[94:97], v[164:167], v[212:215], v[94:97]
	v_mfma_f32_16x16x32_bf16 v[90:93], v[172:175], v[212:215], v[90:93]
	v_mfma_f32_16x16x32_bf16 v[86:89], v[180:183], v[212:215], v[86:89]
	v_mfma_f32_16x16x32_bf16 v[82:85], v[188:191], v[212:215], v[82:85]
	v_mfma_f32_16x16x32_bf16 v[78:81], v[164:167], v[222:225], v[78:81]
	v_mfma_f32_16x16x32_bf16 v[74:77], v[172:175], v[222:225], v[74:77]
	v_mfma_f32_16x16x32_bf16 v[70:73], v[180:183], v[222:225], v[70:73]
	v_mfma_f32_16x16x32_bf16 v[66:69], v[188:191], v[222:225], v[66:69]
	s_setprio 0
	s_barrier
	s_add_i32 s53, s53, s12
	v_lshl_add_u64 v[152:153], v[152:153], 0, s[40:41]
	s_mov_b32 m0, s53
	ds_read_b128 v[192:195], v157 offset:49152
	ds_read_b128 v[196:199], v157 offset:50176
	ds_read_b128 v[200:203], v157 offset:51200
	ds_read_b128 v[204:207], v157 offset:52224
	ds_read_b128 v[208:211], v157 offset:53248
	ds_read_b128 v[212:215], v157 offset:54272
	ds_read_b128 v[218:221], v157 offset:55296
	ds_read_b128 v[222:225], v157 offset:56320
	global_load_lds_dwordx4 v[152:153], off
	s_add_i32 m0, s53, 0x2000
	s_add_u32 s34, s34, 0x80080
	v_lshl_add_u64 v[152:153], v[226:227], 0, s[40:41]
	s_addc_u32 s35, s35, 0
	s_add_i32 s53, s62, s12
	global_load_lds_dwordx4 v[152:153], off
	v_lshl_add_u64 v[152:153], s[34:35], 0, v[132:133]
	s_mov_b32 m0, s53
	s_nop 0
	global_load_lds_dwordx4 v[152:153], off
	v_lshl_add_u64 v[152:153], s[34:35], 0, v[136:137]
	s_add_i32 m0, s53, 0x2000
	s_nop 0
	global_load_lds_dwordx4 v[152:153], off
	v_lshl_add_u64 v[152:153], v[228:229], 0, s[40:41]
	s_mov_b32 m0, s59
	s_nop 0
	global_load_lds_dwordx4 v[152:153], off
	v_lshl_add_u64 v[152:153], v[230:231], 0, s[40:41]
	s_mov_b32 m0, s60
	s_nop 0
	global_load_lds_dwordx4 v[152:153], off
	s_waitcnt vmcnt(8)
	s_waitcnt lgkmcnt(0)
	s_barrier
	s_setprio 1
	s_waitcnt lgkmcnt(0)
	v_mfma_f32_16x16x32_bf16 v[62:65], v[160:163], v[192:195], v[62:65]
	v_mfma_f32_16x16x32_bf16 v[58:61], v[168:171], v[192:195], v[58:61]
	v_mfma_f32_16x16x32_bf16 v[54:57], v[176:179], v[192:195], v[54:57]
	v_mfma_f32_16x16x32_bf16 v[50:53], v[184:187], v[192:195], v[50:53]
	v_mfma_f32_16x16x32_bf16 v[46:49], v[160:163], v[200:203], v[46:49]
	v_mfma_f32_16x16x32_bf16 v[42:45], v[168:171], v[200:203], v[42:45]
	v_mfma_f32_16x16x32_bf16 v[38:41], v[176:179], v[200:203], v[38:41]
	v_mfma_f32_16x16x32_bf16 v[34:37], v[184:187], v[200:203], v[34:37]
	v_mfma_f32_16x16x32_bf16 v[30:33], v[160:163], v[208:211], v[30:33]
	v_mfma_f32_16x16x32_bf16 v[26:29], v[168:171], v[208:211], v[26:29]
	v_mfma_f32_16x16x32_bf16 v[22:25], v[176:179], v[208:211], v[22:25]
	v_mfma_f32_16x16x32_bf16 v[18:21], v[184:187], v[208:211], v[18:21]
	v_mfma_f32_16x16x32_bf16 v[14:17], v[160:163], v[218:221], v[14:17]
	v_mfma_f32_16x16x32_bf16 v[10:13], v[168:171], v[218:221], v[10:13]
	v_mfma_f32_16x16x32_bf16 v[6:9], v[176:179], v[218:221], v[6:9]
	v_mfma_f32_16x16x32_bf16 v[2:5], v[184:187], v[218:221], v[2:5]
	s_setprio 0
	s_setprio 1
	v_mfma_f32_16x16x32_bf16 v[62:65], v[164:167], v[196:199], v[62:65]
	v_mfma_f32_16x16x32_bf16 v[58:61], v[172:175], v[196:199], v[58:61]
	v_mfma_f32_16x16x32_bf16 v[54:57], v[180:183], v[196:199], v[54:57]
	v_mfma_f32_16x16x32_bf16 v[50:53], v[188:191], v[196:199], v[50:53]
	v_mfma_f32_16x16x32_bf16 v[46:49], v[164:167], v[204:207], v[46:49]
	v_mfma_f32_16x16x32_bf16 v[42:45], v[172:175], v[204:207], v[42:45]
	v_mfma_f32_16x16x32_bf16 v[38:41], v[180:183], v[204:207], v[38:41]
	v_mfma_f32_16x16x32_bf16 v[34:37], v[188:191], v[204:207], v[34:37]
	v_mfma_f32_16x16x32_bf16 v[30:33], v[164:167], v[212:215], v[30:33]
	v_mfma_f32_16x16x32_bf16 v[26:29], v[172:175], v[212:215], v[26:29]
	v_mfma_f32_16x16x32_bf16 v[22:25], v[180:183], v[212:215], v[22:25]
	v_mfma_f32_16x16x32_bf16 v[18:21], v[188:191], v[212:215], v[18:21]
	v_mfma_f32_16x16x32_bf16 v[14:17], v[164:167], v[222:225], v[14:17]
	v_mfma_f32_16x16x32_bf16 v[10:13], v[172:175], v[222:225], v[10:13]
	v_mfma_f32_16x16x32_bf16 v[6:9], v[180:183], v[222:225], v[6:9]
	v_mfma_f32_16x16x32_bf16 v[2:5], v[188:191], v[222:225], v[2:5]
	s_setprio 0
	s_barrier
	s_add_i32 s74, s74, 2
	s_add_u32 s76, s76, 0x100
	s_addc_u32 s77, s77, 0
	s_add_u32 s36, s36, 0x100
	s_addc_u32 s52, s52, 0
	s_cmp_gt_u32 s74, 29
	s_cbranch_scc0 .LBB0_2462
	s_and_b64 vcc, exec, s[46:47]
	s_cbranch_vccz .LBB0_2465
	s_barrier

.LBB0_2629:
	ds_read_b128 v[146:149], v165
	ds_read_b128 v[150:153], v165 offset:1024
	ds_read_b128 v[168:171], v165 offset:2048
	ds_read_b128 v[172:175], v165 offset:3072
	ds_read_b128 v[176:179], v166
	ds_read_b128 v[180:183], v166 offset:1024
	ds_read_b128 v[184:187], v166 offset:2048
	ds_read_b128 v[188:191], v166 offset:3072
	s_add_u32 s34, s74, 0xfffe0080
	s_addc_u32 s35, s75, -1
	s_cmp_eq_u32 s79, 4
	s_cselect_b32 s77, s0, s35
	s_cselect_b32 s76, s1, s34
	s_cselect_b32 s35, s27, s78
	s_cselect_b32 s34, s37, s52
	v_lshl_add_u64 v[226:227], s[74:75], 0, v[138:139]
	s_add_i32 m0, s33, 0xc000
	ds_read_b128 v[192:195], v167
	ds_read_b128 v[196:199], v167 offset:1024
	ds_read_b128 v[200:203], v167 offset:2048
	ds_read_b128 v[204:207], v167 offset:3072
	ds_read_b128 v[208:211], v167 offset:4096
	ds_read_b128 v[212:215], v167 offset:5120
	ds_read_b128 v[218:221], v167 offset:6144
	ds_read_b128 v[222:225], v167 offset:7168
	global_load_lds_dwordx4 v[226:227], off
	v_lshl_add_u64 v[226:227], s[74:75], 0, v[140:141]
	s_add_i32 m0, s33, 0xe000
	s_nop 0
	global_load_lds_dwordx4 v[226:227], off
	s_waitcnt vmcnt(8)
	s_waitcnt lgkmcnt(0)
	s_barrier
	s_setprio 1
	s_waitcnt lgkmcnt(0)
	v_mfma_f32_16x16x32_bf16 v[126:129], v[146:149], v[192:195], v[126:129]
	v_mfma_f32_16x16x32_bf16 v[122:125], v[168:171], v[192:195], v[122:125]
	v_mfma_f32_16x16x32_bf16 v[118:121], v[176:179], v[192:195], v[118:121]
	v_mfma_f32_16x16x32_bf16 v[110:113], v[184:187], v[192:195], v[110:113]
	v_mfma_f32_16x16x32_bf16 v[114:117], v[146:149], v[200:203], v[114:117]
	v_mfma_f32_16x16x32_bf16 v[106:109], v[168:171], v[200:203], v[106:109]
	v_mfma_f32_16x16x32_bf16 v[102:105], v[176:179], v[200:203], v[102:105]
	v_mfma_f32_16x16x32_bf16 v[94:97], v[184:187], v[200:203], v[94:97]
	v_mfma_f32_16x16x32_bf16 v[98:101], v[146:149], v[208:211], v[98:101]
	v_mfma_f32_16x16x32_bf16 v[90:93], v[168:171], v[208:211], v[90:93]
	v_mfma_f32_16x16x32_bf16 v[86:89], v[176:179], v[208:211], v[86:89]
	v_mfma_f32_16x16x32_bf16 v[78:81], v[184:187], v[208:211], v[78:81]
	v_mfma_f32_16x16x32_bf16 v[82:85], v[146:149], v[218:221], v[82:85]
	v_mfma_f32_16x16x32_bf16 v[74:77], v[168:171], v[218:221], v[74:77]
	v_mfma_f32_16x16x32_bf16 v[70:73], v[176:179], v[218:221], v[70:73]
	v_mfma_f32_16x16x32_bf16 v[66:69], v[184:187], v[218:221], v[66:69]
	s_setprio 0
	s_setprio 1
	v_mfma_f32_16x16x32_bf16 v[126:129], v[150:153], v[196:199], v[126:129]
	v_mfma_f32_16x16x32_bf16 v[122:125], v[172:175], v[196:199], v[122:125]
	v_mfma_f32_16x16x32_bf16 v[118:121], v[180:183], v[196:199], v[118:121]
	v_mfma_f32_16x16x32_bf16 v[110:113], v[188:191], v[196:199], v[110:113]
	v_mfma_f32_16x16x32_bf16 v[114:117], v[150:153], v[204:207], v[114:117]
	v_mfma_f32_16x16x32_bf16 v[106:109], v[172:175], v[204:207], v[106:109]
	v_mfma_f32_16x16x32_bf16 v[102:105], v[180:183], v[204:207], v[102:105]
	v_mfma_f32_16x16x32_bf16 v[94:97], v[188:191], v[204:207], v[94:97]
	v_mfma_f32_16x16x32_bf16 v[98:101], v[150:153], v[212:215], v[98:101]
	v_mfma_f32_16x16x32_bf16 v[90:93], v[172:175], v[212:215], v[90:93]
	v_mfma_f32_16x16x32_bf16 v[86:89], v[180:183], v[212:215], v[86:89]
	v_mfma_f32_16x16x32_bf16 v[78:81], v[188:191], v[212:215], v[78:81]
	v_mfma_f32_16x16x32_bf16 v[82:85], v[150:153], v[222:225], v[82:85]
	v_mfma_f32_16x16x32_bf16 v[74:77], v[172:175], v[222:225], v[74:77]
	v_mfma_f32_16x16x32_bf16 v[70:73], v[180:183], v[222:225], v[70:73]
	v_mfma_f32_16x16x32_bf16 v[66:69], v[188:191], v[222:225], v[66:69]
	s_setprio 0
	s_barrier
	s_add_i32 s53, s70, s12
	v_lshl_add_u64 v[226:227], s[34:35], 0, v[132:133]
	s_mov_b32 m0, s53
	ds_read_b128 v[192:195], v167 offset:16384
	ds_read_b128 v[196:199], v167 offset:17408
	ds_read_b128 v[200:203], v167 offset:18432
	ds_read_b128 v[204:207], v167 offset:19456
	ds_read_b128 v[208:211], v167 offset:20480
	ds_read_b128 v[212:215], v167 offset:21504
	ds_read_b128 v[218:221], v167 offset:22528
	ds_read_b128 v[222:225], v167 offset:23552
	global_load_lds_dwordx4 v[226:227], off
	s_add_i32 m0, s53, 0x2000
	s_add_u32 s54, s34, 0x20000
	v_lshl_add_u64 v[228:229], s[34:35], 0, v[136:137]
	s_addc_u32 s55, s35, 0
	s_add_i32 s53, s71, s12
	global_load_lds_dwordx4 v[228:229], off
	v_lshl_add_u64 v[230:231], s[54:55], 0, v[132:133]
	s_mov_b32 m0, s53
	v_lshl_add_u64 v[232:233], s[76:77], 0, v[134:135]
	global_load_lds_dwordx4 v[230:231], off
	v_lshl_add_u64 v[230:231], s[54:55], 0, v[136:137]
	s_add_i32 m0, s53, 0x2000
	s_nop 0
	global_load_lds_dwordx4 v[230:231], off
	v_lshl_add_u64 v[230:231], s[76:77], 0, v[130:131]
	s_mov_b32 m0, s33
	s_nop 0
	global_load_lds_dwordx4 v[230:231], off
	s_mov_b32 m0, s47
	s_nop 0
	global_load_lds_dwordx4 v[232:233], off
	s_waitcnt vmcnt(8)
	s_waitcnt lgkmcnt(0)
	s_barrier
	s_setprio 1
	s_waitcnt lgkmcnt(0)
	v_mfma_f32_16x16x32_bf16 v[62:65], v[146:149], v[192:195], v[62:65]
	v_mfma_f32_16x16x32_bf16 v[58:61], v[168:171], v[192:195], v[58:61]
	v_mfma_f32_16x16x32_bf16 v[54:57], v[176:179], v[192:195], v[54:57]
	v_mfma_f32_16x16x32_bf16 v[46:49], v[184:187], v[192:195], v[46:49]
	v_mfma_f32_16x16x32_bf16 v[50:53], v[146:149], v[200:203], v[50:53]
	v_mfma_f32_16x16x32_bf16 v[42:45], v[168:171], v[200:203], v[42:45]
	v_mfma_f32_16x16x32_bf16 v[38:41], v[176:179], v[200:203], v[38:41]
	v_mfma_f32_16x16x32_bf16 v[30:33], v[184:187], v[200:203], v[30:33]
	v_mfma_f32_16x16x32_bf16 v[34:37], v[146:149], v[208:211], v[34:37]
	v_mfma_f32_16x16x32_bf16 v[26:29], v[168:171], v[208:211], v[26:29]
	v_mfma_f32_16x16x32_bf16 v[22:25], v[176:179], v[208:211], v[22:25]
	v_mfma_f32_16x16x32_bf16 v[14:17], v[184:187], v[208:211], v[14:17]
	v_mfma_f32_16x16x32_bf16 v[18:21], v[146:149], v[218:221], v[18:21]
	v_mfma_f32_16x16x32_bf16 v[10:13], v[168:171], v[218:221], v[10:13]
	v_mfma_f32_16x16x32_bf16 v[6:9], v[176:179], v[218:221], v[6:9]
	v_mfma_f32_16x16x32_bf16 v[2:5], v[184:187], v[218:221], v[2:5]
	s_setprio 0
	s_setprio 1
	v_mfma_f32_16x16x32_bf16 v[62:65], v[150:153], v[196:199], v[62:65]
	v_mfma_f32_16x16x32_bf16 v[58:61], v[172:175], v[196:199], v[58:61]
	v_mfma_f32_16x16x32_bf16 v[54:57], v[180:183], v[196:199], v[54:57]
	v_mfma_f32_16x16x32_bf16 v[46:49], v[188:191], v[196:199], v[46:49]
	v_mfma_f32_16x16x32_bf16 v[50:53], v[150:153], v[204:207], v[50:53]
	v_mfma_f32_16x16x32_bf16 v[42:45], v[172:175], v[204:207], v[42:45]
	v_mfma_f32_16x16x32_bf16 v[38:41], v[180:183], v[204:207], v[38:41]
	v_mfma_f32_16x16x32_bf16 v[30:33], v[188:191], v[204:207], v[30:33]
	v_mfma_f32_16x16x32_bf16 v[34:37], v[150:153], v[212:215], v[34:37]
	v_mfma_f32_16x16x32_bf16 v[26:29], v[172:175], v[212:215], v[26:29]
	v_mfma_f32_16x16x32_bf16 v[22:25], v[180:183], v[212:215], v[22:25]
	v_mfma_f32_16x16x32_bf16 v[14:17], v[188:191], v[212:215], v[14:17]
	v_mfma_f32_16x16x32_bf16 v[18:21], v[150:153], v[222:225], v[18:21]
	v_mfma_f32_16x16x32_bf16 v[10:13], v[172:175], v[222:225], v[10:13]
	v_mfma_f32_16x16x32_bf16 v[6:9], v[180:183], v[222:225], v[6:9]
	v_mfma_f32_16x16x32_bf16 v[2:5], v[188:191], v[222:225], v[2:5]
	s_setprio 0
	s_barrier
	s_add_i32 s53, 0, 0x18000
	s_add_i32 s62, 0, 0x1c000
	v_add_u32_e32 v172, s53, v162
	v_add_u32_e32 v188, s62, v162
	ds_read_b128 v[146:149], v172
	ds_read_b128 v[150:153], v172 offset:1024
	ds_read_b128 v[168:171], v172 offset:2048
	ds_read_b128 v[172:175], v172 offset:3072
	ds_read_b128 v[176:179], v188
	ds_read_b128 v[180:183], v188 offset:1024
	ds_read_b128 v[184:187], v188 offset:2048
	ds_read_b128 v[188:191], v188 offset:3072
	s_add_u32 s54, s76, 0x20000
	s_addc_u32 s55, s77, 0
	s_mov_b32 m0, s56
	v_lshl_add_u64 v[234:235], s[54:55], 0, v[130:131]
	ds_read_b128 v[192:195], v167 offset:32768
	ds_read_b128 v[196:199], v167 offset:33792
	ds_read_b128 v[200:203], v167 offset:34816
	ds_read_b128 v[204:207], v167 offset:35840
	ds_read_b128 v[208:211], v167 offset:36864
	ds_read_b128 v[212:215], v167 offset:37888
	ds_read_b128 v[218:221], v167 offset:38912
	ds_read_b128 v[222:225], v167 offset:39936
	global_load_lds_dwordx4 v[234:235], off
	v_lshl_add_u64 v[234:235], s[54:55], 0, v[134:135]
	s_mov_b32 m0, s57
	s_nop 0
	global_load_lds_dwordx4 v[234:235], off
	s_waitcnt vmcnt(8)
	s_waitcnt lgkmcnt(0)
	s_barrier
	s_setprio 1
	s_waitcnt lgkmcnt(0)
	v_mfma_f32_16x16x32_bf16 v[126:129], v[146:149], v[192:195], v[126:129]
	v_mfma_f32_16x16x32_bf16 v[122:125], v[168:171], v[192:195], v[122:125]
	v_mfma_f32_16x16x32_bf16 v[118:121], v[176:179], v[192:195], v[118:121]
	v_mfma_f32_16x16x32_bf16 v[110:113], v[184:187], v[192:195], v[110:113]
	v_mfma_f32_16x16x32_bf16 v[114:117], v[146:149], v[200:203], v[114:117]
	v_mfma_f32_16x16x32_bf16 v[106:109], v[168:171], v[200:203], v[106:109]
	v_mfma_f32_16x16x32_bf16 v[102:105], v[176:179], v[200:203], v[102:105]
	v_mfma_f32_16x16x32_bf16 v[94:97], v[184:187], v[200:203], v[94:97]
	v_mfma_f32_16x16x32_bf16 v[98:101], v[146:149], v[208:211], v[98:101]
	v_mfma_f32_16x16x32_bf16 v[90:93], v[168:171], v[208:211], v[90:93]
	v_mfma_f32_16x16x32_bf16 v[86:89], v[176:179], v[208:211], v[86:89]
	v_mfma_f32_16x16x32_bf16 v[78:81], v[184:187], v[208:211], v[78:81]
	v_mfma_f32_16x16x32_bf16 v[82:85], v[146:149], v[218:221], v[82:85]
	v_mfma_f32_16x16x32_bf16 v[74:77], v[168:171], v[218:221], v[74:77]
	v_mfma_f32_16x16x32_bf16 v[70:73], v[176:179], v[218:221], v[70:73]
	v_mfma_f32_16x16x32_bf16 v[66:69], v[184:187], v[218:221], v[66:69]
	s_setprio 0
	s_setprio 1
	v_mfma_f32_16x16x32_bf16 v[126:129], v[150:153], v[196:199], v[126:129]
	v_mfma_f32_16x16x32_bf16 v[122:125], v[172:175], v[196:199], v[122:125]
	v_mfma_f32_16x16x32_bf16 v[118:121], v[180:183], v[196:199], v[118:121]
	v_mfma_f32_16x16x32_bf16 v[110:113], v[188:191], v[196:199], v[110:113]
	v_mfma_f32_16x16x32_bf16 v[114:117], v[150:153], v[204:207], v[114:117]
	v_mfma_f32_16x16x32_bf16 v[106:109], v[172:175], v[204:207], v[106:109]
	v_mfma_f32_16x16x32_bf16 v[102:105], v[180:183], v[204:207], v[102:105]
	v_mfma_f32_16x16x32_bf16 v[94:97], v[188:191], v[204:207], v[94:97]
	v_mfma_f32_16x16x32_bf16 v[98:101], v[150:153], v[212:215], v[98:101]
	v_mfma_f32_16x16x32_bf16 v[90:93], v[172:175], v[212:215], v[90:93]
	v_mfma_f32_16x16x32_bf16 v[86:89], v[180:183], v[212:215], v[86:89]
	v_mfma_f32_16x16x32_bf16 v[78:81], v[188:191], v[212:215], v[78:81]
	v_mfma_f32_16x16x32_bf16 v[82:85], v[150:153], v[222:225], v[82:85]
	v_mfma_f32_16x16x32_bf16 v[74:77], v[172:175], v[222:225], v[74:77]
	v_mfma_f32_16x16x32_bf16 v[70:73], v[180:183], v[222:225], v[70:73]
	v_mfma_f32_16x16x32_bf16 v[66:69], v[188:191], v[222:225], v[66:69]
	s_setprio 0
	s_barrier
	s_add_i32 s53, s53, s12
	v_lshl_add_u64 v[226:227], v[226:227], 0, s[8:9]
	s_mov_b32 m0, s53
	ds_read_b128 v[192:195], v167 offset:49152
	ds_read_b128 v[196:199], v167 offset:50176
	ds_read_b128 v[200:203], v167 offset:51200
	ds_read_b128 v[204:207], v167 offset:52224
	ds_read_b128 v[208:211], v167 offset:53248
	ds_read_b128 v[212:215], v167 offset:54272
	ds_read_b128 v[218:221], v167 offset:55296
	ds_read_b128 v[222:225], v167 offset:56320
	global_load_lds_dwordx4 v[226:227], off
	s_add_i32 m0, s53, 0x2000
	s_add_u32 s34, s34, 0x20080
	v_lshl_add_u64 v[226:227], v[228:229], 0, s[8:9]
	s_addc_u32 s35, s35, 0
	s_add_i32 s53, s62, s12
	global_load_lds_dwordx4 v[226:227], off
	v_lshl_add_u64 v[226:227], s[34:35], 0, v[132:133]
	s_mov_b32 m0, s53
	s_nop 0
	global_load_lds_dwordx4 v[226:227], off
	v_lshl_add_u64 v[226:227], s[34:35], 0, v[136:137]
	s_add_i32 m0, s53, 0x2000
	s_nop 0
	global_load_lds_dwordx4 v[226:227], off
	v_lshl_add_u64 v[226:227], v[230:231], 0, s[8:9]
	s_mov_b32 m0, s59
	s_nop 0
	global_load_lds_dwordx4 v[226:227], off
	v_lshl_add_u64 v[226:227], v[232:233], 0, s[8:9]
	s_mov_b32 m0, s60
	s_nop 0
	global_load_lds_dwordx4 v[226:227], off
	s_waitcnt vmcnt(8)
	s_waitcnt lgkmcnt(0)
	s_barrier
	s_setprio 1
	s_waitcnt lgkmcnt(0)
	v_mfma_f32_16x16x32_bf16 v[62:65], v[146:149], v[192:195], v[62:65]
	v_mfma_f32_16x16x32_bf16 v[58:61], v[168:171], v[192:195], v[58:61]
	v_mfma_f32_16x16x32_bf16 v[54:57], v[176:179], v[192:195], v[54:57]
	v_mfma_f32_16x16x32_bf16 v[46:49], v[184:187], v[192:195], v[46:49]
	v_mfma_f32_16x16x32_bf16 v[50:53], v[146:149], v[200:203], v[50:53]
	v_mfma_f32_16x16x32_bf16 v[42:45], v[168:171], v[200:203], v[42:45]
	v_mfma_f32_16x16x32_bf16 v[38:41], v[176:179], v[200:203], v[38:41]
	v_mfma_f32_16x16x32_bf16 v[30:33], v[184:187], v[200:203], v[30:33]
	v_mfma_f32_16x16x32_bf16 v[34:37], v[146:149], v[208:211], v[34:37]
	v_mfma_f32_16x16x32_bf16 v[26:29], v[168:171], v[208:211], v[26:29]
	v_mfma_f32_16x16x32_bf16 v[22:25], v[176:179], v[208:211], v[22:25]
	v_mfma_f32_16x16x32_bf16 v[14:17], v[184:187], v[208:211], v[14:17]
	v_mfma_f32_16x16x32_bf16 v[18:21], v[146:149], v[218:221], v[18:21]
	v_mfma_f32_16x16x32_bf16 v[10:13], v[168:171], v[218:221], v[10:13]
	v_mfma_f32_16x16x32_bf16 v[6:9], v[176:179], v[218:221], v[6:9]
	v_mfma_f32_16x16x32_bf16 v[2:5], v[184:187], v[218:221], v[2:5]
	s_setprio 0
	s_setprio 1
	v_mfma_f32_16x16x32_bf16 v[62:65], v[150:153], v[196:199], v[62:65]
	v_mfma_f32_16x16x32_bf16 v[58:61], v[172:175], v[196:199], v[58:61]
	v_mfma_f32_16x16x32_bf16 v[54:57], v[180:183], v[196:199], v[54:57]
	v_mfma_f32_16x16x32_bf16 v[46:49], v[188:191], v[196:199], v[46:49]
	v_mfma_f32_16x16x32_bf16 v[50:53], v[150:153], v[204:207], v[50:53]
	v_mfma_f32_16x16x32_bf16 v[42:45], v[172:175], v[204:207], v[42:45]
	v_mfma_f32_16x16x32_bf16 v[38:41], v[180:183], v[204:207], v[38:41]
	v_mfma_f32_16x16x32_bf16 v[30:33], v[188:191], v[204:207], v[30:33]
	v_mfma_f32_16x16x32_bf16 v[34:37], v[150:153], v[212:215], v[34:37]
	v_mfma_f32_16x16x32_bf16 v[26:29], v[172:175], v[212:215], v[26:29]
	v_mfma_f32_16x16x32_bf16 v[22:25], v[180:183], v[212:215], v[22:25]
	v_mfma_f32_16x16x32_bf16 v[14:17], v[188:191], v[212:215], v[14:17]
	v_mfma_f32_16x16x32_bf16 v[18:21], v[150:153], v[222:225], v[18:21]
	v_mfma_f32_16x16x32_bf16 v[10:13], v[172:175], v[222:225], v[10:13]
	v_mfma_f32_16x16x32_bf16 v[6:9], v[180:183], v[222:225], v[6:9]
	v_mfma_f32_16x16x32_bf16 v[2:5], v[188:191], v[222:225], v[2:5]
	s_setprio 0
	s_barrier
	s_add_i32 s79, s79, 2
	s_add_u32 s74, s74, 0x100
	s_addc_u32 s75, s75, 0
	s_add_u32 s52, s52, 0x100
	s_addc_u32 s78, s78, 0
	s_cmp_gt_u32 s79, 5
	s_cbranch_scc0 .LBB0_2629
	s_and_b64 vcc, exec, s[24:25]
	s_cbranch_vccz .LBB0_2632
	s_barrier

.LBB0_2659:
	ds_read_b128 v[146:149], v1
	ds_read_b128 v[160:163], v1 offset:1024
	ds_read_b128 v[164:167], v1 offset:2048
	ds_read_b128 v[168:171], v1 offset:3072
	ds_read_b128 v[172:175], v154
	ds_read_b128 v[176:179], v154 offset:1024
	ds_read_b128 v[180:183], v154 offset:2048
	ds_read_b128 v[184:187], v154 offset:3072
	s_add_u32 s34, s74, 0xfffe0080
	s_addc_u32 s35, s75, -1
	s_cmp_eq_u32 s72, 4
	s_cselect_b32 s77, s0, s35
	s_cselect_b32 s76, s1, s34
	s_cselect_b32 s35, s27, s71
	s_cselect_b32 s34, s37, s52
	v_lshl_add_u64 v[150:151], s[74:75], 0, v[138:139]
	s_add_i32 m0, s33, 0xc000
	ds_read_b128 v[188:191], v155
	ds_read_b128 v[192:195], v155 offset:1024
	ds_read_b128 v[196:199], v155 offset:2048
	ds_read_b128 v[200:203], v155 offset:3072
	ds_read_b128 v[204:207], v155 offset:4096
	ds_read_b128 v[208:211], v155 offset:5120
	ds_read_b128 v[212:215], v155 offset:6144
	ds_read_b128 v[218:221], v155 offset:7168
	global_load_lds_dwordx4 v[150:151], off
	v_lshl_add_u64 v[150:151], s[74:75], 0, v[140:141]
	s_add_i32 m0, s33, 0xe000
	s_nop 0
	global_load_lds_dwordx4 v[150:151], off
	s_waitcnt vmcnt(8)
	s_waitcnt lgkmcnt(0)
	s_barrier
	s_setprio 1
	s_waitcnt lgkmcnt(0)
	v_mfma_f32_16x16x32_bf16 v[126:129], v[146:149], v[188:191], v[126:129]
	v_mfma_f32_16x16x32_bf16 v[122:125], v[164:167], v[188:191], v[122:125]
	v_mfma_f32_16x16x32_bf16 v[118:121], v[172:175], v[188:191], v[118:121]
	v_mfma_f32_16x16x32_bf16 v[114:117], v[180:183], v[188:191], v[114:117]
	v_mfma_f32_16x16x32_bf16 v[110:113], v[146:149], v[196:199], v[110:113]
	v_mfma_f32_16x16x32_bf16 v[106:109], v[164:167], v[196:199], v[106:109]
	v_mfma_f32_16x16x32_bf16 v[102:105], v[172:175], v[196:199], v[102:105]
	v_mfma_f32_16x16x32_bf16 v[98:101], v[180:183], v[196:199], v[98:101]
	v_mfma_f32_16x16x32_bf16 v[94:97], v[146:149], v[204:207], v[94:97]
	v_mfma_f32_16x16x32_bf16 v[90:93], v[164:167], v[204:207], v[90:93]
	v_mfma_f32_16x16x32_bf16 v[86:89], v[172:175], v[204:207], v[86:89]
	v_mfma_f32_16x16x32_bf16 v[82:85], v[180:183], v[204:207], v[82:85]
	v_mfma_f32_16x16x32_bf16 v[78:81], v[146:149], v[212:215], v[78:81]
	v_mfma_f32_16x16x32_bf16 v[74:77], v[164:167], v[212:215], v[74:77]
	v_mfma_f32_16x16x32_bf16 v[70:73], v[172:175], v[212:215], v[70:73]
	v_mfma_f32_16x16x32_bf16 v[66:69], v[180:183], v[212:215], v[66:69]
	s_setprio 0
	s_setprio 1
	v_mfma_f32_16x16x32_bf16 v[126:129], v[160:163], v[192:195], v[126:129]
	v_mfma_f32_16x16x32_bf16 v[122:125], v[168:171], v[192:195], v[122:125]
	v_mfma_f32_16x16x32_bf16 v[118:121], v[176:179], v[192:195], v[118:121]
	v_mfma_f32_16x16x32_bf16 v[114:117], v[184:187], v[192:195], v[114:117]
	v_mfma_f32_16x16x32_bf16 v[110:113], v[160:163], v[200:203], v[110:113]
	v_mfma_f32_16x16x32_bf16 v[106:109], v[168:171], v[200:203], v[106:109]
	v_mfma_f32_16x16x32_bf16 v[102:105], v[176:179], v[200:203], v[102:105]
	v_mfma_f32_16x16x32_bf16 v[98:101], v[184:187], v[200:203], v[98:101]
	v_mfma_f32_16x16x32_bf16 v[94:97], v[160:163], v[208:211], v[94:97]
	v_mfma_f32_16x16x32_bf16 v[90:93], v[168:171], v[208:211], v[90:93]
	v_mfma_f32_16x16x32_bf16 v[86:89], v[176:179], v[208:211], v[86:89]
	v_mfma_f32_16x16x32_bf16 v[82:85], v[184:187], v[208:211], v[82:85]
	v_mfma_f32_16x16x32_bf16 v[78:81], v[160:163], v[218:221], v[78:81]
	v_mfma_f32_16x16x32_bf16 v[74:77], v[168:171], v[218:221], v[74:77]
	v_mfma_f32_16x16x32_bf16 v[70:73], v[176:179], v[218:221], v[70:73]
	v_mfma_f32_16x16x32_bf16 v[66:69], v[184:187], v[218:221], v[66:69]
	s_setprio 0
	s_barrier
	s_add_i32 s53, s60, s13
	v_lshl_add_u64 v[150:151], s[34:35], 0, v[132:133]
	s_mov_b32 m0, s53
	ds_read_b128 v[188:191], v155 offset:16384
	ds_read_b128 v[192:195], v155 offset:17408
	ds_read_b128 v[196:199], v155 offset:18432
	ds_read_b128 v[200:203], v155 offset:19456
	ds_read_b128 v[204:207], v155 offset:20480
	ds_read_b128 v[208:211], v155 offset:21504
	ds_read_b128 v[212:215], v155 offset:22528
	ds_read_b128 v[218:221], v155 offset:23552
	global_load_lds_dwordx4 v[150:151], off
	s_add_i32 m0, s53, 0x2000
	s_add_u32 s62, s34, 0x20000
	v_lshl_add_u64 v[222:223], s[34:35], 0, v[136:137]
	s_addc_u32 s63, s35, 0
	s_add_i32 s53, s61, s13
	global_load_lds_dwordx4 v[222:223], off
	v_lshl_add_u64 v[224:225], s[62:63], 0, v[132:133]
	s_mov_b32 m0, s53
	v_lshl_add_u64 v[226:227], s[76:77], 0, v[134:135]
	global_load_lds_dwordx4 v[224:225], off
	v_lshl_add_u64 v[224:225], s[62:63], 0, v[136:137]
	s_add_i32 m0, s53, 0x2000
	s_nop 0
	global_load_lds_dwordx4 v[224:225], off
	v_lshl_add_u64 v[224:225], s[76:77], 0, v[130:131]
	s_mov_b32 m0, s33
	s_nop 0
	global_load_lds_dwordx4 v[224:225], off
	s_mov_b32 m0, s47
	s_nop 0
	global_load_lds_dwordx4 v[226:227], off
	s_waitcnt vmcnt(8)
	s_waitcnt lgkmcnt(0)
	s_barrier
	s_setprio 1
	s_waitcnt lgkmcnt(0)
	v_mfma_f32_16x16x32_bf16 v[62:65], v[146:149], v[188:191], v[62:65]
	v_mfma_f32_16x16x32_bf16 v[58:61], v[164:167], v[188:191], v[58:61]
	v_mfma_f32_16x16x32_bf16 v[54:57], v[172:175], v[188:191], v[54:57]
	v_mfma_f32_16x16x32_bf16 v[46:49], v[180:183], v[188:191], v[46:49]
	v_mfma_f32_16x16x32_bf16 v[50:53], v[146:149], v[196:199], v[50:53]
	v_mfma_f32_16x16x32_bf16 v[42:45], v[164:167], v[196:199], v[42:45]
	v_mfma_f32_16x16x32_bf16 v[38:41], v[172:175], v[196:199], v[38:41]
	v_mfma_f32_16x16x32_bf16 v[30:33], v[180:183], v[196:199], v[30:33]
	v_mfma_f32_16x16x32_bf16 v[34:37], v[146:149], v[204:207], v[34:37]
	v_mfma_f32_16x16x32_bf16 v[26:29], v[164:167], v[204:207], v[26:29]
	v_mfma_f32_16x16x32_bf16 v[22:25], v[172:175], v[204:207], v[22:25]
	v_mfma_f32_16x16x32_bf16 v[14:17], v[180:183], v[204:207], v[14:17]
	v_mfma_f32_16x16x32_bf16 v[18:21], v[146:149], v[212:215], v[18:21]
	v_mfma_f32_16x16x32_bf16 v[10:13], v[164:167], v[212:215], v[10:13]
	v_mfma_f32_16x16x32_bf16 v[6:9], v[172:175], v[212:215], v[6:9]
	v_mfma_f32_16x16x32_bf16 v[2:5], v[180:183], v[212:215], v[2:5]
	s_setprio 0
	s_setprio 1
	v_mfma_f32_16x16x32_bf16 v[62:65], v[160:163], v[192:195], v[62:65]
	v_mfma_f32_16x16x32_bf16 v[58:61], v[168:171], v[192:195], v[58:61]
	v_mfma_f32_16x16x32_bf16 v[54:57], v[176:179], v[192:195], v[54:57]
	v_mfma_f32_16x16x32_bf16 v[46:49], v[184:187], v[192:195], v[46:49]
	v_mfma_f32_16x16x32_bf16 v[50:53], v[160:163], v[200:203], v[50:53]
	v_mfma_f32_16x16x32_bf16 v[42:45], v[168:171], v[200:203], v[42:45]
	v_mfma_f32_16x16x32_bf16 v[38:41], v[176:179], v[200:203], v[38:41]
	v_mfma_f32_16x16x32_bf16 v[30:33], v[184:187], v[200:203], v[30:33]
	v_mfma_f32_16x16x32_bf16 v[34:37], v[160:163], v[208:211], v[34:37]
	v_mfma_f32_16x16x32_bf16 v[26:29], v[168:171], v[208:211], v[26:29]
	v_mfma_f32_16x16x32_bf16 v[22:25], v[176:179], v[208:211], v[22:25]
	v_mfma_f32_16x16x32_bf16 v[14:17], v[184:187], v[208:211], v[14:17]
	v_mfma_f32_16x16x32_bf16 v[18:21], v[160:163], v[218:221], v[18:21]
	v_mfma_f32_16x16x32_bf16 v[10:13], v[168:171], v[218:221], v[10:13]
	v_mfma_f32_16x16x32_bf16 v[6:9], v[176:179], v[218:221], v[6:9]
	v_mfma_f32_16x16x32_bf16 v[2:5], v[184:187], v[218:221], v[2:5]
	s_setprio 0
	s_barrier
	s_add_i32 s53, 0, 0x18000
	v_add_u32_e32 v156, s53, v153
	s_add_i32 s66, 0, 0x1c000
	ds_read_b128 v[146:149], v156
	ds_read_b128 v[160:163], v156 offset:1024
	ds_read_b128 v[164:167], v156 offset:2048
	ds_read_b128 v[168:171], v156 offset:3072
	v_add_u32_e32 v156, s66, v153
	ds_read_b128 v[172:175], v156
	ds_read_b128 v[176:179], v156 offset:1024
	ds_read_b128 v[180:183], v156 offset:2048
	ds_read_b128 v[184:187], v156 offset:3072
	s_add_u32 s62, s76, 0x20000
	s_addc_u32 s63, s77, 0
	s_mov_b32 m0, s54
	v_lshl_add_u64 v[228:229], s[62:63], 0, v[130:131]
	ds_read_b128 v[188:191], v155 offset:32768
	ds_read_b128 v[192:195], v155 offset:33792
	ds_read_b128 v[196:199], v155 offset:34816
	ds_read_b128 v[200:203], v155 offset:35840
	ds_read_b128 v[204:207], v155 offset:36864
	ds_read_b128 v[208:211], v155 offset:37888
	ds_read_b128 v[212:215], v155 offset:38912
	ds_read_b128 v[218:221], v155 offset:39936
	global_load_lds_dwordx4 v[228:229], off
	v_lshl_add_u64 v[228:229], s[62:63], 0, v[134:135]
	s_mov_b32 m0, s55
	s_nop 0
	global_load_lds_dwordx4 v[228:229], off
	s_waitcnt vmcnt(8)
	s_waitcnt lgkmcnt(0)
	s_barrier
	s_setprio 1
	s_waitcnt lgkmcnt(0)
	v_mfma_f32_16x16x32_bf16 v[126:129], v[146:149], v[188:191], v[126:129]
	v_mfma_f32_16x16x32_bf16 v[122:125], v[164:167], v[188:191], v[122:125]
	v_mfma_f32_16x16x32_bf16 v[118:121], v[172:175], v[188:191], v[118:121]
	v_mfma_f32_16x16x32_bf16 v[114:117], v[180:183], v[188:191], v[114:117]
	v_mfma_f32_16x16x32_bf16 v[110:113], v[146:149], v[196:199], v[110:113]
	v_mfma_f32_16x16x32_bf16 v[106:109], v[164:167], v[196:199], v[106:109]
	v_mfma_f32_16x16x32_bf16 v[102:105], v[172:175], v[196:199], v[102:105]
	v_mfma_f32_16x16x32_bf16 v[98:101], v[180:183], v[196:199], v[98:101]
	v_mfma_f32_16x16x32_bf16 v[94:97], v[146:149], v[204:207], v[94:97]
	v_mfma_f32_16x16x32_bf16 v[90:93], v[164:167], v[204:207], v[90:93]
	v_mfma_f32_16x16x32_bf16 v[86:89], v[172:175], v[204:207], v[86:89]
	v_mfma_f32_16x16x32_bf16 v[82:85], v[180:183], v[204:207], v[82:85]
	v_mfma_f32_16x16x32_bf16 v[78:81], v[146:149], v[212:215], v[78:81]
	v_mfma_f32_16x16x32_bf16 v[74:77], v[164:167], v[212:215], v[74:77]
	v_mfma_f32_16x16x32_bf16 v[70:73], v[172:175], v[212:215], v[70:73]
	v_mfma_f32_16x16x32_bf16 v[66:69], v[180:183], v[212:215], v[66:69]
	s_setprio 0
	s_setprio 1
	v_mfma_f32_16x16x32_bf16 v[126:129], v[160:163], v[192:195], v[126:129]
	v_mfma_f32_16x16x32_bf16 v[122:125], v[168:171], v[192:195], v[122:125]
	v_mfma_f32_16x16x32_bf16 v[118:121], v[176:179], v[192:195], v[118:121]
	v_mfma_f32_16x16x32_bf16 v[114:117], v[184:187], v[192:195], v[114:117]
	v_mfma_f32_16x16x32_bf16 v[110:113], v[160:163], v[200:203], v[110:113]
	v_mfma_f32_16x16x32_bf16 v[106:109], v[168:171], v[200:203], v[106:109]
	v_mfma_f32_16x16x32_bf16 v[102:105], v[176:179], v[200:203], v[102:105]
	v_mfma_f32_16x16x32_bf16 v[98:101], v[184:187], v[200:203], v[98:101]
	v_mfma_f32_16x16x32_bf16 v[94:97], v[160:163], v[208:211], v[94:97]
	v_mfma_f32_16x16x32_bf16 v[90:93], v[168:171], v[208:211], v[90:93]
	v_mfma_f32_16x16x32_bf16 v[86:89], v[176:179], v[208:211], v[86:89]
	v_mfma_f32_16x16x32_bf16 v[82:85], v[184:187], v[208:211], v[82:85]
	v_mfma_f32_16x16x32_bf16 v[78:81], v[160:163], v[218:221], v[78:81]
	v_mfma_f32_16x16x32_bf16 v[74:77], v[168:171], v[218:221], v[74:77]
	v_mfma_f32_16x16x32_bf16 v[70:73], v[176:179], v[218:221], v[70:73]
	v_mfma_f32_16x16x32_bf16 v[66:69], v[184:187], v[218:221], v[66:69]
	s_setprio 0
	s_barrier
	s_add_i32 s53, s53, s13
	v_lshl_add_u64 v[150:151], v[150:151], 0, s[8:9]
	s_mov_b32 m0, s53
	ds_read_b128 v[188:191], v155 offset:49152
	ds_read_b128 v[192:195], v155 offset:50176
	ds_read_b128 v[196:199], v155 offset:51200
	ds_read_b128 v[200:203], v155 offset:52224
	ds_read_b128 v[204:207], v155 offset:53248
	ds_read_b128 v[208:211], v155 offset:54272
	ds_read_b128 v[212:215], v155 offset:55296
	ds_read_b128 v[218:221], v155 offset:56320
	global_load_lds_dwordx4 v[150:151], off
	s_add_i32 m0, s53, 0x2000
	s_add_u32 s34, s34, 0x20080
	v_lshl_add_u64 v[150:151], v[222:223], 0, s[8:9]
	s_addc_u32 s35, s35, 0
	s_add_i32 s53, s66, s13
	global_load_lds_dwordx4 v[150:151], off
	v_lshl_add_u64 v[150:151], s[34:35], 0, v[132:133]
	s_mov_b32 m0, s53
	s_nop 0
	global_load_lds_dwordx4 v[150:151], off
	v_lshl_add_u64 v[150:151], s[34:35], 0, v[136:137]
	s_add_i32 m0, s53, 0x2000
	s_nop 0
	global_load_lds_dwordx4 v[150:151], off
	v_lshl_add_u64 v[150:151], v[224:225], 0, s[8:9]
	s_mov_b32 m0, s57
	s_nop 0
	global_load_lds_dwordx4 v[150:151], off
	v_lshl_add_u64 v[150:151], v[226:227], 0, s[8:9]
	s_mov_b32 m0, s58
	s_nop 0
	global_load_lds_dwordx4 v[150:151], off
	s_waitcnt vmcnt(8)
	s_waitcnt lgkmcnt(0)
	s_barrier
	s_setprio 1
	s_waitcnt lgkmcnt(0)
	v_mfma_f32_16x16x32_bf16 v[62:65], v[146:149], v[188:191], v[62:65]
	v_mfma_f32_16x16x32_bf16 v[58:61], v[164:167], v[188:191], v[58:61]
	v_mfma_f32_16x16x32_bf16 v[54:57], v[172:175], v[188:191], v[54:57]
	v_mfma_f32_16x16x32_bf16 v[46:49], v[180:183], v[188:191], v[46:49]
	v_mfma_f32_16x16x32_bf16 v[50:53], v[146:149], v[196:199], v[50:53]
	v_mfma_f32_16x16x32_bf16 v[42:45], v[164:167], v[196:199], v[42:45]
	v_mfma_f32_16x16x32_bf16 v[38:41], v[172:175], v[196:199], v[38:41]
	v_mfma_f32_16x16x32_bf16 v[30:33], v[180:183], v[196:199], v[30:33]
	v_mfma_f32_16x16x32_bf16 v[34:37], v[146:149], v[204:207], v[34:37]
	v_mfma_f32_16x16x32_bf16 v[26:29], v[164:167], v[204:207], v[26:29]
	v_mfma_f32_16x16x32_bf16 v[22:25], v[172:175], v[204:207], v[22:25]
	v_mfma_f32_16x16x32_bf16 v[14:17], v[180:183], v[204:207], v[14:17]
	v_mfma_f32_16x16x32_bf16 v[18:21], v[146:149], v[212:215], v[18:21]
	v_mfma_f32_16x16x32_bf16 v[10:13], v[164:167], v[212:215], v[10:13]
	v_mfma_f32_16x16x32_bf16 v[6:9], v[172:175], v[212:215], v[6:9]
	v_mfma_f32_16x16x32_bf16 v[2:5], v[180:183], v[212:215], v[2:5]
	s_setprio 0
	s_setprio 1
	v_mfma_f32_16x16x32_bf16 v[62:65], v[160:163], v[192:195], v[62:65]
	v_mfma_f32_16x16x32_bf16 v[58:61], v[168:171], v[192:195], v[58:61]
	v_mfma_f32_16x16x32_bf16 v[54:57], v[176:179], v[192:195], v[54:57]
	v_mfma_f32_16x16x32_bf16 v[46:49], v[184:187], v[192:195], v[46:49]
	v_mfma_f32_16x16x32_bf16 v[50:53], v[160:163], v[200:203], v[50:53]
	v_mfma_f32_16x16x32_bf16 v[42:45], v[168:171], v[200:203], v[42:45]
	v_mfma_f32_16x16x32_bf16 v[38:41], v[176:179], v[200:203], v[38:41]
	v_mfma_f32_16x16x32_bf16 v[30:33], v[184:187], v[200:203], v[30:33]
	v_mfma_f32_16x16x32_bf16 v[34:37], v[160:163], v[208:211], v[34:37]
	v_mfma_f32_16x16x32_bf16 v[26:29], v[168:171], v[208:211], v[26:29]
	v_mfma_f32_16x16x32_bf16 v[22:25], v[176:179], v[208:211], v[22:25]
	v_mfma_f32_16x16x32_bf16 v[14:17], v[184:187], v[208:211], v[14:17]
	v_mfma_f32_16x16x32_bf16 v[18:21], v[160:163], v[218:221], v[18:21]
	v_mfma_f32_16x16x32_bf16 v[10:13], v[168:171], v[218:221], v[10:13]
	v_mfma_f32_16x16x32_bf16 v[6:9], v[176:179], v[218:221], v[6:9]
	v_mfma_f32_16x16x32_bf16 v[2:5], v[184:187], v[218:221], v[2:5]
	s_setprio 0
	s_barrier
	s_add_i32 s72, s72, 2
	s_add_u32 s74, s74, 0x100
	s_addc_u32 s75, s75, 0
	s_add_u32 s52, s52, 0x100
	s_addc_u32 s71, s71, 0
	s_cmp_gt_u32 s72, 5
	s_cbranch_scc0 .LBB0_2659
	s_and_b64 vcc, exec, s[24:25]
	s_cbranch_vccz .LBB0_2662
	s_barrier

.LBB0_2938:
	ds_read_b128 v[130:133], v174
	ds_read_b128 v[134:137], v174 offset:1024
	ds_read_b128 v[138:141], v174 offset:2048
	ds_read_b128 v[158:161], v174 offset:3072
	ds_read_b128 v[162:165], v175
	ds_read_b128 v[166:169], v175 offset:1024
	ds_read_b128 v[178:181], v175 offset:2048
	ds_read_b128 v[182:185], v175 offset:3072
	s_add_u32 s34, s46, 0xfff80080
	s_addc_u32 s35, s47, -1
	s_cmp_eq_u32 s72, 28
	s_cselect_b32 s69, s0, s35
	s_cselect_b32 s68, s1, s34
	s_cselect_b32 s35, s37, s71
	s_cselect_b32 s34, s39, s70
	v_lshl_add_u64 v[170:171], s[46:47], 0, v[150:151]
	s_add_i32 m0, s33, 0xc000
	ds_read_b128 v[186:189], v176
	ds_read_b128 v[190:193], v176 offset:1024
	ds_read_b128 v[194:197], v176 offset:2048
	ds_read_b128 v[198:201], v176 offset:3072
	ds_read_b128 v[202:205], v176 offset:4096
	ds_read_b128 v[206:209], v176 offset:5120
	ds_read_b128 v[210:213], v176 offset:6144
	ds_read_b128 v[218:221], v176 offset:7168
	global_load_lds_dwordx4 v[170:171], off
	v_lshl_add_u64 v[170:171], s[46:47], 0, v[152:153]
	s_add_i32 m0, s33, 0xe000
	s_nop 0
	global_load_lds_dwordx4 v[170:171], off
	s_waitcnt vmcnt(8)
	s_waitcnt lgkmcnt(0)
	s_barrier
	s_setprio 1
	s_waitcnt lgkmcnt(0)
	v_mfma_f32_16x16x32_bf16 v[126:129], v[130:133], v[186:189], v[126:129]
	v_mfma_f32_16x16x32_bf16 v[122:125], v[138:141], v[186:189], v[122:125]
	v_mfma_f32_16x16x32_bf16 v[118:121], v[162:165], v[186:189], v[118:121]
	v_mfma_f32_16x16x32_bf16 v[114:117], v[178:181], v[186:189], v[114:117]
	v_mfma_f32_16x16x32_bf16 v[110:113], v[130:133], v[194:197], v[110:113]
	v_mfma_f32_16x16x32_bf16 v[106:109], v[138:141], v[194:197], v[106:109]
	v_mfma_f32_16x16x32_bf16 v[102:105], v[162:165], v[194:197], v[102:105]
	v_mfma_f32_16x16x32_bf16 v[98:101], v[178:181], v[194:197], v[98:101]
	v_mfma_f32_16x16x32_bf16 v[94:97], v[130:133], v[202:205], v[94:97]
	v_mfma_f32_16x16x32_bf16 v[90:93], v[138:141], v[202:205], v[90:93]
	v_mfma_f32_16x16x32_bf16 v[86:89], v[162:165], v[202:205], v[86:89]
	v_mfma_f32_16x16x32_bf16 v[82:85], v[178:181], v[202:205], v[82:85]
	v_mfma_f32_16x16x32_bf16 v[78:81], v[130:133], v[210:213], v[78:81]
	v_mfma_f32_16x16x32_bf16 v[74:77], v[138:141], v[210:213], v[74:77]
	v_mfma_f32_16x16x32_bf16 v[70:73], v[162:165], v[210:213], v[70:73]
	v_mfma_f32_16x16x32_bf16 v[66:69], v[178:181], v[210:213], v[66:69]
	s_setprio 0
	s_setprio 1
	v_mfma_f32_16x16x32_bf16 v[126:129], v[134:137], v[190:193], v[126:129]
	v_mfma_f32_16x16x32_bf16 v[122:125], v[158:161], v[190:193], v[122:125]
	v_mfma_f32_16x16x32_bf16 v[118:121], v[166:169], v[190:193], v[118:121]
	v_mfma_f32_16x16x32_bf16 v[114:117], v[182:185], v[190:193], v[114:117]
	v_mfma_f32_16x16x32_bf16 v[110:113], v[134:137], v[198:201], v[110:113]
	v_mfma_f32_16x16x32_bf16 v[106:109], v[158:161], v[198:201], v[106:109]
	v_mfma_f32_16x16x32_bf16 v[102:105], v[166:169], v[198:201], v[102:105]
	v_mfma_f32_16x16x32_bf16 v[98:101], v[182:185], v[198:201], v[98:101]
	v_mfma_f32_16x16x32_bf16 v[94:97], v[134:137], v[206:209], v[94:97]
	v_mfma_f32_16x16x32_bf16 v[90:93], v[158:161], v[206:209], v[90:93]
	v_mfma_f32_16x16x32_bf16 v[86:89], v[166:169], v[206:209], v[86:89]
	v_mfma_f32_16x16x32_bf16 v[82:85], v[182:185], v[206:209], v[82:85]
	v_mfma_f32_16x16x32_bf16 v[78:81], v[134:137], v[218:221], v[78:81]
	v_mfma_f32_16x16x32_bf16 v[74:77], v[158:161], v[218:221], v[74:77]
	v_mfma_f32_16x16x32_bf16 v[70:73], v[166:169], v[218:221], v[70:73]
	v_mfma_f32_16x16x32_bf16 v[66:69], v[182:185], v[218:221], v[66:69]
	s_setprio 0
	s_barrier
	s_add_i32 s62, s58, s31
	v_lshl_add_u64 v[170:171], s[34:35], 0, v[144:145]
	s_mov_b32 m0, s62
	ds_read_b128 v[186:189], v176 offset:16384
	ds_read_b128 v[190:193], v176 offset:17408
	ds_read_b128 v[194:197], v176 offset:18432
	ds_read_b128 v[198:201], v176 offset:19456
	ds_read_b128 v[202:205], v176 offset:20480
	ds_read_b128 v[206:209], v176 offset:21504
	ds_read_b128 v[210:213], v176 offset:22528
	ds_read_b128 v[218:221], v176 offset:23552
	global_load_lds_dwordx4 v[170:171], off
	s_add_i32 m0, s62, 0x2000
	s_add_u32 s62, s34, 0x80000
	v_lshl_add_u64 v[214:215], s[34:35], 0, v[148:149]
	s_addc_u32 s63, s35, 0
	s_add_i32 s66, s59, s31
	global_load_lds_dwordx4 v[214:215], off
	v_lshl_add_u64 v[222:223], s[62:63], 0, v[144:145]
	s_mov_b32 m0, s66
	v_lshl_add_u64 v[224:225], s[68:69], 0, v[146:147]
	global_load_lds_dwordx4 v[222:223], off
	v_lshl_add_u64 v[222:223], s[62:63], 0, v[148:149]
	s_add_i32 m0, s66, 0x2000
	s_nop 0
	global_load_lds_dwordx4 v[222:223], off
	v_lshl_add_u64 v[222:223], s[68:69], 0, v[142:143]
	s_mov_b32 m0, s33
	s_nop 0
	global_load_lds_dwordx4 v[222:223], off
	s_mov_b32 m0, s45
	s_nop 0
	global_load_lds_dwordx4 v[224:225], off
	s_waitcnt vmcnt(8)
	s_waitcnt lgkmcnt(0)
	s_barrier
	s_setprio 1
	s_waitcnt lgkmcnt(0)
	v_mfma_f32_16x16x32_bf16 v[62:65], v[130:133], v[186:189], v[62:65]
	v_mfma_f32_16x16x32_bf16 v[58:61], v[138:141], v[186:189], v[58:61]
	v_mfma_f32_16x16x32_bf16 v[54:57], v[162:165], v[186:189], v[54:57]
	v_mfma_f32_16x16x32_bf16 v[46:49], v[178:181], v[186:189], v[46:49]
	v_mfma_f32_16x16x32_bf16 v[50:53], v[130:133], v[194:197], v[50:53]
	v_mfma_f32_16x16x32_bf16 v[42:45], v[138:141], v[194:197], v[42:45]
	v_mfma_f32_16x16x32_bf16 v[30:33], v[162:165], v[194:197], v[30:33]
	v_mfma_f32_16x16x32_bf16 v[26:29], v[178:181], v[194:197], v[26:29]
	v_mfma_f32_16x16x32_bf16 v[38:41], v[130:133], v[202:205], v[38:41]
	v_mfma_f32_16x16x32_bf16 v[34:37], v[138:141], v[202:205], v[34:37]
	v_mfma_f32_16x16x32_bf16 v[22:25], v[162:165], v[202:205], v[22:25]
	v_mfma_f32_16x16x32_bf16 v[18:21], v[178:181], v[202:205], v[18:21]
	v_mfma_f32_16x16x32_bf16 v[14:17], v[130:133], v[210:213], v[14:17]
	v_mfma_f32_16x16x32_bf16 v[10:13], v[138:141], v[210:213], v[10:13]
	v_mfma_f32_16x16x32_bf16 v[6:9], v[162:165], v[210:213], v[6:9]
	v_mfma_f32_16x16x32_bf16 v[2:5], v[178:181], v[210:213], v[2:5]
	s_setprio 0
	s_setprio 1
	v_mfma_f32_16x16x32_bf16 v[62:65], v[134:137], v[190:193], v[62:65]
	v_mfma_f32_16x16x32_bf16 v[58:61], v[158:161], v[190:193], v[58:61]
	v_mfma_f32_16x16x32_bf16 v[54:57], v[166:169], v[190:193], v[54:57]
	v_mfma_f32_16x16x32_bf16 v[46:49], v[182:185], v[190:193], v[46:49]
	v_mfma_f32_16x16x32_bf16 v[50:53], v[134:137], v[198:201], v[50:53]
	v_mfma_f32_16x16x32_bf16 v[42:45], v[158:161], v[198:201], v[42:45]
	v_mfma_f32_16x16x32_bf16 v[30:33], v[166:169], v[198:201], v[30:33]
	v_mfma_f32_16x16x32_bf16 v[26:29], v[182:185], v[198:201], v[26:29]
	v_mfma_f32_16x16x32_bf16 v[38:41], v[134:137], v[206:209], v[38:41]
	v_mfma_f32_16x16x32_bf16 v[34:37], v[158:161], v[206:209], v[34:37]
	v_mfma_f32_16x16x32_bf16 v[22:25], v[166:169], v[206:209], v[22:25]
	v_mfma_f32_16x16x32_bf16 v[18:21], v[182:185], v[206:209], v[18:21]
	v_mfma_f32_16x16x32_bf16 v[14:17], v[134:137], v[218:221], v[14:17]
	v_mfma_f32_16x16x32_bf16 v[10:13], v[158:161], v[218:221], v[10:13]
	v_mfma_f32_16x16x32_bf16 v[6:9], v[166:169], v[218:221], v[6:9]
	v_mfma_f32_16x16x32_bf16 v[2:5], v[182:185], v[218:221], v[2:5]
	s_setprio 0
	s_barrier
	s_add_i32 s66, 0, 0x18000
	s_add_i32 s67, 0, 0x1c000
	v_add_u32_e32 v158, s66, v172
	v_add_u32_e32 v177, s67, v172
	ds_read_b128 v[130:133], v158
	ds_read_b128 v[134:137], v158 offset:1024
	ds_read_b128 v[138:141], v158 offset:2048
	ds_read_b128 v[158:161], v158 offset:3072
	ds_read_b128 v[162:165], v177
	ds_read_b128 v[166:169], v177 offset:1024
	ds_read_b128 v[178:181], v177 offset:2048
	ds_read_b128 v[182:185], v177 offset:3072
	s_add_u32 s62, s68, 0x80000
	s_addc_u32 s63, s69, 0
	s_mov_b32 m0, s52
	v_lshl_add_u64 v[226:227], s[62:63], 0, v[142:143]
	ds_read_b128 v[186:189], v176 offset:32768
	ds_read_b128 v[190:193], v176 offset:33792
	ds_read_b128 v[194:197], v176 offset:34816
	ds_read_b128 v[198:201], v176 offset:35840
	ds_read_b128 v[202:205], v176 offset:36864
	ds_read_b128 v[206:209], v176 offset:37888
	ds_read_b128 v[210:213], v176 offset:38912
	ds_read_b128 v[218:221], v176 offset:39936
	global_load_lds_dwordx4 v[226:227], off
	v_lshl_add_u64 v[226:227], s[62:63], 0, v[146:147]
	s_mov_b32 m0, s53
	s_nop 0
	global_load_lds_dwordx4 v[226:227], off
	s_waitcnt vmcnt(8)
	s_waitcnt lgkmcnt(0)
	s_barrier
	s_setprio 1
	s_waitcnt lgkmcnt(0)
	v_mfma_f32_16x16x32_bf16 v[126:129], v[130:133], v[186:189], v[126:129]
	v_mfma_f32_16x16x32_bf16 v[122:125], v[138:141], v[186:189], v[122:125]
	v_mfma_f32_16x16x32_bf16 v[118:121], v[162:165], v[186:189], v[118:121]
	v_mfma_f32_16x16x32_bf16 v[114:117], v[178:181], v[186:189], v[114:117]
	v_mfma_f32_16x16x32_bf16 v[110:113], v[130:133], v[194:197], v[110:113]
	v_mfma_f32_16x16x32_bf16 v[106:109], v[138:141], v[194:197], v[106:109]
	v_mfma_f32_16x16x32_bf16 v[102:105], v[162:165], v[194:197], v[102:105]
	v_mfma_f32_16x16x32_bf16 v[98:101], v[178:181], v[194:197], v[98:101]
	v_mfma_f32_16x16x32_bf16 v[94:97], v[130:133], v[202:205], v[94:97]
	v_mfma_f32_16x16x32_bf16 v[90:93], v[138:141], v[202:205], v[90:93]
	v_mfma_f32_16x16x32_bf16 v[86:89], v[162:165], v[202:205], v[86:89]
	v_mfma_f32_16x16x32_bf16 v[82:85], v[178:181], v[202:205], v[82:85]
	v_mfma_f32_16x16x32_bf16 v[78:81], v[130:133], v[210:213], v[78:81]
	v_mfma_f32_16x16x32_bf16 v[74:77], v[138:141], v[210:213], v[74:77]
	v_mfma_f32_16x16x32_bf16 v[70:73], v[162:165], v[210:213], v[70:73]
	v_mfma_f32_16x16x32_bf16 v[66:69], v[178:181], v[210:213], v[66:69]
	s_setprio 0
	s_setprio 1
	v_mfma_f32_16x16x32_bf16 v[126:129], v[134:137], v[190:193], v[126:129]
	v_mfma_f32_16x16x32_bf16 v[122:125], v[158:161], v[190:193], v[122:125]
	v_mfma_f32_16x16x32_bf16 v[118:121], v[166:169], v[190:193], v[118:121]
	v_mfma_f32_16x16x32_bf16 v[114:117], v[182:185], v[190:193], v[114:117]
	v_mfma_f32_16x16x32_bf16 v[110:113], v[134:137], v[198:201], v[110:113]
	v_mfma_f32_16x16x32_bf16 v[106:109], v[158:161], v[198:201], v[106:109]
	v_mfma_f32_16x16x32_bf16 v[102:105], v[166:169], v[198:201], v[102:105]
	v_mfma_f32_16x16x32_bf16 v[98:101], v[182:185], v[198:201], v[98:101]
	v_mfma_f32_16x16x32_bf16 v[94:97], v[134:137], v[206:209], v[94:97]
	v_mfma_f32_16x16x32_bf16 v[90:93], v[158:161], v[206:209], v[90:93]
	v_mfma_f32_16x16x32_bf16 v[86:89], v[166:169], v[206:209], v[86:89]
	v_mfma_f32_16x16x32_bf16 v[82:85], v[182:185], v[206:209], v[82:85]
	v_mfma_f32_16x16x32_bf16 v[78:81], v[134:137], v[218:221], v[78:81]
	v_mfma_f32_16x16x32_bf16 v[74:77], v[158:161], v[218:221], v[74:77]
	v_mfma_f32_16x16x32_bf16 v[70:73], v[166:169], v[218:221], v[70:73]
	v_mfma_f32_16x16x32_bf16 v[66:69], v[182:185], v[218:221], v[66:69]
	s_setprio 0
	s_barrier
	s_add_i32 s62, s66, s31
	v_lshl_add_u64 v[170:171], v[170:171], 0, s[24:25]
	s_mov_b32 m0, s62
	ds_read_b128 v[186:189], v176 offset:49152
	ds_read_b128 v[190:193], v176 offset:50176
	ds_read_b128 v[194:197], v176 offset:51200
	ds_read_b128 v[198:201], v176 offset:52224
	ds_read_b128 v[202:205], v176 offset:53248
	ds_read_b128 v[206:209], v176 offset:54272
	ds_read_b128 v[210:213], v176 offset:55296
	ds_read_b128 v[218:221], v176 offset:56320
	global_load_lds_dwordx4 v[170:171], off
	s_add_i32 m0, s62, 0x2000
	s_add_u32 s34, s34, 0x80080
	v_lshl_add_u64 v[170:171], v[214:215], 0, s[24:25]
	s_addc_u32 s35, s35, 0
	s_add_i32 s62, s67, s31
	global_load_lds_dwordx4 v[170:171], off
	v_lshl_add_u64 v[170:171], s[34:35], 0, v[144:145]
	s_mov_b32 m0, s62
	s_nop 0
	global_load_lds_dwordx4 v[170:171], off
	v_lshl_add_u64 v[170:171], s[34:35], 0, v[148:149]
	s_add_i32 m0, s62, 0x2000
	s_nop 0
	global_load_lds_dwordx4 v[170:171], off
	v_lshl_add_u64 v[170:171], v[222:223], 0, s[24:25]
	s_mov_b32 m0, s55
	s_nop 0
	global_load_lds_dwordx4 v[170:171], off
	v_lshl_add_u64 v[170:171], v[224:225], 0, s[24:25]
	s_mov_b32 m0, s56
	s_nop 0
	global_load_lds_dwordx4 v[170:171], off
	s_waitcnt vmcnt(8)
	s_waitcnt lgkmcnt(0)
	s_barrier
	s_setprio 1
	s_waitcnt lgkmcnt(0)
	v_mfma_f32_16x16x32_bf16 v[62:65], v[130:133], v[186:189], v[62:65]
	v_mfma_f32_16x16x32_bf16 v[58:61], v[138:141], v[186:189], v[58:61]
	v_mfma_f32_16x16x32_bf16 v[54:57], v[162:165], v[186:189], v[54:57]
	v_mfma_f32_16x16x32_bf16 v[46:49], v[178:181], v[186:189], v[46:49]
	v_mfma_f32_16x16x32_bf16 v[50:53], v[130:133], v[194:197], v[50:53]
	v_mfma_f32_16x16x32_bf16 v[42:45], v[138:141], v[194:197], v[42:45]
	v_mfma_f32_16x16x32_bf16 v[30:33], v[162:165], v[194:197], v[30:33]
	v_mfma_f32_16x16x32_bf16 v[26:29], v[178:181], v[194:197], v[26:29]
	v_mfma_f32_16x16x32_bf16 v[38:41], v[130:133], v[202:205], v[38:41]
	v_mfma_f32_16x16x32_bf16 v[34:37], v[138:141], v[202:205], v[34:37]
	v_mfma_f32_16x16x32_bf16 v[22:25], v[162:165], v[202:205], v[22:25]
	v_mfma_f32_16x16x32_bf16 v[18:21], v[178:181], v[202:205], v[18:21]
	v_mfma_f32_16x16x32_bf16 v[14:17], v[130:133], v[210:213], v[14:17]
	v_mfma_f32_16x16x32_bf16 v[10:13], v[138:141], v[210:213], v[10:13]
	v_mfma_f32_16x16x32_bf16 v[6:9], v[162:165], v[210:213], v[6:9]
	v_mfma_f32_16x16x32_bf16 v[2:5], v[178:181], v[210:213], v[2:5]
	s_setprio 0
	s_setprio 1
	v_mfma_f32_16x16x32_bf16 v[62:65], v[134:137], v[190:193], v[62:65]
	v_mfma_f32_16x16x32_bf16 v[58:61], v[158:161], v[190:193], v[58:61]
	v_mfma_f32_16x16x32_bf16 v[54:57], v[166:169], v[190:193], v[54:57]
	v_mfma_f32_16x16x32_bf16 v[46:49], v[182:185], v[190:193], v[46:49]
	v_mfma_f32_16x16x32_bf16 v[50:53], v[134:137], v[198:201], v[50:53]
	v_mfma_f32_16x16x32_bf16 v[42:45], v[158:161], v[198:201], v[42:45]
	v_mfma_f32_16x16x32_bf16 v[30:33], v[166:169], v[198:201], v[30:33]
	v_mfma_f32_16x16x32_bf16 v[26:29], v[182:185], v[198:201], v[26:29]
	v_mfma_f32_16x16x32_bf16 v[38:41], v[134:137], v[206:209], v[38:41]
	v_mfma_f32_16x16x32_bf16 v[34:37], v[158:161], v[206:209], v[34:37]
	v_mfma_f32_16x16x32_bf16 v[22:25], v[166:169], v[206:209], v[22:25]
	v_mfma_f32_16x16x32_bf16 v[18:21], v[182:185], v[206:209], v[18:21]
	v_mfma_f32_16x16x32_bf16 v[14:17], v[134:137], v[218:221], v[14:17]
	v_mfma_f32_16x16x32_bf16 v[10:13], v[158:161], v[218:221], v[10:13]
	v_mfma_f32_16x16x32_bf16 v[6:9], v[166:169], v[218:221], v[6:9]
	v_mfma_f32_16x16x32_bf16 v[2:5], v[182:185], v[218:221], v[2:5]
	s_setprio 0
	s_barrier
	s_add_i32 s72, s72, 2
	s_add_u32 s46, s46, 0x100
	s_addc_u32 s47, s47, 0
	s_add_u32 s70, s70, 0x100
	s_addc_u32 s71, s71, 0
	s_cmp_gt_u32 s72, 29
	s_cbranch_scc0 .LBB0_2938
	s_and_b64 vcc, exec, s[26:27]
	s_cbranch_vccz .LBB0_2941
	s_barrier

.LBB0_3067:
	ds_read_b128 v[146:149], v153
	ds_read_b128 v[156:159], v153 offset:1024
	ds_read_b128 v[160:163], v153 offset:2048
	ds_read_b128 v[164:167], v153 offset:3072
	ds_read_b128 v[168:171], v154
	ds_read_b128 v[172:175], v154 offset:1024
	ds_read_b128 v[176:179], v154 offset:2048
	ds_read_b128 v[180:183], v154 offset:3072
	s_add_u32 s34, s44, 0xfff80080
	s_addc_u32 s35, s45, -1
	s_cmp_eq_u32 s71, 28
	s_cselect_b32 s47, s0, s35
	s_cselect_b32 s46, s1, s34
	s_cselect_b32 s35, s27, s70
	s_cselect_b32 s34, s37, s69
	v_lshl_add_u64 v[218:219], s[44:45], 0, v[138:139]
	s_add_i32 m0, s43, 0xc000
	ds_read_b128 v[184:187], v155
	ds_read_b128 v[188:191], v155 offset:1024
	ds_read_b128 v[192:195], v155 offset:2048
	ds_read_b128 v[196:199], v155 offset:3072
	ds_read_b128 v[200:203], v155 offset:4096
	ds_read_b128 v[204:207], v155 offset:5120
	ds_read_b128 v[208:211], v155 offset:6144
	ds_read_b128 v[212:215], v155 offset:7168
	global_load_lds_dwordx4 v[218:219], off
	v_lshl_add_u64 v[218:219], s[44:45], 0, v[140:141]
	s_add_i32 m0, s43, 0xe000
	s_nop 0
	global_load_lds_dwordx4 v[218:219], off
	s_waitcnt vmcnt(8)
	s_waitcnt lgkmcnt(0)
	s_barrier
	s_setprio 1
	s_waitcnt lgkmcnt(0)
	v_mfma_f32_16x16x32_bf16 v[126:129], v[146:149], v[184:187], v[126:129]
	v_mfma_f32_16x16x32_bf16 v[118:121], v[160:163], v[184:187], v[118:121]
	v_mfma_f32_16x16x32_bf16 v[122:125], v[168:171], v[184:187], v[122:125]
	v_mfma_f32_16x16x32_bf16 v[114:117], v[176:179], v[184:187], v[114:117]
	v_mfma_f32_16x16x32_bf16 v[110:113], v[146:149], v[192:195], v[110:113]
	v_mfma_f32_16x16x32_bf16 v[102:105], v[160:163], v[192:195], v[102:105]
	v_mfma_f32_16x16x32_bf16 v[106:109], v[168:171], v[192:195], v[106:109]
	v_mfma_f32_16x16x32_bf16 v[98:101], v[176:179], v[192:195], v[98:101]
	v_mfma_f32_16x16x32_bf16 v[94:97], v[146:149], v[200:203], v[94:97]
	v_mfma_f32_16x16x32_bf16 v[86:89], v[160:163], v[200:203], v[86:89]
	v_mfma_f32_16x16x32_bf16 v[90:93], v[168:171], v[200:203], v[90:93]
	v_mfma_f32_16x16x32_bf16 v[82:85], v[176:179], v[200:203], v[82:85]
	v_mfma_f32_16x16x32_bf16 v[78:81], v[146:149], v[208:211], v[78:81]
	v_mfma_f32_16x16x32_bf16 v[70:73], v[160:163], v[208:211], v[70:73]
	v_mfma_f32_16x16x32_bf16 v[74:77], v[168:171], v[208:211], v[74:77]
	v_mfma_f32_16x16x32_bf16 v[66:69], v[176:179], v[208:211], v[66:69]
	s_setprio 0
	s_setprio 1
	v_mfma_f32_16x16x32_bf16 v[126:129], v[156:159], v[188:191], v[126:129]
	v_mfma_f32_16x16x32_bf16 v[118:121], v[164:167], v[188:191], v[118:121]
	v_mfma_f32_16x16x32_bf16 v[122:125], v[172:175], v[188:191], v[122:125]
	v_mfma_f32_16x16x32_bf16 v[114:117], v[180:183], v[188:191], v[114:117]
	v_mfma_f32_16x16x32_bf16 v[110:113], v[156:159], v[196:199], v[110:113]
	v_mfma_f32_16x16x32_bf16 v[102:105], v[164:167], v[196:199], v[102:105]
	v_mfma_f32_16x16x32_bf16 v[106:109], v[172:175], v[196:199], v[106:109]
	v_mfma_f32_16x16x32_bf16 v[98:101], v[180:183], v[196:199], v[98:101]
	v_mfma_f32_16x16x32_bf16 v[94:97], v[156:159], v[204:207], v[94:97]
	v_mfma_f32_16x16x32_bf16 v[86:89], v[164:167], v[204:207], v[86:89]
	v_mfma_f32_16x16x32_bf16 v[90:93], v[172:175], v[204:207], v[90:93]
	v_mfma_f32_16x16x32_bf16 v[82:85], v[180:183], v[204:207], v[82:85]
	v_mfma_f32_16x16x32_bf16 v[78:81], v[156:159], v[212:215], v[78:81]
	v_mfma_f32_16x16x32_bf16 v[70:73], v[164:167], v[212:215], v[70:73]
	v_mfma_f32_16x16x32_bf16 v[74:77], v[172:175], v[212:215], v[74:77]
	v_mfma_f32_16x16x32_bf16 v[66:69], v[180:183], v[212:215], v[66:69]
	s_setprio 0
	s_barrier
	s_add_i32 s62, s59, s30
	v_lshl_add_u64 v[218:219], s[34:35], 0, v[134:135]
	s_mov_b32 m0, s62
	ds_read_b128 v[184:187], v155 offset:16384
	ds_read_b128 v[188:191], v155 offset:17408
	ds_read_b128 v[192:195], v155 offset:18432
	ds_read_b128 v[196:199], v155 offset:19456
	ds_read_b128 v[200:203], v155 offset:20480
	ds_read_b128 v[204:207], v155 offset:21504
	ds_read_b128 v[208:211], v155 offset:22528
	ds_read_b128 v[212:215], v155 offset:23552
	global_load_lds_dwordx4 v[218:219], off
	s_add_i32 m0, s62, 0x2000
	s_add_u32 s62, s34, 0x80000
	v_lshl_add_u64 v[220:221], s[34:35], 0, v[130:131]
	s_addc_u32 s63, s35, 0
	s_add_i32 s66, s60, s30
	global_load_lds_dwordx4 v[220:221], off
	v_lshl_add_u64 v[222:223], s[62:63], 0, v[134:135]
	s_mov_b32 m0, s66
	v_lshl_add_u64 v[224:225], s[46:47], 0, v[132:133]
	global_load_lds_dwordx4 v[222:223], off
	v_lshl_add_u64 v[222:223], s[62:63], 0, v[130:131]
	s_add_i32 m0, s66, 0x2000
	s_nop 0
	global_load_lds_dwordx4 v[222:223], off
	v_lshl_add_u64 v[222:223], s[46:47], 0, v[136:137]
	s_mov_b32 m0, s43
	s_nop 0
	global_load_lds_dwordx4 v[222:223], off
	s_mov_b32 m0, s52
	s_nop 0
	global_load_lds_dwordx4 v[224:225], off
	s_waitcnt vmcnt(8)
	s_waitcnt lgkmcnt(0)
	s_barrier
	s_setprio 1
	s_waitcnt lgkmcnt(0)
	v_mfma_f32_16x16x32_bf16 v[62:65], v[146:149], v[184:187], v[62:65]
	v_mfma_f32_16x16x32_bf16 v[54:57], v[160:163], v[184:187], v[54:57]
	v_mfma_f32_16x16x32_bf16 v[58:61], v[168:171], v[184:187], v[58:61]
	v_mfma_f32_16x16x32_bf16 v[50:53], v[176:179], v[184:187], v[50:53]
	v_mfma_f32_16x16x32_bf16 v[46:49], v[146:149], v[192:195], v[46:49]
	v_mfma_f32_16x16x32_bf16 v[38:41], v[160:163], v[192:195], v[38:41]
	v_mfma_f32_16x16x32_bf16 v[42:45], v[168:171], v[192:195], v[42:45]
	v_mfma_f32_16x16x32_bf16 v[34:37], v[176:179], v[192:195], v[34:37]
	v_mfma_f32_16x16x32_bf16 v[30:33], v[146:149], v[200:203], v[30:33]
	v_mfma_f32_16x16x32_bf16 v[22:25], v[160:163], v[200:203], v[22:25]
	v_mfma_f32_16x16x32_bf16 v[26:29], v[168:171], v[200:203], v[26:29]
	v_mfma_f32_16x16x32_bf16 v[18:21], v[176:179], v[200:203], v[18:21]
	v_mfma_f32_16x16x32_bf16 v[14:17], v[146:149], v[208:211], v[14:17]
	v_mfma_f32_16x16x32_bf16 v[6:9], v[160:163], v[208:211], v[6:9]
	v_mfma_f32_16x16x32_bf16 v[10:13], v[168:171], v[208:211], v[10:13]
	v_mfma_f32_16x16x32_bf16 v[2:5], v[176:179], v[208:211], v[2:5]
	s_setprio 0
	s_setprio 1
	v_mfma_f32_16x16x32_bf16 v[62:65], v[156:159], v[188:191], v[62:65]
	v_mfma_f32_16x16x32_bf16 v[54:57], v[164:167], v[188:191], v[54:57]
	v_mfma_f32_16x16x32_bf16 v[58:61], v[172:175], v[188:191], v[58:61]
	v_mfma_f32_16x16x32_bf16 v[50:53], v[180:183], v[188:191], v[50:53]
	v_mfma_f32_16x16x32_bf16 v[46:49], v[156:159], v[196:199], v[46:49]
	v_mfma_f32_16x16x32_bf16 v[38:41], v[164:167], v[196:199], v[38:41]
	v_mfma_f32_16x16x32_bf16 v[42:45], v[172:175], v[196:199], v[42:45]
	v_mfma_f32_16x16x32_bf16 v[34:37], v[180:183], v[196:199], v[34:37]
	v_mfma_f32_16x16x32_bf16 v[30:33], v[156:159], v[204:207], v[30:33]
	v_mfma_f32_16x16x32_bf16 v[22:25], v[164:167], v[204:207], v[22:25]
	v_mfma_f32_16x16x32_bf16 v[26:29], v[172:175], v[204:207], v[26:29]
	v_mfma_f32_16x16x32_bf16 v[18:21], v[180:183], v[204:207], v[18:21]
	v_mfma_f32_16x16x32_bf16 v[14:17], v[156:159], v[212:215], v[14:17]
	v_mfma_f32_16x16x32_bf16 v[6:9], v[164:167], v[212:215], v[6:9]
	v_mfma_f32_16x16x32_bf16 v[10:13], v[172:175], v[212:215], v[10:13]
	v_mfma_f32_16x16x32_bf16 v[2:5], v[180:183], v[212:215], v[2:5]
	s_setprio 0
	s_barrier
	s_add_i32 s62, 0, 0x18000
	s_add_i32 s63, 0, 0x1c000
	v_add_u32_e32 v164, s62, v151
	v_add_u32_e32 v180, s63, v151
	ds_read_b128 v[146:149], v164
	ds_read_b128 v[156:159], v164 offset:1024
	ds_read_b128 v[160:163], v164 offset:2048
	ds_read_b128 v[164:167], v164 offset:3072
	ds_read_b128 v[168:171], v180
	ds_read_b128 v[172:175], v180 offset:1024
	ds_read_b128 v[176:179], v180 offset:2048
	ds_read_b128 v[180:183], v180 offset:3072
	s_add_u32 s46, s46, 0x80000
	s_addc_u32 s47, s47, 0
	s_mov_b32 m0, s53
	v_lshl_add_u64 v[226:227], s[46:47], 0, v[136:137]
	ds_read_b128 v[184:187], v155 offset:32768
	ds_read_b128 v[188:191], v155 offset:33792
	ds_read_b128 v[192:195], v155 offset:34816
	ds_read_b128 v[196:199], v155 offset:35840
	ds_read_b128 v[200:203], v155 offset:36864
	ds_read_b128 v[204:207], v155 offset:37888
	ds_read_b128 v[208:211], v155 offset:38912
	ds_read_b128 v[212:215], v155 offset:39936
	global_load_lds_dwordx4 v[226:227], off
	v_lshl_add_u64 v[226:227], s[46:47], 0, v[132:133]
	s_mov_b32 m0, s54
	s_nop 0
	global_load_lds_dwordx4 v[226:227], off
	s_waitcnt vmcnt(8)
	s_waitcnt lgkmcnt(0)
	s_barrier
	s_setprio 1
	s_waitcnt lgkmcnt(0)
	v_mfma_f32_16x16x32_bf16 v[126:129], v[146:149], v[184:187], v[126:129]
	v_mfma_f32_16x16x32_bf16 v[118:121], v[160:163], v[184:187], v[118:121]
	v_mfma_f32_16x16x32_bf16 v[122:125], v[168:171], v[184:187], v[122:125]
	v_mfma_f32_16x16x32_bf16 v[114:117], v[176:179], v[184:187], v[114:117]
	v_mfma_f32_16x16x32_bf16 v[110:113], v[146:149], v[192:195], v[110:113]
	v_mfma_f32_16x16x32_bf16 v[102:105], v[160:163], v[192:195], v[102:105]
	v_mfma_f32_16x16x32_bf16 v[106:109], v[168:171], v[192:195], v[106:109]
	v_mfma_f32_16x16x32_bf16 v[98:101], v[176:179], v[192:195], v[98:101]
	v_mfma_f32_16x16x32_bf16 v[94:97], v[146:149], v[200:203], v[94:97]
	v_mfma_f32_16x16x32_bf16 v[86:89], v[160:163], v[200:203], v[86:89]
	v_mfma_f32_16x16x32_bf16 v[90:93], v[168:171], v[200:203], v[90:93]
	v_mfma_f32_16x16x32_bf16 v[82:85], v[176:179], v[200:203], v[82:85]
	v_mfma_f32_16x16x32_bf16 v[78:81], v[146:149], v[208:211], v[78:81]
	v_mfma_f32_16x16x32_bf16 v[70:73], v[160:163], v[208:211], v[70:73]
	v_mfma_f32_16x16x32_bf16 v[74:77], v[168:171], v[208:211], v[74:77]
	v_mfma_f32_16x16x32_bf16 v[66:69], v[176:179], v[208:211], v[66:69]
	s_setprio 0
	s_setprio 1
	v_mfma_f32_16x16x32_bf16 v[126:129], v[156:159], v[188:191], v[126:129]
	v_mfma_f32_16x16x32_bf16 v[118:121], v[164:167], v[188:191], v[118:121]
	v_mfma_f32_16x16x32_bf16 v[122:125], v[172:175], v[188:191], v[122:125]
	v_mfma_f32_16x16x32_bf16 v[114:117], v[180:183], v[188:191], v[114:117]
	v_mfma_f32_16x16x32_bf16 v[110:113], v[156:159], v[196:199], v[110:113]
	v_mfma_f32_16x16x32_bf16 v[102:105], v[164:167], v[196:199], v[102:105]
	v_mfma_f32_16x16x32_bf16 v[106:109], v[172:175], v[196:199], v[106:109]
	v_mfma_f32_16x16x32_bf16 v[98:101], v[180:183], v[196:199], v[98:101]
	v_mfma_f32_16x16x32_bf16 v[94:97], v[156:159], v[204:207], v[94:97]
	v_mfma_f32_16x16x32_bf16 v[86:89], v[164:167], v[204:207], v[86:89]
	v_mfma_f32_16x16x32_bf16 v[90:93], v[172:175], v[204:207], v[90:93]
	v_mfma_f32_16x16x32_bf16 v[82:85], v[180:183], v[204:207], v[82:85]
	v_mfma_f32_16x16x32_bf16 v[78:81], v[156:159], v[212:215], v[78:81]
	v_mfma_f32_16x16x32_bf16 v[70:73], v[164:167], v[212:215], v[70:73]
	v_mfma_f32_16x16x32_bf16 v[74:77], v[172:175], v[212:215], v[74:77]
	v_mfma_f32_16x16x32_bf16 v[66:69], v[180:183], v[212:215], v[66:69]
	s_setprio 0
	s_barrier
	s_add_i32 s46, s62, s30
	v_lshl_add_u64 v[218:219], v[218:219], 0, s[8:9]
	s_mov_b32 m0, s46
	ds_read_b128 v[184:187], v155 offset:49152
	ds_read_b128 v[188:191], v155 offset:50176
	ds_read_b128 v[192:195], v155 offset:51200
	ds_read_b128 v[196:199], v155 offset:52224
	ds_read_b128 v[200:203], v155 offset:53248
	ds_read_b128 v[204:207], v155 offset:54272
	ds_read_b128 v[208:211], v155 offset:55296
	ds_read_b128 v[212:215], v155 offset:56320
	global_load_lds_dwordx4 v[218:219], off
	s_add_i32 m0, s46, 0x2000
	s_add_u32 s34, s34, 0x80080
	v_lshl_add_u64 v[218:219], v[220:221], 0, s[8:9]
	s_addc_u32 s35, s35, 0
	s_add_i32 s46, s63, s30
	global_load_lds_dwordx4 v[218:219], off
	v_lshl_add_u64 v[218:219], s[34:35], 0, v[134:135]
	s_mov_b32 m0, s46
	s_nop 0
	global_load_lds_dwordx4 v[218:219], off
	v_lshl_add_u64 v[218:219], s[34:35], 0, v[130:131]
	s_add_i32 m0, s46, 0x2000
	s_nop 0
	global_load_lds_dwordx4 v[218:219], off
	v_lshl_add_u64 v[218:219], v[222:223], 0, s[8:9]
	s_mov_b32 m0, s56
	s_nop 0
	global_load_lds_dwordx4 v[218:219], off
	v_lshl_add_u64 v[218:219], v[224:225], 0, s[8:9]
	s_mov_b32 m0, s57
	s_nop 0
	global_load_lds_dwordx4 v[218:219], off
	s_waitcnt vmcnt(8)
	s_waitcnt lgkmcnt(0)
	s_barrier
	s_setprio 1
	s_waitcnt lgkmcnt(0)
	v_mfma_f32_16x16x32_bf16 v[62:65], v[146:149], v[184:187], v[62:65]
	v_mfma_f32_16x16x32_bf16 v[54:57], v[160:163], v[184:187], v[54:57]
	v_mfma_f32_16x16x32_bf16 v[58:61], v[168:171], v[184:187], v[58:61]
	v_mfma_f32_16x16x32_bf16 v[50:53], v[176:179], v[184:187], v[50:53]
	v_mfma_f32_16x16x32_bf16 v[46:49], v[146:149], v[192:195], v[46:49]
	v_mfma_f32_16x16x32_bf16 v[38:41], v[160:163], v[192:195], v[38:41]
	v_mfma_f32_16x16x32_bf16 v[42:45], v[168:171], v[192:195], v[42:45]
	v_mfma_f32_16x16x32_bf16 v[34:37], v[176:179], v[192:195], v[34:37]
	v_mfma_f32_16x16x32_bf16 v[30:33], v[146:149], v[200:203], v[30:33]
	v_mfma_f32_16x16x32_bf16 v[22:25], v[160:163], v[200:203], v[22:25]
	v_mfma_f32_16x16x32_bf16 v[26:29], v[168:171], v[200:203], v[26:29]
	v_mfma_f32_16x16x32_bf16 v[18:21], v[176:179], v[200:203], v[18:21]
	v_mfma_f32_16x16x32_bf16 v[14:17], v[146:149], v[208:211], v[14:17]
	v_mfma_f32_16x16x32_bf16 v[6:9], v[160:163], v[208:211], v[6:9]
	v_mfma_f32_16x16x32_bf16 v[10:13], v[168:171], v[208:211], v[10:13]
	v_mfma_f32_16x16x32_bf16 v[2:5], v[176:179], v[208:211], v[2:5]
	s_setprio 0
	s_setprio 1
	v_mfma_f32_16x16x32_bf16 v[62:65], v[156:159], v[188:191], v[62:65]
	v_mfma_f32_16x16x32_bf16 v[54:57], v[164:167], v[188:191], v[54:57]
	v_mfma_f32_16x16x32_bf16 v[58:61], v[172:175], v[188:191], v[58:61]
	v_mfma_f32_16x16x32_bf16 v[50:53], v[180:183], v[188:191], v[50:53]
	v_mfma_f32_16x16x32_bf16 v[46:49], v[156:159], v[196:199], v[46:49]
	v_mfma_f32_16x16x32_bf16 v[38:41], v[164:167], v[196:199], v[38:41]
	v_mfma_f32_16x16x32_bf16 v[42:45], v[172:175], v[196:199], v[42:45]
	v_mfma_f32_16x16x32_bf16 v[34:37], v[180:183], v[196:199], v[34:37]
	v_mfma_f32_16x16x32_bf16 v[30:33], v[156:159], v[204:207], v[30:33]
	v_mfma_f32_16x16x32_bf16 v[22:25], v[164:167], v[204:207], v[22:25]
	v_mfma_f32_16x16x32_bf16 v[26:29], v[172:175], v[204:207], v[26:29]
	v_mfma_f32_16x16x32_bf16 v[18:21], v[180:183], v[204:207], v[18:21]
	v_mfma_f32_16x16x32_bf16 v[14:17], v[156:159], v[212:215], v[14:17]
	v_mfma_f32_16x16x32_bf16 v[6:9], v[164:167], v[212:215], v[6:9]
	v_mfma_f32_16x16x32_bf16 v[10:13], v[172:175], v[212:215], v[10:13]
	v_mfma_f32_16x16x32_bf16 v[2:5], v[180:183], v[212:215], v[2:5]
	s_setprio 0
	s_barrier
	s_add_i32 s71, s71, 2
	s_add_u32 s44, s44, 0x100
	s_addc_u32 s45, s45, 0
	s_add_u32 s69, s69, 0x100
	s_addc_u32 s70, s70, 0
	s_cmp_gt_u32 s71, 29
	s_cbranch_scc0 .LBB0_3067
	v_mov_b32_e32 v160, 0xbfb8aa3b
	s_and_b64 vcc, exec, s[24:25]
	s_cbranch_vccz .LBB0_3070
	s_barrier

.LBB0_3180:
	ds_read_b128 v[130:133], v174
	ds_read_b128 v[134:137], v174 offset:1024
	ds_read_b128 v[138:141], v174 offset:2048
	ds_read_b128 v[158:161], v174 offset:3072
	ds_read_b128 v[162:165], v175
	ds_read_b128 v[166:169], v175 offset:1024
	ds_read_b128 v[178:181], v175 offset:2048
	ds_read_b128 v[182:185], v175 offset:3072
	s_add_u32 s34, s40, 0xffea0080
	s_addc_u32 s35, s41, -1
	s_cmpk_eq_i32 s60, 0x54
	s_cselect_b32 s43, s5, s35
	s_cselect_b32 s42, s4, s34
	s_cselect_b32 s35, s39, s1
	s_cselect_b32 s34, s38, s0
	v_lshl_add_u64 v[170:171], s[40:41], 0, v[150:151]
	s_add_i32 m0, s33, 0xc000
	ds_read_b128 v[186:189], v176
	ds_read_b128 v[190:193], v176 offset:1024
	ds_read_b128 v[194:197], v176 offset:2048
	ds_read_b128 v[198:201], v176 offset:3072
	ds_read_b128 v[202:205], v176 offset:4096
	ds_read_b128 v[206:209], v176 offset:5120
	ds_read_b128 v[210:213], v176 offset:6144
	ds_read_b128 v[218:221], v176 offset:7168
	global_load_lds_dwordx4 v[170:171], off
	v_lshl_add_u64 v[170:171], s[40:41], 0, v[152:153]
	s_add_i32 m0, s33, 0xe000
	s_nop 0
	global_load_lds_dwordx4 v[170:171], off
	s_waitcnt vmcnt(8)
	s_waitcnt lgkmcnt(0)
	s_barrier
	s_setprio 1
	s_waitcnt lgkmcnt(0)
	v_mfma_f32_16x16x32_bf16 v[126:129], v[130:133], v[186:189], v[126:129]
	v_mfma_f32_16x16x32_bf16 v[122:125], v[138:141], v[186:189], v[122:125]
	v_mfma_f32_16x16x32_bf16 v[118:121], v[162:165], v[186:189], v[118:121]
	v_mfma_f32_16x16x32_bf16 v[114:117], v[178:181], v[186:189], v[114:117]
	v_mfma_f32_16x16x32_bf16 v[110:113], v[130:133], v[194:197], v[110:113]
	v_mfma_f32_16x16x32_bf16 v[106:109], v[138:141], v[194:197], v[106:109]
	v_mfma_f32_16x16x32_bf16 v[102:105], v[162:165], v[194:197], v[102:105]
	v_mfma_f32_16x16x32_bf16 v[98:101], v[178:181], v[194:197], v[98:101]
	v_mfma_f32_16x16x32_bf16 v[94:97], v[130:133], v[202:205], v[94:97]
	v_mfma_f32_16x16x32_bf16 v[90:93], v[138:141], v[202:205], v[90:93]
	v_mfma_f32_16x16x32_bf16 v[86:89], v[162:165], v[202:205], v[86:89]
	v_mfma_f32_16x16x32_bf16 v[82:85], v[178:181], v[202:205], v[82:85]
	v_mfma_f32_16x16x32_bf16 v[78:81], v[130:133], v[210:213], v[78:81]
	v_mfma_f32_16x16x32_bf16 v[74:77], v[138:141], v[210:213], v[74:77]
	v_mfma_f32_16x16x32_bf16 v[70:73], v[162:165], v[210:213], v[70:73]
	v_mfma_f32_16x16x32_bf16 v[66:69], v[178:181], v[210:213], v[66:69]
	s_setprio 0
	s_setprio 1
	v_mfma_f32_16x16x32_bf16 v[126:129], v[134:137], v[190:193], v[126:129]
	v_mfma_f32_16x16x32_bf16 v[122:125], v[158:161], v[190:193], v[122:125]
	v_mfma_f32_16x16x32_bf16 v[118:121], v[166:169], v[190:193], v[118:121]
	v_mfma_f32_16x16x32_bf16 v[114:117], v[182:185], v[190:193], v[114:117]
	v_mfma_f32_16x16x32_bf16 v[110:113], v[134:137], v[198:201], v[110:113]
	v_mfma_f32_16x16x32_bf16 v[106:109], v[158:161], v[198:201], v[106:109]
	v_mfma_f32_16x16x32_bf16 v[102:105], v[166:169], v[198:201], v[102:105]
	v_mfma_f32_16x16x32_bf16 v[98:101], v[182:185], v[198:201], v[98:101]
	v_mfma_f32_16x16x32_bf16 v[94:97], v[134:137], v[206:209], v[94:97]
	v_mfma_f32_16x16x32_bf16 v[90:93], v[158:161], v[206:209], v[90:93]
	v_mfma_f32_16x16x32_bf16 v[86:89], v[166:169], v[206:209], v[86:89]
	v_mfma_f32_16x16x32_bf16 v[82:85], v[182:185], v[206:209], v[82:85]
	v_mfma_f32_16x16x32_bf16 v[78:81], v[134:137], v[218:221], v[78:81]
	v_mfma_f32_16x16x32_bf16 v[74:77], v[158:161], v[218:221], v[74:77]
	v_mfma_f32_16x16x32_bf16 v[70:73], v[166:169], v[218:221], v[70:73]
	v_mfma_f32_16x16x32_bf16 v[66:69], v[182:185], v[218:221], v[66:69]
	s_setprio 0
	s_barrier
	s_add_i32 s61, s53, s31
	v_lshl_add_u64 v[170:171], s[34:35], 0, v[144:145]
	s_mov_b32 m0, s61
	ds_read_b128 v[186:189], v176 offset:16384
	ds_read_b128 v[190:193], v176 offset:17408
	ds_read_b128 v[194:197], v176 offset:18432
	ds_read_b128 v[198:201], v176 offset:19456
	ds_read_b128 v[202:205], v176 offset:20480
	ds_read_b128 v[206:209], v176 offset:21504
	ds_read_b128 v[210:213], v176 offset:22528
	ds_read_b128 v[218:221], v176 offset:23552
	global_load_lds_dwordx4 v[170:171], off
	s_add_i32 m0, s61, 0x2000
	s_add_u32 s62, s34, 0x160000
	v_lshl_add_u64 v[214:215], s[34:35], 0, v[148:149]
	s_addc_u32 s63, s35, 0
	s_add_i32 s61, s54, s31
	global_load_lds_dwordx4 v[214:215], off
	v_lshl_add_u64 v[222:223], s[62:63], 0, v[144:145]
	s_mov_b32 m0, s61
	v_lshl_add_u64 v[224:225], s[42:43], 0, v[146:147]
	global_load_lds_dwordx4 v[222:223], off
	v_lshl_add_u64 v[222:223], s[62:63], 0, v[148:149]
	s_add_i32 m0, s61, 0x2000
	s_nop 0
	global_load_lds_dwordx4 v[222:223], off
	v_lshl_add_u64 v[222:223], s[42:43], 0, v[142:143]
	s_mov_b32 m0, s33
	s_nop 0
	global_load_lds_dwordx4 v[222:223], off
	s_mov_b32 m0, s44
	s_nop 0
	global_load_lds_dwordx4 v[224:225], off
	s_waitcnt vmcnt(8)
	s_waitcnt lgkmcnt(0)
	s_barrier
	s_setprio 1
	s_waitcnt lgkmcnt(0)
	v_mfma_f32_16x16x32_bf16 v[62:65], v[130:133], v[186:189], v[62:65]
	v_mfma_f32_16x16x32_bf16 v[58:61], v[138:141], v[186:189], v[58:61]
	v_mfma_f32_16x16x32_bf16 v[54:57], v[162:165], v[186:189], v[54:57]
	v_mfma_f32_16x16x32_bf16 v[46:49], v[178:181], v[186:189], v[46:49]
	v_mfma_f32_16x16x32_bf16 v[50:53], v[130:133], v[194:197], v[50:53]
	v_mfma_f32_16x16x32_bf16 v[42:45], v[138:141], v[194:197], v[42:45]
	v_mfma_f32_16x16x32_bf16 v[30:33], v[162:165], v[194:197], v[30:33]
	v_mfma_f32_16x16x32_bf16 v[26:29], v[178:181], v[194:197], v[26:29]
	v_mfma_f32_16x16x32_bf16 v[38:41], v[130:133], v[202:205], v[38:41]
	v_mfma_f32_16x16x32_bf16 v[34:37], v[138:141], v[202:205], v[34:37]
	v_mfma_f32_16x16x32_bf16 v[22:25], v[162:165], v[202:205], v[22:25]
	v_mfma_f32_16x16x32_bf16 v[18:21], v[178:181], v[202:205], v[18:21]
	v_mfma_f32_16x16x32_bf16 v[14:17], v[130:133], v[210:213], v[14:17]
	v_mfma_f32_16x16x32_bf16 v[10:13], v[138:141], v[210:213], v[10:13]
	v_mfma_f32_16x16x32_bf16 v[6:9], v[162:165], v[210:213], v[6:9]
	v_mfma_f32_16x16x32_bf16 v[2:5], v[178:181], v[210:213], v[2:5]
	s_setprio 0
	s_setprio 1
	v_mfma_f32_16x16x32_bf16 v[62:65], v[134:137], v[190:193], v[62:65]
	v_mfma_f32_16x16x32_bf16 v[58:61], v[158:161], v[190:193], v[58:61]
	v_mfma_f32_16x16x32_bf16 v[54:57], v[166:169], v[190:193], v[54:57]
	v_mfma_f32_16x16x32_bf16 v[46:49], v[182:185], v[190:193], v[46:49]
	v_mfma_f32_16x16x32_bf16 v[50:53], v[134:137], v[198:201], v[50:53]
	v_mfma_f32_16x16x32_bf16 v[42:45], v[158:161], v[198:201], v[42:45]
	v_mfma_f32_16x16x32_bf16 v[30:33], v[166:169], v[198:201], v[30:33]
	v_mfma_f32_16x16x32_bf16 v[26:29], v[182:185], v[198:201], v[26:29]
	v_mfma_f32_16x16x32_bf16 v[38:41], v[134:137], v[206:209], v[38:41]
	v_mfma_f32_16x16x32_bf16 v[34:37], v[158:161], v[206:209], v[34:37]
	v_mfma_f32_16x16x32_bf16 v[22:25], v[166:169], v[206:209], v[22:25]
	v_mfma_f32_16x16x32_bf16 v[18:21], v[182:185], v[206:209], v[18:21]
	v_mfma_f32_16x16x32_bf16 v[14:17], v[134:137], v[218:221], v[14:17]
	v_mfma_f32_16x16x32_bf16 v[10:13], v[158:161], v[218:221], v[10:13]
	v_mfma_f32_16x16x32_bf16 v[6:9], v[166:169], v[218:221], v[6:9]
	v_mfma_f32_16x16x32_bf16 v[2:5], v[182:185], v[218:221], v[2:5]
	s_setprio 0
	s_barrier
	s_add_i32 s61, 0, 0x18000
	s_add_i32 s62, 0, 0x1c000
	v_add_u32_e32 v158, s61, v172
	v_add_u32_e32 v177, s62, v172
	ds_read_b128 v[130:133], v158
	ds_read_b128 v[134:137], v158 offset:1024
	ds_read_b128 v[138:141], v158 offset:2048
	ds_read_b128 v[158:161], v158 offset:3072
	ds_read_b128 v[162:165], v177
	ds_read_b128 v[166:169], v177 offset:1024
	ds_read_b128 v[178:181], v177 offset:2048
	ds_read_b128 v[182:185], v177 offset:3072
	s_add_u32 s42, s42, 0x160000
	s_addc_u32 s43, s43, 0
	s_mov_b32 m0, s45
	v_lshl_add_u64 v[226:227], s[42:43], 0, v[142:143]
	ds_read_b128 v[186:189], v176 offset:32768
	ds_read_b128 v[190:193], v176 offset:33792
	ds_read_b128 v[194:197], v176 offset:34816
	ds_read_b128 v[198:201], v176 offset:35840
	ds_read_b128 v[202:205], v176 offset:36864
	ds_read_b128 v[206:209], v176 offset:37888
	ds_read_b128 v[210:213], v176 offset:38912
	ds_read_b128 v[218:221], v176 offset:39936
	global_load_lds_dwordx4 v[226:227], off
	v_lshl_add_u64 v[226:227], s[42:43], 0, v[146:147]
	s_mov_b32 m0, s46
	s_nop 0
	global_load_lds_dwordx4 v[226:227], off
	s_waitcnt vmcnt(8)
	s_waitcnt lgkmcnt(0)
	s_barrier
	s_setprio 1
	s_waitcnt lgkmcnt(0)
	v_mfma_f32_16x16x32_bf16 v[126:129], v[130:133], v[186:189], v[126:129]
	v_mfma_f32_16x16x32_bf16 v[122:125], v[138:141], v[186:189], v[122:125]
	v_mfma_f32_16x16x32_bf16 v[118:121], v[162:165], v[186:189], v[118:121]
	v_mfma_f32_16x16x32_bf16 v[114:117], v[178:181], v[186:189], v[114:117]
	v_mfma_f32_16x16x32_bf16 v[110:113], v[130:133], v[194:197], v[110:113]
	v_mfma_f32_16x16x32_bf16 v[106:109], v[138:141], v[194:197], v[106:109]
	v_mfma_f32_16x16x32_bf16 v[102:105], v[162:165], v[194:197], v[102:105]
	v_mfma_f32_16x16x32_bf16 v[98:101], v[178:181], v[194:197], v[98:101]
	v_mfma_f32_16x16x32_bf16 v[94:97], v[130:133], v[202:205], v[94:97]
	v_mfma_f32_16x16x32_bf16 v[90:93], v[138:141], v[202:205], v[90:93]
	v_mfma_f32_16x16x32_bf16 v[86:89], v[162:165], v[202:205], v[86:89]
	v_mfma_f32_16x16x32_bf16 v[82:85], v[178:181], v[202:205], v[82:85]
	v_mfma_f32_16x16x32_bf16 v[78:81], v[130:133], v[210:213], v[78:81]
	v_mfma_f32_16x16x32_bf16 v[74:77], v[138:141], v[210:213], v[74:77]
	v_mfma_f32_16x16x32_bf16 v[70:73], v[162:165], v[210:213], v[70:73]
	v_mfma_f32_16x16x32_bf16 v[66:69], v[178:181], v[210:213], v[66:69]
	s_setprio 0
	s_setprio 1
	v_mfma_f32_16x16x32_bf16 v[126:129], v[134:137], v[190:193], v[126:129]
	v_mfma_f32_16x16x32_bf16 v[122:125], v[158:161], v[190:193], v[122:125]
	v_mfma_f32_16x16x32_bf16 v[118:121], v[166:169], v[190:193], v[118:121]
	v_mfma_f32_16x16x32_bf16 v[114:117], v[182:185], v[190:193], v[114:117]
	v_mfma_f32_16x16x32_bf16 v[110:113], v[134:137], v[198:201], v[110:113]
	v_mfma_f32_16x16x32_bf16 v[106:109], v[158:161], v[198:201], v[106:109]
	v_mfma_f32_16x16x32_bf16 v[102:105], v[166:169], v[198:201], v[102:105]
	v_mfma_f32_16x16x32_bf16 v[98:101], v[182:185], v[198:201], v[98:101]
	v_mfma_f32_16x16x32_bf16 v[94:97], v[134:137], v[206:209], v[94:97]
	v_mfma_f32_16x16x32_bf16 v[90:93], v[158:161], v[206:209], v[90:93]
	v_mfma_f32_16x16x32_bf16 v[86:89], v[166:169], v[206:209], v[86:89]
	v_mfma_f32_16x16x32_bf16 v[82:85], v[182:185], v[206:209], v[82:85]
	v_mfma_f32_16x16x32_bf16 v[78:81], v[134:137], v[218:221], v[78:81]
	v_mfma_f32_16x16x32_bf16 v[74:77], v[158:161], v[218:221], v[74:77]
	v_mfma_f32_16x16x32_bf16 v[70:73], v[166:169], v[218:221], v[70:73]
	v_mfma_f32_16x16x32_bf16 v[66:69], v[182:185], v[218:221], v[66:69]
	s_setprio 0
	s_barrier
	s_add_i32 s42, s61, s31
	v_lshl_add_u64 v[170:171], v[170:171], 0, s[24:25]
	s_mov_b32 m0, s42
	ds_read_b128 v[186:189], v176 offset:49152
	ds_read_b128 v[190:193], v176 offset:50176
	ds_read_b128 v[194:197], v176 offset:51200
	ds_read_b128 v[198:201], v176 offset:52224
	ds_read_b128 v[202:205], v176 offset:53248
	ds_read_b128 v[206:209], v176 offset:54272
	ds_read_b128 v[210:213], v176 offset:55296
	ds_read_b128 v[218:221], v176 offset:56320
	global_load_lds_dwordx4 v[170:171], off
	s_add_i32 m0, s42, 0x2000
	s_add_u32 s34, s34, 0x160080
	v_lshl_add_u64 v[170:171], v[214:215], 0, s[24:25]
	s_addc_u32 s35, s35, 0
	s_add_i32 s42, s62, s31
	global_load_lds_dwordx4 v[170:171], off
	v_lshl_add_u64 v[170:171], s[34:35], 0, v[144:145]
	s_mov_b32 m0, s42
	s_nop 0
	global_load_lds_dwordx4 v[170:171], off
	v_lshl_add_u64 v[170:171], s[34:35], 0, v[148:149]
	s_add_i32 m0, s42, 0x2000
	s_nop 0
	global_load_lds_dwordx4 v[170:171], off
	v_lshl_add_u64 v[170:171], v[222:223], 0, s[24:25]
	s_mov_b32 m0, s48
	s_nop 0
	global_load_lds_dwordx4 v[170:171], off
	v_lshl_add_u64 v[170:171], v[224:225], 0, s[24:25]
	s_mov_b32 m0, s49
	s_nop 0
	global_load_lds_dwordx4 v[170:171], off
	s_waitcnt vmcnt(8)
	s_waitcnt lgkmcnt(0)
	s_barrier
	s_setprio 1
	s_waitcnt lgkmcnt(0)
	v_mfma_f32_16x16x32_bf16 v[62:65], v[130:133], v[186:189], v[62:65]
	v_mfma_f32_16x16x32_bf16 v[58:61], v[138:141], v[186:189], v[58:61]
	v_mfma_f32_16x16x32_bf16 v[54:57], v[162:165], v[186:189], v[54:57]
	v_mfma_f32_16x16x32_bf16 v[46:49], v[178:181], v[186:189], v[46:49]
	v_mfma_f32_16x16x32_bf16 v[50:53], v[130:133], v[194:197], v[50:53]
	v_mfma_f32_16x16x32_bf16 v[42:45], v[138:141], v[194:197], v[42:45]
	v_mfma_f32_16x16x32_bf16 v[30:33], v[162:165], v[194:197], v[30:33]
	v_mfma_f32_16x16x32_bf16 v[26:29], v[178:181], v[194:197], v[26:29]
	v_mfma_f32_16x16x32_bf16 v[38:41], v[130:133], v[202:205], v[38:41]
	v_mfma_f32_16x16x32_bf16 v[34:37], v[138:141], v[202:205], v[34:37]
	v_mfma_f32_16x16x32_bf16 v[22:25], v[162:165], v[202:205], v[22:25]
	v_mfma_f32_16x16x32_bf16 v[18:21], v[178:181], v[202:205], v[18:21]
	v_mfma_f32_16x16x32_bf16 v[14:17], v[130:133], v[210:213], v[14:17]
	v_mfma_f32_16x16x32_bf16 v[10:13], v[138:141], v[210:213], v[10:13]
	v_mfma_f32_16x16x32_bf16 v[6:9], v[162:165], v[210:213], v[6:9]
	v_mfma_f32_16x16x32_bf16 v[2:5], v[178:181], v[210:213], v[2:5]
	s_setprio 0
	s_setprio 1
	v_mfma_f32_16x16x32_bf16 v[62:65], v[134:137], v[190:193], v[62:65]
	v_mfma_f32_16x16x32_bf16 v[58:61], v[158:161], v[190:193], v[58:61]
	v_mfma_f32_16x16x32_bf16 v[54:57], v[166:169], v[190:193], v[54:57]
	v_mfma_f32_16x16x32_bf16 v[46:49], v[182:185], v[190:193], v[46:49]
	v_mfma_f32_16x16x32_bf16 v[50:53], v[134:137], v[198:201], v[50:53]
	v_mfma_f32_16x16x32_bf16 v[42:45], v[158:161], v[198:201], v[42:45]
	v_mfma_f32_16x16x32_bf16 v[30:33], v[166:169], v[198:201], v[30:33]
	v_mfma_f32_16x16x32_bf16 v[26:29], v[182:185], v[198:201], v[26:29]
	v_mfma_f32_16x16x32_bf16 v[38:41], v[134:137], v[206:209], v[38:41]
	v_mfma_f32_16x16x32_bf16 v[34:37], v[158:161], v[206:209], v[34:37]
	v_mfma_f32_16x16x32_bf16 v[22:25], v[166:169], v[206:209], v[22:25]
	v_mfma_f32_16x16x32_bf16 v[18:21], v[182:185], v[206:209], v[18:21]
	v_mfma_f32_16x16x32_bf16 v[14:17], v[134:137], v[218:221], v[14:17]
	v_mfma_f32_16x16x32_bf16 v[10:13], v[158:161], v[218:221], v[10:13]
	v_mfma_f32_16x16x32_bf16 v[6:9], v[166:169], v[218:221], v[6:9]
	v_mfma_f32_16x16x32_bf16 v[2:5], v[182:185], v[218:221], v[2:5]
	s_setprio 0
	s_barrier
	s_add_i32 s60, s60, 2
	s_add_u32 s40, s40, 0x100
	s_addc_u32 s41, s41, 0
	s_add_u32 s0, s0, 0x100
	s_addc_u32 s1, s1, 0
	s_cmpk_gt_u32 s60, 0x55
	s_cbranch_scc0 .LBB0_3180
	s_and_b64 vcc, exec, s[26:27]
	s_cbranch_vccz .LBB0_3183
	s_barrier

.LBB0_3309:
	ds_read_b128 v[146:149], v153
	ds_read_b128 v[156:159], v153 offset:1024
	ds_read_b128 v[160:163], v153 offset:2048
	ds_read_b128 v[164:167], v153 offset:3072
	ds_read_b128 v[168:171], v154
	ds_read_b128 v[172:175], v154 offset:1024
	ds_read_b128 v[176:179], v154 offset:2048
	ds_read_b128 v[180:183], v154 offset:3072
	s_add_u32 s34, s44, 0xfff80080
	s_addc_u32 s35, s45, -1
	s_cmp_eq_u32 s69, 28
	s_cselect_b32 s47, s0, s35
	s_cselect_b32 s46, s1, s34
	s_cselect_b32 s35, s27, s68
	s_cselect_b32 s34, s37, s61
	v_lshl_add_u64 v[218:219], s[44:45], 0, v[138:139]
	s_add_i32 m0, s43, 0xc000
	ds_read_b128 v[184:187], v155
	ds_read_b128 v[188:191], v155 offset:1024
	ds_read_b128 v[192:195], v155 offset:2048
	ds_read_b128 v[196:199], v155 offset:3072
	ds_read_b128 v[200:203], v155 offset:4096
	ds_read_b128 v[204:207], v155 offset:5120
	ds_read_b128 v[208:211], v155 offset:6144
	ds_read_b128 v[212:215], v155 offset:7168
	global_load_lds_dwordx4 v[218:219], off
	v_lshl_add_u64 v[218:219], s[44:45], 0, v[140:141]
	s_add_i32 m0, s43, 0xe000
	s_nop 0
	global_load_lds_dwordx4 v[218:219], off
	s_waitcnt vmcnt(8)
	s_waitcnt lgkmcnt(0)
	s_barrier
	s_setprio 1
	s_waitcnt lgkmcnt(0)
	v_mfma_f32_16x16x32_bf16 v[126:129], v[146:149], v[184:187], v[126:129]
	v_mfma_f32_16x16x32_bf16 v[118:121], v[160:163], v[184:187], v[118:121]
	v_mfma_f32_16x16x32_bf16 v[122:125], v[168:171], v[184:187], v[122:125]
	v_mfma_f32_16x16x32_bf16 v[114:117], v[176:179], v[184:187], v[114:117]
	v_mfma_f32_16x16x32_bf16 v[110:113], v[146:149], v[192:195], v[110:113]
	v_mfma_f32_16x16x32_bf16 v[102:105], v[160:163], v[192:195], v[102:105]
	v_mfma_f32_16x16x32_bf16 v[106:109], v[168:171], v[192:195], v[106:109]
	v_mfma_f32_16x16x32_bf16 v[98:101], v[176:179], v[192:195], v[98:101]
	v_mfma_f32_16x16x32_bf16 v[94:97], v[146:149], v[200:203], v[94:97]
	v_mfma_f32_16x16x32_bf16 v[86:89], v[160:163], v[200:203], v[86:89]
	v_mfma_f32_16x16x32_bf16 v[90:93], v[168:171], v[200:203], v[90:93]
	v_mfma_f32_16x16x32_bf16 v[82:85], v[176:179], v[200:203], v[82:85]
	v_mfma_f32_16x16x32_bf16 v[78:81], v[146:149], v[208:211], v[78:81]
	v_mfma_f32_16x16x32_bf16 v[70:73], v[160:163], v[208:211], v[70:73]
	v_mfma_f32_16x16x32_bf16 v[74:77], v[168:171], v[208:211], v[74:77]
	v_mfma_f32_16x16x32_bf16 v[66:69], v[176:179], v[208:211], v[66:69]
	s_setprio 0
	s_setprio 1
	v_mfma_f32_16x16x32_bf16 v[126:129], v[156:159], v[188:191], v[126:129]
	v_mfma_f32_16x16x32_bf16 v[118:121], v[164:167], v[188:191], v[118:121]
	v_mfma_f32_16x16x32_bf16 v[122:125], v[172:175], v[188:191], v[122:125]
	v_mfma_f32_16x16x32_bf16 v[114:117], v[180:183], v[188:191], v[114:117]
	v_mfma_f32_16x16x32_bf16 v[110:113], v[156:159], v[196:199], v[110:113]
	v_mfma_f32_16x16x32_bf16 v[102:105], v[164:167], v[196:199], v[102:105]
	v_mfma_f32_16x16x32_bf16 v[106:109], v[172:175], v[196:199], v[106:109]
	v_mfma_f32_16x16x32_bf16 v[98:101], v[180:183], v[196:199], v[98:101]
	v_mfma_f32_16x16x32_bf16 v[94:97], v[156:159], v[204:207], v[94:97]
	v_mfma_f32_16x16x32_bf16 v[86:89], v[164:167], v[204:207], v[86:89]
	v_mfma_f32_16x16x32_bf16 v[90:93], v[172:175], v[204:207], v[90:93]
	v_mfma_f32_16x16x32_bf16 v[82:85], v[180:183], v[204:207], v[82:85]
	v_mfma_f32_16x16x32_bf16 v[78:81], v[156:159], v[212:215], v[78:81]
	v_mfma_f32_16x16x32_bf16 v[70:73], v[164:167], v[212:215], v[70:73]
	v_mfma_f32_16x16x32_bf16 v[74:77], v[172:175], v[212:215], v[74:77]
	v_mfma_f32_16x16x32_bf16 v[66:69], v[180:183], v[212:215], v[66:69]
	s_setprio 0
	s_barrier
	s_add_i32 s62, s57, s30
	v_lshl_add_u64 v[218:219], s[34:35], 0, v[134:135]
	s_mov_b32 m0, s62
	ds_read_b128 v[184:187], v155 offset:16384
	ds_read_b128 v[188:191], v155 offset:17408
	ds_read_b128 v[192:195], v155 offset:18432
	ds_read_b128 v[196:199], v155 offset:19456
	ds_read_b128 v[200:203], v155 offset:20480
	ds_read_b128 v[204:207], v155 offset:21504
	ds_read_b128 v[208:211], v155 offset:22528
	ds_read_b128 v[212:215], v155 offset:23552
	global_load_lds_dwordx4 v[218:219], off
	s_add_i32 m0, s62, 0x2000
	s_add_u32 s62, s34, 0x80000
	v_lshl_add_u64 v[220:221], s[34:35], 0, v[130:131]
	s_addc_u32 s63, s35, 0
	s_add_i32 s66, s58, s30
	global_load_lds_dwordx4 v[220:221], off
	v_lshl_add_u64 v[222:223], s[62:63], 0, v[134:135]
	s_mov_b32 m0, s66
	v_lshl_add_u64 v[224:225], s[46:47], 0, v[132:133]
	global_load_lds_dwordx4 v[222:223], off
	v_lshl_add_u64 v[222:223], s[62:63], 0, v[130:131]
	s_add_i32 m0, s66, 0x2000
	s_nop 0
	global_load_lds_dwordx4 v[222:223], off
	v_lshl_add_u64 v[222:223], s[46:47], 0, v[136:137]
	s_mov_b32 m0, s43
	s_nop 0
	global_load_lds_dwordx4 v[222:223], off
	s_mov_b32 m0, s48
	s_nop 0
	global_load_lds_dwordx4 v[224:225], off
	s_waitcnt vmcnt(8)
	s_waitcnt lgkmcnt(0)
	s_barrier
	s_setprio 1
	s_waitcnt lgkmcnt(0)
	v_mfma_f32_16x16x32_bf16 v[62:65], v[146:149], v[184:187], v[62:65]
	v_mfma_f32_16x16x32_bf16 v[54:57], v[160:163], v[184:187], v[54:57]
	v_mfma_f32_16x16x32_bf16 v[58:61], v[168:171], v[184:187], v[58:61]
	v_mfma_f32_16x16x32_bf16 v[50:53], v[176:179], v[184:187], v[50:53]
	v_mfma_f32_16x16x32_bf16 v[46:49], v[146:149], v[192:195], v[46:49]
	v_mfma_f32_16x16x32_bf16 v[38:41], v[160:163], v[192:195], v[38:41]
	v_mfma_f32_16x16x32_bf16 v[42:45], v[168:171], v[192:195], v[42:45]
	v_mfma_f32_16x16x32_bf16 v[34:37], v[176:179], v[192:195], v[34:37]
	v_mfma_f32_16x16x32_bf16 v[30:33], v[146:149], v[200:203], v[30:33]
	v_mfma_f32_16x16x32_bf16 v[22:25], v[160:163], v[200:203], v[22:25]
	v_mfma_f32_16x16x32_bf16 v[26:29], v[168:171], v[200:203], v[26:29]
	v_mfma_f32_16x16x32_bf16 v[18:21], v[176:179], v[200:203], v[18:21]
	v_mfma_f32_16x16x32_bf16 v[14:17], v[146:149], v[208:211], v[14:17]
	v_mfma_f32_16x16x32_bf16 v[6:9], v[160:163], v[208:211], v[6:9]
	v_mfma_f32_16x16x32_bf16 v[10:13], v[168:171], v[208:211], v[10:13]
	v_mfma_f32_16x16x32_bf16 v[2:5], v[176:179], v[208:211], v[2:5]
	s_setprio 0
	s_setprio 1
	v_mfma_f32_16x16x32_bf16 v[62:65], v[156:159], v[188:191], v[62:65]
	v_mfma_f32_16x16x32_bf16 v[54:57], v[164:167], v[188:191], v[54:57]
	v_mfma_f32_16x16x32_bf16 v[58:61], v[172:175], v[188:191], v[58:61]
	v_mfma_f32_16x16x32_bf16 v[50:53], v[180:183], v[188:191], v[50:53]
	v_mfma_f32_16x16x32_bf16 v[46:49], v[156:159], v[196:199], v[46:49]
	v_mfma_f32_16x16x32_bf16 v[38:41], v[164:167], v[196:199], v[38:41]
	v_mfma_f32_16x16x32_bf16 v[42:45], v[172:175], v[196:199], v[42:45]
	v_mfma_f32_16x16x32_bf16 v[34:37], v[180:183], v[196:199], v[34:37]
	v_mfma_f32_16x16x32_bf16 v[30:33], v[156:159], v[204:207], v[30:33]
	v_mfma_f32_16x16x32_bf16 v[22:25], v[164:167], v[204:207], v[22:25]
	v_mfma_f32_16x16x32_bf16 v[26:29], v[172:175], v[204:207], v[26:29]
	v_mfma_f32_16x16x32_bf16 v[18:21], v[180:183], v[204:207], v[18:21]
	v_mfma_f32_16x16x32_bf16 v[14:17], v[156:159], v[212:215], v[14:17]
	v_mfma_f32_16x16x32_bf16 v[6:9], v[164:167], v[212:215], v[6:9]
	v_mfma_f32_16x16x32_bf16 v[10:13], v[172:175], v[212:215], v[10:13]
	v_mfma_f32_16x16x32_bf16 v[2:5], v[180:183], v[212:215], v[2:5]
	s_setprio 0
	s_barrier
	s_add_i32 s62, 0, 0x18000
	s_add_i32 s63, 0, 0x1c000
	v_add_u32_e32 v164, s62, v151
	v_add_u32_e32 v180, s63, v151
	ds_read_b128 v[146:149], v164
	ds_read_b128 v[156:159], v164 offset:1024
	ds_read_b128 v[160:163], v164 offset:2048
	ds_read_b128 v[164:167], v164 offset:3072
	ds_read_b128 v[168:171], v180
	ds_read_b128 v[172:175], v180 offset:1024
	ds_read_b128 v[176:179], v180 offset:2048
	ds_read_b128 v[180:183], v180 offset:3072
	s_add_u32 s46, s46, 0x80000
	s_addc_u32 s47, s47, 0
	s_mov_b32 m0, s49
	v_lshl_add_u64 v[226:227], s[46:47], 0, v[136:137]
	ds_read_b128 v[184:187], v155 offset:32768
	ds_read_b128 v[188:191], v155 offset:33792
	ds_read_b128 v[192:195], v155 offset:34816
	ds_read_b128 v[196:199], v155 offset:35840
	ds_read_b128 v[200:203], v155 offset:36864
	ds_read_b128 v[204:207], v155 offset:37888
	ds_read_b128 v[208:211], v155 offset:38912
	ds_read_b128 v[212:215], v155 offset:39936
	global_load_lds_dwordx4 v[226:227], off
	v_lshl_add_u64 v[226:227], s[46:47], 0, v[132:133]
	s_mov_b32 m0, s52
	s_nop 0
	global_load_lds_dwordx4 v[226:227], off
	s_waitcnt vmcnt(8)
	s_waitcnt lgkmcnt(0)
	s_barrier
	s_setprio 1
	s_waitcnt lgkmcnt(0)
	v_mfma_f32_16x16x32_bf16 v[126:129], v[146:149], v[184:187], v[126:129]
	v_mfma_f32_16x16x32_bf16 v[118:121], v[160:163], v[184:187], v[118:121]
	v_mfma_f32_16x16x32_bf16 v[122:125], v[168:171], v[184:187], v[122:125]
	v_mfma_f32_16x16x32_bf16 v[114:117], v[176:179], v[184:187], v[114:117]
	v_mfma_f32_16x16x32_bf16 v[110:113], v[146:149], v[192:195], v[110:113]
	v_mfma_f32_16x16x32_bf16 v[102:105], v[160:163], v[192:195], v[102:105]
	v_mfma_f32_16x16x32_bf16 v[106:109], v[168:171], v[192:195], v[106:109]
	v_mfma_f32_16x16x32_bf16 v[98:101], v[176:179], v[192:195], v[98:101]
	v_mfma_f32_16x16x32_bf16 v[94:97], v[146:149], v[200:203], v[94:97]
	v_mfma_f32_16x16x32_bf16 v[86:89], v[160:163], v[200:203], v[86:89]
	v_mfma_f32_16x16x32_bf16 v[90:93], v[168:171], v[200:203], v[90:93]
	v_mfma_f32_16x16x32_bf16 v[82:85], v[176:179], v[200:203], v[82:85]
	v_mfma_f32_16x16x32_bf16 v[78:81], v[146:149], v[208:211], v[78:81]
	v_mfma_f32_16x16x32_bf16 v[70:73], v[160:163], v[208:211], v[70:73]
	v_mfma_f32_16x16x32_bf16 v[74:77], v[168:171], v[208:211], v[74:77]
	v_mfma_f32_16x16x32_bf16 v[66:69], v[176:179], v[208:211], v[66:69]
	s_setprio 0
	s_setprio 1
	v_mfma_f32_16x16x32_bf16 v[126:129], v[156:159], v[188:191], v[126:129]
	v_mfma_f32_16x16x32_bf16 v[118:121], v[164:167], v[188:191], v[118:121]
	v_mfma_f32_16x16x32_bf16 v[122:125], v[172:175], v[188:191], v[122:125]
	v_mfma_f32_16x16x32_bf16 v[114:117], v[180:183], v[188:191], v[114:117]
	v_mfma_f32_16x16x32_bf16 v[110:113], v[156:159], v[196:199], v[110:113]
	v_mfma_f32_16x16x32_bf16 v[102:105], v[164:167], v[196:199], v[102:105]
	v_mfma_f32_16x16x32_bf16 v[106:109], v[172:175], v[196:199], v[106:109]
	v_mfma_f32_16x16x32_bf16 v[98:101], v[180:183], v[196:199], v[98:101]
	v_mfma_f32_16x16x32_bf16 v[94:97], v[156:159], v[204:207], v[94:97]
	v_mfma_f32_16x16x32_bf16 v[86:89], v[164:167], v[204:207], v[86:89]
	v_mfma_f32_16x16x32_bf16 v[90:93], v[172:175], v[204:207], v[90:93]
	v_mfma_f32_16x16x32_bf16 v[82:85], v[180:183], v[204:207], v[82:85]
	v_mfma_f32_16x16x32_bf16 v[78:81], v[156:159], v[212:215], v[78:81]
	v_mfma_f32_16x16x32_bf16 v[70:73], v[164:167], v[212:215], v[70:73]
	v_mfma_f32_16x16x32_bf16 v[74:77], v[172:175], v[212:215], v[74:77]
	v_mfma_f32_16x16x32_bf16 v[66:69], v[180:183], v[212:215], v[66:69]
	s_setprio 0
	s_barrier
	s_add_i32 s46, s62, s30
	v_lshl_add_u64 v[218:219], v[218:219], 0, s[8:9]
	s_mov_b32 m0, s46
	ds_read_b128 v[184:187], v155 offset:49152
	ds_read_b128 v[188:191], v155 offset:50176
	ds_read_b128 v[192:195], v155 offset:51200
	ds_read_b128 v[196:199], v155 offset:52224
	ds_read_b128 v[200:203], v155 offset:53248
	ds_read_b128 v[204:207], v155 offset:54272
	ds_read_b128 v[208:211], v155 offset:55296
	ds_read_b128 v[212:215], v155 offset:56320
	global_load_lds_dwordx4 v[218:219], off
	s_add_i32 m0, s46, 0x2000
	s_add_u32 s34, s34, 0x80080
	v_lshl_add_u64 v[218:219], v[220:221], 0, s[8:9]
	s_addc_u32 s35, s35, 0
	s_add_i32 s46, s63, s30
	global_load_lds_dwordx4 v[218:219], off
	v_lshl_add_u64 v[218:219], s[34:35], 0, v[134:135]
	s_mov_b32 m0, s46
	s_nop 0
	global_load_lds_dwordx4 v[218:219], off
	v_lshl_add_u64 v[218:219], s[34:35], 0, v[130:131]
	s_add_i32 m0, s46, 0x2000
	s_nop 0
	global_load_lds_dwordx4 v[218:219], off
	v_lshl_add_u64 v[218:219], v[222:223], 0, s[8:9]
	s_mov_b32 m0, s54
	s_nop 0
	global_load_lds_dwordx4 v[218:219], off
	v_lshl_add_u64 v[218:219], v[224:225], 0, s[8:9]
	s_mov_b32 m0, s55
	s_nop 0
	global_load_lds_dwordx4 v[218:219], off
	s_waitcnt vmcnt(8)
	s_waitcnt lgkmcnt(0)
	s_barrier
	s_setprio 1
	s_waitcnt lgkmcnt(0)
	v_mfma_f32_16x16x32_bf16 v[62:65], v[146:149], v[184:187], v[62:65]
	v_mfma_f32_16x16x32_bf16 v[54:57], v[160:163], v[184:187], v[54:57]
	v_mfma_f32_16x16x32_bf16 v[58:61], v[168:171], v[184:187], v[58:61]
	v_mfma_f32_16x16x32_bf16 v[50:53], v[176:179], v[184:187], v[50:53]
	v_mfma_f32_16x16x32_bf16 v[46:49], v[146:149], v[192:195], v[46:49]
	v_mfma_f32_16x16x32_bf16 v[38:41], v[160:163], v[192:195], v[38:41]
	v_mfma_f32_16x16x32_bf16 v[42:45], v[168:171], v[192:195], v[42:45]
	v_mfma_f32_16x16x32_bf16 v[34:37], v[176:179], v[192:195], v[34:37]
	v_mfma_f32_16x16x32_bf16 v[30:33], v[146:149], v[200:203], v[30:33]
	v_mfma_f32_16x16x32_bf16 v[22:25], v[160:163], v[200:203], v[22:25]
	v_mfma_f32_16x16x32_bf16 v[26:29], v[168:171], v[200:203], v[26:29]
	v_mfma_f32_16x16x32_bf16 v[18:21], v[176:179], v[200:203], v[18:21]
	v_mfma_f32_16x16x32_bf16 v[14:17], v[146:149], v[208:211], v[14:17]
	v_mfma_f32_16x16x32_bf16 v[6:9], v[160:163], v[208:211], v[6:9]
	v_mfma_f32_16x16x32_bf16 v[10:13], v[168:171], v[208:211], v[10:13]
	v_mfma_f32_16x16x32_bf16 v[2:5], v[176:179], v[208:211], v[2:5]
	s_setprio 0
	s_setprio 1
	v_mfma_f32_16x16x32_bf16 v[62:65], v[156:159], v[188:191], v[62:65]
	v_mfma_f32_16x16x32_bf16 v[54:57], v[164:167], v[188:191], v[54:57]
	v_mfma_f32_16x16x32_bf16 v[58:61], v[172:175], v[188:191], v[58:61]
	v_mfma_f32_16x16x32_bf16 v[50:53], v[180:183], v[188:191], v[50:53]
	v_mfma_f32_16x16x32_bf16 v[46:49], v[156:159], v[196:199], v[46:49]
	v_mfma_f32_16x16x32_bf16 v[38:41], v[164:167], v[196:199], v[38:41]
	v_mfma_f32_16x16x32_bf16 v[42:45], v[172:175], v[196:199], v[42:45]
	v_mfma_f32_16x16x32_bf16 v[34:37], v[180:183], v[196:199], v[34:37]
	v_mfma_f32_16x16x32_bf16 v[30:33], v[156:159], v[204:207], v[30:33]
	v_mfma_f32_16x16x32_bf16 v[22:25], v[164:167], v[204:207], v[22:25]
	v_mfma_f32_16x16x32_bf16 v[26:29], v[172:175], v[204:207], v[26:29]
	v_mfma_f32_16x16x32_bf16 v[18:21], v[180:183], v[204:207], v[18:21]
	v_mfma_f32_16x16x32_bf16 v[14:17], v[156:159], v[212:215], v[14:17]
	v_mfma_f32_16x16x32_bf16 v[6:9], v[164:167], v[212:215], v[6:9]
	v_mfma_f32_16x16x32_bf16 v[10:13], v[172:175], v[212:215], v[10:13]
	v_mfma_f32_16x16x32_bf16 v[2:5], v[180:183], v[212:215], v[2:5]
	s_setprio 0
	s_barrier
	s_add_i32 s69, s69, 2
	s_add_u32 s44, s44, 0x100
	s_addc_u32 s45, s45, 0
	s_add_u32 s61, s61, 0x100
	s_addc_u32 s68, s68, 0
	s_cmp_gt_u32 s69, 29
	s_cbranch_scc0 .LBB0_3309
	v_mov_b32_e32 v160, 0xbfb8aa3b
	s_and_b64 vcc, exec, s[24:25]
	s_cbranch_vccz .LBB0_3312
	s_barrier

.LBB0_3533:
	ds_read_b128 v[154:157], v151
	ds_read_b128 v[158:161], v151 offset:1024
	ds_read_b128 v[162:165], v151 offset:2048
	ds_read_b128 v[166:169], v151 offset:3072
	ds_read_b128 v[170:173], v152
	ds_read_b128 v[174:177], v152 offset:1024
	ds_read_b128 v[178:181], v152 offset:2048
	ds_read_b128 v[182:185], v152 offset:3072
	s_add_u32 s34, s44, 0xfff80080
	s_addc_u32 s35, s45, -1
	s_cmp_eq_u32 s68, 28
	s_cselect_b32 s47, s0, s35
	s_cselect_b32 s46, s1, s34
	s_cselect_b32 s35, s27, s61
	s_cselect_b32 s34, s37, s60
	v_lshl_add_u64 v[146:147], s[44:45], 0, v[138:139]
	s_add_i32 m0, s33, 0xc000
	ds_read_b128 v[186:189], v153
	ds_read_b128 v[190:193], v153 offset:1024
	ds_read_b128 v[194:197], v153 offset:2048
	ds_read_b128 v[198:201], v153 offset:3072
	ds_read_b128 v[202:205], v153 offset:4096
	ds_read_b128 v[206:209], v153 offset:5120
	ds_read_b128 v[210:213], v153 offset:6144
	ds_read_b128 v[218:221], v153 offset:7168
	global_load_lds_dwordx4 v[146:147], off
	v_lshl_add_u64 v[146:147], s[44:45], 0, v[140:141]
	s_add_i32 m0, s33, 0xe000
	s_nop 0
	global_load_lds_dwordx4 v[146:147], off
	s_waitcnt vmcnt(8)
	s_waitcnt lgkmcnt(0)
	s_barrier
	s_setprio 1
	s_waitcnt lgkmcnt(0)
	v_mfma_f32_16x16x32_bf16 v[126:129], v[154:157], v[186:189], v[126:129]
	v_mfma_f32_16x16x32_bf16 v[122:125], v[162:165], v[186:189], v[122:125]
	v_mfma_f32_16x16x32_bf16 v[118:121], v[170:173], v[186:189], v[118:121]
	v_mfma_f32_16x16x32_bf16 v[110:113], v[178:181], v[186:189], v[110:113]
	v_mfma_f32_16x16x32_bf16 v[114:117], v[154:157], v[194:197], v[114:117]
	v_mfma_f32_16x16x32_bf16 v[106:109], v[162:165], v[194:197], v[106:109]
	v_mfma_f32_16x16x32_bf16 v[102:105], v[170:173], v[194:197], v[102:105]
	v_mfma_f32_16x16x32_bf16 v[94:97], v[178:181], v[194:197], v[94:97]
	v_mfma_f32_16x16x32_bf16 v[98:101], v[154:157], v[202:205], v[98:101]
	v_mfma_f32_16x16x32_bf16 v[90:93], v[162:165], v[202:205], v[90:93]
	v_mfma_f32_16x16x32_bf16 v[86:89], v[170:173], v[202:205], v[86:89]
	v_mfma_f32_16x16x32_bf16 v[78:81], v[178:181], v[202:205], v[78:81]
	v_mfma_f32_16x16x32_bf16 v[82:85], v[154:157], v[210:213], v[82:85]
	v_mfma_f32_16x16x32_bf16 v[74:77], v[162:165], v[210:213], v[74:77]
	v_mfma_f32_16x16x32_bf16 v[70:73], v[170:173], v[210:213], v[70:73]
	v_mfma_f32_16x16x32_bf16 v[66:69], v[178:181], v[210:213], v[66:69]
	s_setprio 0
	s_setprio 1
	v_mfma_f32_16x16x32_bf16 v[126:129], v[158:161], v[190:193], v[126:129]
	v_mfma_f32_16x16x32_bf16 v[122:125], v[166:169], v[190:193], v[122:125]
	v_mfma_f32_16x16x32_bf16 v[118:121], v[174:177], v[190:193], v[118:121]
	v_mfma_f32_16x16x32_bf16 v[110:113], v[182:185], v[190:193], v[110:113]
	v_mfma_f32_16x16x32_bf16 v[114:117], v[158:161], v[198:201], v[114:117]
	v_mfma_f32_16x16x32_bf16 v[106:109], v[166:169], v[198:201], v[106:109]
	v_mfma_f32_16x16x32_bf16 v[102:105], v[174:177], v[198:201], v[102:105]
	v_mfma_f32_16x16x32_bf16 v[94:97], v[182:185], v[198:201], v[94:97]
	v_mfma_f32_16x16x32_bf16 v[98:101], v[158:161], v[206:209], v[98:101]
	v_mfma_f32_16x16x32_bf16 v[90:93], v[166:169], v[206:209], v[90:93]
	v_mfma_f32_16x16x32_bf16 v[86:89], v[174:177], v[206:209], v[86:89]
	v_mfma_f32_16x16x32_bf16 v[78:81], v[182:185], v[206:209], v[78:81]
	v_mfma_f32_16x16x32_bf16 v[82:85], v[158:161], v[218:221], v[82:85]
	v_mfma_f32_16x16x32_bf16 v[74:77], v[166:169], v[218:221], v[74:77]
	v_mfma_f32_16x16x32_bf16 v[70:73], v[174:177], v[218:221], v[70:73]
	v_mfma_f32_16x16x32_bf16 v[66:69], v[182:185], v[218:221], v[66:69]
	s_setprio 0
	s_barrier
	s_add_i32 s62, s56, s12
	v_lshl_add_u64 v[146:147], s[34:35], 0, v[134:135]
	s_mov_b32 m0, s62
	ds_read_b128 v[186:189], v153 offset:16384
	ds_read_b128 v[190:193], v153 offset:17408
	ds_read_b128 v[194:197], v153 offset:18432
	ds_read_b128 v[198:201], v153 offset:19456
	ds_read_b128 v[202:205], v153 offset:20480
	ds_read_b128 v[206:209], v153 offset:21504
	ds_read_b128 v[210:213], v153 offset:22528
	ds_read_b128 v[218:221], v153 offset:23552
	global_load_lds_dwordx4 v[146:147], off
	s_add_i32 m0, s62, 0x2000
	s_add_u32 s62, s34, 0x80000
	v_lshl_add_u64 v[214:215], s[34:35], 0, v[130:131]
	s_addc_u32 s63, s35, 0
	s_add_i32 s66, s57, s12
	global_load_lds_dwordx4 v[214:215], off
	v_lshl_add_u64 v[222:223], s[62:63], 0, v[134:135]
	s_mov_b32 m0, s66
	v_lshl_add_u64 v[224:225], s[46:47], 0, v[132:133]
	global_load_lds_dwordx4 v[222:223], off
	v_lshl_add_u64 v[222:223], s[62:63], 0, v[130:131]
	s_add_i32 m0, s66, 0x2000
	s_nop 0
	global_load_lds_dwordx4 v[222:223], off
	v_lshl_add_u64 v[222:223], s[46:47], 0, v[136:137]
	s_mov_b32 m0, s33
	s_nop 0
	global_load_lds_dwordx4 v[222:223], off
	s_mov_b32 m0, s43
	s_nop 0
	global_load_lds_dwordx4 v[224:225], off
	s_waitcnt vmcnt(8)
	s_waitcnt lgkmcnt(0)
	s_barrier
	s_setprio 1
	s_waitcnt lgkmcnt(0)
	v_mfma_f32_16x16x32_bf16 v[62:65], v[154:157], v[186:189], v[62:65]
	v_mfma_f32_16x16x32_bf16 v[58:61], v[162:165], v[186:189], v[58:61]
	v_mfma_f32_16x16x32_bf16 v[54:57], v[170:173], v[186:189], v[54:57]
	v_mfma_f32_16x16x32_bf16 v[46:49], v[178:181], v[186:189], v[46:49]
	v_mfma_f32_16x16x32_bf16 v[50:53], v[154:157], v[194:197], v[50:53]
	v_mfma_f32_16x16x32_bf16 v[42:45], v[162:165], v[194:197], v[42:45]
	v_mfma_f32_16x16x32_bf16 v[38:41], v[170:173], v[194:197], v[38:41]
	v_mfma_f32_16x16x32_bf16 v[30:33], v[178:181], v[194:197], v[30:33]
	v_mfma_f32_16x16x32_bf16 v[34:37], v[154:157], v[202:205], v[34:37]
	v_mfma_f32_16x16x32_bf16 v[26:29], v[162:165], v[202:205], v[26:29]
	v_mfma_f32_16x16x32_bf16 v[22:25], v[170:173], v[202:205], v[22:25]
	v_mfma_f32_16x16x32_bf16 v[14:17], v[178:181], v[202:205], v[14:17]
	v_mfma_f32_16x16x32_bf16 v[18:21], v[154:157], v[210:213], v[18:21]
	v_mfma_f32_16x16x32_bf16 v[10:13], v[162:165], v[210:213], v[10:13]
	v_mfma_f32_16x16x32_bf16 v[6:9], v[170:173], v[210:213], v[6:9]
	v_mfma_f32_16x16x32_bf16 v[2:5], v[178:181], v[210:213], v[2:5]
	s_setprio 0
	s_setprio 1
	v_mfma_f32_16x16x32_bf16 v[62:65], v[158:161], v[190:193], v[62:65]
	v_mfma_f32_16x16x32_bf16 v[58:61], v[166:169], v[190:193], v[58:61]
	v_mfma_f32_16x16x32_bf16 v[54:57], v[174:177], v[190:193], v[54:57]
	v_mfma_f32_16x16x32_bf16 v[46:49], v[182:185], v[190:193], v[46:49]
	v_mfma_f32_16x16x32_bf16 v[50:53], v[158:161], v[198:201], v[50:53]
	v_mfma_f32_16x16x32_bf16 v[42:45], v[166:169], v[198:201], v[42:45]
	v_mfma_f32_16x16x32_bf16 v[38:41], v[174:177], v[198:201], v[38:41]
	v_mfma_f32_16x16x32_bf16 v[30:33], v[182:185], v[198:201], v[30:33]
	v_mfma_f32_16x16x32_bf16 v[34:37], v[158:161], v[206:209], v[34:37]
	v_mfma_f32_16x16x32_bf16 v[26:29], v[166:169], v[206:209], v[26:29]
	v_mfma_f32_16x16x32_bf16 v[22:25], v[174:177], v[206:209], v[22:25]
	v_mfma_f32_16x16x32_bf16 v[14:17], v[182:185], v[206:209], v[14:17]
	v_mfma_f32_16x16x32_bf16 v[18:21], v[158:161], v[218:221], v[18:21]
	v_mfma_f32_16x16x32_bf16 v[10:13], v[166:169], v[218:221], v[10:13]
	v_mfma_f32_16x16x32_bf16 v[6:9], v[174:177], v[218:221], v[6:9]
	v_mfma_f32_16x16x32_bf16 v[2:5], v[182:185], v[218:221], v[2:5]
	s_setprio 0
	s_barrier
	s_add_i32 s62, 0, 0x18000
	s_add_i32 s63, 0, 0x1c000
	v_add_u32_e32 v166, s62, v149
	v_add_u32_e32 v182, s63, v149
	ds_read_b128 v[154:157], v166
	ds_read_b128 v[158:161], v166 offset:1024
	ds_read_b128 v[162:165], v166 offset:2048
	ds_read_b128 v[166:169], v166 offset:3072
	ds_read_b128 v[170:173], v182
	ds_read_b128 v[174:177], v182 offset:1024
	ds_read_b128 v[178:181], v182 offset:2048
	ds_read_b128 v[182:185], v182 offset:3072
	s_add_u32 s46, s46, 0x80000
	s_addc_u32 s47, s47, 0
	s_mov_b32 m0, s48
	v_lshl_add_u64 v[226:227], s[46:47], 0, v[136:137]
	ds_read_b128 v[186:189], v153 offset:32768
	ds_read_b128 v[190:193], v153 offset:33792
	ds_read_b128 v[194:197], v153 offset:34816
	ds_read_b128 v[198:201], v153 offset:35840
	ds_read_b128 v[202:205], v153 offset:36864
	ds_read_b128 v[206:209], v153 offset:37888
	ds_read_b128 v[210:213], v153 offset:38912
	ds_read_b128 v[218:221], v153 offset:39936
	global_load_lds_dwordx4 v[226:227], off
	v_lshl_add_u64 v[226:227], s[46:47], 0, v[132:133]
	s_mov_b32 m0, s49
	s_nop 0
	global_load_lds_dwordx4 v[226:227], off
	s_waitcnt vmcnt(8)
	s_waitcnt lgkmcnt(0)
	s_barrier
	s_setprio 1
	s_waitcnt lgkmcnt(0)
	v_mfma_f32_16x16x32_bf16 v[126:129], v[154:157], v[186:189], v[126:129]
	v_mfma_f32_16x16x32_bf16 v[122:125], v[162:165], v[186:189], v[122:125]
	v_mfma_f32_16x16x32_bf16 v[118:121], v[170:173], v[186:189], v[118:121]
	v_mfma_f32_16x16x32_bf16 v[110:113], v[178:181], v[186:189], v[110:113]
	v_mfma_f32_16x16x32_bf16 v[114:117], v[154:157], v[194:197], v[114:117]
	v_mfma_f32_16x16x32_bf16 v[106:109], v[162:165], v[194:197], v[106:109]
	v_mfma_f32_16x16x32_bf16 v[102:105], v[170:173], v[194:197], v[102:105]
	v_mfma_f32_16x16x32_bf16 v[94:97], v[178:181], v[194:197], v[94:97]
	v_mfma_f32_16x16x32_bf16 v[98:101], v[154:157], v[202:205], v[98:101]
	v_mfma_f32_16x16x32_bf16 v[90:93], v[162:165], v[202:205], v[90:93]
	v_mfma_f32_16x16x32_bf16 v[86:89], v[170:173], v[202:205], v[86:89]
	v_mfma_f32_16x16x32_bf16 v[78:81], v[178:181], v[202:205], v[78:81]
	v_mfma_f32_16x16x32_bf16 v[82:85], v[154:157], v[210:213], v[82:85]
	v_mfma_f32_16x16x32_bf16 v[74:77], v[162:165], v[210:213], v[74:77]
	v_mfma_f32_16x16x32_bf16 v[70:73], v[170:173], v[210:213], v[70:73]
	v_mfma_f32_16x16x32_bf16 v[66:69], v[178:181], v[210:213], v[66:69]
	s_setprio 0
	s_setprio 1
	v_mfma_f32_16x16x32_bf16 v[126:129], v[158:161], v[190:193], v[126:129]
	v_mfma_f32_16x16x32_bf16 v[122:125], v[166:169], v[190:193], v[122:125]
	v_mfma_f32_16x16x32_bf16 v[118:121], v[174:177], v[190:193], v[118:121]
	v_mfma_f32_16x16x32_bf16 v[110:113], v[182:185], v[190:193], v[110:113]
	v_mfma_f32_16x16x32_bf16 v[114:117], v[158:161], v[198:201], v[114:117]
	v_mfma_f32_16x16x32_bf16 v[106:109], v[166:169], v[198:201], v[106:109]
	v_mfma_f32_16x16x32_bf16 v[102:105], v[174:177], v[198:201], v[102:105]
	v_mfma_f32_16x16x32_bf16 v[94:97], v[182:185], v[198:201], v[94:97]
	v_mfma_f32_16x16x32_bf16 v[98:101], v[158:161], v[206:209], v[98:101]
	v_mfma_f32_16x16x32_bf16 v[90:93], v[166:169], v[206:209], v[90:93]
	v_mfma_f32_16x16x32_bf16 v[86:89], v[174:177], v[206:209], v[86:89]
	v_mfma_f32_16x16x32_bf16 v[78:81], v[182:185], v[206:209], v[78:81]
	v_mfma_f32_16x16x32_bf16 v[82:85], v[158:161], v[218:221], v[82:85]
	v_mfma_f32_16x16x32_bf16 v[74:77], v[166:169], v[218:221], v[74:77]
	v_mfma_f32_16x16x32_bf16 v[70:73], v[174:177], v[218:221], v[70:73]
	v_mfma_f32_16x16x32_bf16 v[66:69], v[182:185], v[218:221], v[66:69]
	s_setprio 0
	s_barrier
	s_add_i32 s46, s62, s12
	v_lshl_add_u64 v[146:147], v[146:147], 0, s[8:9]
	s_mov_b32 m0, s46
	ds_read_b128 v[186:189], v153 offset:49152
	ds_read_b128 v[190:193], v153 offset:50176
	ds_read_b128 v[194:197], v153 offset:51200
	ds_read_b128 v[198:201], v153 offset:52224
	ds_read_b128 v[202:205], v153 offset:53248
	ds_read_b128 v[206:209], v153 offset:54272
	ds_read_b128 v[210:213], v153 offset:55296
	ds_read_b128 v[218:221], v153 offset:56320
	global_load_lds_dwordx4 v[146:147], off
	s_add_i32 m0, s46, 0x2000
	s_add_u32 s34, s34, 0x80080
	v_lshl_add_u64 v[146:147], v[214:215], 0, s[8:9]
	s_addc_u32 s35, s35, 0
	s_add_i32 s46, s63, s12
	global_load_lds_dwordx4 v[146:147], off
	v_lshl_add_u64 v[146:147], s[34:35], 0, v[134:135]
	s_mov_b32 m0, s46
	s_nop 0
	global_load_lds_dwordx4 v[146:147], off
	v_lshl_add_u64 v[146:147], s[34:35], 0, v[130:131]
	s_add_i32 m0, s46, 0x2000
	s_nop 0
	global_load_lds_dwordx4 v[146:147], off
	v_lshl_add_u64 v[146:147], v[222:223], 0, s[8:9]
	s_mov_b32 m0, s53
	s_nop 0
	global_load_lds_dwordx4 v[146:147], off
	v_lshl_add_u64 v[146:147], v[224:225], 0, s[8:9]
	s_mov_b32 m0, s54
	s_nop 0
	global_load_lds_dwordx4 v[146:147], off
	s_waitcnt vmcnt(8)
	s_waitcnt lgkmcnt(0)
	s_barrier
	s_setprio 1
	s_waitcnt lgkmcnt(0)
	v_mfma_f32_16x16x32_bf16 v[62:65], v[154:157], v[186:189], v[62:65]
	v_mfma_f32_16x16x32_bf16 v[58:61], v[162:165], v[186:189], v[58:61]
	v_mfma_f32_16x16x32_bf16 v[54:57], v[170:173], v[186:189], v[54:57]
	v_mfma_f32_16x16x32_bf16 v[46:49], v[178:181], v[186:189], v[46:49]
	v_mfma_f32_16x16x32_bf16 v[50:53], v[154:157], v[194:197], v[50:53]
	v_mfma_f32_16x16x32_bf16 v[42:45], v[162:165], v[194:197], v[42:45]
	v_mfma_f32_16x16x32_bf16 v[38:41], v[170:173], v[194:197], v[38:41]
	v_mfma_f32_16x16x32_bf16 v[30:33], v[178:181], v[194:197], v[30:33]
	v_mfma_f32_16x16x32_bf16 v[34:37], v[154:157], v[202:205], v[34:37]
	v_mfma_f32_16x16x32_bf16 v[26:29], v[162:165], v[202:205], v[26:29]
	v_mfma_f32_16x16x32_bf16 v[22:25], v[170:173], v[202:205], v[22:25]
	v_mfma_f32_16x16x32_bf16 v[14:17], v[178:181], v[202:205], v[14:17]
	v_mfma_f32_16x16x32_bf16 v[18:21], v[154:157], v[210:213], v[18:21]
	v_mfma_f32_16x16x32_bf16 v[10:13], v[162:165], v[210:213], v[10:13]
	v_mfma_f32_16x16x32_bf16 v[6:9], v[170:173], v[210:213], v[6:9]
	v_mfma_f32_16x16x32_bf16 v[2:5], v[178:181], v[210:213], v[2:5]
	s_setprio 0
	s_setprio 1
	v_mfma_f32_16x16x32_bf16 v[62:65], v[158:161], v[190:193], v[62:65]
	v_mfma_f32_16x16x32_bf16 v[58:61], v[166:169], v[190:193], v[58:61]
	v_mfma_f32_16x16x32_bf16 v[54:57], v[174:177], v[190:193], v[54:57]
	v_mfma_f32_16x16x32_bf16 v[46:49], v[182:185], v[190:193], v[46:49]
	v_mfma_f32_16x16x32_bf16 v[50:53], v[158:161], v[198:201], v[50:53]
	v_mfma_f32_16x16x32_bf16 v[42:45], v[166:169], v[198:201], v[42:45]
	v_mfma_f32_16x16x32_bf16 v[38:41], v[174:177], v[198:201], v[38:41]
	v_mfma_f32_16x16x32_bf16 v[30:33], v[182:185], v[198:201], v[30:33]
	v_mfma_f32_16x16x32_bf16 v[34:37], v[158:161], v[206:209], v[34:37]
	v_mfma_f32_16x16x32_bf16 v[26:29], v[166:169], v[206:209], v[26:29]
	v_mfma_f32_16x16x32_bf16 v[22:25], v[174:177], v[206:209], v[22:25]
	v_mfma_f32_16x16x32_bf16 v[14:17], v[182:185], v[206:209], v[14:17]
	v_mfma_f32_16x16x32_bf16 v[18:21], v[158:161], v[218:221], v[18:21]
	v_mfma_f32_16x16x32_bf16 v[10:13], v[166:169], v[218:221], v[10:13]
	v_mfma_f32_16x16x32_bf16 v[6:9], v[174:177], v[218:221], v[6:9]
	v_mfma_f32_16x16x32_bf16 v[2:5], v[182:185], v[218:221], v[2:5]
	s_setprio 0
	s_barrier
	s_add_i32 s68, s68, 2
	s_add_u32 s44, s44, 0x100
	s_addc_u32 s45, s45, 0
	s_add_u32 s60, s60, 0x100
	s_addc_u32 s61, s61, 0
	s_cmp_gt_u32 s68, 29
	s_cbranch_scc0 .LBB0_3533
	s_and_b64 vcc, exec, s[24:25]
	s_cbranch_vccz .LBB0_3536
	s_barrier

.LBB0_3706:
	ds_read_b128 v[130:133], v174
	ds_read_b128 v[134:137], v174 offset:1024
	ds_read_b128 v[138:141], v174 offset:2048
	ds_read_b128 v[158:161], v174 offset:3072
	ds_read_b128 v[162:165], v175
	ds_read_b128 v[166:169], v175 offset:1024
	ds_read_b128 v[178:181], v175 offset:2048
	ds_read_b128 v[182:185], v175 offset:3072
	s_add_u32 s34, s42, 0xfff80080
	s_addc_u32 s35, s43, -1
	s_cmp_eq_u32 s60, 28
	s_cselect_b32 s45, s0, s35
	s_cselect_b32 s44, s1, s34
	s_cselect_b32 s35, s25, s59
	s_cselect_b32 s34, s27, s58
	v_lshl_add_u64 v[170:171], s[42:43], 0, v[150:151]
	s_add_i32 m0, s41, 0xc000
	ds_read_b128 v[186:189], v176
	ds_read_b128 v[190:193], v176 offset:1024
	ds_read_b128 v[194:197], v176 offset:2048
	ds_read_b128 v[198:201], v176 offset:3072
	ds_read_b128 v[202:205], v176 offset:4096
	ds_read_b128 v[206:209], v176 offset:5120
	ds_read_b128 v[210:213], v176 offset:6144
	ds_read_b128 v[218:221], v176 offset:7168
	global_load_lds_dwordx4 v[170:171], off
	v_lshl_add_u64 v[170:171], s[42:43], 0, v[152:153]
	s_add_i32 m0, s41, 0xe000
	s_nop 0
	global_load_lds_dwordx4 v[170:171], off
	s_waitcnt vmcnt(8)
	s_waitcnt lgkmcnt(0)
	s_barrier
	s_setprio 1
	s_waitcnt lgkmcnt(0)
	v_mfma_f32_16x16x32_bf16 v[126:129], v[130:133], v[186:189], v[126:129]
	v_mfma_f32_16x16x32_bf16 v[122:125], v[138:141], v[186:189], v[122:125]
	v_mfma_f32_16x16x32_bf16 v[118:121], v[162:165], v[186:189], v[118:121]
	v_mfma_f32_16x16x32_bf16 v[114:117], v[178:181], v[186:189], v[114:117]
	v_mfma_f32_16x16x32_bf16 v[110:113], v[130:133], v[194:197], v[110:113]
	v_mfma_f32_16x16x32_bf16 v[106:109], v[138:141], v[194:197], v[106:109]
	v_mfma_f32_16x16x32_bf16 v[102:105], v[162:165], v[194:197], v[102:105]
	v_mfma_f32_16x16x32_bf16 v[98:101], v[178:181], v[194:197], v[98:101]
	v_mfma_f32_16x16x32_bf16 v[94:97], v[130:133], v[202:205], v[94:97]
	v_mfma_f32_16x16x32_bf16 v[90:93], v[138:141], v[202:205], v[90:93]
	v_mfma_f32_16x16x32_bf16 v[86:89], v[162:165], v[202:205], v[86:89]
	v_mfma_f32_16x16x32_bf16 v[82:85], v[178:181], v[202:205], v[82:85]
	v_mfma_f32_16x16x32_bf16 v[78:81], v[130:133], v[210:213], v[78:81]
	v_mfma_f32_16x16x32_bf16 v[74:77], v[138:141], v[210:213], v[74:77]
	v_mfma_f32_16x16x32_bf16 v[70:73], v[162:165], v[210:213], v[70:73]
	v_mfma_f32_16x16x32_bf16 v[66:69], v[178:181], v[210:213], v[66:69]
	s_setprio 0
	s_setprio 1
	v_mfma_f32_16x16x32_bf16 v[126:129], v[134:137], v[190:193], v[126:129]
	v_mfma_f32_16x16x32_bf16 v[122:125], v[158:161], v[190:193], v[122:125]
	v_mfma_f32_16x16x32_bf16 v[118:121], v[166:169], v[190:193], v[118:121]
	v_mfma_f32_16x16x32_bf16 v[114:117], v[182:185], v[190:193], v[114:117]
	v_mfma_f32_16x16x32_bf16 v[110:113], v[134:137], v[198:201], v[110:113]
	v_mfma_f32_16x16x32_bf16 v[106:109], v[158:161], v[198:201], v[106:109]
	v_mfma_f32_16x16x32_bf16 v[102:105], v[166:169], v[198:201], v[102:105]
	v_mfma_f32_16x16x32_bf16 v[98:101], v[182:185], v[198:201], v[98:101]
	v_mfma_f32_16x16x32_bf16 v[94:97], v[134:137], v[206:209], v[94:97]
	v_mfma_f32_16x16x32_bf16 v[90:93], v[158:161], v[206:209], v[90:93]
	v_mfma_f32_16x16x32_bf16 v[86:89], v[166:169], v[206:209], v[86:89]
	v_mfma_f32_16x16x32_bf16 v[82:85], v[182:185], v[206:209], v[82:85]
	v_mfma_f32_16x16x32_bf16 v[78:81], v[134:137], v[218:221], v[78:81]
	v_mfma_f32_16x16x32_bf16 v[74:77], v[158:161], v[218:221], v[74:77]
	v_mfma_f32_16x16x32_bf16 v[70:73], v[166:169], v[218:221], v[70:73]
	v_mfma_f32_16x16x32_bf16 v[66:69], v[182:185], v[218:221], v[66:69]
	s_setprio 0
	s_barrier
	s_add_i32 s61, s54, s46
	v_lshl_add_u64 v[170:171], s[34:35], 0, v[144:145]
	s_mov_b32 m0, s61
	ds_read_b128 v[186:189], v176 offset:16384
	ds_read_b128 v[190:193], v176 offset:17408
	ds_read_b128 v[194:197], v176 offset:18432
	ds_read_b128 v[198:201], v176 offset:19456
	ds_read_b128 v[202:205], v176 offset:20480
	ds_read_b128 v[206:209], v176 offset:21504
	ds_read_b128 v[210:213], v176 offset:22528
	ds_read_b128 v[218:221], v176 offset:23552
	global_load_lds_dwordx4 v[170:171], off
	s_add_i32 m0, s61, 0x2000
	s_add_u32 s62, s34, 0x80000
	v_lshl_add_u64 v[214:215], s[34:35], 0, v[148:149]
	s_addc_u32 s63, s35, 0
	s_add_i32 s61, s55, s46
	global_load_lds_dwordx4 v[214:215], off
	v_lshl_add_u64 v[222:223], s[62:63], 0, v[144:145]
	s_mov_b32 m0, s61
	v_lshl_add_u64 v[224:225], s[44:45], 0, v[146:147]
	global_load_lds_dwordx4 v[222:223], off
	v_lshl_add_u64 v[222:223], s[62:63], 0, v[148:149]
	s_add_i32 m0, s61, 0x2000
	s_nop 0
	global_load_lds_dwordx4 v[222:223], off
	v_lshl_add_u64 v[222:223], s[44:45], 0, v[142:143]
	s_mov_b32 m0, s41
	s_nop 0
	global_load_lds_dwordx4 v[222:223], off
	s_mov_b32 m0, s47
	s_nop 0
	global_load_lds_dwordx4 v[224:225], off
	s_waitcnt vmcnt(8)
	s_waitcnt lgkmcnt(0)
	s_barrier
	s_setprio 1
	s_waitcnt lgkmcnt(0)
	v_mfma_f32_16x16x32_bf16 v[62:65], v[130:133], v[186:189], v[62:65]
	v_mfma_f32_16x16x32_bf16 v[58:61], v[138:141], v[186:189], v[58:61]
	v_mfma_f32_16x16x32_bf16 v[54:57], v[162:165], v[186:189], v[54:57]
	v_mfma_f32_16x16x32_bf16 v[46:49], v[178:181], v[186:189], v[46:49]
	v_mfma_f32_16x16x32_bf16 v[50:53], v[130:133], v[194:197], v[50:53]
	v_mfma_f32_16x16x32_bf16 v[42:45], v[138:141], v[194:197], v[42:45]
	v_mfma_f32_16x16x32_bf16 v[30:33], v[162:165], v[194:197], v[30:33]
	v_mfma_f32_16x16x32_bf16 v[26:29], v[178:181], v[194:197], v[26:29]
	v_mfma_f32_16x16x32_bf16 v[38:41], v[130:133], v[202:205], v[38:41]
	v_mfma_f32_16x16x32_bf16 v[34:37], v[138:141], v[202:205], v[34:37]
	v_mfma_f32_16x16x32_bf16 v[22:25], v[162:165], v[202:205], v[22:25]
	v_mfma_f32_16x16x32_bf16 v[18:21], v[178:181], v[202:205], v[18:21]
	v_mfma_f32_16x16x32_bf16 v[14:17], v[130:133], v[210:213], v[14:17]
	v_mfma_f32_16x16x32_bf16 v[10:13], v[138:141], v[210:213], v[10:13]
	v_mfma_f32_16x16x32_bf16 v[6:9], v[162:165], v[210:213], v[6:9]
	v_mfma_f32_16x16x32_bf16 v[2:5], v[178:181], v[210:213], v[2:5]
	s_setprio 0
	s_setprio 1
	v_mfma_f32_16x16x32_bf16 v[62:65], v[134:137], v[190:193], v[62:65]
	v_mfma_f32_16x16x32_bf16 v[58:61], v[158:161], v[190:193], v[58:61]
	v_mfma_f32_16x16x32_bf16 v[54:57], v[166:169], v[190:193], v[54:57]
	v_mfma_f32_16x16x32_bf16 v[46:49], v[182:185], v[190:193], v[46:49]
	v_mfma_f32_16x16x32_bf16 v[50:53], v[134:137], v[198:201], v[50:53]
	v_mfma_f32_16x16x32_bf16 v[42:45], v[158:161], v[198:201], v[42:45]
	v_mfma_f32_16x16x32_bf16 v[30:33], v[166:169], v[198:201], v[30:33]
	v_mfma_f32_16x16x32_bf16 v[26:29], v[182:185], v[198:201], v[26:29]
	v_mfma_f32_16x16x32_bf16 v[38:41], v[134:137], v[206:209], v[38:41]
	v_mfma_f32_16x16x32_bf16 v[34:37], v[158:161], v[206:209], v[34:37]
	v_mfma_f32_16x16x32_bf16 v[22:25], v[166:169], v[206:209], v[22:25]
	v_mfma_f32_16x16x32_bf16 v[18:21], v[182:185], v[206:209], v[18:21]
	v_mfma_f32_16x16x32_bf16 v[14:17], v[134:137], v[218:221], v[14:17]
	v_mfma_f32_16x16x32_bf16 v[10:13], v[158:161], v[218:221], v[10:13]
	v_mfma_f32_16x16x32_bf16 v[6:9], v[166:169], v[218:221], v[6:9]
	v_mfma_f32_16x16x32_bf16 v[2:5], v[182:185], v[218:221], v[2:5]
	s_setprio 0
	s_barrier
	s_add_i32 s61, 0, 0x18000
	s_add_i32 s62, 0, 0x1c000
	v_add_u32_e32 v158, s61, v172
	v_add_u32_e32 v177, s62, v172
	ds_read_b128 v[130:133], v158
	ds_read_b128 v[134:137], v158 offset:1024
	ds_read_b128 v[138:141], v158 offset:2048
	ds_read_b128 v[158:161], v158 offset:3072
	ds_read_b128 v[162:165], v177
	ds_read_b128 v[166:169], v177 offset:1024
	ds_read_b128 v[178:181], v177 offset:2048
	ds_read_b128 v[182:185], v177 offset:3072
	s_add_u32 s44, s44, 0x80000
	s_addc_u32 s45, s45, 0
	s_mov_b32 m0, s48
	v_lshl_add_u64 v[226:227], s[44:45], 0, v[142:143]
	ds_read_b128 v[186:189], v176 offset:32768
	ds_read_b128 v[190:193], v176 offset:33792
	ds_read_b128 v[194:197], v176 offset:34816
	ds_read_b128 v[198:201], v176 offset:35840
	ds_read_b128 v[202:205], v176 offset:36864
	ds_read_b128 v[206:209], v176 offset:37888
	ds_read_b128 v[210:213], v176 offset:38912
	ds_read_b128 v[218:221], v176 offset:39936
	global_load_lds_dwordx4 v[226:227], off
	v_lshl_add_u64 v[226:227], s[44:45], 0, v[146:147]
	s_mov_b32 m0, s49
	s_nop 0
	global_load_lds_dwordx4 v[226:227], off
	s_waitcnt vmcnt(8)
	s_waitcnt lgkmcnt(0)
	s_barrier
	s_setprio 1
	s_waitcnt lgkmcnt(0)
	v_mfma_f32_16x16x32_bf16 v[126:129], v[130:133], v[186:189], v[126:129]
	v_mfma_f32_16x16x32_bf16 v[122:125], v[138:141], v[186:189], v[122:125]
	v_mfma_f32_16x16x32_bf16 v[118:121], v[162:165], v[186:189], v[118:121]
	v_mfma_f32_16x16x32_bf16 v[114:117], v[178:181], v[186:189], v[114:117]
	v_mfma_f32_16x16x32_bf16 v[110:113], v[130:133], v[194:197], v[110:113]
	v_mfma_f32_16x16x32_bf16 v[106:109], v[138:141], v[194:197], v[106:109]
	v_mfma_f32_16x16x32_bf16 v[102:105], v[162:165], v[194:197], v[102:105]
	v_mfma_f32_16x16x32_bf16 v[98:101], v[178:181], v[194:197], v[98:101]
	v_mfma_f32_16x16x32_bf16 v[94:97], v[130:133], v[202:205], v[94:97]
	v_mfma_f32_16x16x32_bf16 v[90:93], v[138:141], v[202:205], v[90:93]
	v_mfma_f32_16x16x32_bf16 v[86:89], v[162:165], v[202:205], v[86:89]
	v_mfma_f32_16x16x32_bf16 v[82:85], v[178:181], v[202:205], v[82:85]
	v_mfma_f32_16x16x32_bf16 v[78:81], v[130:133], v[210:213], v[78:81]
	v_mfma_f32_16x16x32_bf16 v[74:77], v[138:141], v[210:213], v[74:77]
	v_mfma_f32_16x16x32_bf16 v[70:73], v[162:165], v[210:213], v[70:73]
	v_mfma_f32_16x16x32_bf16 v[66:69], v[178:181], v[210:213], v[66:69]
	s_setprio 0
	s_setprio 1
	v_mfma_f32_16x16x32_bf16 v[126:129], v[134:137], v[190:193], v[126:129]
	v_mfma_f32_16x16x32_bf16 v[122:125], v[158:161], v[190:193], v[122:125]
	v_mfma_f32_16x16x32_bf16 v[118:121], v[166:169], v[190:193], v[118:121]
	v_mfma_f32_16x16x32_bf16 v[114:117], v[182:185], v[190:193], v[114:117]
	v_mfma_f32_16x16x32_bf16 v[110:113], v[134:137], v[198:201], v[110:113]
	v_mfma_f32_16x16x32_bf16 v[106:109], v[158:161], v[198:201], v[106:109]
	v_mfma_f32_16x16x32_bf16 v[102:105], v[166:169], v[198:201], v[102:105]
	v_mfma_f32_16x16x32_bf16 v[98:101], v[182:185], v[198:201], v[98:101]
	v_mfma_f32_16x16x32_bf16 v[94:97], v[134:137], v[206:209], v[94:97]
	v_mfma_f32_16x16x32_bf16 v[90:93], v[158:161], v[206:209], v[90:93]
	v_mfma_f32_16x16x32_bf16 v[86:89], v[166:169], v[206:209], v[86:89]
	v_mfma_f32_16x16x32_bf16 v[82:85], v[182:185], v[206:209], v[82:85]
	v_mfma_f32_16x16x32_bf16 v[78:81], v[134:137], v[218:221], v[78:81]
	v_mfma_f32_16x16x32_bf16 v[74:77], v[158:161], v[218:221], v[74:77]
	v_mfma_f32_16x16x32_bf16 v[70:73], v[166:169], v[218:221], v[70:73]
	v_mfma_f32_16x16x32_bf16 v[66:69], v[182:185], v[218:221], v[66:69]
	s_setprio 0
	s_barrier
	s_add_i32 s44, s61, s46
	v_lshl_add_u64 v[170:171], v[170:171], 0, s[12:13]
	s_mov_b32 m0, s44
	ds_read_b128 v[186:189], v176 offset:49152
	ds_read_b128 v[190:193], v176 offset:50176
	ds_read_b128 v[194:197], v176 offset:51200
	ds_read_b128 v[198:201], v176 offset:52224
	ds_read_b128 v[202:205], v176 offset:53248
	ds_read_b128 v[206:209], v176 offset:54272
	ds_read_b128 v[210:213], v176 offset:55296
	ds_read_b128 v[218:221], v176 offset:56320
	global_load_lds_dwordx4 v[170:171], off
	s_add_i32 m0, s44, 0x2000
	s_add_u32 s34, s34, 0x80080
	v_lshl_add_u64 v[170:171], v[214:215], 0, s[12:13]
	s_addc_u32 s35, s35, 0
	s_add_i32 s44, s62, s46
	global_load_lds_dwordx4 v[170:171], off
	v_lshl_add_u64 v[170:171], s[34:35], 0, v[144:145]
	s_mov_b32 m0, s44
	s_nop 0
	global_load_lds_dwordx4 v[170:171], off
	v_lshl_add_u64 v[170:171], s[34:35], 0, v[148:149]
	s_add_i32 m0, s44, 0x2000
	s_nop 0
	global_load_lds_dwordx4 v[170:171], off
	v_lshl_add_u64 v[170:171], v[222:223], 0, s[12:13]
	s_mov_b32 m0, s51
	s_nop 0
	global_load_lds_dwordx4 v[170:171], off
	v_lshl_add_u64 v[170:171], v[224:225], 0, s[12:13]
	s_mov_b32 m0, s52
	s_nop 0
	global_load_lds_dwordx4 v[170:171], off
	s_waitcnt vmcnt(8)
	s_waitcnt lgkmcnt(0)
	s_barrier
	s_setprio 1
	s_waitcnt lgkmcnt(0)
	v_mfma_f32_16x16x32_bf16 v[62:65], v[130:133], v[186:189], v[62:65]
	v_mfma_f32_16x16x32_bf16 v[58:61], v[138:141], v[186:189], v[58:61]
	v_mfma_f32_16x16x32_bf16 v[54:57], v[162:165], v[186:189], v[54:57]
	v_mfma_f32_16x16x32_bf16 v[46:49], v[178:181], v[186:189], v[46:49]
	v_mfma_f32_16x16x32_bf16 v[50:53], v[130:133], v[194:197], v[50:53]
	v_mfma_f32_16x16x32_bf16 v[42:45], v[138:141], v[194:197], v[42:45]
	v_mfma_f32_16x16x32_bf16 v[30:33], v[162:165], v[194:197], v[30:33]
	v_mfma_f32_16x16x32_bf16 v[26:29], v[178:181], v[194:197], v[26:29]
	v_mfma_f32_16x16x32_bf16 v[38:41], v[130:133], v[202:205], v[38:41]
	v_mfma_f32_16x16x32_bf16 v[34:37], v[138:141], v[202:205], v[34:37]
	v_mfma_f32_16x16x32_bf16 v[22:25], v[162:165], v[202:205], v[22:25]
	v_mfma_f32_16x16x32_bf16 v[18:21], v[178:181], v[202:205], v[18:21]
	v_mfma_f32_16x16x32_bf16 v[14:17], v[130:133], v[210:213], v[14:17]
	v_mfma_f32_16x16x32_bf16 v[10:13], v[138:141], v[210:213], v[10:13]
	v_mfma_f32_16x16x32_bf16 v[6:9], v[162:165], v[210:213], v[6:9]
	v_mfma_f32_16x16x32_bf16 v[2:5], v[178:181], v[210:213], v[2:5]
	s_setprio 0
	s_setprio 1
	v_mfma_f32_16x16x32_bf16 v[62:65], v[134:137], v[190:193], v[62:65]
	v_mfma_f32_16x16x32_bf16 v[58:61], v[158:161], v[190:193], v[58:61]
	v_mfma_f32_16x16x32_bf16 v[54:57], v[166:169], v[190:193], v[54:57]
	v_mfma_f32_16x16x32_bf16 v[46:49], v[182:185], v[190:193], v[46:49]
	v_mfma_f32_16x16x32_bf16 v[50:53], v[134:137], v[198:201], v[50:53]
	v_mfma_f32_16x16x32_bf16 v[42:45], v[158:161], v[198:201], v[42:45]
	v_mfma_f32_16x16x32_bf16 v[30:33], v[166:169], v[198:201], v[30:33]
	v_mfma_f32_16x16x32_bf16 v[26:29], v[182:185], v[198:201], v[26:29]
	v_mfma_f32_16x16x32_bf16 v[38:41], v[134:137], v[206:209], v[38:41]
	v_mfma_f32_16x16x32_bf16 v[34:37], v[158:161], v[206:209], v[34:37]
	v_mfma_f32_16x16x32_bf16 v[22:25], v[166:169], v[206:209], v[22:25]
	v_mfma_f32_16x16x32_bf16 v[18:21], v[182:185], v[206:209], v[18:21]
	v_mfma_f32_16x16x32_bf16 v[14:17], v[134:137], v[218:221], v[14:17]
	v_mfma_f32_16x16x32_bf16 v[10:13], v[158:161], v[218:221], v[10:13]
	v_mfma_f32_16x16x32_bf16 v[6:9], v[166:169], v[218:221], v[6:9]
	v_mfma_f32_16x16x32_bf16 v[2:5], v[182:185], v[218:221], v[2:5]
	s_setprio 0
	s_barrier
	s_add_i32 s60, s60, 2
	s_add_u32 s42, s42, 0x100
	s_addc_u32 s43, s43, 0
	s_add_u32 s58, s58, 0x100
	s_addc_u32 s59, s59, 0
	s_cmp_gt_u32 s60, 29
	s_cbranch_scc0 .LBB0_3706
	s_and_b64 vcc, exec, s[14:15]
	s_cbranch_vccz .LBB0_3709
	s_barrier

.LBB0_3835:
	ds_read_b128 v[146:149], v153
	ds_read_b128 v[156:159], v153 offset:1024
	ds_read_b128 v[160:163], v153 offset:2048
	ds_read_b128 v[164:167], v153 offset:3072
	ds_read_b128 v[168:171], v154
	ds_read_b128 v[172:175], v154 offset:1024
	ds_read_b128 v[176:179], v154 offset:2048
	ds_read_b128 v[180:183], v154 offset:3072
	s_add_u32 s34, s38, 0xfff80080
	s_addc_u32 s35, s39, -1
	s_cmp_eq_u32 s57, 28
	s_cselect_b32 s41, s0, s35
	s_cselect_b32 s40, s1, s34
	s_cselect_b32 s35, s15, s56
	s_cselect_b32 s34, s17, s55
	v_lshl_add_u64 v[218:219], s[38:39], 0, v[138:139]
	s_add_i32 m0, s37, 0xc000
	ds_read_b128 v[184:187], v155
	ds_read_b128 v[188:191], v155 offset:1024
	ds_read_b128 v[192:195], v155 offset:2048
	ds_read_b128 v[196:199], v155 offset:3072
	ds_read_b128 v[200:203], v155 offset:4096
	ds_read_b128 v[204:207], v155 offset:5120
	ds_read_b128 v[208:211], v155 offset:6144
	ds_read_b128 v[212:215], v155 offset:7168
	global_load_lds_dwordx4 v[218:219], off
	v_lshl_add_u64 v[218:219], s[38:39], 0, v[140:141]
	s_add_i32 m0, s37, 0xe000
	s_nop 0
	global_load_lds_dwordx4 v[218:219], off
	s_waitcnt vmcnt(8)
	s_waitcnt lgkmcnt(0)
	s_barrier
	s_setprio 1
	s_waitcnt lgkmcnt(0)
	v_mfma_f32_16x16x32_bf16 v[126:129], v[146:149], v[184:187], v[126:129]
	v_mfma_f32_16x16x32_bf16 v[118:121], v[160:163], v[184:187], v[118:121]
	v_mfma_f32_16x16x32_bf16 v[122:125], v[168:171], v[184:187], v[122:125]
	v_mfma_f32_16x16x32_bf16 v[114:117], v[176:179], v[184:187], v[114:117]
	v_mfma_f32_16x16x32_bf16 v[110:113], v[146:149], v[192:195], v[110:113]
	v_mfma_f32_16x16x32_bf16 v[102:105], v[160:163], v[192:195], v[102:105]
	v_mfma_f32_16x16x32_bf16 v[106:109], v[168:171], v[192:195], v[106:109]
	v_mfma_f32_16x16x32_bf16 v[98:101], v[176:179], v[192:195], v[98:101]
	v_mfma_f32_16x16x32_bf16 v[94:97], v[146:149], v[200:203], v[94:97]
	v_mfma_f32_16x16x32_bf16 v[86:89], v[160:163], v[200:203], v[86:89]
	v_mfma_f32_16x16x32_bf16 v[90:93], v[168:171], v[200:203], v[90:93]
	v_mfma_f32_16x16x32_bf16 v[82:85], v[176:179], v[200:203], v[82:85]
	v_mfma_f32_16x16x32_bf16 v[78:81], v[146:149], v[208:211], v[78:81]
	v_mfma_f32_16x16x32_bf16 v[70:73], v[160:163], v[208:211], v[70:73]
	v_mfma_f32_16x16x32_bf16 v[74:77], v[168:171], v[208:211], v[74:77]
	v_mfma_f32_16x16x32_bf16 v[66:69], v[176:179], v[208:211], v[66:69]
	s_setprio 0
	s_setprio 1
	v_mfma_f32_16x16x32_bf16 v[126:129], v[156:159], v[188:191], v[126:129]
	v_mfma_f32_16x16x32_bf16 v[118:121], v[164:167], v[188:191], v[118:121]
	v_mfma_f32_16x16x32_bf16 v[122:125], v[172:175], v[188:191], v[122:125]
	v_mfma_f32_16x16x32_bf16 v[114:117], v[180:183], v[188:191], v[114:117]
	v_mfma_f32_16x16x32_bf16 v[110:113], v[156:159], v[196:199], v[110:113]
	v_mfma_f32_16x16x32_bf16 v[102:105], v[164:167], v[196:199], v[102:105]
	v_mfma_f32_16x16x32_bf16 v[106:109], v[172:175], v[196:199], v[106:109]
	v_mfma_f32_16x16x32_bf16 v[98:101], v[180:183], v[196:199], v[98:101]
	v_mfma_f32_16x16x32_bf16 v[94:97], v[156:159], v[204:207], v[94:97]
	v_mfma_f32_16x16x32_bf16 v[86:89], v[164:167], v[204:207], v[86:89]
	v_mfma_f32_16x16x32_bf16 v[90:93], v[172:175], v[204:207], v[90:93]
	v_mfma_f32_16x16x32_bf16 v[82:85], v[180:183], v[204:207], v[82:85]
	v_mfma_f32_16x16x32_bf16 v[78:81], v[156:159], v[212:215], v[78:81]
	v_mfma_f32_16x16x32_bf16 v[70:73], v[164:167], v[212:215], v[70:73]
	v_mfma_f32_16x16x32_bf16 v[74:77], v[172:175], v[212:215], v[74:77]
	v_mfma_f32_16x16x32_bf16 v[66:69], v[180:183], v[212:215], v[66:69]
	s_setprio 0
	s_barrier
	s_add_i32 s58, s51, s33
	v_lshl_add_u64 v[218:219], s[34:35], 0, v[134:135]
	s_mov_b32 m0, s58
	ds_read_b128 v[184:187], v155 offset:16384
	ds_read_b128 v[188:191], v155 offset:17408
	ds_read_b128 v[192:195], v155 offset:18432
	ds_read_b128 v[196:199], v155 offset:19456
	ds_read_b128 v[200:203], v155 offset:20480
	ds_read_b128 v[204:207], v155 offset:21504
	ds_read_b128 v[208:211], v155 offset:22528
	ds_read_b128 v[212:215], v155 offset:23552
	global_load_lds_dwordx4 v[218:219], off
	s_add_i32 m0, s58, 0x2000
	s_add_u32 s58, s34, 0x80000
	v_lshl_add_u64 v[220:221], s[34:35], 0, v[130:131]
	s_addc_u32 s59, s35, 0
	s_add_i32 s60, s52, s33
	global_load_lds_dwordx4 v[220:221], off
	v_lshl_add_u64 v[222:223], s[58:59], 0, v[134:135]
	s_mov_b32 m0, s60
	v_lshl_add_u64 v[224:225], s[40:41], 0, v[132:133]
	global_load_lds_dwordx4 v[222:223], off
	v_lshl_add_u64 v[222:223], s[58:59], 0, v[130:131]
	s_add_i32 m0, s60, 0x2000
	s_nop 0
	global_load_lds_dwordx4 v[222:223], off
	v_lshl_add_u64 v[222:223], s[40:41], 0, v[136:137]
	s_mov_b32 m0, s37
	s_nop 0
	global_load_lds_dwordx4 v[222:223], off
	s_mov_b32 m0, s44
	s_nop 0
	global_load_lds_dwordx4 v[224:225], off
	s_waitcnt vmcnt(8)
	s_waitcnt lgkmcnt(0)
	s_barrier
	s_setprio 1
	s_waitcnt lgkmcnt(0)
	v_mfma_f32_16x16x32_bf16 v[62:65], v[146:149], v[184:187], v[62:65]
	v_mfma_f32_16x16x32_bf16 v[54:57], v[160:163], v[184:187], v[54:57]
	v_mfma_f32_16x16x32_bf16 v[58:61], v[168:171], v[184:187], v[58:61]
	v_mfma_f32_16x16x32_bf16 v[50:53], v[176:179], v[184:187], v[50:53]
	v_mfma_f32_16x16x32_bf16 v[46:49], v[146:149], v[192:195], v[46:49]
	v_mfma_f32_16x16x32_bf16 v[38:41], v[160:163], v[192:195], v[38:41]
	v_mfma_f32_16x16x32_bf16 v[42:45], v[168:171], v[192:195], v[42:45]
	v_mfma_f32_16x16x32_bf16 v[34:37], v[176:179], v[192:195], v[34:37]
	v_mfma_f32_16x16x32_bf16 v[30:33], v[146:149], v[200:203], v[30:33]
	v_mfma_f32_16x16x32_bf16 v[22:25], v[160:163], v[200:203], v[22:25]
	v_mfma_f32_16x16x32_bf16 v[26:29], v[168:171], v[200:203], v[26:29]
	v_mfma_f32_16x16x32_bf16 v[18:21], v[176:179], v[200:203], v[18:21]
	v_mfma_f32_16x16x32_bf16 v[14:17], v[146:149], v[208:211], v[14:17]
	v_mfma_f32_16x16x32_bf16 v[6:9], v[160:163], v[208:211], v[6:9]
	v_mfma_f32_16x16x32_bf16 v[10:13], v[168:171], v[208:211], v[10:13]
	v_mfma_f32_16x16x32_bf16 v[2:5], v[176:179], v[208:211], v[2:5]
	s_setprio 0
	s_setprio 1
	v_mfma_f32_16x16x32_bf16 v[62:65], v[156:159], v[188:191], v[62:65]
	v_mfma_f32_16x16x32_bf16 v[54:57], v[164:167], v[188:191], v[54:57]
	v_mfma_f32_16x16x32_bf16 v[58:61], v[172:175], v[188:191], v[58:61]
	v_mfma_f32_16x16x32_bf16 v[50:53], v[180:183], v[188:191], v[50:53]
	v_mfma_f32_16x16x32_bf16 v[46:49], v[156:159], v[196:199], v[46:49]
	v_mfma_f32_16x16x32_bf16 v[38:41], v[164:167], v[196:199], v[38:41]
	v_mfma_f32_16x16x32_bf16 v[42:45], v[172:175], v[196:199], v[42:45]
	v_mfma_f32_16x16x32_bf16 v[34:37], v[180:183], v[196:199], v[34:37]
	v_mfma_f32_16x16x32_bf16 v[30:33], v[156:159], v[204:207], v[30:33]
	v_mfma_f32_16x16x32_bf16 v[22:25], v[164:167], v[204:207], v[22:25]
	v_mfma_f32_16x16x32_bf16 v[26:29], v[172:175], v[204:207], v[26:29]
	v_mfma_f32_16x16x32_bf16 v[18:21], v[180:183], v[204:207], v[18:21]
	v_mfma_f32_16x16x32_bf16 v[14:17], v[156:159], v[212:215], v[14:17]
	v_mfma_f32_16x16x32_bf16 v[6:9], v[164:167], v[212:215], v[6:9]
	v_mfma_f32_16x16x32_bf16 v[10:13], v[172:175], v[212:215], v[10:13]
	v_mfma_f32_16x16x32_bf16 v[2:5], v[180:183], v[212:215], v[2:5]
	s_setprio 0
	s_barrier
	s_add_i32 s58, 0, 0x18000
	s_add_i32 s59, 0, 0x1c000
	v_add_u32_e32 v164, s58, v151
	v_add_u32_e32 v180, s59, v151
	ds_read_b128 v[146:149], v164
	ds_read_b128 v[156:159], v164 offset:1024
	ds_read_b128 v[160:163], v164 offset:2048
	ds_read_b128 v[164:167], v164 offset:3072
	ds_read_b128 v[168:171], v180
	ds_read_b128 v[172:175], v180 offset:1024
	ds_read_b128 v[176:179], v180 offset:2048
	ds_read_b128 v[180:183], v180 offset:3072
	s_add_u32 s40, s40, 0x80000
	s_addc_u32 s41, s41, 0
	s_mov_b32 m0, s45
	v_lshl_add_u64 v[226:227], s[40:41], 0, v[136:137]
	ds_read_b128 v[184:187], v155 offset:32768
	ds_read_b128 v[188:191], v155 offset:33792
	ds_read_b128 v[192:195], v155 offset:34816
	ds_read_b128 v[196:199], v155 offset:35840
	ds_read_b128 v[200:203], v155 offset:36864
	ds_read_b128 v[204:207], v155 offset:37888
	ds_read_b128 v[208:211], v155 offset:38912
	ds_read_b128 v[212:215], v155 offset:39936
	global_load_lds_dwordx4 v[226:227], off
	v_lshl_add_u64 v[226:227], s[40:41], 0, v[132:133]
	s_mov_b32 m0, s46
	s_nop 0
	global_load_lds_dwordx4 v[226:227], off
	s_waitcnt vmcnt(8)
	s_waitcnt lgkmcnt(0)
	s_barrier
	s_setprio 1
	s_waitcnt lgkmcnt(0)
	v_mfma_f32_16x16x32_bf16 v[126:129], v[146:149], v[184:187], v[126:129]
	v_mfma_f32_16x16x32_bf16 v[118:121], v[160:163], v[184:187], v[118:121]
	v_mfma_f32_16x16x32_bf16 v[122:125], v[168:171], v[184:187], v[122:125]
	v_mfma_f32_16x16x32_bf16 v[114:117], v[176:179], v[184:187], v[114:117]
	v_mfma_f32_16x16x32_bf16 v[110:113], v[146:149], v[192:195], v[110:113]
	v_mfma_f32_16x16x32_bf16 v[102:105], v[160:163], v[192:195], v[102:105]
	v_mfma_f32_16x16x32_bf16 v[106:109], v[168:171], v[192:195], v[106:109]
	v_mfma_f32_16x16x32_bf16 v[98:101], v[176:179], v[192:195], v[98:101]
	v_mfma_f32_16x16x32_bf16 v[94:97], v[146:149], v[200:203], v[94:97]
	v_mfma_f32_16x16x32_bf16 v[86:89], v[160:163], v[200:203], v[86:89]
	v_mfma_f32_16x16x32_bf16 v[90:93], v[168:171], v[200:203], v[90:93]
	v_mfma_f32_16x16x32_bf16 v[82:85], v[176:179], v[200:203], v[82:85]
	v_mfma_f32_16x16x32_bf16 v[78:81], v[146:149], v[208:211], v[78:81]
	v_mfma_f32_16x16x32_bf16 v[70:73], v[160:163], v[208:211], v[70:73]
	v_mfma_f32_16x16x32_bf16 v[74:77], v[168:171], v[208:211], v[74:77]
	v_mfma_f32_16x16x32_bf16 v[66:69], v[176:179], v[208:211], v[66:69]
	s_setprio 0
	s_setprio 1
	v_mfma_f32_16x16x32_bf16 v[126:129], v[156:159], v[188:191], v[126:129]
	v_mfma_f32_16x16x32_bf16 v[118:121], v[164:167], v[188:191], v[118:121]
	v_mfma_f32_16x16x32_bf16 v[122:125], v[172:175], v[188:191], v[122:125]
	v_mfma_f32_16x16x32_bf16 v[114:117], v[180:183], v[188:191], v[114:117]
	v_mfma_f32_16x16x32_bf16 v[110:113], v[156:159], v[196:199], v[110:113]
	v_mfma_f32_16x16x32_bf16 v[102:105], v[164:167], v[196:199], v[102:105]
	v_mfma_f32_16x16x32_bf16 v[106:109], v[172:175], v[196:199], v[106:109]
	v_mfma_f32_16x16x32_bf16 v[98:101], v[180:183], v[196:199], v[98:101]
	v_mfma_f32_16x16x32_bf16 v[94:97], v[156:159], v[204:207], v[94:97]
	v_mfma_f32_16x16x32_bf16 v[86:89], v[164:167], v[204:207], v[86:89]
	v_mfma_f32_16x16x32_bf16 v[90:93], v[172:175], v[204:207], v[90:93]
	v_mfma_f32_16x16x32_bf16 v[82:85], v[180:183], v[204:207], v[82:85]
	v_mfma_f32_16x16x32_bf16 v[78:81], v[156:159], v[212:215], v[78:81]
	v_mfma_f32_16x16x32_bf16 v[70:73], v[164:167], v[212:215], v[70:73]
	v_mfma_f32_16x16x32_bf16 v[74:77], v[172:175], v[212:215], v[74:77]
	v_mfma_f32_16x16x32_bf16 v[66:69], v[180:183], v[212:215], v[66:69]
	s_setprio 0
	s_barrier
	s_add_i32 s40, s58, s33
	v_lshl_add_u64 v[218:219], v[218:219], 0, s[8:9]
	s_mov_b32 m0, s40
	ds_read_b128 v[184:187], v155 offset:49152
	ds_read_b128 v[188:191], v155 offset:50176
	ds_read_b128 v[192:195], v155 offset:51200
	ds_read_b128 v[196:199], v155 offset:52224
	ds_read_b128 v[200:203], v155 offset:53248
	ds_read_b128 v[204:207], v155 offset:54272
	ds_read_b128 v[208:211], v155 offset:55296
	ds_read_b128 v[212:215], v155 offset:56320
	global_load_lds_dwordx4 v[218:219], off
	s_add_i32 m0, s40, 0x2000
	s_add_u32 s34, s34, 0x80080
	v_lshl_add_u64 v[218:219], v[220:221], 0, s[8:9]
	s_addc_u32 s35, s35, 0
	s_add_i32 s40, s59, s33
	global_load_lds_dwordx4 v[218:219], off
	v_lshl_add_u64 v[218:219], s[34:35], 0, v[134:135]
	s_mov_b32 m0, s40
	s_nop 0
	global_load_lds_dwordx4 v[218:219], off
	v_lshl_add_u64 v[218:219], s[34:35], 0, v[130:131]
	s_add_i32 m0, s40, 0x2000
	s_nop 0
	global_load_lds_dwordx4 v[218:219], off
	v_lshl_add_u64 v[218:219], v[222:223], 0, s[8:9]
	s_mov_b32 m0, s48
	s_nop 0
	global_load_lds_dwordx4 v[218:219], off
	v_lshl_add_u64 v[218:219], v[224:225], 0, s[8:9]
	s_mov_b32 m0, s49
	s_nop 0
	global_load_lds_dwordx4 v[218:219], off
	s_waitcnt vmcnt(8)
	s_waitcnt lgkmcnt(0)
	s_barrier
	s_setprio 1
	s_waitcnt lgkmcnt(0)
	v_mfma_f32_16x16x32_bf16 v[62:65], v[146:149], v[184:187], v[62:65]
	v_mfma_f32_16x16x32_bf16 v[54:57], v[160:163], v[184:187], v[54:57]
	v_mfma_f32_16x16x32_bf16 v[58:61], v[168:171], v[184:187], v[58:61]
	v_mfma_f32_16x16x32_bf16 v[50:53], v[176:179], v[184:187], v[50:53]
	v_mfma_f32_16x16x32_bf16 v[46:49], v[146:149], v[192:195], v[46:49]
	v_mfma_f32_16x16x32_bf16 v[38:41], v[160:163], v[192:195], v[38:41]
	v_mfma_f32_16x16x32_bf16 v[42:45], v[168:171], v[192:195], v[42:45]
	v_mfma_f32_16x16x32_bf16 v[34:37], v[176:179], v[192:195], v[34:37]
	v_mfma_f32_16x16x32_bf16 v[30:33], v[146:149], v[200:203], v[30:33]
	v_mfma_f32_16x16x32_bf16 v[22:25], v[160:163], v[200:203], v[22:25]
	v_mfma_f32_16x16x32_bf16 v[26:29], v[168:171], v[200:203], v[26:29]
	v_mfma_f32_16x16x32_bf16 v[18:21], v[176:179], v[200:203], v[18:21]
	v_mfma_f32_16x16x32_bf16 v[14:17], v[146:149], v[208:211], v[14:17]
	v_mfma_f32_16x16x32_bf16 v[6:9], v[160:163], v[208:211], v[6:9]
	v_mfma_f32_16x16x32_bf16 v[10:13], v[168:171], v[208:211], v[10:13]
	v_mfma_f32_16x16x32_bf16 v[2:5], v[176:179], v[208:211], v[2:5]
	s_setprio 0
	s_setprio 1
	v_mfma_f32_16x16x32_bf16 v[62:65], v[156:159], v[188:191], v[62:65]
	v_mfma_f32_16x16x32_bf16 v[54:57], v[164:167], v[188:191], v[54:57]
	v_mfma_f32_16x16x32_bf16 v[58:61], v[172:175], v[188:191], v[58:61]
	v_mfma_f32_16x16x32_bf16 v[50:53], v[180:183], v[188:191], v[50:53]
	v_mfma_f32_16x16x32_bf16 v[46:49], v[156:159], v[196:199], v[46:49]
	v_mfma_f32_16x16x32_bf16 v[38:41], v[164:167], v[196:199], v[38:41]
	v_mfma_f32_16x16x32_bf16 v[42:45], v[172:175], v[196:199], v[42:45]
	v_mfma_f32_16x16x32_bf16 v[34:37], v[180:183], v[196:199], v[34:37]
	v_mfma_f32_16x16x32_bf16 v[30:33], v[156:159], v[204:207], v[30:33]
	v_mfma_f32_16x16x32_bf16 v[22:25], v[164:167], v[204:207], v[22:25]
	v_mfma_f32_16x16x32_bf16 v[26:29], v[172:175], v[204:207], v[26:29]
	v_mfma_f32_16x16x32_bf16 v[18:21], v[180:183], v[204:207], v[18:21]
	v_mfma_f32_16x16x32_bf16 v[14:17], v[156:159], v[212:215], v[14:17]
	v_mfma_f32_16x16x32_bf16 v[6:9], v[164:167], v[212:215], v[6:9]
	v_mfma_f32_16x16x32_bf16 v[10:13], v[172:175], v[212:215], v[10:13]
	v_mfma_f32_16x16x32_bf16 v[2:5], v[180:183], v[212:215], v[2:5]
	s_setprio 0
	s_barrier
	s_add_i32 s57, s57, 2
	s_add_u32 s38, s38, 0x100
	s_addc_u32 s39, s39, 0
	s_add_u32 s55, s55, 0x100
	s_addc_u32 s56, s56, 0
	s_cmp_gt_u32 s57, 29
	s_cbranch_scc0 .LBB0_3835
	v_mov_b32_e32 v160, 0xbfb8aa3b
	s_and_b64 vcc, exec, s[12:13]
	s_cbranch_vccz .LBB0_3838
	s_barrier

.LBB0_3930:
	ds_read_b128 v[144:147], v155
	ds_read_b128 v[148:151], v155 offset:1024
	ds_read_b128 v[158:161], v155 offset:2048
	ds_read_b128 v[162:165], v155 offset:3072
	ds_read_b128 v[166:169], v156
	ds_read_b128 v[170:173], v156 offset:1024
	ds_read_b128 v[174:177], v156 offset:2048
	ds_read_b128 v[178:181], v156 offset:3072
	s_add_u32 s20, s18, 0xffea0080
	s_addc_u32 s21, s19, -1
	s_cmpk_eq_i32 s45, 0x54
	s_cselect_b32 s23, s5, s21
	s_cselect_b32 s22, s4, s20
	s_cselect_b32 s21, s17, s1
	s_cselect_b32 s20, s16, s0
	v_lshl_add_u64 v[214:215], s[18:19], 0, v[136:137]
	s_add_i32 m0, s30, 0xc000
	ds_read_b128 v[182:185], v157
	ds_read_b128 v[186:189], v157 offset:1024
	ds_read_b128 v[190:193], v157 offset:2048
	ds_read_b128 v[194:197], v157 offset:3072
	ds_read_b128 v[198:201], v157 offset:4096
	ds_read_b128 v[202:205], v157 offset:5120
	ds_read_b128 v[206:209], v157 offset:6144
	ds_read_b128 v[210:213], v157 offset:7168
	global_load_lds_dwordx4 v[214:215], off
	v_lshl_add_u64 v[214:215], s[18:19], 0, v[138:139]
	s_add_i32 m0, s30, 0xe000
	s_nop 0
	global_load_lds_dwordx4 v[214:215], off
	s_waitcnt vmcnt(8)
	s_waitcnt lgkmcnt(0)
	s_barrier
	s_setprio 1
	s_waitcnt lgkmcnt(0)
	v_mfma_f32_16x16x32_bf16 v[124:127], v[144:147], v[182:185], v[124:127]
	v_mfma_f32_16x16x32_bf16 v[120:123], v[158:161], v[182:185], v[120:123]
	v_mfma_f32_16x16x32_bf16 v[108:111], v[166:169], v[182:185], v[108:111]
	v_mfma_f32_16x16x32_bf16 v[104:107], v[174:177], v[182:185], v[104:107]
	v_mfma_f32_16x16x32_bf16 v[116:119], v[144:147], v[190:193], v[116:119]
	v_mfma_f32_16x16x32_bf16 v[112:115], v[158:161], v[190:193], v[112:115]
	v_mfma_f32_16x16x32_bf16 v[100:103], v[166:169], v[190:193], v[100:103]
	v_mfma_f32_16x16x32_bf16 v[96:99], v[174:177], v[190:193], v[96:99]
	v_mfma_f32_16x16x32_bf16 v[92:95], v[144:147], v[198:201], v[92:95]
	v_mfma_f32_16x16x32_bf16 v[88:91], v[158:161], v[198:201], v[88:91]
	v_mfma_f32_16x16x32_bf16 v[76:79], v[166:169], v[198:201], v[76:79]
	v_mfma_f32_16x16x32_bf16 v[72:75], v[174:177], v[198:201], v[72:75]
	v_mfma_f32_16x16x32_bf16 v[84:87], v[144:147], v[206:209], v[84:87]
	v_mfma_f32_16x16x32_bf16 v[80:83], v[158:161], v[206:209], v[80:83]
	v_mfma_f32_16x16x32_bf16 v[68:71], v[166:169], v[206:209], v[68:71]
	v_mfma_f32_16x16x32_bf16 v[64:67], v[174:177], v[206:209], v[64:67]
	s_setprio 0
	s_setprio 1
	v_mfma_f32_16x16x32_bf16 v[124:127], v[148:151], v[186:189], v[124:127]
	v_mfma_f32_16x16x32_bf16 v[120:123], v[162:165], v[186:189], v[120:123]
	v_mfma_f32_16x16x32_bf16 v[108:111], v[170:173], v[186:189], v[108:111]
	v_mfma_f32_16x16x32_bf16 v[104:107], v[178:181], v[186:189], v[104:107]
	v_mfma_f32_16x16x32_bf16 v[116:119], v[148:151], v[194:197], v[116:119]
	v_mfma_f32_16x16x32_bf16 v[112:115], v[162:165], v[194:197], v[112:115]
	v_mfma_f32_16x16x32_bf16 v[100:103], v[170:173], v[194:197], v[100:103]
	v_mfma_f32_16x16x32_bf16 v[96:99], v[178:181], v[194:197], v[96:99]
	v_mfma_f32_16x16x32_bf16 v[92:95], v[148:151], v[202:205], v[92:95]
	v_mfma_f32_16x16x32_bf16 v[88:91], v[162:165], v[202:205], v[88:91]
	v_mfma_f32_16x16x32_bf16 v[76:79], v[170:173], v[202:205], v[76:79]
	v_mfma_f32_16x16x32_bf16 v[72:75], v[178:181], v[202:205], v[72:75]
	v_mfma_f32_16x16x32_bf16 v[84:87], v[148:151], v[210:213], v[84:87]
	v_mfma_f32_16x16x32_bf16 v[80:83], v[162:165], v[210:213], v[80:83]
	v_mfma_f32_16x16x32_bf16 v[68:71], v[170:173], v[210:213], v[68:71]
	v_mfma_f32_16x16x32_bf16 v[64:67], v[178:181], v[210:213], v[64:67]
	s_setprio 0
	s_barrier
	s_add_i32 s46, s39, s27
	v_lshl_add_u64 v[214:215], s[20:21], 0, v[130:131]
	s_mov_b32 m0, s46
	ds_read_b128 v[182:185], v157 offset:16384
	ds_read_b128 v[186:189], v157 offset:17408
	ds_read_b128 v[190:193], v157 offset:18432
	ds_read_b128 v[194:197], v157 offset:19456
	ds_read_b128 v[198:201], v157 offset:20480
	ds_read_b128 v[202:205], v157 offset:21504
	ds_read_b128 v[206:209], v157 offset:22528
	ds_read_b128 v[210:213], v157 offset:23552
	global_load_lds_dwordx4 v[214:215], off
	s_add_i32 m0, s46, 0x2000
	s_add_u32 s46, s20, 0x160000
	v_lshl_add_u64 v[216:217], s[20:21], 0, v[134:135]
	s_addc_u32 s47, s21, 0
	s_add_i32 s48, s40, s27
	global_load_lds_dwordx4 v[216:217], off
	v_lshl_add_u64 v[218:219], s[46:47], 0, v[130:131]
	s_mov_b32 m0, s48
	v_lshl_add_u64 v[220:221], s[22:23], 0, v[132:133]
	global_load_lds_dwordx4 v[218:219], off
	v_lshl_add_u64 v[218:219], s[46:47], 0, v[134:135]
	s_add_i32 m0, s48, 0x2000
	s_nop 0
	global_load_lds_dwordx4 v[218:219], off
	v_lshl_add_u64 v[218:219], s[22:23], 0, v[128:129]
	s_mov_b32 m0, s30
	s_nop 0
	global_load_lds_dwordx4 v[218:219], off
	s_mov_b32 m0, s31
	s_nop 0
	global_load_lds_dwordx4 v[220:221], off
	s_waitcnt vmcnt(8)
	s_waitcnt lgkmcnt(0)
	s_barrier
	s_setprio 1
	s_waitcnt lgkmcnt(0)
	v_mfma_f32_16x16x32_bf16 v[60:63], v[144:147], v[182:185], v[60:63]
	v_mfma_f32_16x16x32_bf16 v[56:59], v[158:161], v[182:185], v[56:59]
	v_mfma_f32_16x16x32_bf16 v[44:47], v[166:169], v[182:185], v[44:47]
	v_mfma_f32_16x16x32_bf16 v[40:43], v[174:177], v[182:185], v[40:43]
	v_mfma_f32_16x16x32_bf16 v[52:55], v[144:147], v[190:193], v[52:55]
	v_mfma_f32_16x16x32_bf16 v[48:51], v[158:161], v[190:193], v[48:51]
	v_mfma_f32_16x16x32_bf16 v[36:39], v[166:169], v[190:193], v[36:39]
	v_mfma_f32_16x16x32_bf16 v[32:35], v[174:177], v[190:193], v[32:35]
	v_mfma_f32_16x16x32_bf16 v[28:31], v[144:147], v[198:201], v[28:31]
	v_mfma_f32_16x16x32_bf16 v[24:27], v[158:161], v[198:201], v[24:27]
	v_mfma_f32_16x16x32_bf16 v[12:15], v[166:169], v[198:201], v[12:15]
	v_mfma_f32_16x16x32_bf16 v[8:11], v[174:177], v[198:201], v[8:11]
	v_mfma_f32_16x16x32_bf16 v[20:23], v[144:147], v[206:209], v[20:23]
	v_mfma_f32_16x16x32_bf16 v[16:19], v[158:161], v[206:209], v[16:19]
	v_mfma_f32_16x16x32_bf16 v[4:7], v[166:169], v[206:209], v[4:7]
	v_mfma_f32_16x16x32_bf16 v[0:3], v[174:177], v[206:209], v[0:3]
	s_setprio 0
	s_setprio 1
	v_mfma_f32_16x16x32_bf16 v[60:63], v[148:151], v[186:189], v[60:63]
	v_mfma_f32_16x16x32_bf16 v[56:59], v[162:165], v[186:189], v[56:59]
	v_mfma_f32_16x16x32_bf16 v[44:47], v[170:173], v[186:189], v[44:47]
	v_mfma_f32_16x16x32_bf16 v[40:43], v[178:181], v[186:189], v[40:43]
	v_mfma_f32_16x16x32_bf16 v[52:55], v[148:151], v[194:197], v[52:55]
	v_mfma_f32_16x16x32_bf16 v[48:51], v[162:165], v[194:197], v[48:51]
	v_mfma_f32_16x16x32_bf16 v[36:39], v[170:173], v[194:197], v[36:39]
	v_mfma_f32_16x16x32_bf16 v[32:35], v[178:181], v[194:197], v[32:35]
	v_mfma_f32_16x16x32_bf16 v[28:31], v[148:151], v[202:205], v[28:31]
	v_mfma_f32_16x16x32_bf16 v[24:27], v[162:165], v[202:205], v[24:27]
	v_mfma_f32_16x16x32_bf16 v[12:15], v[170:173], v[202:205], v[12:15]
	v_mfma_f32_16x16x32_bf16 v[8:11], v[178:181], v[202:205], v[8:11]
	v_mfma_f32_16x16x32_bf16 v[20:23], v[148:151], v[210:213], v[20:23]
	v_mfma_f32_16x16x32_bf16 v[16:19], v[162:165], v[210:213], v[16:19]
	v_mfma_f32_16x16x32_bf16 v[4:7], v[170:173], v[210:213], v[4:7]
	v_mfma_f32_16x16x32_bf16 v[0:3], v[178:181], v[210:213], v[0:3]
	s_setprio 0
	s_barrier
	s_add_i32 s46, 0, 0x18000
	s_add_i32 s47, 0, 0x1c000
	v_add_u32_e32 v162, s46, v153
	v_add_u32_e32 v178, s47, v153
	ds_read_b128 v[144:147], v162
	ds_read_b128 v[148:151], v162 offset:1024
	ds_read_b128 v[158:161], v162 offset:2048
	ds_read_b128 v[162:165], v162 offset:3072
	ds_read_b128 v[166:169], v178
	ds_read_b128 v[170:173], v178 offset:1024
	ds_read_b128 v[174:177], v178 offset:2048
	ds_read_b128 v[178:181], v178 offset:3072
	s_add_u32 s22, s22, 0x160000
	s_addc_u32 s23, s23, 0
	s_mov_b32 m0, s33
	v_lshl_add_u64 v[222:223], s[22:23], 0, v[128:129]
	ds_read_b128 v[182:185], v157 offset:32768
	ds_read_b128 v[186:189], v157 offset:33792
	ds_read_b128 v[190:193], v157 offset:34816
	ds_read_b128 v[194:197], v157 offset:35840
	ds_read_b128 v[198:201], v157 offset:36864
	ds_read_b128 v[202:205], v157 offset:37888
	ds_read_b128 v[206:209], v157 offset:38912
	ds_read_b128 v[210:213], v157 offset:39936
	global_load_lds_dwordx4 v[222:223], off
	v_lshl_add_u64 v[222:223], s[22:23], 0, v[132:133]
	s_mov_b32 m0, s34
	s_nop 0
	global_load_lds_dwordx4 v[222:223], off
	s_waitcnt vmcnt(8)
	s_waitcnt lgkmcnt(0)
	s_barrier
	s_setprio 1
	s_waitcnt lgkmcnt(0)
	v_mfma_f32_16x16x32_bf16 v[124:127], v[144:147], v[182:185], v[124:127]
	v_mfma_f32_16x16x32_bf16 v[120:123], v[158:161], v[182:185], v[120:123]
	v_mfma_f32_16x16x32_bf16 v[108:111], v[166:169], v[182:185], v[108:111]
	v_mfma_f32_16x16x32_bf16 v[104:107], v[174:177], v[182:185], v[104:107]
	v_mfma_f32_16x16x32_bf16 v[116:119], v[144:147], v[190:193], v[116:119]
	v_mfma_f32_16x16x32_bf16 v[112:115], v[158:161], v[190:193], v[112:115]
	v_mfma_f32_16x16x32_bf16 v[100:103], v[166:169], v[190:193], v[100:103]
	v_mfma_f32_16x16x32_bf16 v[96:99], v[174:177], v[190:193], v[96:99]
	v_mfma_f32_16x16x32_bf16 v[92:95], v[144:147], v[198:201], v[92:95]
	v_mfma_f32_16x16x32_bf16 v[88:91], v[158:161], v[198:201], v[88:91]
	v_mfma_f32_16x16x32_bf16 v[76:79], v[166:169], v[198:201], v[76:79]
	v_mfma_f32_16x16x32_bf16 v[72:75], v[174:177], v[198:201], v[72:75]
	v_mfma_f32_16x16x32_bf16 v[84:87], v[144:147], v[206:209], v[84:87]
	v_mfma_f32_16x16x32_bf16 v[80:83], v[158:161], v[206:209], v[80:83]
	v_mfma_f32_16x16x32_bf16 v[68:71], v[166:169], v[206:209], v[68:71]
	v_mfma_f32_16x16x32_bf16 v[64:67], v[174:177], v[206:209], v[64:67]
	s_setprio 0
	s_setprio 1
	v_mfma_f32_16x16x32_bf16 v[124:127], v[148:151], v[186:189], v[124:127]
	v_mfma_f32_16x16x32_bf16 v[120:123], v[162:165], v[186:189], v[120:123]
	v_mfma_f32_16x16x32_bf16 v[108:111], v[170:173], v[186:189], v[108:111]
	v_mfma_f32_16x16x32_bf16 v[104:107], v[178:181], v[186:189], v[104:107]
	v_mfma_f32_16x16x32_bf16 v[116:119], v[148:151], v[194:197], v[116:119]
	v_mfma_f32_16x16x32_bf16 v[112:115], v[162:165], v[194:197], v[112:115]
	v_mfma_f32_16x16x32_bf16 v[100:103], v[170:173], v[194:197], v[100:103]
	v_mfma_f32_16x16x32_bf16 v[96:99], v[178:181], v[194:197], v[96:99]
	v_mfma_f32_16x16x32_bf16 v[92:95], v[148:151], v[202:205], v[92:95]
	v_mfma_f32_16x16x32_bf16 v[88:91], v[162:165], v[202:205], v[88:91]
	v_mfma_f32_16x16x32_bf16 v[76:79], v[170:173], v[202:205], v[76:79]
	v_mfma_f32_16x16x32_bf16 v[72:75], v[178:181], v[202:205], v[72:75]
	v_mfma_f32_16x16x32_bf16 v[84:87], v[148:151], v[210:213], v[84:87]
	v_mfma_f32_16x16x32_bf16 v[80:83], v[162:165], v[210:213], v[80:83]
	v_mfma_f32_16x16x32_bf16 v[68:71], v[170:173], v[210:213], v[68:71]
	v_mfma_f32_16x16x32_bf16 v[64:67], v[178:181], v[210:213], v[64:67]
	s_setprio 0
	s_barrier
	s_add_i32 s22, s46, s27
	v_lshl_add_u64 v[214:215], v[214:215], 0, s[12:13]
	s_mov_b32 m0, s22
	ds_read_b128 v[182:185], v157 offset:49152
	ds_read_b128 v[186:189], v157 offset:50176
	ds_read_b128 v[190:193], v157 offset:51200
	ds_read_b128 v[194:197], v157 offset:52224
	ds_read_b128 v[198:201], v157 offset:53248
	ds_read_b128 v[202:205], v157 offset:54272
	ds_read_b128 v[206:209], v157 offset:55296
	ds_read_b128 v[210:213], v157 offset:56320
	global_load_lds_dwordx4 v[214:215], off
	s_add_i32 m0, s22, 0x2000
	s_add_u32 s20, s20, 0x160080
	v_lshl_add_u64 v[214:215], v[216:217], 0, s[12:13]
	s_addc_u32 s21, s21, 0
	s_add_i32 s22, s47, s27
	global_load_lds_dwordx4 v[214:215], off
	v_lshl_add_u64 v[214:215], s[20:21], 0, v[130:131]
	s_mov_b32 m0, s22
	s_nop 0
	global_load_lds_dwordx4 v[214:215], off
	v_lshl_add_u64 v[214:215], s[20:21], 0, v[134:135]
	s_add_i32 m0, s22, 0x2000
	s_nop 0
	global_load_lds_dwordx4 v[214:215], off
	v_lshl_add_u64 v[214:215], v[218:219], 0, s[12:13]
	s_mov_b32 m0, s36
	s_nop 0
	global_load_lds_dwordx4 v[214:215], off
	v_lshl_add_u64 v[214:215], v[220:221], 0, s[12:13]
	s_mov_b32 m0, s37
	s_nop 0
	global_load_lds_dwordx4 v[214:215], off
	s_waitcnt vmcnt(8)
	s_waitcnt lgkmcnt(0)
	s_barrier
	s_setprio 1
	s_waitcnt lgkmcnt(0)
	v_mfma_f32_16x16x32_bf16 v[60:63], v[144:147], v[182:185], v[60:63]
	v_mfma_f32_16x16x32_bf16 v[56:59], v[158:161], v[182:185], v[56:59]
	v_mfma_f32_16x16x32_bf16 v[44:47], v[166:169], v[182:185], v[44:47]
	v_mfma_f32_16x16x32_bf16 v[40:43], v[174:177], v[182:185], v[40:43]
	v_mfma_f32_16x16x32_bf16 v[52:55], v[144:147], v[190:193], v[52:55]
	v_mfma_f32_16x16x32_bf16 v[48:51], v[158:161], v[190:193], v[48:51]
	v_mfma_f32_16x16x32_bf16 v[36:39], v[166:169], v[190:193], v[36:39]
	v_mfma_f32_16x16x32_bf16 v[32:35], v[174:177], v[190:193], v[32:35]
	v_mfma_f32_16x16x32_bf16 v[28:31], v[144:147], v[198:201], v[28:31]
	v_mfma_f32_16x16x32_bf16 v[24:27], v[158:161], v[198:201], v[24:27]
	v_mfma_f32_16x16x32_bf16 v[12:15], v[166:169], v[198:201], v[12:15]
	v_mfma_f32_16x16x32_bf16 v[8:11], v[174:177], v[198:201], v[8:11]
	v_mfma_f32_16x16x32_bf16 v[20:23], v[144:147], v[206:209], v[20:23]
	v_mfma_f32_16x16x32_bf16 v[16:19], v[158:161], v[206:209], v[16:19]
	v_mfma_f32_16x16x32_bf16 v[4:7], v[166:169], v[206:209], v[4:7]
	v_mfma_f32_16x16x32_bf16 v[0:3], v[174:177], v[206:209], v[0:3]
	s_setprio 0
	s_setprio 1
	v_mfma_f32_16x16x32_bf16 v[60:63], v[148:151], v[186:189], v[60:63]
	v_mfma_f32_16x16x32_bf16 v[56:59], v[162:165], v[186:189], v[56:59]
	v_mfma_f32_16x16x32_bf16 v[44:47], v[170:173], v[186:189], v[44:47]
	v_mfma_f32_16x16x32_bf16 v[40:43], v[178:181], v[186:189], v[40:43]
	v_mfma_f32_16x16x32_bf16 v[52:55], v[148:151], v[194:197], v[52:55]
	v_mfma_f32_16x16x32_bf16 v[48:51], v[162:165], v[194:197], v[48:51]
	v_mfma_f32_16x16x32_bf16 v[36:39], v[170:173], v[194:197], v[36:39]
	v_mfma_f32_16x16x32_bf16 v[32:35], v[178:181], v[194:197], v[32:35]
	v_mfma_f32_16x16x32_bf16 v[28:31], v[148:151], v[202:205], v[28:31]
	v_mfma_f32_16x16x32_bf16 v[24:27], v[162:165], v[202:205], v[24:27]
	v_mfma_f32_16x16x32_bf16 v[12:15], v[170:173], v[202:205], v[12:15]
	v_mfma_f32_16x16x32_bf16 v[8:11], v[178:181], v[202:205], v[8:11]
	v_mfma_f32_16x16x32_bf16 v[20:23], v[148:151], v[210:213], v[20:23]
	v_mfma_f32_16x16x32_bf16 v[16:19], v[162:165], v[210:213], v[16:19]
	v_mfma_f32_16x16x32_bf16 v[4:7], v[170:173], v[210:213], v[4:7]
	v_mfma_f32_16x16x32_bf16 v[0:3], v[178:181], v[210:213], v[0:3]
	s_setprio 0
	s_barrier
	s_add_i32 s45, s45, 2
	s_add_u32 s18, s18, 0x100
	s_addc_u32 s19, s19, 0
	s_add_u32 s0, s0, 0x100
	s_addc_u32 s1, s1, 0
	s_cmpk_gt_u32 s45, 0x55
	s_cbranch_scc0 .LBB0_3930
	s_and_b64 vcc, exec, s[14:15]
	s_cbranch_vccz .LBB0_3933
	s_barrier
